# k10
# speedup vs baseline: 1.0808x; 1.0242x over previous
.LBB0_5:
	s_cmpk_lt_i32 s72, 0x200
	s_cselect_b64 s[2:3], -1, 0
	v_writelane_b32 v254, s2, 38
	s_add_u32 s0, s0, 0x88
	s_addc_u32 s1, s1, 0
	v_writelane_b32 v254, s3, 39
	v_writelane_b32 v254, s0, 40
	s_cmpk_lt_i32 s72, 0x800
	v_mov_b32_e32 v253, 0
	v_writelane_b32 v254, s1, 41
	s_cselect_b64 s[0:1], -1, 0
	v_writelane_b32 v254, s0, 42
	s_movk_i32 s74, 0xe000
	s_movk_i32 s61, 0xff00
	v_writelane_b32 v254, s1, 43
	s_lshl_b32 s0, s72, 4
	s_cmpk_lt_i32 s72, 0x400
	v_writelane_b32 v254, s0, 44
	s_cselect_b64 s[0:1], -1, 0
	v_writelane_b32 v254, s0, 45
	s_mov_b32 s94, 0x1ffff80
	s_movk_i32 s95, 0x410
	v_writelane_b32 v254, s1, 46
	s_lshl_b32 s0, s72, 2
	v_writelane_b32 v254, s0, 47
	s_lshl_b32 s0, s72, 5
	s_cmpk_lt_i32 s72, 0x100
	v_writelane_b32 v254, s0, 48
	s_cselect_b64 s[0:1], -1, 0
	v_writelane_b32 v254, s0, 49
	s_cmpk_lt_i32 s72, 0xc00
	v_mov_b32_e32 v251, 0x3727c5ac
	v_writelane_b32 v254, s1, 50
	s_cselect_b64 s[0:1], -1, 0
	v_writelane_b32 v254, s0, 51
	s_movk_i32 s27, 0x90
	s_movk_i32 s23, 0x110
	v_writelane_b32 v254, s1, 52
	s_movk_i32 s33, 0xff80
	v_readlane_b32 s0, v254, 1
	v_readlane_b32 s14, v254, 15
	v_readlane_b32 s1, v254, 2
	v_readlane_b32 s15, v254, 16
	s_add_u32 s0, s14, 0x4031200
	s_addc_u32 s1, s15, 0
	s_add_u32 s30, s14, 0x4031400
	s_addc_u32 s31, s15, 0
	s_add_u32 s40, s14, 0x4031500
	s_addc_u32 s41, s15, 0
	s_add_u32 s66, s14, 0x4031600
	s_addc_u32 s67, s15, 0
	s_add_u32 s68, s14, 0x4031700
	s_addc_u32 s69, s15, 0
	s_add_u32 s70, s14, 0x4031800
	s_addc_u32 s71, s15, 0
	s_add_u32 s76, s14, 0x4031900
	s_addc_u32 s77, s15, 0
	s_add_u32 s78, s14, 0x4031a00
	s_addc_u32 s79, s15, 0
	s_add_u32 s80, s14, 0x4031b00
	s_addc_u32 s81, s15, 0
	s_add_u32 s82, s14, 0x4031c00
	s_addc_u32 s83, s15, 0
	s_add_u32 s84, s14, 0x4031d00
	s_addc_u32 s85, s15, 0
	s_add_u32 s86, s14, 0x4031e00
	s_addc_u32 s87, s15, 0
	s_add_u32 s88, s14, 0x4031f00
	s_addc_u32 s89, s15, 0
	s_add_u32 s90, s14, 0x4032000
	s_addc_u32 s91, s15, 0
	s_add_u32 s92, s14, 0x4032100
	v_readlane_b32 s2, v254, 3
	v_readlane_b32 s3, v254, 4
	v_readlane_b32 s4, v254, 5
	v_readlane_b32 s5, v254, 6
	v_readlane_b32 s6, v254, 7
	v_readlane_b32 s7, v254, 8
	v_readlane_b32 s8, v254, 9
	v_readlane_b32 s9, v254, 10
	v_readlane_b32 s10, v254, 11
	v_readlane_b32 s11, v254, 12
	v_readlane_b32 s12, v254, 13
	v_readlane_b32 s13, v254, 14
	v_writelane_b32 v254, s0, 53
	s_addc_u32 s93, s15, 0
	s_movk_i32 s25, 0x210
	v_writelane_b32 v254, s1, 54
	s_add_u32 s0, s14, 0x4032200
	s_addc_u32 s1, s15, 0
	v_writelane_b32 v254, s0, 55
	s_mov_b32 s43, 0x43e00000
	s_movk_i32 s37, 0x3fff
	v_writelane_b32 v254, s1, 56
	s_add_u32 s0, s14, 0x4032300
	s_addc_u32 s1, s15, 0
	v_writelane_b32 v254, s0, 57
	s_movk_i32 s63, 0x7fff
	s_brev_b32 s75, 1
	v_writelane_b32 v254, s1, 58
	s_add_u32 s0, s14, 0x4034400
	s_addc_u32 s1, s15, 0
	v_writelane_b32 v254, s0, 59
	s_mov_b32 s59, 0x15000
	s_mov_b32 s36, 0x1a100000
	v_writelane_b32 v254, s1, 60
	s_add_u32 s0, s14, 0x4034500
	s_addc_u32 s1, s15, 0
	v_writelane_b32 v254, s0, 61
	s_mov_b32 s35, 0
	s_mov_b64 s[48:49], 0x2418080
	v_writelane_b32 v254, s1, 62
	s_add_u32 s0, s4, 0xc00303c
	s_addc_u32 s1, s5, 0
	v_writelane_b32 v254, s0, 63
	s_mov_b64 s[28:29], 0x241c080
	s_mov_b32 s24, 0x3fd744fd
	v_writelane_b32 v255, s1, 0
	s_add_u32 s0, s14, 0x4100800
	s_addc_u32 s1, s15, 0
	v_writelane_b32 v255, s0, 1
	s_mov_b64 s[38:39], 0x8100080
	s_mov_b64 s[44:45], 0x8104080
	v_writelane_b32 v255, s1, 2
	s_add_u32 s0, s6, 0xc00303c
	s_addc_u32 s1, s7, 0
	v_writelane_b32 v255, s0, 3
	s_mov_b64 s[2:3], 0x8108080
	s_mov_b64 s[46:47], 0x810c080
	v_writelane_b32 v255, s1, 4
	s_add_u32 s0, s14, 0x6100800
	s_addc_u32 s1, s15, 0
	v_writelane_b32 v255, s0, 5
	s_mov_b64 s[50:51], 0x8110080
	s_mov_b64 s[52:53], 0x8114080
	v_writelane_b32 v255, s1, 6
	s_add_u32 s0, s4, 0x800303c
	s_addc_u32 s1, s5, 0
	v_writelane_b32 v255, s0, 7
	s_mov_b64 s[54:55], 0x8118080
	s_mov_b64 s[56:57], 0x811c080
	v_writelane_b32 v255, s1, 8
	s_add_u32 s0, s6, 0x800303c
	s_addc_u32 s1, s7, 0
	v_writelane_b32 v255, s0, 9
	s_mov_b32 s58, 0x3e38aa3b
	s_nop 0
	v_writelane_b32 v255, s1, 10
	s_add_u32 s0, s4, 0x303c
	s_addc_u32 s1, s5, 0
	v_writelane_b32 v255, s0, 11
	s_nop 1
	v_writelane_b32 v255, s1, 12
	s_add_u32 s0, s6, 0x303c
	s_addc_u32 s1, s7, 0
	v_writelane_b32 v255, s0, 13
	s_nop 1
	v_writelane_b32 v255, s1, 14
	v_writelane_b32 v255, s72, 15
	v_writelane_b32 v255, 0, 63
	v_writelane_b32 v255, 0, 62
	s_nop 1
	v_writelane_b32 v255, s73, 16
	v_writelane_b32 v255, s30, 17
	s_nop 1
	v_writelane_b32 v255, s31, 18
	v_writelane_b32 v255, s40, 19
	s_nop 1
	v_writelane_b32 v255, s41, 20
	v_writelane_b32 v255, s66, 21
	s_nop 1
	v_writelane_b32 v255, s67, 22
	v_writelane_b32 v255, s68, 23
	s_nop 1
	v_writelane_b32 v255, s69, 24
	v_writelane_b32 v255, s70, 25
	s_nop 1
	v_writelane_b32 v255, s71, 26
	v_writelane_b32 v255, s76, 27
	s_nop 1
	v_writelane_b32 v255, s77, 28
	v_writelane_b32 v255, s78, 29
	s_nop 1
	v_writelane_b32 v255, s79, 30
	v_writelane_b32 v255, s80, 31
	s_nop 1
	v_writelane_b32 v255, s81, 32
	v_writelane_b32 v255, s82, 33
	s_nop 1
	v_writelane_b32 v255, s83, 34
	v_writelane_b32 v255, s84, 35
	s_nop 1
	v_writelane_b32 v255, s85, 36
	v_writelane_b32 v255, s86, 37
	s_nop 1
	v_writelane_b32 v255, s87, 38
	v_writelane_b32 v255, s88, 39
	s_nop 1
	v_writelane_b32 v255, s89, 40
	v_writelane_b32 v255, s90, 41
	s_nop 1
	v_writelane_b32 v255, s91, 42
	v_writelane_b32 v255, s92, 43
	s_nop 1
	v_writelane_b32 v255, s93, 44
	s_branch .LBB0_9

.LBB0_17:
	s_add_i32 s9, s8, 0xffff8000
	s_and_b32 s9, s9, 0x8000
	s_lshl_b32 s9, s9, 1
	v_lshl_or_b32 v250, v14, 1, s9
	v_add_u32_e32 v249, v250, v10
	v_add_u32_e32 v250, v250, v9
	ds_read_b128 v[16:19], v249
	ds_read_b128 v[20:23], v250 offset:32768
	ds_read_b128 v[24:27], v250 offset:36864
	ds_read_b128 v[28:31], v250 offset:40960
	ds_read_b128 v[32:35], v250 offset:45056
	ds_read_b128 v[48:51], v249 offset:4096
	s_waitcnt lgkmcnt(4)
	v_mfma_f32_32x32x16_bf16 a[192:207], v[16:19], v[20:23], a[192:207]
	s_waitcnt lgkmcnt(3)
	v_mfma_f32_32x32x16_bf16 a[128:143], v[16:19], v[24:27], a[128:143]
	s_and_b32 s98, s8, 0x8000
	s_lshl_b32 s98, s98, 1
	s_add_i32 s98, s22, s98
	v_lshl_add_u64 v[38:39], v[0:1], 0, s[0:1]
	v_lshl_add_u64 v[40:41], v[38:39], 0, s[70:71]
	s_mov_b32 m0, s98
	s_add_i32 s19, s98, 0x8000
	global_load_lds_dwordx4 v[40:41], off
	s_waitcnt lgkmcnt(2)
	v_mfma_f32_32x32x16_bf16 a[64:79], v[16:19], v[28:31], a[64:79]
	v_lshl_add_u64 v[40:41], v[4:5], 0, s[0:1]
	s_mov_b64 s[10:11], 0x22100080
	v_lshl_add_u64 v[42:43], v[40:41], 0, s[10:11]
	s_mov_b32 m0, s19
	s_mov_b64 s[10:11], 0x22104080
	global_load_lds_dwordx4 v[42:43], off
	s_waitcnt lgkmcnt(1)
	v_mfma_f32_32x32x16_bf16 a[0:15], v[16:19], v[32:35], a[0:15]
	v_lshl_add_u64 v[42:43], v[2:3], 0, s[0:1]
	v_lshl_add_u64 v[44:45], v[42:43], 0, s[76:77]
	s_add_i32 m0, s98, 0x400
	s_nop 0
	global_load_lds_dwordx4 v[44:45], off
	ds_read_b128 v[16:19], v249 offset:8192
	s_waitcnt lgkmcnt(1)
	v_mfma_f32_32x32x16_bf16 a[208:223], v[48:51], v[20:23], a[208:223]
	v_lshl_add_u64 v[44:45], v[6:7], 0, s[0:1]
	v_lshl_add_u64 v[46:47], v[44:45], 0, s[10:11]
	s_add_i32 m0, s98, 0x8400
	s_mov_b64 s[10:11], 0x22108080
	global_load_lds_dwordx4 v[46:47], off
	v_mfma_f32_32x32x16_bf16 a[144:159], v[48:51], v[24:27], a[144:159]
	v_lshl_add_u64 v[46:47], v[38:39], 0, s[78:79]
	s_add_i32 m0, s98, 0x800
	s_nop 0
	global_load_lds_dwordx4 v[46:47], off
	v_mfma_f32_32x32x16_bf16 a[80:95], v[48:51], v[28:31], a[80:95]
	v_lshl_add_u64 v[46:47], v[40:41], 0, s[10:11]
	s_add_i32 m0, s98, 0x8800
	s_mov_b64 s[10:11], 0x2210c080
	global_load_lds_dwordx4 v[46:47], off
	v_mfma_f32_32x32x16_bf16 a[16:31], v[48:51], v[32:35], a[16:31]
	v_lshl_add_u64 v[46:47], v[42:43], 0, s[80:81]
	s_add_i32 m0, s98, 0xc00
	s_nop 0
	global_load_lds_dwordx4 v[46:47], off
	ds_read_b128 v[48:51], v249 offset:12288
	s_waitcnt lgkmcnt(1)
	v_mfma_f32_32x32x16_bf16 a[224:239], v[16:19], v[20:23], a[224:239]
	v_lshl_add_u64 v[46:47], v[44:45], 0, s[10:11]
	s_add_i32 m0, s98, 0x8c00
	s_mov_b64 s[10:11], 0x22110080
	global_load_lds_dwordx4 v[46:47], off
	v_mfma_f32_32x32x16_bf16 a[160:175], v[16:19], v[24:27], a[160:175]
	v_lshl_add_u64 v[46:47], v[38:39], 0, s[82:83]
	s_add_i32 m0, s98, 0x1000
	v_lshl_add_u64 v[38:39], v[38:39], 0, s[48:49]
	global_load_lds_dwordx4 v[46:47], off
	v_mfma_f32_32x32x16_bf16 a[96:111], v[16:19], v[28:31], a[96:111]
	v_lshl_add_u64 v[46:47], v[40:41], 0, s[10:11]
	s_add_i32 m0, s98, 0x9000
	s_mov_b64 s[10:11], 0x22114080
	global_load_lds_dwordx4 v[46:47], off
	v_mfma_f32_32x32x16_bf16 a[32:47], v[16:19], v[32:35], a[32:47]
	v_lshl_add_u64 v[46:47], v[42:43], 0, s[84:85]
	s_add_i32 m0, s98, 0x1400
	s_nop 0
	global_load_lds_dwordx4 v[46:47], off
	v_lshl_or_b32 v250, v13, 1, s9
	v_add_u32_e32 v249, v250, v10
	v_add_u32_e32 v250, v250, v9
	ds_read_b128 v[16:19], v249
	s_waitcnt lgkmcnt(1)
	v_mfma_f32_32x32x16_bf16 a[240:255], v[48:51], v[20:23], a[240:255]
	v_lshl_add_u64 v[46:47], v[44:45], 0, s[10:11]
	s_add_i32 m0, s98, 0x9400
	s_mov_b64 s[10:11], 0x22118080
	global_load_lds_dwordx4 v[46:47], off
	ds_read_b128 v[20:23], v250 offset:32768
	v_mfma_f32_32x32x16_bf16 a[176:191], v[48:51], v[24:27], a[176:191]
	s_add_i32 m0, s98, 0x1800
	s_nop 0
	global_load_lds_dwordx4 v[38:39], off
	ds_read_b128 v[24:27], v250 offset:36864
	v_mfma_f32_32x32x16_bf16 a[112:127], v[48:51], v[28:31], a[112:127]
	v_lshl_add_u64 v[38:39], v[40:41], 0, s[10:11]
	s_add_i32 m0, s98, 0x9800
	s_mov_b64 s[10:11], 0x2211c080
	global_load_lds_dwordx4 v[38:39], off
	ds_read_b128 v[28:31], v250 offset:40960
	v_mfma_f32_32x32x16_bf16 a[48:63], v[48:51], v[32:35], a[48:63]
	v_lshl_add_u64 v[38:39], v[42:43], 0, s[28:29]
	s_add_i32 m0, s98, 0x1c00
	s_nop 0
	global_load_lds_dwordx4 v[38:39], off
	ds_read_b128 v[32:35], v250 offset:45056
	ds_read_b128 v[48:51], v249 offset:4096
	s_waitcnt lgkmcnt(4)
	v_mfma_f32_32x32x16_bf16 a[192:207], v[16:19], v[20:23], a[192:207]
	v_lshl_add_u64 v[38:39], v[44:45], 0, s[10:11]
	s_add_i32 m0, s98, 0x9c00
	s_nop 0
	global_load_lds_dwordx4 v[38:39], off
	s_waitcnt lgkmcnt(3)
	v_mfma_f32_32x32x16_bf16 a[128:143], v[16:19], v[24:27], a[128:143]
	s_waitcnt lgkmcnt(2)
	v_mfma_f32_32x32x16_bf16 a[64:79], v[16:19], v[28:31], a[64:79]
	s_waitcnt lgkmcnt(1)
	v_mfma_f32_32x32x16_bf16 a[0:15], v[16:19], v[32:35], a[0:15]
	ds_read_b128 v[16:19], v249 offset:8192
	s_waitcnt lgkmcnt(1)
	v_mfma_f32_32x32x16_bf16 a[208:223], v[48:51], v[20:23], a[208:223]
	v_mfma_f32_32x32x16_bf16 a[144:159], v[48:51], v[24:27], a[144:159]
	v_mfma_f32_32x32x16_bf16 a[80:95], v[48:51], v[28:31], a[80:95]
	v_mfma_f32_32x32x16_bf16 a[16:31], v[48:51], v[32:35], a[16:31]
	ds_read_b128 v[48:51], v249 offset:12288
	s_waitcnt lgkmcnt(1)
	v_mfma_f32_32x32x16_bf16 a[224:239], v[16:19], v[20:23], a[224:239]
	v_mfma_f32_32x32x16_bf16 a[160:175], v[16:19], v[24:27], a[160:175]
	v_mfma_f32_32x32x16_bf16 a[96:111], v[16:19], v[28:31], a[96:111]
	v_mfma_f32_32x32x16_bf16 a[32:47], v[16:19], v[32:35], a[32:47]
	v_lshl_or_b32 v250, v12, 1, s9
	v_add_u32_e32 v249, v250, v10
	v_add_u32_e32 v250, v250, v9
	ds_read_b128 v[16:19], v249
	s_waitcnt lgkmcnt(1)
	v_mfma_f32_32x32x16_bf16 a[240:255], v[48:51], v[20:23], a[240:255]
	ds_read_b128 v[20:23], v250 offset:32768
	v_mfma_f32_32x32x16_bf16 a[176:191], v[48:51], v[24:27], a[176:191]
	ds_read_b128 v[24:27], v250 offset:36864
	v_mfma_f32_32x32x16_bf16 a[112:127], v[48:51], v[28:31], a[112:127]
	ds_read_b128 v[28:31], v250 offset:40960
	v_mfma_f32_32x32x16_bf16 a[48:63], v[48:51], v[32:35], a[48:63]
	ds_read_b128 v[32:35], v250 offset:45056
	ds_read_b128 v[48:51], v249 offset:4096
	s_waitcnt lgkmcnt(4)
	v_mfma_f32_32x32x16_bf16 a[192:207], v[16:19], v[20:23], a[192:207]
	s_waitcnt lgkmcnt(3)
	v_mfma_f32_32x32x16_bf16 a[128:143], v[16:19], v[24:27], a[128:143]
	s_waitcnt lgkmcnt(2)
	v_mfma_f32_32x32x16_bf16 a[64:79], v[16:19], v[28:31], a[64:79]
	s_waitcnt lgkmcnt(1)
	v_mfma_f32_32x32x16_bf16 a[0:15], v[16:19], v[32:35], a[0:15]
	ds_read_b128 v[16:19], v249 offset:8192
	s_waitcnt lgkmcnt(1)
	v_mfma_f32_32x32x16_bf16 a[208:223], v[48:51], v[20:23], a[208:223]
	v_mfma_f32_32x32x16_bf16 a[144:159], v[48:51], v[24:27], a[144:159]
	v_mfma_f32_32x32x16_bf16 a[80:95], v[48:51], v[28:31], a[80:95]
	v_mfma_f32_32x32x16_bf16 a[16:31], v[48:51], v[32:35], a[16:31]
	ds_read_b128 v[48:51], v249 offset:12288
	s_waitcnt lgkmcnt(1)
	v_mfma_f32_32x32x16_bf16 a[224:239], v[16:19], v[20:23], a[224:239]
	v_mfma_f32_32x32x16_bf16 a[160:175], v[16:19], v[24:27], a[160:175]
	v_mfma_f32_32x32x16_bf16 a[96:111], v[16:19], v[28:31], a[96:111]
	v_mfma_f32_32x32x16_bf16 a[32:47], v[16:19], v[32:35], a[32:47]
	v_lshl_or_b32 v250, v11, 1, s9
	v_add_u32_e32 v249, v250, v10
	v_add_u32_e32 v250, v250, v9
	ds_read_b128 v[16:19], v249
	s_waitcnt lgkmcnt(1)
	v_mfma_f32_32x32x16_bf16 a[240:255], v[48:51], v[20:23], a[240:255]
	ds_read_b128 v[20:23], v250 offset:32768
	v_mfma_f32_32x32x16_bf16 a[176:191], v[48:51], v[24:27], a[176:191]
	ds_read_b128 v[24:27], v250 offset:36864
	v_mfma_f32_32x32x16_bf16 a[112:127], v[48:51], v[28:31], a[112:127]
	ds_read_b128 v[28:31], v250 offset:40960
	v_mfma_f32_32x32x16_bf16 a[48:63], v[48:51], v[32:35], a[48:63]
	ds_read_b128 v[32:35], v250 offset:45056
	ds_read_b128 v[48:51], v249 offset:4096
	s_waitcnt lgkmcnt(4)
	v_mfma_f32_32x32x16_bf16 a[192:207], v[16:19], v[20:23], a[192:207]
	s_waitcnt lgkmcnt(3)
	v_mfma_f32_32x32x16_bf16 a[128:143], v[16:19], v[24:27], a[128:143]
	s_waitcnt lgkmcnt(2)
	v_mfma_f32_32x32x16_bf16 a[64:79], v[16:19], v[28:31], a[64:79]
	s_waitcnt lgkmcnt(1)
	v_mfma_f32_32x32x16_bf16 a[0:15], v[16:19], v[32:35], a[0:15]
	ds_read_b128 v[16:19], v249 offset:8192
	s_waitcnt lgkmcnt(1)
	v_mfma_f32_32x32x16_bf16 a[208:223], v[48:51], v[20:23], a[208:223]
	v_mfma_f32_32x32x16_bf16 a[144:159], v[48:51], v[24:27], a[144:159]
	v_mfma_f32_32x32x16_bf16 a[80:95], v[48:51], v[28:31], a[80:95]
	v_mfma_f32_32x32x16_bf16 a[16:31], v[48:51], v[32:35], a[16:31]
	ds_read_b128 v[48:51], v249 offset:12288
	s_waitcnt lgkmcnt(1)
	v_mfma_f32_32x32x16_bf16 a[224:239], v[16:19], v[20:23], a[224:239]
	v_mfma_f32_32x32x16_bf16 a[160:175], v[16:19], v[24:27], a[160:175]
	v_mfma_f32_32x32x16_bf16 a[96:111], v[16:19], v[28:31], a[96:111]
	v_mfma_f32_32x32x16_bf16 a[32:47], v[16:19], v[32:35], a[32:47]
	s_waitcnt vmcnt(0)
	s_waitcnt vmcnt(0) lgkmcnt(0)
	s_barrier
	s_add_u32 s0, s0, 0x80
	s_addc_u32 s1, s1, 0
	s_add_i32 s8, s8, 0x8000
	s_cmpk_lg_i32 s0, 0x780
	v_mfma_f32_32x32x16_bf16 a[240:255], v[48:51], v[20:23], a[240:255]
	v_mfma_f32_32x32x16_bf16 a[176:191], v[48:51], v[24:27], a[176:191]
	v_mfma_f32_32x32x16_bf16 a[112:127], v[48:51], v[28:31], a[112:127]
	v_mfma_f32_32x32x16_bf16 a[48:63], v[48:51], v[32:35], a[48:63]
	s_cbranch_scc1 .LBB0_17
	v_lshlrev_b32_e32 v22, 1, v14
	s_mov_b32 s0, 0x10000
	s_mov_b32 s1, 0x18000
	v_add3_u32 v18, v10, v22, s0
	v_add3_u32 v34, v9, v22, s1
	ds_read_b128 v[0:3], v18
	ds_read_b128 v[4:7], v18 offset:4096
	ds_read_b128 v[14:17], v18 offset:8192
	ds_read_b128 v[18:21], v18 offset:12288
	ds_read_b128 v[22:25], v34
	ds_read_b128 v[26:29], v34 offset:4096
	ds_read_b128 v[30:33], v34 offset:8192
	ds_read_b128 v[34:37], v34 offset:12288
	s_waitcnt lgkmcnt(3)
	v_mfma_f32_32x32x16_bf16 a[192:207], v[0:3], v[22:25], a[192:207]
	v_lshlrev_b32_e32 v13, 1, v13
	s_waitcnt lgkmcnt(2)
	v_mfma_f32_32x32x16_bf16 a[128:143], v[0:3], v[26:29], a[128:143]
	s_waitcnt lgkmcnt(1)
	v_mfma_f32_32x32x16_bf16 a[64:79], v[0:3], v[30:33], a[64:79]
	s_waitcnt lgkmcnt(0)
	v_mfma_f32_32x32x16_bf16 a[0:15], v[0:3], v[34:37], a[0:15]
	v_mfma_f32_32x32x16_bf16 a[208:223], v[4:7], v[22:25], a[208:223]
	v_mfma_f32_32x32x16_bf16 a[144:159], v[4:7], v[26:29], a[144:159]
	v_mfma_f32_32x32x16_bf16 a[80:95], v[4:7], v[30:33], a[80:95]
	v_mfma_f32_32x32x16_bf16 a[16:31], v[4:7], v[34:37], a[16:31]
	v_mfma_f32_32x32x16_bf16 a[224:239], v[14:17], v[22:25], a[224:239]
	v_mfma_f32_32x32x16_bf16 a[160:175], v[14:17], v[26:29], a[160:175]
	v_mfma_f32_32x32x16_bf16 a[96:111], v[14:17], v[30:33], a[96:111]
	v_mfma_f32_32x32x16_bf16 a[32:47], v[14:17], v[34:37], a[32:47]
	v_mfma_f32_32x32x16_bf16 a[240:255], v[18:21], v[22:25], a[240:255]
	v_mfma_f32_32x32x16_bf16 a[176:191], v[18:21], v[26:29], a[176:191]
	v_mfma_f32_32x32x16_bf16 a[112:127], v[18:21], v[30:33], a[112:127]
	v_mfma_f32_32x32x16_bf16 a[48:63], v[18:21], v[34:37], a[48:63]
	v_add3_u32 v18, v10, v13, s0
	v_add3_u32 v13, v9, v13, s1
	ds_read_b128 v[0:3], v18
	ds_read_b128 v[4:7], v18 offset:4096
	ds_read_b128 v[14:17], v18 offset:8192
	ds_read_b128 v[18:21], v18 offset:12288
	ds_read_b128 v[22:25], v13
	ds_read_b128 v[26:29], v13 offset:4096
	ds_read_b128 v[30:33], v13 offset:8192
	ds_read_b128 v[34:37], v13 offset:12288
	s_waitcnt lgkmcnt(3)
	v_mfma_f32_32x32x16_bf16 a[192:207], v[0:3], v[22:25], a[192:207]
	s_waitcnt lgkmcnt(2)
	v_mfma_f32_32x32x16_bf16 a[128:143], v[0:3], v[26:29], a[128:143]
	s_waitcnt lgkmcnt(1)
	v_mfma_f32_32x32x16_bf16 a[64:79], v[0:3], v[30:33], a[64:79]
	s_waitcnt lgkmcnt(0)
	v_mfma_f32_32x32x16_bf16 a[0:15], v[0:3], v[34:37], a[0:15]
	v_mfma_f32_32x32x16_bf16 a[208:223], v[4:7], v[22:25], a[208:223]
	v_mfma_f32_32x32x16_bf16 a[144:159], v[4:7], v[26:29], a[144:159]
	v_mfma_f32_32x32x16_bf16 a[80:95], v[4:7], v[30:33], a[80:95]
	v_mfma_f32_32x32x16_bf16 a[16:31], v[4:7], v[34:37], a[16:31]
	v_mfma_f32_32x32x16_bf16 a[224:239], v[14:17], v[22:25], a[224:239]
	v_mfma_f32_32x32x16_bf16 a[160:175], v[14:17], v[26:29], a[160:175]
	v_mfma_f32_32x32x16_bf16 a[96:111], v[14:17], v[30:33], a[96:111]
	v_mfma_f32_32x32x16_bf16 a[32:47], v[14:17], v[34:37], a[32:47]
	v_mfma_f32_32x32x16_bf16 a[240:255], v[18:21], v[22:25], a[240:255]
	v_mfma_f32_32x32x16_bf16 a[176:191], v[18:21], v[26:29], a[176:191]
	v_mfma_f32_32x32x16_bf16 a[112:127], v[18:21], v[30:33], a[112:127]
	v_mfma_f32_32x32x16_bf16 a[48:63], v[18:21], v[34:37], a[48:63]
	v_lshlrev_b32_e32 v20, 1, v12
	v_add3_u32 v16, v10, v20, s0
	v_add3_u32 v32, v9, v20, s1
	ds_read_b128 v[0:3], v16
	ds_read_b128 v[4:7], v16 offset:4096
	ds_read_b128 v[12:15], v16 offset:8192
	ds_read_b128 v[16:19], v16 offset:12288
	ds_read_b128 v[20:23], v32
	ds_read_b128 v[24:27], v32 offset:4096
	ds_read_b128 v[28:31], v32 offset:8192
	ds_read_b128 v[32:35], v32 offset:12288
	s_waitcnt lgkmcnt(3)
	v_mfma_f32_32x32x16_bf16 a[192:207], v[0:3], v[20:23], a[192:207]
	s_waitcnt lgkmcnt(2)
	v_mfma_f32_32x32x16_bf16 a[128:143], v[0:3], v[24:27], a[128:143]
	s_waitcnt lgkmcnt(1)
	v_mfma_f32_32x32x16_bf16 a[64:79], v[0:3], v[28:31], a[64:79]
	s_waitcnt lgkmcnt(0)
	v_mfma_f32_32x32x16_bf16 a[0:15], v[0:3], v[32:35], a[0:15]
	v_mfma_f32_32x32x16_bf16 a[208:223], v[4:7], v[20:23], a[208:223]
	v_mfma_f32_32x32x16_bf16 a[144:159], v[4:7], v[24:27], a[144:159]
	v_mfma_f32_32x32x16_bf16 a[80:95], v[4:7], v[28:31], a[80:95]
	v_mfma_f32_32x32x16_bf16 a[16:31], v[4:7], v[32:35], a[16:31]
	v_mfma_f32_32x32x16_bf16 a[224:239], v[12:15], v[20:23], a[224:239]
	v_mfma_f32_32x32x16_bf16 a[160:175], v[12:15], v[24:27], a[160:175]
	v_mfma_f32_32x32x16_bf16 a[96:111], v[12:15], v[28:31], a[96:111]
	v_mfma_f32_32x32x16_bf16 a[32:47], v[12:15], v[32:35], a[32:47]
	v_mfma_f32_32x32x16_bf16 a[240:255], v[16:19], v[20:23], a[240:255]
	v_mfma_f32_32x32x16_bf16 a[176:191], v[16:19], v[24:27], a[176:191]
	v_mfma_f32_32x32x16_bf16 a[112:127], v[16:19], v[28:31], a[112:127]
	v_mfma_f32_32x32x16_bf16 a[48:63], v[16:19], v[32:35], a[48:63]
	v_lshlrev_b32_e32 v18, 1, v11
	v_add3_u32 v14, v10, v18, s0
	v_add3_u32 v9, v9, v18, s1
	ds_read_b128 v[0:3], v14
	ds_read_b128 v[4:7], v14 offset:4096
	ds_read_b128 v[10:13], v14 offset:8192
	ds_read_b128 v[14:17], v14 offset:12288
	ds_read_b128 v[18:21], v9
	ds_read_b128 v[22:25], v9 offset:4096
	ds_read_b128 v[26:29], v9 offset:8192
	ds_read_b128 v[30:33], v9 offset:12288
	s_mov_b32 s0, s35
	s_waitcnt vmcnt(0)
	s_waitcnt lgkmcnt(3)
	v_mfma_f32_32x32x16_bf16 a[192:207], v[0:3], v[18:21], a[192:207]
	s_waitcnt lgkmcnt(0)
	s_barrier
	v_mfma_f32_32x32x16_bf16 a[128:143], v[0:3], v[22:25], a[128:143]
	v_mfma_f32_32x32x16_bf16 a[64:79], v[0:3], v[26:29], a[64:79]
	v_mfma_f32_32x32x16_bf16 a[0:15], v[0:3], v[30:33], a[0:15]
	v_mbcnt_lo_u32_b32 v0, -1, s0
	v_mbcnt_hi_u32_b32 v0, -1, v0
	s_mov_b32 s0, 0x3fffff80
	v_bitop3_b32 v3, v0, s0, v8 bitop3:0xc8
	v_or_b32_e32 v1, s21, v0
	v_and_b32_e32 v2, 31, v0
	v_and_b32_e32 v1, 64, v1
	v_mfma_f32_32x32x16_bf16 a[208:223], v[4:7], v[18:21], a[208:223]
	v_cmp_ne_u32_e32 vcc, 0, v1
	v_mfma_f32_32x32x16_bf16 a[144:159], v[4:7], v[22:25], a[144:159]
	v_mfma_f32_32x32x16_bf16 a[80:95], v[4:7], v[26:29], a[80:95]
	v_mfma_f32_32x32x16_bf16 a[16:31], v[4:7], v[30:33], a[16:31]
	v_lshrrev_b32_e32 v4, 1, v0
	v_and_b32_e32 v4, 16, v4
	v_lshl_or_b32 v3, v3, 2, v4
	v_bitop3_b32 v0, v0, 64, s21 bitop3:0xc8
	v_mad_u32_u24 v37, v2, s95, v3
	v_cmp_eq_u32_e64 s[0:1], 0, v0
	v_add_u32_e32 v36, 0x10400, v37
	v_mfma_f32_32x32x16_bf16 a[224:239], v[10:13], v[18:21], a[224:239]
	v_add_u32_e32 v35, 0x10420, v37
	v_add_u32_e32 v34, 0x10440, v37
	v_add_u32_e32 v9, 0x18760, v37
	v_add_u32_e32 v7, 0x18780, v37
	v_add_u32_e32 v6, 0x187a0, v37
	v_add_u32_e32 v5, 0x187c0, v37
	v_add_u32_e32 v4, 0x187e0, v37
	v_mfma_f32_32x32x16_bf16 a[160:175], v[10:13], v[22:25], a[160:175]
	v_mfma_f32_32x32x16_bf16 a[96:111], v[10:13], v[26:29], a[96:111]
	v_mfma_f32_32x32x16_bf16 a[32:47], v[10:13], v[30:33], a[32:47]
	v_add_u32_e32 v13, 0x186e0, v37
	v_add_u32_e32 v12, 0x18700, v37
	v_add_u32_e32 v11, 0x18720, v37
	v_add_u32_e32 v10, 0x18740, v37
	v_mfma_f32_32x32x16_bf16 a[240:255], v[14:17], v[18:21], a[240:255]
	v_add_u32_e32 v21, 0x105e0, v37
	v_add_u32_e32 v20, 0x18600, v37
	v_add_u32_e32 v19, 0x18620, v37
	v_add_u32_e32 v18, 0x18640, v37
	v_mfma_f32_32x32x16_bf16 a[176:191], v[14:17], v[22:25], a[176:191]
	v_add_u32_e32 v25, 0x10560, v37
	v_add_u32_e32 v24, 0x10580, v37
	v_add_u32_e32 v23, 0x105a0, v37
	v_add_u32_e32 v22, 0x105c0, v37
	v_mfma_f32_32x32x16_bf16 a[112:127], v[14:17], v[26:29], a[112:127]
	v_add_u32_e32 v29, 0x104e0, v37
	v_add_u32_e32 v28, 0x10500, v37
	v_add_u32_e32 v27, 0x10520, v37
	v_add_u32_e32 v26, 0x10540, v37
	v_mfma_f32_32x32x16_bf16 a[48:63], v[14:17], v[30:33], a[48:63]
	v_add_u32_e32 v33, 0x10460, v37
	v_add_u32_e32 v32, 0x10480, v37
	v_add_u32_e32 v31, 0x104a0, v37
	v_add_u32_e32 v30, 0x104c0, v37
	v_add_u32_e32 v17, 0x18660, v37
	v_add_u32_e32 v16, 0x18680, v37
	v_add_u32_e32 v15, 0x186a0, v37
	v_add_u32_e32 v14, 0x186c0, v37
	s_and_saveexec_b64 s[8:9], s[0:1]
	s_cbranch_execz .LBB0_20
	ds_write_b128 v37, a[192:195]
	ds_write_b128 v37, a[196:199] offset:32
	ds_write_b128 v37, a[200:203] offset:64
	ds_write_b128 v37, a[204:207] offset:96
	ds_write_b128 v37, a[208:211] offset:128
	ds_write_b128 v37, a[212:215] offset:160
	ds_write_b128 v37, a[216:219] offset:192
	ds_write_b128 v37, a[220:223] offset:224
	ds_write_b128 v37, a[224:227] offset:256
	ds_write_b128 v37, a[228:231] offset:288
	ds_write_b128 v37, a[232:235] offset:320
	ds_write_b128 v37, a[236:239] offset:352
	ds_write_b128 v37, a[240:243] offset:384
	ds_write_b128 v37, a[244:247] offset:416
	ds_write_b128 v37, a[248:251] offset:448
	ds_write_b128 v37, a[252:255] offset:480
	ds_write_b128 v37, a[128:131] offset:33280
	ds_write_b128 v37, a[132:135] offset:33312
	ds_write_b128 v37, a[136:139] offset:33344
	ds_write_b128 v37, a[140:143] offset:33376
	ds_write_b128 v37, a[144:147] offset:33408
	ds_write_b128 v37, a[148:151] offset:33440
	ds_write_b128 v37, a[152:155] offset:33472
	ds_write_b128 v37, a[156:159] offset:33504
	ds_write_b128 v37, a[160:163] offset:33536
	ds_write_b128 v37, a[164:167] offset:33568
	ds_write_b128 v37, a[168:171] offset:33600
	ds_write_b128 v37, a[172:175] offset:33632
	ds_write_b128 v37, a[176:179] offset:33664
	ds_write_b128 v37, a[180:183] offset:33696
	ds_write_b128 v37, a[184:187] offset:33728
	ds_write_b128 v37, a[188:191] offset:33760
	ds_write_b128 v36, a[64:67]
	ds_write_b128 v35, a[68:71]
	ds_write_b128 v34, a[72:75]
	ds_write_b128 v33, a[76:79]
	ds_write_b128 v32, a[80:83]
	ds_write_b128 v31, a[84:87]
	ds_write_b128 v30, a[88:91]
	ds_write_b128 v29, a[92:95]
	ds_write_b128 v28, a[96:99]
	ds_write_b128 v27, a[100:103]
	ds_write_b128 v26, a[104:107]
	ds_write_b128 v25, a[108:111]
	ds_write_b128 v24, a[112:115]
	ds_write_b128 v23, a[116:119]
	ds_write_b128 v22, a[120:123]
	ds_write_b128 v21, a[124:127]
	ds_write_b128 v20, a[0:3]
	ds_write_b128 v19, a[4:7]
	ds_write_b128 v18, a[8:11]
	ds_write_b128 v17, a[12:15]
	ds_write_b128 v16, a[16:19]
	ds_write_b128 v15, a[20:23]
	ds_write_b128 v14, a[24:27]
	ds_write_b128 v13, a[28:31]
	ds_write_b128 v12, a[32:35]
	ds_write_b128 v11, a[36:39]
	ds_write_b128 v10, a[40:43]
	ds_write_b128 v9, a[44:47]
	ds_write_b128 v7, a[48:51]
	ds_write_b128 v6, a[52:55]
	ds_write_b128 v5, a[56:59]
	ds_write_b128 v4, a[60:63]

.LBB0_50:
	s_add_i32 s14, s11, 0xffff8000
	s_and_b32 s14, s14, 0x8000
	s_lshl_b32 s14, s14, 1
	v_lshl_or_b32 v181, v10, 1, s14
	v_add_u32_e32 v180, v181, v21
	v_add_u32_e32 v181, v181, v20
	ds_read_b128 v[12:15], v180
	ds_read_b128 v[24:27], v181 offset:32768
	ds_read_b128 v[28:31], v181 offset:36864
	ds_read_b128 v[32:35], v181 offset:40960
	ds_read_b128 v[36:39], v181 offset:45056
	ds_read_b128 v[112:115], v180 offset:4096
	s_waitcnt lgkmcnt(4)
	v_mfma_f32_32x32x16_bf16 a[240:255], v[12:15], v[24:27], a[240:255]
	s_waitcnt lgkmcnt(3)
	v_mfma_f32_32x32x16_bf16 a[176:191], v[12:15], v[28:31], a[176:191]
	s_and_b32 s98, s11, 0x8000
	s_lshl_b32 s98, s98, 1
	s_add_i32 s16, s40, s98
	v_lshl_add_u64 v[88:89], v[0:1], 0, s[12:13]
	s_mov_b64 s[98:99], 0x2600080
	v_lshl_add_u64 v[90:91], v[88:89], 0, s[98:99]
	s_mov_b32 m0, s16
	s_add_i32 s17, s16, 0x8000
	global_load_lds_dwordx4 v[90:91], off
	s_waitcnt lgkmcnt(2)
	v_mfma_f32_32x32x16_bf16 a[112:127], v[12:15], v[32:35], a[112:127]
	v_lshl_add_u64 v[90:91], v[4:5], 0, s[12:13]
	v_lshl_add_u64 v[92:93], v[90:91], 0, s[38:39]
	s_mov_b32 m0, s17
	s_mov_b64 s[98:99], 0x2604080
	global_load_lds_dwordx4 v[92:93], off
	s_waitcnt lgkmcnt(1)
	v_mfma_f32_32x32x16_bf16 a[48:63], v[12:15], v[36:39], a[48:63]
	v_lshl_add_u64 v[92:93], v[2:3], 0, s[12:13]
	v_lshl_add_u64 v[98:99], v[92:93], 0, s[98:99]
	s_add_i32 m0, s16, 0x400
	s_mov_b64 s[98:99], 0x2608080
	global_load_lds_dwordx4 v[98:99], off
	ds_read_b128 v[12:15], v180 offset:8192
	s_waitcnt lgkmcnt(1)
	v_mfma_f32_32x32x16_bf16 a[224:239], v[112:115], v[24:27], a[224:239]
	v_lshl_add_u64 v[98:99], v[6:7], 0, s[12:13]
	v_lshl_add_u64 v[106:107], v[98:99], 0, s[44:45]
	s_add_i32 m0, s16, 0x8400
	s_nop 0
	global_load_lds_dwordx4 v[106:107], off
	v_mfma_f32_32x32x16_bf16 a[160:175], v[112:115], v[28:31], a[160:175]
	v_lshl_add_u64 v[106:107], v[88:89], 0, s[98:99]
	s_add_i32 m0, s16, 0x800
	s_mov_b64 s[98:99], 0x260c080
	global_load_lds_dwordx4 v[106:107], off
	v_mfma_f32_32x32x16_bf16 a[96:111], v[112:115], v[32:35], a[96:111]
	v_lshl_add_u64 v[106:107], v[90:91], 0, s[2:3]
	s_add_i32 m0, s16, 0x8800
	s_nop 0
	global_load_lds_dwordx4 v[106:107], off
	v_mfma_f32_32x32x16_bf16 a[32:47], v[112:115], v[36:39], a[32:47]
	v_lshl_add_u64 v[106:107], v[92:93], 0, s[98:99]
	s_add_i32 m0, s16, 0xc00
	s_mov_b64 s[98:99], 0x2610080
	global_load_lds_dwordx4 v[106:107], off
	ds_read_b128 v[112:115], v180 offset:12288
	s_waitcnt lgkmcnt(1)
	v_mfma_f32_32x32x16_bf16 a[208:223], v[12:15], v[24:27], a[208:223]
	v_lshl_add_u64 v[106:107], v[98:99], 0, s[46:47]
	s_add_i32 m0, s16, 0x8c00
	s_nop 0
	global_load_lds_dwordx4 v[106:107], off
	v_mfma_f32_32x32x16_bf16 a[144:159], v[12:15], v[28:31], a[144:159]
	v_lshl_add_u64 v[106:107], v[88:89], 0, s[98:99]
	s_add_i32 m0, s16, 0x1000
	s_mov_b64 s[98:99], 0x2614080
	global_load_lds_dwordx4 v[106:107], off
	v_mfma_f32_32x32x16_bf16 a[80:95], v[12:15], v[32:35], a[80:95]
	v_lshl_add_u64 v[106:107], v[90:91], 0, s[50:51]
	s_add_i32 m0, s16, 0x9000
	s_nop 0
	global_load_lds_dwordx4 v[106:107], off
	v_mfma_f32_32x32x16_bf16 a[16:31], v[12:15], v[36:39], a[16:31]
	v_lshl_add_u64 v[106:107], v[92:93], 0, s[98:99]
	s_add_i32 m0, s16, 0x1400
	s_mov_b64 s[98:99], 0x2618080
	global_load_lds_dwordx4 v[106:107], off
	v_lshl_or_b32 v181, v9, 1, s14
	v_add_u32_e32 v180, v181, v21
	v_add_u32_e32 v181, v181, v20
	ds_read_b128 v[12:15], v180
	s_waitcnt lgkmcnt(1)
	v_mfma_f32_32x32x16_bf16 a[192:207], v[112:115], v[24:27], a[192:207]
	v_lshl_add_u64 v[106:107], v[98:99], 0, s[52:53]
	s_add_i32 m0, s16, 0x9400
	v_lshl_add_u64 v[88:89], v[88:89], 0, s[98:99]
	global_load_lds_dwordx4 v[106:107], off
	ds_read_b128 v[24:27], v181 offset:32768
	v_mfma_f32_32x32x16_bf16 a[128:143], v[112:115], v[28:31], a[128:143]
	s_add_i32 m0, s16, 0x1800
	s_mov_b64 s[98:99], 0x261c080
	global_load_lds_dwordx4 v[88:89], off
	ds_read_b128 v[28:31], v181 offset:36864
	v_mfma_f32_32x32x16_bf16 a[64:79], v[112:115], v[32:35], a[64:79]
	v_lshl_add_u64 v[88:89], v[90:91], 0, s[54:55]
	s_add_i32 m0, s16, 0x9800
	s_nop 0
	global_load_lds_dwordx4 v[88:89], off
	ds_read_b128 v[32:35], v181 offset:40960
	v_mfma_f32_32x32x16_bf16 a[0:15], v[112:115], v[36:39], a[0:15]
	v_lshl_add_u64 v[88:89], v[92:93], 0, s[98:99]
	s_add_i32 m0, s16, 0x1c00
	s_nop 0
	global_load_lds_dwordx4 v[88:89], off
	ds_read_b128 v[36:39], v181 offset:45056
	ds_read_b128 v[112:115], v180 offset:4096
	s_waitcnt lgkmcnt(4)
	v_mfma_f32_32x32x16_bf16 a[240:255], v[12:15], v[24:27], a[240:255]
	v_lshl_add_u64 v[88:89], v[98:99], 0, s[56:57]
	s_add_i32 m0, s16, 0x9c00
	s_nop 0
	global_load_lds_dwordx4 v[88:89], off
	s_waitcnt lgkmcnt(3)
	v_mfma_f32_32x32x16_bf16 a[176:191], v[12:15], v[28:31], a[176:191]
	s_waitcnt lgkmcnt(2)
	v_mfma_f32_32x32x16_bf16 a[112:127], v[12:15], v[32:35], a[112:127]
	s_waitcnt lgkmcnt(1)
	v_mfma_f32_32x32x16_bf16 a[48:63], v[12:15], v[36:39], a[48:63]
	ds_read_b128 v[12:15], v180 offset:8192
	s_waitcnt lgkmcnt(1)
	v_mfma_f32_32x32x16_bf16 a[224:239], v[112:115], v[24:27], a[224:239]
	v_mfma_f32_32x32x16_bf16 a[160:175], v[112:115], v[28:31], a[160:175]
	v_mfma_f32_32x32x16_bf16 a[96:111], v[112:115], v[32:35], a[96:111]
	v_mfma_f32_32x32x16_bf16 a[32:47], v[112:115], v[36:39], a[32:47]
	ds_read_b128 v[112:115], v180 offset:12288
	s_waitcnt lgkmcnt(1)
	v_mfma_f32_32x32x16_bf16 a[208:223], v[12:15], v[24:27], a[208:223]
	v_mfma_f32_32x32x16_bf16 a[144:159], v[12:15], v[28:31], a[144:159]
	v_mfma_f32_32x32x16_bf16 a[80:95], v[12:15], v[32:35], a[80:95]
	v_mfma_f32_32x32x16_bf16 a[16:31], v[12:15], v[36:39], a[16:31]
	v_lshl_or_b32 v181, v16, 1, s14
	v_add_u32_e32 v180, v181, v21
	v_add_u32_e32 v181, v181, v20
	ds_read_b128 v[12:15], v180
	s_waitcnt lgkmcnt(1)
	v_mfma_f32_32x32x16_bf16 a[192:207], v[112:115], v[24:27], a[192:207]
	ds_read_b128 v[24:27], v181 offset:32768
	v_mfma_f32_32x32x16_bf16 a[128:143], v[112:115], v[28:31], a[128:143]
	ds_read_b128 v[28:31], v181 offset:36864
	v_mfma_f32_32x32x16_bf16 a[64:79], v[112:115], v[32:35], a[64:79]
	ds_read_b128 v[32:35], v181 offset:40960
	v_mfma_f32_32x32x16_bf16 a[0:15], v[112:115], v[36:39], a[0:15]
	ds_read_b128 v[36:39], v181 offset:45056
	ds_read_b128 v[112:115], v180 offset:4096
	s_waitcnt lgkmcnt(4)
	v_mfma_f32_32x32x16_bf16 a[240:255], v[12:15], v[24:27], a[240:255]
	s_waitcnt lgkmcnt(3)
	v_mfma_f32_32x32x16_bf16 a[176:191], v[12:15], v[28:31], a[176:191]
	s_waitcnt lgkmcnt(2)
	v_mfma_f32_32x32x16_bf16 a[112:127], v[12:15], v[32:35], a[112:127]
	s_waitcnt lgkmcnt(1)
	v_mfma_f32_32x32x16_bf16 a[48:63], v[12:15], v[36:39], a[48:63]
	ds_read_b128 v[12:15], v180 offset:8192
	s_waitcnt lgkmcnt(1)
	v_mfma_f32_32x32x16_bf16 a[224:239], v[112:115], v[24:27], a[224:239]
	v_mfma_f32_32x32x16_bf16 a[160:175], v[112:115], v[28:31], a[160:175]
	v_mfma_f32_32x32x16_bf16 a[96:111], v[112:115], v[32:35], a[96:111]
	v_mfma_f32_32x32x16_bf16 a[32:47], v[112:115], v[36:39], a[32:47]
	ds_read_b128 v[112:115], v180 offset:12288
	s_waitcnt lgkmcnt(1)
	v_mfma_f32_32x32x16_bf16 a[208:223], v[12:15], v[24:27], a[208:223]
	v_mfma_f32_32x32x16_bf16 a[144:159], v[12:15], v[28:31], a[144:159]
	v_mfma_f32_32x32x16_bf16 a[80:95], v[12:15], v[32:35], a[80:95]
	v_mfma_f32_32x32x16_bf16 a[16:31], v[12:15], v[36:39], a[16:31]
	v_lshl_or_b32 v181, v22, 1, s14
	v_add_u32_e32 v180, v181, v21
	v_add_u32_e32 v181, v181, v20
	ds_read_b128 v[12:15], v180
	s_waitcnt lgkmcnt(1)
	v_mfma_f32_32x32x16_bf16 a[192:207], v[112:115], v[24:27], a[192:207]
	ds_read_b128 v[24:27], v181 offset:32768
	v_mfma_f32_32x32x16_bf16 a[128:143], v[112:115], v[28:31], a[128:143]
	ds_read_b128 v[28:31], v181 offset:36864
	v_mfma_f32_32x32x16_bf16 a[64:79], v[112:115], v[32:35], a[64:79]
	ds_read_b128 v[32:35], v181 offset:40960
	v_mfma_f32_32x32x16_bf16 a[0:15], v[112:115], v[36:39], a[0:15]
	ds_read_b128 v[36:39], v181 offset:45056
	ds_read_b128 v[112:115], v180 offset:4096
	s_waitcnt lgkmcnt(4)
	v_mfma_f32_32x32x16_bf16 a[240:255], v[12:15], v[24:27], a[240:255]
	s_waitcnt lgkmcnt(3)
	v_mfma_f32_32x32x16_bf16 a[176:191], v[12:15], v[28:31], a[176:191]
	s_waitcnt lgkmcnt(2)
	v_mfma_f32_32x32x16_bf16 a[112:127], v[12:15], v[32:35], a[112:127]
	s_waitcnt lgkmcnt(1)
	v_mfma_f32_32x32x16_bf16 a[48:63], v[12:15], v[36:39], a[48:63]
	ds_read_b128 v[12:15], v180 offset:8192
	s_waitcnt lgkmcnt(1)
	v_mfma_f32_32x32x16_bf16 a[224:239], v[112:115], v[24:27], a[224:239]
	v_mfma_f32_32x32x16_bf16 a[160:175], v[112:115], v[28:31], a[160:175]
	v_mfma_f32_32x32x16_bf16 a[96:111], v[112:115], v[32:35], a[96:111]
	v_mfma_f32_32x32x16_bf16 a[32:47], v[112:115], v[36:39], a[32:47]
	ds_read_b128 v[112:115], v180 offset:12288
	s_waitcnt lgkmcnt(1)
	v_mfma_f32_32x32x16_bf16 a[208:223], v[12:15], v[24:27], a[208:223]
	v_mfma_f32_32x32x16_bf16 a[144:159], v[12:15], v[28:31], a[144:159]
	v_mfma_f32_32x32x16_bf16 a[80:95], v[12:15], v[32:35], a[80:95]
	v_mfma_f32_32x32x16_bf16 a[16:31], v[12:15], v[36:39], a[16:31]
	s_waitcnt vmcnt(0)
	s_waitcnt vmcnt(0) lgkmcnt(0)
	s_barrier
	s_add_u32 s12, s12, 0x80
	s_addc_u32 s13, s13, 0
	s_add_i32 s11, s11, 0x8000
	s_cmpk_lg_i32 s12, 0x780
	v_mfma_f32_32x32x16_bf16 a[192:207], v[112:115], v[24:27], a[192:207]
	v_mfma_f32_32x32x16_bf16 a[128:143], v[112:115], v[28:31], a[128:143]
	v_mfma_f32_32x32x16_bf16 a[64:79], v[112:115], v[32:35], a[64:79]
	v_mfma_f32_32x32x16_bf16 a[0:15], v[112:115], v[36:39], a[0:15]
	s_cbranch_scc1 .LBB0_50
	s_and_b32 s10, s10, 0x700
	v_lshlrev_b32_e32 v4, 1, v10
	s_mov_b32 s11, 0x10000
	v_add3_u32 v8, v21, v4, s11
	ds_read_b128 v[0:3], v8
	s_mov_b32 s12, 0x18000
	v_add3_u32 v10, v20, v4, s12
	ds_read_b128 v[4:7], v10
	ds_read_b128 v[24:27], v8 offset:4096
	ds_read_b128 v[28:31], v10 offset:4096
	ds_read_b128 v[32:35], v10 offset:8192
	ds_read_b128 v[12:15], v10 offset:12288
	s_waitcnt lgkmcnt(3)
	v_mfma_f32_32x32x16_bf16 a[224:239], v[24:27], v[4:7], a[224:239]
	v_lshlrev_b32_e32 v16, 1, v16
	v_lshlrev_b32_e32 v22, 1, v22
	v_add3_u32 v23, v21, v16, s11
	v_mfma_f32_32x32x16_bf16 a[240:255], v[0:3], v[4:7], a[240:255]
	s_waitcnt lgkmcnt(2)
	v_mfma_f32_32x32x16_bf16 a[176:191], v[0:3], v[28:31], a[176:191]
	s_waitcnt lgkmcnt(1)
	v_mfma_f32_32x32x16_bf16 a[112:127], v[0:3], v[32:35], a[112:127]
	s_waitcnt lgkmcnt(0)
	v_mfma_f32_32x32x16_bf16 a[48:63], v[0:3], v[12:15], a[48:63]
	v_mfma_f32_32x32x16_bf16 a[160:175], v[24:27], v[28:31], a[160:175]
	v_mfma_f32_32x32x16_bf16 a[96:111], v[24:27], v[32:35], a[96:111]
	v_mfma_f32_32x32x16_bf16 a[32:47], v[24:27], v[12:15], a[32:47]
	ds_read_b128 v[0:3], v8 offset:8192
	ds_read_b128 v[24:27], v8 offset:12288
	s_waitcnt lgkmcnt(1)
	v_mfma_f32_32x32x16_bf16 a[208:223], v[0:3], v[4:7], a[208:223]
	v_mfma_f32_32x32x16_bf16 a[144:159], v[0:3], v[28:31], a[144:159]
	v_mfma_f32_32x32x16_bf16 a[80:95], v[0:3], v[32:35], a[80:95]
	v_mfma_f32_32x32x16_bf16 a[16:31], v[0:3], v[12:15], a[16:31]
	v_lshlrev_b32_e32 v0, 1, v9
	v_add3_u32 v17, v21, v0, s11
	ds_read_b128 v[8:11], v17
	v_add3_u32 v0, v20, v0, s12
	s_waitcnt lgkmcnt(1)
	v_mfma_f32_32x32x16_bf16 a[192:207], v[24:27], v[4:7], a[192:207]
	v_mfma_f32_32x32x16_bf16 a[128:143], v[24:27], v[28:31], a[128:143]
	v_mfma_f32_32x32x16_bf16 a[64:79], v[24:27], v[32:35], a[64:79]
	ds_read_b128 v[28:31], v0
	ds_read_b128 v[32:35], v17 offset:4096
	ds_read_b128 v[44:47], v0 offset:4096
	ds_read_b128 v[4:7], v0 offset:8192
	ds_read_b128 v[0:3], v0 offset:12288
	s_waitcnt lgkmcnt(4)
	v_mfma_f32_32x32x16_bf16 a[240:255], v[8:11], v[28:31], a[240:255]
	s_waitcnt lgkmcnt(2)
	v_mfma_f32_32x32x16_bf16 a[176:191], v[8:11], v[44:47], a[176:191]
	s_waitcnt lgkmcnt(1)
	v_mfma_f32_32x32x16_bf16 a[112:127], v[8:11], v[4:7], a[112:127]
	s_waitcnt lgkmcnt(0)
	v_mfma_f32_32x32x16_bf16 a[48:63], v[8:11], v[0:3], a[48:63]
	v_mfma_f32_32x32x16_bf16 a[224:239], v[32:35], v[28:31], a[224:239]
	v_mfma_f32_32x32x16_bf16 a[160:175], v[32:35], v[44:47], a[160:175]
	v_mfma_f32_32x32x16_bf16 a[96:111], v[32:35], v[4:7], a[96:111]
	v_mfma_f32_32x32x16_bf16 a[32:47], v[32:35], v[0:3], a[32:47]
	ds_read_b128 v[32:35], v17 offset:8192
	ds_read_b128 v[8:11], v17 offset:12288
	ds_read_b128 v[72:75], v23
	v_mfma_f32_32x32x16_bf16 a[0:15], v[24:27], v[12:15], a[0:15]
	s_waitcnt lgkmcnt(2)
	v_mfma_f32_32x32x16_bf16 a[208:223], v[32:35], v[28:31], a[208:223]
	v_mfma_f32_32x32x16_bf16 a[144:159], v[32:35], v[44:47], a[144:159]
	v_mfma_f32_32x32x16_bf16 a[80:95], v[32:35], v[4:7], a[80:95]
	v_mfma_f32_32x32x16_bf16 a[16:31], v[32:35], v[0:3], a[16:31]
	v_add3_u32 v32, v20, v22, s12
	s_waitcnt lgkmcnt(1)
	v_mfma_f32_32x32x16_bf16 a[192:207], v[8:11], v[28:31], a[192:207]
	v_add3_u32 v28, v20, v16, s12
	v_add3_u32 v29, v21, v22, s11
	s_mov_b32 s11, 0
	ds_read_b128 v[56:59], v28
	ds_read_b128 v[80:83], v23 offset:4096
	ds_read_b128 v[16:19], v28 offset:4096
	ds_read_b128 v[76:79], v29
	ds_read_b128 v[60:63], v32
	ds_read_b128 v[64:67], v23 offset:8192
	ds_read_b128 v[20:23], v23 offset:12288
	ds_read_b128 v[84:87], v29 offset:4096
	ds_read_b128 v[52:55], v32 offset:4096
	ds_read_b128 v[48:51], v28 offset:8192
	ds_read_b128 v[36:39], v28 offset:12288
	ds_read_b128 v[68:71], v29 offset:8192
	ds_read_b128 v[28:31], v29 offset:12288
	ds_read_b128 v[40:43], v32 offset:8192
	ds_read_b128 v[32:35], v32 offset:12288
	s_waitcnt vmcnt(0)
	s_waitcnt lgkmcnt(0)
	s_barrier
	v_mfma_f32_32x32x16_bf16 a[64:79], v[8:11], v[4:7], a[64:79]
	v_mbcnt_lo_u32_b32 v12, -1, s11
	v_mbcnt_hi_u32_b32 v4, -1, v12
	v_or_b32_e32 v248, s34, v4
	v_and_b32_e32 v5, 31, v4
	v_lshlrev_b32_e32 v6, 1, v248
	v_lshrrev_b32_e32 v4, 3, v4
	v_and_or_b32 v249, v6, s19, v5
	v_and_b32_e32 v250, 4, v4
	v_mfma_f32_32x32x16_bf16 a[0:15], v[8:11], v[0:3], a[0:15]
	v_lshlrev_b32_e32 v252, 2, v250
	v_or_b32_e32 v0, s10, v249
	v_lshl_add_u64 v[24:25], s[0:1], 0, v[252:253]
	v_lshl_add_u64 v[14:15], s[4:5], 0, v[252:253]
	v_lshlrev_b32_e32 v252, 5, v0
	v_lshl_add_u64 v[0:1], v[24:25], 0, v[252:253]
	v_lshl_add_u64 v[2:3], v[14:15], 0, v[252:253]
	global_load_dwordx4 v[234:237], v[0:1], off
	global_load_dwordx4 v[238:241], v[2:3], off
	v_mfma_f32_32x32x16_bf16 a[240:255], v[72:75], v[56:59], a[240:255]
	s_mov_b32 s11, 0x7fffff80
	s_mov_b32 s10, 0
	v_mfma_f32_32x32x16_bf16 a[128:143], v[8:11], v[44:47], a[128:143]
	v_mfma_f32_32x32x16_bf16 a[240:255], v[76:79], v[60:63], a[240:255]
	v_mfma_f32_32x32x16_bf16 a[192:207], v[20:23], v[56:59], a[192:207]
	s_nop 10
	v_accvgpr_read_b32 v193, a247
	v_accvgpr_read_b32 v192, a246
	v_accvgpr_read_b32 v197, a245
	v_mfma_f32_32x32x16_bf16 a[128:143], v[20:23], v[16:19], a[128:143]
	v_accvgpr_read_b32 v196, a244
	v_accvgpr_read_b32 v195, a243
	v_accvgpr_read_b32 v194, a242
	v_accvgpr_read_b32 v189, a251
	v_accvgpr_read_b32 v188, a250
	v_accvgpr_read_b32 v191, a249
	v_accvgpr_read_b32 v190, a248
	v_mfma_f32_32x32x16_bf16 a[64:79], v[20:23], v[48:51], a[64:79]
	v_accvgpr_read_b32 v185, a255
	v_accvgpr_read_b32 v184, a254
	v_accvgpr_read_b32 v187, a253
	v_accvgpr_read_b32 v186, a252
	v_mfma_f32_32x32x16_bf16 a[0:15], v[20:23], v[36:39], a[0:15]
	v_mfma_f32_32x32x16_bf16 a[48:63], v[72:75], v[36:39], a[48:63]
	v_mfma_f32_32x32x16_bf16 a[32:47], v[80:83], v[36:39], a[32:47]
	v_mfma_f32_32x32x16_bf16 a[16:31], v[64:67], v[36:39], a[16:31]
	v_mfma_f32_32x32x16_bf16 a[224:239], v[80:83], v[56:59], a[224:239]
	v_mfma_f32_32x32x16_bf16 a[192:207], v[28:31], v[60:63], a[192:207]
	v_mfma_f32_32x32x16_bf16 a[128:143], v[28:31], v[52:55], a[128:143]
	s_nop 10
	v_accvgpr_read_b32 v247, a195
	v_accvgpr_read_b32 v246, a194
	v_accvgpr_read_b32 v243, a199
	v_mfma_f32_32x32x16_bf16 a[64:79], v[28:31], v[40:43], a[64:79]
	v_accvgpr_read_b32 v242, a198
	v_accvgpr_read_b32 v245, a197
	v_accvgpr_read_b32 v244, a196
	v_accvgpr_read_b32 v231, a203
	v_accvgpr_read_b32 v230, a202
	v_accvgpr_read_b32 v233, a201
	v_accvgpr_read_b32 v232, a200
	v_mfma_f32_32x32x16_bf16 a[0:15], v[28:31], v[32:35], a[0:15]
	v_accvgpr_read_b32 v30, a240
	v_accvgpr_read_b32 v31, a241
	v_and_or_b32 v28, v248, s11, v250
	v_mul_u32_u24_e32 v29, 0x210, v249
	v_lshl_add_u32 v28, v28, 1, v29
	v_accvgpr_read_b32 v227, a207
	v_accvgpr_read_b32 v226, a206
	v_mfma_f32_32x32x16_bf16 a[48:63], v[76:79], v[32:35], a[48:63]
	v_accvgpr_read_b32 v229, a205
	v_accvgpr_read_b32 v228, a204
	v_accvgpr_read_b32 v45, a143
	v_accvgpr_read_b32 v44, a142
	v_accvgpr_read_b32 v1, a15
	v_accvgpr_read_b32 v0, a14
	v_accvgpr_read_b32 v2, a12
	v_mfma_f32_32x32x16_bf16 a[32:47], v[84:87], v[32:35], a[32:47]
	v_accvgpr_read_b32 v47, a141
	v_accvgpr_read_b32 v46, a140
	v_accvgpr_read_b32 v183, a131
	v_accvgpr_read_b32 v182, a130
	v_accvgpr_read_b32 v95, a55
	v_accvgpr_read_b32 v94, a54
	v_accvgpr_read_b32 v97, a51
	v_mfma_f32_32x32x16_bf16 a[16:31], v[68:71], v[32:35], a[16:31]
	s_waitcnt vmcnt(0)
	v_mul_f32_e64 v32, v196, v238
	v_mul_f32_e64 v33, v197, v239
	v_mul_f32_e64 v34, v192, v240
	v_mul_f32_e64 v35, v193, v241
	v_pk_fma_f32 v[32:33], v[30:31], v[234:235], v[32:33] neg_lo:[0,0,1] neg_hi:[0,0,1]
	v_pk_fma_f32 v[34:35], v[194:195], v[236:237], v[34:35] neg_lo:[0,0,1] neg_hi:[0,0,1]
	v_pk_mul_f32 v[32:33], v[32:33], s[58:59] op_sel_hi:[1,0]
	v_pk_mul_f32 v[34:35], v[34:35], s[58:59] op_sel_hi:[1,0]
	v_cvt_pk_bf16_f32 v32, v32, v33
	v_mfma_f32_32x32x16_bf16 a[224:239], v[84:87], v[60:63], a[224:239]
	v_cvt_pk_bf16_f32 v33, v34, v35
	v_mul_f32_e64 v30, v30, v238
	v_mul_f32_e64 v31, v31, v239
	v_mul_f32_e64 v34, v194, v240
	v_mul_f32_e64 v35, v195, v241
	v_pk_fma_f32 v[30:31], v[196:197], v[234:235], v[30:31]
	v_pk_fma_f32 v[34:35], v[192:193], v[236:237], v[34:35]
	v_pk_mul_f32 v[30:31], v[30:31], s[58:59] op_sel_hi:[1,0]
	v_pk_mul_f32 v[34:35], v[34:35], s[58:59] op_sel_hi:[1,0]
	v_mfma_f32_32x32x16_bf16 a[208:223], v[64:67], v[56:59], a[208:223]
	v_cvt_pk_bf16_f32 v30, v30, v31
	v_cvt_pk_bf16_f32 v31, v34, v35
	ds_write2_b64 v28, v[32:33], v[30:31] offset1:2
	v_mul_f32_e64 v30, v190, s58
	v_mul_f32_e64 v31, v191, s58
	v_pk_mul_f32 v[32:33], v[188:189], s[58:59] op_sel_hi:[1,0]
	v_cvt_pk_bf16_f32 v30, v30, v31
	v_cvt_pk_bf16_f32 v31, v32, v33
	v_pk_mul_f32 v[32:33], v[186:187], s[58:59] op_sel_hi:[1,0]
	v_pk_mul_f32 v[34:35], v[184:185], s[58:59] op_sel_hi:[1,0]
	v_cvt_pk_bf16_f32 v32, v32, v33
	v_cvt_pk_bf16_f32 v33, v34, v35
	v_mfma_f32_32x32x16_bf16 a[208:223], v[68:71], v[60:63], a[208:223]
	ds_write2_b64 v28, v[30:31], v[32:33] offset0:4 offset1:6
	v_accvgpr_read_b32 v30, a224
	v_accvgpr_read_b32 v211, a227
	v_accvgpr_read_b32 v210, a226
	v_accvgpr_read_b32 v31, a225
	v_accvgpr_read_b32 v207, a231
	v_accvgpr_read_b32 v206, a230
	v_accvgpr_read_b32 v209, a229
	v_accvgpr_read_b32 v208, a228
	v_pk_mul_f32 v[30:31], v[30:31], s[58:59] op_sel_hi:[1,0]
	v_pk_mul_f32 v[32:33], v[210:211], s[58:59] op_sel_hi:[1,0]
	v_cvt_pk_bf16_f32 v30, v30, v31
	v_cvt_pk_bf16_f32 v31, v32, v33
	v_pk_mul_f32 v[32:33], v[208:209], s[58:59] op_sel_hi:[1,0]
	v_pk_mul_f32 v[34:35], v[206:207], s[58:59] op_sel_hi:[1,0]
	v_accvgpr_read_b32 v203, a235
	v_accvgpr_read_b32 v202, a234
	v_accvgpr_read_b32 v205, a233
	v_accvgpr_read_b32 v204, a232
	v_cvt_pk_bf16_f32 v32, v32, v33
	v_cvt_pk_bf16_f32 v33, v34, v35
	v_accvgpr_read_b32 v199, a239
	v_accvgpr_read_b32 v198, a238
	v_accvgpr_read_b32 v201, a237
	v_accvgpr_read_b32 v200, a236
	ds_write2_b64 v28, v[30:31], v[32:33] offset0:8 offset1:10
	v_pk_mul_f32 v[30:31], v[204:205], s[58:59] op_sel_hi:[1,0]
	v_pk_mul_f32 v[32:33], v[202:203], s[58:59] op_sel_hi:[1,0]
	v_cvt_pk_bf16_f32 v30, v30, v31
	v_cvt_pk_bf16_f32 v31, v32, v33
	v_pk_mul_f32 v[32:33], v[200:201], s[58:59] op_sel_hi:[1,0]
	v_pk_mul_f32 v[34:35], v[198:199], s[58:59] op_sel_hi:[1,0]
	v_cvt_pk_bf16_f32 v32, v32, v33
	v_cvt_pk_bf16_f32 v33, v34, v35
	v_accvgpr_read_b32 v221, a215
	v_accvgpr_read_b32 v220, a214
	v_accvgpr_read_b32 v225, a213
	v_accvgpr_read_b32 v224, a212
	ds_write2_b64 v28, v[30:31], v[32:33] offset0:12 offset1:14
	v_accvgpr_read_b32 v30, a208
	v_accvgpr_read_b32 v223, a211
	v_accvgpr_read_b32 v222, a210
	v_accvgpr_read_b32 v31, a209
	v_pk_mul_f32 v[32:33], v[224:225], v[238:239]
	v_pk_mul_f32 v[34:35], v[220:221], v[240:241]
	v_pk_fma_f32 v[32:33], v[30:31], v[234:235], v[32:33] neg_lo:[0,0,1] neg_hi:[0,0,1]
	v_pk_fma_f32 v[34:35], v[222:223], v[236:237], v[34:35] neg_lo:[0,0,1] neg_hi:[0,0,1]
	v_mfma_f32_32x32x16_bf16 a[176:191], v[72:75], v[16:19], a[176:191]
	v_mul_f32_e64 v32, v32, s58
	v_mul_f32_e64 v33, v33, s58
	v_mul_f32_e64 v34, v34, s58
	v_mul_f32_e64 v35, v35, s58
	v_cvt_pk_bf16_f32 v32, v32, v33
	v_cvt_pk_bf16_f32 v33, v34, v35
	v_pk_mul_f32 v[30:31], v[30:31], v[238:239]
	v_pk_mul_f32 v[34:35], v[222:223], v[240:241]
	v_pk_fma_f32 v[30:31], v[224:225], v[234:235], v[30:31]
	v_mfma_f32_32x32x16_bf16 a[112:127], v[72:75], v[48:51], a[112:127]
	v_fma_f32 v34, v220, v236, v34
	v_fma_f32 v35, v221, v237, v35
	v_mul_f32_e64 v30, v30, s58
	v_mul_f32_e64 v31, v31, s58
	v_mul_f32_e64 v34, v34, s58
	v_mul_f32_e64 v35, v35, s58
	v_accvgpr_read_b32 v217, a219
	v_accvgpr_read_b32 v216, a218
	v_accvgpr_read_b32 v219, a217
	v_accvgpr_read_b32 v218, a216
	v_mfma_f32_32x32x16_bf16 a[160:175], v[80:83], v[16:19], a[160:175]
	v_cvt_pk_bf16_f32 v30, v30, v31
	v_cvt_pk_bf16_f32 v31, v34, v35
	v_accvgpr_read_b32 v213, a223
	v_accvgpr_read_b32 v212, a222
	v_accvgpr_read_b32 v215, a221
	v_accvgpr_read_b32 v214, a220
	ds_write2_b64 v28, v[32:33], v[30:31] offset0:16 offset1:18
	v_mfma_f32_32x32x16_bf16 a[96:111], v[80:83], v[48:51], a[96:111]
	v_mul_f32_e64 v30, v218, s58
	v_mul_f32_e64 v31, v219, s58
	v_mul_f32_e64 v32, v216, s58
	v_mul_f32_e64 v33, v217, s58
	v_cvt_pk_bf16_f32 v30, v30, v31
	v_cvt_pk_bf16_f32 v31, v32, v33
	v_pk_mul_f32 v[32:33], v[214:215], s[58:59] op_sel_hi:[1,0]
	v_pk_mul_f32 v[34:35], v[212:213], s[58:59] op_sel_hi:[1,0]
	v_cvt_pk_bf16_f32 v32, v32, v33
	v_mfma_f32_32x32x16_bf16 a[144:159], v[64:67], v[16:19], a[144:159]
	v_cvt_pk_bf16_f32 v33, v34, v35
	ds_write2_b64 v28, v[30:31], v[32:33] offset0:20 offset1:22
	v_accvgpr_read_b32 v30, a192
	v_accvgpr_read_b32 v31, a193
	v_mul_f32_e64 v30, v30, s58
	v_mul_f32_e64 v31, v31, s58
	v_pk_mul_f32 v[32:33], v[246:247], s[58:59] op_sel_hi:[1,0]
	v_cvt_pk_bf16_f32 v30, v30, v31
	v_mfma_f32_32x32x16_bf16 a[80:95], v[64:67], v[48:51], a[80:95]
	v_cvt_pk_bf16_f32 v31, v32, v33
	v_mul_f32_e64 v32, v244, s58
	v_mul_f32_e64 v33, v245, s58
	v_mul_f32_e64 v34, v242, s58
	v_mul_f32_e64 v35, v243, s58
	v_cvt_pk_bf16_f32 v32, v32, v33
	v_cvt_pk_bf16_f32 v33, v34, v35
	ds_write2_b64 v28, v[30:31], v[32:33] offset0:24 offset1:26
	v_pk_mul_f32 v[30:31], v[232:233], s[58:59] op_sel_hi:[1,0]
	v_mfma_f32_32x32x16_bf16 a[176:191], v[76:79], v[52:55], a[176:191]
	v_mul_f32_e64 v32, v230, s58
	v_mul_f32_e64 v33, v231, s58
	v_cvt_pk_bf16_f32 v30, v30, v31
	v_cvt_pk_bf16_f32 v31, v32, v33
	v_mul_f32_e64 v32, v228, s58
	v_mul_f32_e64 v33, v229, s58
	v_pk_mul_f32 v[34:35], v[226:227], s[58:59] op_sel_hi:[1,0]
	v_cvt_pk_bf16_f32 v32, v32, v33
	v_cvt_pk_bf16_f32 v33, v34, v35
	v_mfma_f32_32x32x16_bf16 a[112:127], v[76:79], v[40:43], a[112:127]
	v_accvgpr_read_b32 v73, a63
	v_accvgpr_read_b32 v72, a62
	v_accvgpr_read_b32 v75, a61
	v_accvgpr_read_b32 v74, a60
	v_accvgpr_read_b32 v141, a191
	v_accvgpr_read_b32 v140, a190
	v_accvgpr_read_b32 v143, a189
	v_mfma_f32_32x32x16_bf16 a[160:175], v[84:87], v[52:55], a[160:175]
	v_accvgpr_read_b32 v142, a188
	v_accvgpr_read_b32 v145, a187
	v_accvgpr_read_b32 v144, a186
	v_accvgpr_read_b32 v149, a185
	v_accvgpr_read_b32 v148, a184
	v_accvgpr_read_b32 v171, a183
	v_accvgpr_read_b32 v170, a182
	v_mfma_f32_32x32x16_bf16 a[96:111], v[84:87], v[40:43], a[96:111]
	v_accvgpr_read_b32 v173, a179
	v_accvgpr_read_b32 v172, a178
	v_accvgpr_read_b32 v175, a181
	v_accvgpr_read_b32 v174, a180
	v_accvgpr_read_b32 v101, a127
	v_accvgpr_read_b32 v100, a126
	v_accvgpr_read_b32 v103, a125
	v_mfma_f32_32x32x16_bf16 a[144:159], v[68:71], v[52:55], a[144:159]
	v_accvgpr_read_b32 v102, a124
	v_accvgpr_read_b32 v105, a123
	v_accvgpr_read_b32 v104, a122
	v_accvgpr_read_b32 v109, a121
	v_accvgpr_read_b32 v108, a120
	v_accvgpr_read_b32 v131, a119
	v_accvgpr_read_b32 v130, a118
	v_mfma_f32_32x32x16_bf16 a[80:95], v[68:71], v[40:43], a[80:95]
	v_accvgpr_read_b32 v133, a115
	v_accvgpr_read_b32 v132, a114
	v_accvgpr_read_b32 v135, a117
	v_accvgpr_read_b32 v134, a116
	v_accvgpr_read_b32 v77, a59
	v_accvgpr_read_b32 v76, a58
	v_accvgpr_read_b32 v79, a57
	v_accvgpr_read_b32 v78, a56
	v_accvgpr_read_b32 v96, a50
	v_accvgpr_read_b32 v99, a53
	v_accvgpr_read_b32 v98, a52
	v_accvgpr_read_b32 v151, a175
	v_accvgpr_read_b32 v150, a174
	v_accvgpr_read_b32 v155, a173
	v_accvgpr_read_b32 v154, a172
	v_accvgpr_read_b32 v159, a171
	v_accvgpr_read_b32 v158, a170
	v_accvgpr_read_b32 v163, a169
	v_accvgpr_read_b32 v162, a168
	v_accvgpr_read_b32 v165, a167
	v_accvgpr_read_b32 v164, a166
	v_accvgpr_read_b32 v167, a165
	v_accvgpr_read_b32 v166, a164
	v_accvgpr_read_b32 v169, a163
	v_accvgpr_read_b32 v168, a162
	v_accvgpr_read_b32 v111, a111
	v_accvgpr_read_b32 v110, a110
	v_accvgpr_read_b32 v115, a109
	v_accvgpr_read_b32 v114, a108
	v_accvgpr_read_b32 v119, a107
	v_accvgpr_read_b32 v118, a106
	v_accvgpr_read_b32 v123, a105
	v_accvgpr_read_b32 v122, a104
	v_accvgpr_read_b32 v125, a103
	v_accvgpr_read_b32 v124, a102
	v_accvgpr_read_b32 v127, a101
	v_accvgpr_read_b32 v126, a100
	v_accvgpr_read_b32 v129, a99
	v_accvgpr_read_b32 v128, a98
	v_accvgpr_read_b32 v81, a47
	v_accvgpr_read_b32 v80, a46
	v_accvgpr_read_b32 v83, a45
	v_accvgpr_read_b32 v82, a44
	v_accvgpr_read_b32 v85, a43
	v_accvgpr_read_b32 v84, a42
	v_accvgpr_read_b32 v87, a41
	v_accvgpr_read_b32 v86, a40
	v_accvgpr_read_b32 v89, a39
	v_accvgpr_read_b32 v88, a38
	v_accvgpr_read_b32 v91, a37
	v_accvgpr_read_b32 v90, a36
	v_accvgpr_read_b32 v93, a35
	v_accvgpr_read_b32 v92, a34
	v_accvgpr_read_b32 v147, a159
	v_accvgpr_read_b32 v146, a158
	v_accvgpr_read_b32 v153, a157
	v_accvgpr_read_b32 v152, a156
	v_accvgpr_read_b32 v157, a155
	v_accvgpr_read_b32 v156, a154
	v_accvgpr_read_b32 v161, a153
	v_accvgpr_read_b32 v160, a152
	v_accvgpr_read_b32 v177, a151
	v_accvgpr_read_b32 v176, a150
	v_accvgpr_read_b32 v179, a147
	v_accvgpr_read_b32 v178, a146
	v_accvgpr_read_b32 v181, a149
	v_accvgpr_read_b32 v180, a148
	v_accvgpr_read_b32 v107, a95
	v_accvgpr_read_b32 v106, a94
	v_accvgpr_read_b32 v113, a93
	v_accvgpr_read_b32 v112, a92
	v_accvgpr_read_b32 v117, a91
	v_accvgpr_read_b32 v116, a90
	v_accvgpr_read_b32 v121, a89
	v_accvgpr_read_b32 v120, a88
	v_accvgpr_read_b32 v71, a87
	v_accvgpr_read_b32 v70, a86
	v_accvgpr_read_b32 v137, a83
	v_accvgpr_read_b32 v136, a82
	v_accvgpr_read_b32 v139, a85
	v_accvgpr_read_b32 v138, a84
	v_accvgpr_read_b32 v65, a31
	v_accvgpr_read_b32 v64, a30
	v_accvgpr_read_b32 v57, a29
	v_accvgpr_read_b32 v56, a28
	v_accvgpr_read_b32 v59, a27
	v_accvgpr_read_b32 v58, a26
	v_accvgpr_read_b32 v67, a25
	v_accvgpr_read_b32 v66, a24
	v_accvgpr_read_b32 v61, a23
	v_accvgpr_read_b32 v60, a22
	v_accvgpr_read_b32 v63, a19
	v_accvgpr_read_b32 v62, a18
	v_accvgpr_read_b32 v69, a21
	v_accvgpr_read_b32 v68, a20
	v_accvgpr_read_b32 v53, a139
	v_accvgpr_read_b32 v52, a138
	v_accvgpr_read_b32 v55, a137
	v_accvgpr_read_b32 v54, a136
	v_accvgpr_read_b32 v49, a135
	v_accvgpr_read_b32 v48, a134
	v_accvgpr_read_b32 v51, a133
	v_accvgpr_read_b32 v50, a132
	v_accvgpr_read_b32 v17, a79
	v_accvgpr_read_b32 v16, a78
	v_accvgpr_read_b32 v19, a77
	v_accvgpr_read_b32 v18, a76
	v_accvgpr_read_b32 v27, a75
	v_accvgpr_read_b32 v26, a74
	v_accvgpr_read_b32 v41, a73
	v_accvgpr_read_b32 v40, a72
	v_accvgpr_read_b32 v21, a71
	v_accvgpr_read_b32 v20, a70
	v_accvgpr_read_b32 v23, a69
	v_accvgpr_read_b32 v22, a68
	v_accvgpr_read_b32 v37, a67
	v_accvgpr_read_b32 v36, a66
	v_accvgpr_read_b32 v3, a13
	v_accvgpr_read_b32 v5, a11
	v_accvgpr_read_b32 v4, a10
	v_accvgpr_read_b32 v7, a9
	v_accvgpr_read_b32 v6, a8
	v_accvgpr_read_b32 v9, a7
	v_accvgpr_read_b32 v8, a6
	v_accvgpr_read_b32 v11, a5
	v_accvgpr_read_b32 v10, a4
	v_accvgpr_read_b32 v13, a3
	v_accvgpr_read_b32 v12, a2
	ds_write2_b64 v28, v[30:31], v[32:33] offset0:28 offset1:30
	v_or_b32_e32 v30, 0x400, v252
	v_mov_b32_e32 v31, v253
	v_lshl_add_u64 v[32:33], v[24:25], 0, v[30:31]
	v_lshl_add_u64 v[34:35], v[14:15], 0, v[30:31]
	global_load_dwordx4 v[30:33], v[32:33], off
	s_nop 0
	global_load_dwordx4 v[184:187], v[34:35], off
	v_accvgpr_read_b32 v34, a176
	v_accvgpr_read_b32 v35, a177
	v_add_u32_e32 v29, 0x4000, v28
	s_waitcnt vmcnt(0)
	v_pk_mul_f32 v[38:39], v[174:175], v[184:185]
	v_pk_mul_f32 v[42:43], v[170:171], v[186:187]
	v_pk_fma_f32 v[38:39], v[34:35], v[30:31], v[38:39] neg_lo:[0,0,1] neg_hi:[0,0,1]
	v_pk_fma_f32 v[42:43], v[172:173], v[32:33], v[42:43] neg_lo:[0,0,1] neg_hi:[0,0,1]
	v_pk_mul_f32 v[38:39], v[38:39], s[58:59] op_sel_hi:[1,0]
	v_pk_mul_f32 v[42:43], v[42:43], s[58:59] op_sel_hi:[1,0]
	v_cvt_pk_bf16_f32 v38, v38, v39
	v_cvt_pk_bf16_f32 v39, v42, v43
	v_pk_mul_f32 v[34:35], v[34:35], v[184:185]
	v_pk_mul_f32 v[42:43], v[172:173], v[186:187]
	v_pk_fma_f32 v[34:35], v[174:175], v[30:31], v[34:35]
	v_pk_fma_f32 v[42:43], v[170:171], v[32:33], v[42:43]
	v_pk_mul_f32 v[34:35], v[34:35], s[58:59] op_sel_hi:[1,0]
	v_pk_mul_f32 v[42:43], v[42:43], s[58:59] op_sel_hi:[1,0]
	v_cvt_pk_bf16_f32 v34, v34, v35
	v_cvt_pk_bf16_f32 v35, v42, v43
	ds_write2_b64 v29, v[38:39], v[34:35] offset0:64 offset1:66
	v_pk_mul_f32 v[34:35], v[148:149], s[58:59] op_sel_hi:[1,0]
	v_pk_mul_f32 v[38:39], v[144:145], s[58:59] op_sel_hi:[1,0]
	v_cvt_pk_bf16_f32 v34, v34, v35
	v_cvt_pk_bf16_f32 v35, v38, v39
	v_pk_mul_f32 v[38:39], v[142:143], s[58:59] op_sel_hi:[1,0]
	v_pk_mul_f32 v[42:43], v[140:141], s[58:59] op_sel_hi:[1,0]
	v_cvt_pk_bf16_f32 v38, v38, v39
	v_cvt_pk_bf16_f32 v39, v42, v43
	ds_write2_b64 v29, v[34:35], v[38:39] offset0:68 offset1:70
	v_accvgpr_read_b32 v34, a160
	v_accvgpr_read_b32 v35, a161
	v_pk_mul_f32 v[34:35], v[34:35], s[58:59] op_sel_hi:[1,0]
	v_pk_mul_f32 v[38:39], v[168:169], s[58:59] op_sel_hi:[1,0]
	v_cvt_pk_bf16_f32 v34, v34, v35
	v_cvt_pk_bf16_f32 v35, v38, v39
	v_pk_mul_f32 v[38:39], v[166:167], s[58:59] op_sel_hi:[1,0]
	v_pk_mul_f32 v[42:43], v[164:165], s[58:59] op_sel_hi:[1,0]
	v_cvt_pk_bf16_f32 v38, v38, v39
	v_cvt_pk_bf16_f32 v39, v42, v43
	ds_write2_b64 v29, v[34:35], v[38:39] offset0:72 offset1:74
	v_pk_mul_f32 v[34:35], v[162:163], s[58:59] op_sel_hi:[1,0]
	v_pk_mul_f32 v[38:39], v[158:159], s[58:59] op_sel_hi:[1,0]
	v_cvt_pk_bf16_f32 v34, v34, v35
	v_cvt_pk_bf16_f32 v35, v38, v39
	v_pk_mul_f32 v[38:39], v[154:155], s[58:59] op_sel_hi:[1,0]
	v_pk_mul_f32 v[42:43], v[150:151], s[58:59] op_sel_hi:[1,0]
	v_cvt_pk_bf16_f32 v38, v38, v39
	v_cvt_pk_bf16_f32 v39, v42, v43
	ds_write2_b64 v29, v[34:35], v[38:39] offset0:76 offset1:78
	v_accvgpr_read_b32 v34, a144
	v_accvgpr_read_b32 v35, a145
	v_pk_mul_f32 v[38:39], v[180:181], v[184:185]
	v_pk_mul_f32 v[42:43], v[176:177], v[186:187]
	v_pk_fma_f32 v[38:39], v[34:35], v[30:31], v[38:39] neg_lo:[0,0,1] neg_hi:[0,0,1]
	v_pk_mul_f32 v[34:35], v[34:35], v[184:185]
	v_pk_fma_f32 v[42:43], v[178:179], v[32:33], v[42:43] neg_lo:[0,0,1] neg_hi:[0,0,1]
	v_pk_fma_f32 v[30:31], v[180:181], v[30:31], v[34:35]
	v_pk_mul_f32 v[34:35], v[178:179], v[186:187]
	v_pk_mul_f32 v[38:39], v[38:39], s[58:59] op_sel_hi:[1,0]
	v_pk_fma_f32 v[32:33], v[176:177], v[32:33], v[34:35]
	v_pk_mul_f32 v[42:43], v[42:43], s[58:59] op_sel_hi:[1,0]
	v_pk_mul_f32 v[30:31], v[30:31], s[58:59] op_sel_hi:[1,0]
	v_pk_mul_f32 v[32:33], v[32:33], s[58:59] op_sel_hi:[1,0]
	v_cvt_pk_bf16_f32 v38, v38, v39
	v_cvt_pk_bf16_f32 v39, v42, v43
	v_cvt_pk_bf16_f32 v30, v30, v31
	v_cvt_pk_bf16_f32 v31, v32, v33
	ds_write2_b64 v29, v[38:39], v[30:31] offset0:80 offset1:82
	v_pk_mul_f32 v[30:31], v[160:161], s[58:59] op_sel_hi:[1,0]
	v_pk_mul_f32 v[32:33], v[156:157], s[58:59] op_sel_hi:[1,0]
	v_cvt_pk_bf16_f32 v30, v30, v31
	v_cvt_pk_bf16_f32 v31, v32, v33
	v_pk_mul_f32 v[32:33], v[152:153], s[58:59] op_sel_hi:[1,0]
	v_pk_mul_f32 v[34:35], v[146:147], s[58:59] op_sel_hi:[1,0]
	v_cvt_pk_bf16_f32 v32, v32, v33
	v_cvt_pk_bf16_f32 v33, v34, v35
	ds_write2_b64 v29, v[30:31], v[32:33] offset0:84 offset1:86
	v_accvgpr_read_b32 v30, a128
	v_accvgpr_read_b32 v31, a129
	v_pk_mul_f32 v[30:31], v[30:31], s[58:59] op_sel_hi:[1,0]
	v_pk_mul_f32 v[32:33], v[182:183], s[58:59] op_sel_hi:[1,0]
	v_cvt_pk_bf16_f32 v30, v30, v31
	v_cvt_pk_bf16_f32 v31, v32, v33
	v_pk_mul_f32 v[32:33], v[50:51], s[58:59] op_sel_hi:[1,0]
	v_pk_mul_f32 v[34:35], v[48:49], s[58:59] op_sel_hi:[1,0]
	v_cvt_pk_bf16_f32 v32, v32, v33
	v_cvt_pk_bf16_f32 v33, v34, v35
	ds_write2_b64 v29, v[30:31], v[32:33] offset0:88 offset1:90
	v_pk_mul_f32 v[30:31], v[54:55], s[58:59] op_sel_hi:[1,0]
	v_pk_mul_f32 v[32:33], v[52:53], s[58:59] op_sel_hi:[1,0]
	v_cvt_pk_bf16_f32 v30, v30, v31
	v_cvt_pk_bf16_f32 v31, v32, v33
	v_pk_mul_f32 v[32:33], v[46:47], s[58:59] op_sel_hi:[1,0]
	v_pk_mul_f32 v[34:35], v[44:45], s[58:59] op_sel_hi:[1,0]
	v_cvt_pk_bf16_f32 v32, v32, v33
	v_cvt_pk_bf16_f32 v33, v34, v35
	ds_write2_b64 v29, v[30:31], v[32:33] offset0:92 offset1:94
	v_or_b32_e32 v30, 0x800, v252
	v_mov_b32_e32 v31, v253
	v_lshl_add_u64 v[32:33], v[24:25], 0, v[30:31]
	v_lshl_add_u64 v[34:35], v[14:15], 0, v[30:31]
	global_load_dwordx4 v[30:33], v[32:33], off
	s_nop 0
	global_load_dwordx4 v[42:45], v[34:35], off
	v_accvgpr_read_b32 v34, a112
	v_accvgpr_read_b32 v35, a113
	v_add_u32_e32 v29, 0x8000, v28
	v_pk_mul_f32 v[22:23], v[22:23], s[58:59] op_sel_hi:[1,0]
	v_pk_mul_f32 v[20:21], v[20:21], s[58:59] op_sel_hi:[1,0]
	v_cvt_pk_bf16_f32 v22, v22, v23
	v_cvt_pk_bf16_f32 v23, v20, v21
	v_pk_mul_f32 v[20:21], v[40:41], s[58:59] op_sel_hi:[1,0]
	v_pk_mul_f32 v[18:19], v[18:19], s[58:59] op_sel_hi:[1,0]
	v_pk_mul_f32 v[16:17], v[16:17], s[58:59] op_sel_hi:[1,0]
	v_cvt_pk_bf16_f32 v20, v20, v21
	v_cvt_pk_bf16_f32 v18, v18, v19
	v_cvt_pk_bf16_f32 v19, v16, v17
	s_waitcnt vmcnt(0)
	v_pk_mul_f32 v[38:39], v[134:135], v[42:43]
	v_pk_mul_f32 v[46:47], v[130:131], v[44:45]
	v_pk_fma_f32 v[38:39], v[34:35], v[30:31], v[38:39] neg_lo:[0,0,1] neg_hi:[0,0,1]
	v_pk_fma_f32 v[46:47], v[132:133], v[32:33], v[46:47] neg_lo:[0,0,1] neg_hi:[0,0,1]
	v_pk_mul_f32 v[38:39], v[38:39], s[58:59] op_sel_hi:[1,0]
	v_pk_mul_f32 v[46:47], v[46:47], s[58:59] op_sel_hi:[1,0]
	v_cvt_pk_bf16_f32 v38, v38, v39
	v_cvt_pk_bf16_f32 v39, v46, v47
	v_pk_mul_f32 v[34:35], v[34:35], v[42:43]
	v_pk_mul_f32 v[46:47], v[132:133], v[44:45]
	v_pk_fma_f32 v[34:35], v[134:135], v[30:31], v[34:35]
	v_pk_fma_f32 v[46:47], v[130:131], v[32:33], v[46:47]
	v_pk_mul_f32 v[34:35], v[34:35], s[58:59] op_sel_hi:[1,0]
	v_pk_mul_f32 v[46:47], v[46:47], s[58:59] op_sel_hi:[1,0]
	v_cvt_pk_bf16_f32 v34, v34, v35
	v_cvt_pk_bf16_f32 v35, v46, v47
	ds_write2_b64 v29, v[38:39], v[34:35] offset0:128 offset1:130
	v_pk_mul_f32 v[34:35], v[108:109], s[58:59] op_sel_hi:[1,0]
	v_pk_mul_f32 v[38:39], v[104:105], s[58:59] op_sel_hi:[1,0]
	v_cvt_pk_bf16_f32 v34, v34, v35
	v_cvt_pk_bf16_f32 v35, v38, v39
	v_pk_mul_f32 v[38:39], v[102:103], s[58:59] op_sel_hi:[1,0]
	v_pk_mul_f32 v[46:47], v[100:101], s[58:59] op_sel_hi:[1,0]
	v_cvt_pk_bf16_f32 v38, v38, v39
	v_cvt_pk_bf16_f32 v39, v46, v47
	ds_write2_b64 v29, v[34:35], v[38:39] offset0:132 offset1:134
	v_accvgpr_read_b32 v34, a96
	v_accvgpr_read_b32 v35, a97
	v_pk_mul_f32 v[34:35], v[34:35], s[58:59] op_sel_hi:[1,0]
	v_pk_mul_f32 v[38:39], v[128:129], s[58:59] op_sel_hi:[1,0]
	v_cvt_pk_bf16_f32 v34, v34, v35
	v_cvt_pk_bf16_f32 v35, v38, v39
	v_pk_mul_f32 v[38:39], v[126:127], s[58:59] op_sel_hi:[1,0]
	v_pk_mul_f32 v[46:47], v[124:125], s[58:59] op_sel_hi:[1,0]
	v_cvt_pk_bf16_f32 v38, v38, v39
	v_cvt_pk_bf16_f32 v39, v46, v47
	ds_write2_b64 v29, v[34:35], v[38:39] offset0:136 offset1:138
	v_pk_mul_f32 v[34:35], v[122:123], s[58:59] op_sel_hi:[1,0]
	v_pk_mul_f32 v[38:39], v[118:119], s[58:59] op_sel_hi:[1,0]
	v_cvt_pk_bf16_f32 v34, v34, v35
	v_cvt_pk_bf16_f32 v35, v38, v39
	v_pk_mul_f32 v[38:39], v[114:115], s[58:59] op_sel_hi:[1,0]
	v_pk_mul_f32 v[46:47], v[110:111], s[58:59] op_sel_hi:[1,0]
	v_cvt_pk_bf16_f32 v38, v38, v39
	v_cvt_pk_bf16_f32 v39, v46, v47
	ds_write2_b64 v29, v[34:35], v[38:39] offset0:140 offset1:142
	v_accvgpr_read_b32 v34, a80
	v_accvgpr_read_b32 v35, a81
	v_pk_mul_f32 v[38:39], v[138:139], v[42:43]
	v_pk_mul_f32 v[46:47], v[70:71], v[44:45]
	v_pk_fma_f32 v[38:39], v[34:35], v[30:31], v[38:39] neg_lo:[0,0,1] neg_hi:[0,0,1]
	v_pk_mul_f32 v[34:35], v[34:35], v[42:43]
	v_pk_fma_f32 v[46:47], v[136:137], v[32:33], v[46:47] neg_lo:[0,0,1] neg_hi:[0,0,1]
	v_pk_fma_f32 v[30:31], v[138:139], v[30:31], v[34:35]
	v_pk_mul_f32 v[34:35], v[136:137], v[44:45]
	v_pk_mul_f32 v[38:39], v[38:39], s[58:59] op_sel_hi:[1,0]
	v_pk_fma_f32 v[32:33], v[70:71], v[32:33], v[34:35]
	v_pk_mul_f32 v[46:47], v[46:47], s[58:59] op_sel_hi:[1,0]
	v_pk_mul_f32 v[30:31], v[30:31], s[58:59] op_sel_hi:[1,0]
	v_pk_mul_f32 v[32:33], v[32:33], s[58:59] op_sel_hi:[1,0]
	v_cvt_pk_bf16_f32 v38, v38, v39
	v_cvt_pk_bf16_f32 v39, v46, v47
	v_cvt_pk_bf16_f32 v30, v30, v31
	v_cvt_pk_bf16_f32 v31, v32, v33
	ds_write2_b64 v29, v[38:39], v[30:31] offset0:144 offset1:146
	v_pk_mul_f32 v[30:31], v[120:121], s[58:59] op_sel_hi:[1,0]
	v_pk_mul_f32 v[32:33], v[116:117], s[58:59] op_sel_hi:[1,0]
	v_cvt_pk_bf16_f32 v30, v30, v31
	v_cvt_pk_bf16_f32 v31, v32, v33
	v_pk_mul_f32 v[32:33], v[112:113], s[58:59] op_sel_hi:[1,0]
	v_pk_mul_f32 v[34:35], v[106:107], s[58:59] op_sel_hi:[1,0]
	v_cvt_pk_bf16_f32 v32, v32, v33
	v_cvt_pk_bf16_f32 v33, v34, v35
	ds_write2_b64 v29, v[30:31], v[32:33] offset0:148 offset1:150
	v_accvgpr_read_b32 v30, a64
	v_accvgpr_read_b32 v31, a65
	v_pk_mul_f32 v[30:31], v[30:31], s[58:59] op_sel_hi:[1,0]
	v_pk_mul_f32 v[32:33], v[36:37], s[58:59] op_sel_hi:[1,0]
	v_cvt_pk_bf16_f32 v30, v30, v31
	v_cvt_pk_bf16_f32 v31, v32, v33
	ds_write2_b64 v29, v[30:31], v[22:23] offset0:152 offset1:154
	v_pk_mul_f32 v[22:23], v[26:27], s[58:59] op_sel_hi:[1,0]
	s_nop 0
	v_cvt_pk_bf16_f32 v21, v22, v23
	ds_write2_b64 v29, v[20:21], v[18:19] offset0:156 offset1:158
	v_or_b32_e32 v252, 0xc00, v252
	v_lshl_add_u64 v[16:17], v[24:25], 0, v[252:253]
	v_lshl_add_u64 v[18:19], v[14:15], 0, v[252:253]
	global_load_dwordx4 v[14:17], v[16:17], off
	s_nop 0
	global_load_dwordx4 v[18:21], v[18:19], off
	v_accvgpr_read_b32 v22, a48
	v_accvgpr_read_b32 v23, a49
	v_add_u32_e32 v28, 0xc000, v28
	v_pk_mul_f32 v[12:13], v[12:13], s[58:59] op_sel_hi:[1,0]
	v_pk_mul_f32 v[10:11], v[10:11], s[58:59] op_sel_hi:[1,0]
	v_pk_mul_f32 v[8:9], v[8:9], s[58:59] op_sel_hi:[1,0]
	v_pk_mul_f32 v[6:7], v[6:7], s[58:59] op_sel_hi:[1,0]
	v_pk_mul_f32 v[4:5], v[4:5], s[58:59] op_sel_hi:[1,0]
	v_pk_mul_f32 v[2:3], v[2:3], s[58:59] op_sel_hi:[1,0]
	v_pk_mul_f32 v[0:1], v[0:1], s[58:59] op_sel_hi:[1,0]
	v_cvt_pk_bf16_f32 v10, v10, v11
	v_cvt_pk_bf16_f32 v11, v8, v9
	v_cvt_pk_bf16_f32 v6, v6, v7
	v_cvt_pk_bf16_f32 v7, v4, v5
	v_cvt_pk_bf16_f32 v2, v2, v3
	v_cvt_pk_bf16_f32 v3, v0, v1
	ds_write2_b64 v28, v[6:7], v[2:3] offset0:220 offset1:222
	s_waitcnt vmcnt(0)
	v_pk_mul_f32 v[24:25], v[98:99], v[18:19]
	v_pk_mul_f32 v[26:27], v[94:95], v[20:21]
	v_pk_fma_f32 v[24:25], v[22:23], v[14:15], v[24:25] neg_lo:[0,0,1] neg_hi:[0,0,1]
	v_pk_fma_f32 v[26:27], v[96:97], v[16:17], v[26:27] neg_lo:[0,0,1] neg_hi:[0,0,1]
	v_pk_mul_f32 v[24:25], v[24:25], s[58:59] op_sel_hi:[1,0]
	v_pk_mul_f32 v[26:27], v[26:27], s[58:59] op_sel_hi:[1,0]
	v_cvt_pk_bf16_f32 v24, v24, v25
	v_cvt_pk_bf16_f32 v25, v26, v27
	v_pk_mul_f32 v[22:23], v[22:23], v[18:19]
	v_pk_mul_f32 v[26:27], v[96:97], v[20:21]
	v_pk_fma_f32 v[22:23], v[98:99], v[14:15], v[22:23]
	v_pk_fma_f32 v[26:27], v[94:95], v[16:17], v[26:27]
	v_pk_mul_f32 v[22:23], v[22:23], s[58:59] op_sel_hi:[1,0]
	v_pk_mul_f32 v[26:27], v[26:27], s[58:59] op_sel_hi:[1,0]
	v_cvt_pk_bf16_f32 v22, v22, v23
	v_cvt_pk_bf16_f32 v23, v26, v27
	ds_write2_b64 v28, v[24:25], v[22:23] offset0:192 offset1:194
	v_pk_mul_f32 v[22:23], v[78:79], s[58:59] op_sel_hi:[1,0]
	v_pk_mul_f32 v[24:25], v[76:77], s[58:59] op_sel_hi:[1,0]
	v_cvt_pk_bf16_f32 v22, v22, v23
	v_cvt_pk_bf16_f32 v23, v24, v25
	v_pk_mul_f32 v[24:25], v[74:75], s[58:59] op_sel_hi:[1,0]
	v_pk_mul_f32 v[26:27], v[72:73], s[58:59] op_sel_hi:[1,0]
	v_cvt_pk_bf16_f32 v24, v24, v25
	v_cvt_pk_bf16_f32 v25, v26, v27
	ds_write2_b64 v28, v[22:23], v[24:25] offset0:196 offset1:198
	v_accvgpr_read_b32 v22, a32
	v_accvgpr_read_b32 v23, a33
	v_pk_mul_f32 v[22:23], v[22:23], s[58:59] op_sel_hi:[1,0]
	v_pk_mul_f32 v[24:25], v[92:93], s[58:59] op_sel_hi:[1,0]
	v_cvt_pk_bf16_f32 v22, v22, v23
	v_cvt_pk_bf16_f32 v23, v24, v25
	v_pk_mul_f32 v[24:25], v[90:91], s[58:59] op_sel_hi:[1,0]
	v_pk_mul_f32 v[26:27], v[88:89], s[58:59] op_sel_hi:[1,0]
	v_cvt_pk_bf16_f32 v24, v24, v25
	v_cvt_pk_bf16_f32 v25, v26, v27
	ds_write2_b64 v28, v[22:23], v[24:25] offset0:200 offset1:202
	v_pk_mul_f32 v[22:23], v[86:87], s[58:59] op_sel_hi:[1,0]
	v_pk_mul_f32 v[24:25], v[84:85], s[58:59] op_sel_hi:[1,0]
	v_cvt_pk_bf16_f32 v22, v22, v23
	v_cvt_pk_bf16_f32 v23, v24, v25
	v_pk_mul_f32 v[24:25], v[82:83], s[58:59] op_sel_hi:[1,0]
	v_pk_mul_f32 v[26:27], v[80:81], s[58:59] op_sel_hi:[1,0]
	v_cvt_pk_bf16_f32 v24, v24, v25
	v_cvt_pk_bf16_f32 v25, v26, v27
	ds_write2_b64 v28, v[22:23], v[24:25] offset0:204 offset1:206
	v_accvgpr_read_b32 v23, a17
	v_accvgpr_read_b32 v22, a16
	v_pk_mul_f32 v[24:25], v[68:69], v[18:19]
	v_pk_mul_f32 v[18:19], v[22:23], v[18:19]
	v_pk_fma_f32 v[24:25], v[22:23], v[14:15], v[24:25] neg_lo:[0,0,1] neg_hi:[0,0,1]
	v_pk_mul_f32 v[26:27], v[60:61], v[20:21]
	v_pk_fma_f32 v[14:15], v[68:69], v[14:15], v[18:19]
	v_pk_mul_f32 v[18:19], v[62:63], v[20:21]
	v_pk_fma_f32 v[26:27], v[62:63], v[16:17], v[26:27] neg_lo:[0,0,1] neg_hi:[0,0,1]
	v_pk_fma_f32 v[16:17], v[60:61], v[16:17], v[18:19]
	v_pk_mul_f32 v[24:25], v[24:25], s[58:59] op_sel_hi:[1,0]
	v_pk_mul_f32 v[26:27], v[26:27], s[58:59] op_sel_hi:[1,0]
	v_pk_mul_f32 v[14:15], v[14:15], s[58:59] op_sel_hi:[1,0]
	v_pk_mul_f32 v[16:17], v[16:17], s[58:59] op_sel_hi:[1,0]
	v_cvt_pk_bf16_f32 v24, v24, v25
	v_cvt_pk_bf16_f32 v25, v26, v27
	v_cvt_pk_bf16_f32 v14, v14, v15
	v_cvt_pk_bf16_f32 v15, v16, v17
	ds_write2_b64 v28, v[24:25], v[14:15] offset0:208 offset1:210
	v_pk_mul_f32 v[14:15], v[66:67], s[58:59] op_sel_hi:[1,0]
	v_pk_mul_f32 v[16:17], v[58:59], s[58:59] op_sel_hi:[1,0]
	v_cvt_pk_bf16_f32 v14, v14, v15
	v_cvt_pk_bf16_f32 v15, v16, v17
	v_pk_mul_f32 v[16:17], v[56:57], s[58:59] op_sel_hi:[1,0]
	v_pk_mul_f32 v[18:19], v[64:65], s[58:59] op_sel_hi:[1,0]
	v_cvt_pk_bf16_f32 v16, v16, v17
	v_cvt_pk_bf16_f32 v17, v18, v19
	ds_write2_b64 v28, v[14:15], v[16:17] offset0:212 offset1:214
	v_accvgpr_read_b32 v15, a1
	v_accvgpr_read_b32 v14, a0
	v_pk_mul_f32 v[14:15], v[14:15], s[58:59] op_sel_hi:[1,0]
	s_nop 0
	v_cvt_pk_bf16_f32 v14, v14, v15
	v_cvt_pk_bf16_f32 v15, v12, v13
	ds_write2_b64 v28, v[14:15], v[10:11] offset0:216 offset1:218
	s_lshl_b64 s[8:9], s[8:9], 1
	s_add_u32 s8, s41, s8
	s_addc_u32 s9, s42, s9
	s_lshl_b64 s[6:7], s[6:7], 1
	s_add_u32 s6, s8, s6
	s_mov_b32 s8, 0
	s_waitcnt lgkmcnt(0)
	s_barrier
	s_addc_u32 s7, s9, s7
	v_mbcnt_lo_u32_b32 v0, -1, s8
	v_mbcnt_hi_u32_b32 v0, -1, v0
	v_or_b32_e32 v2, s34, v0
	v_lshlrev_b32_e32 v0, 4, v0
	v_and_b32_e32 v252, 0x1f0, v0
	v_lshl_add_u64 v[0:1], s[6:7], 0, v[252:253]

.LBB0_85:
	s_add_i32 s11, s9, 0xffff8000
	s_and_b32 s11, s11, 0x8000
	s_lshl_b32 s11, s11, 1
	v_lshl_or_b32 v250, v13, 1, s11
	v_add_u32_e32 v249, v250, v9
	v_add_u32_e32 v250, v250, v8
	ds_read_b128 v[14:17], v249
	ds_read_b128 v[18:21], v250 offset:32768
	ds_read_b128 v[22:25], v250 offset:36864
	ds_read_b128 v[26:29], v250 offset:40960
	ds_read_b128 v[30:33], v250 offset:45056
	ds_read_b128 v[48:51], v249 offset:4096
	s_waitcnt lgkmcnt(4)
	v_mfma_f32_32x32x16_bf16 a[240:255], v[14:17], v[18:21], a[240:255]
	s_waitcnt lgkmcnt(3)
	v_mfma_f32_32x32x16_bf16 a[176:191], v[14:17], v[22:25], a[176:191]
	s_and_b32 s98, s9, 0x8000
	s_lshl_b32 s98, s98, 1
	s_add_i32 s98, s40, s98
	v_lshl_add_u64 v[38:39], v[0:1], 0, s[4:5]
	v_lshl_add_u64 v[40:41], v[38:39], 0, s[38:39]
	s_mov_b32 m0, s98
	s_add_i32 s12, s98, 0x8000
	global_load_lds_dwordx4 v[40:41], off
	s_waitcnt lgkmcnt(2)
	v_mfma_f32_32x32x16_bf16 a[112:127], v[14:17], v[26:29], a[112:127]
	v_lshl_add_u64 v[40:41], v[4:5], 0, s[4:5]
	v_lshl_add_u64 v[42:43], v[40:41], 0, s[16:17]
	s_mov_b32 m0, s12
	s_nop 0
	global_load_lds_dwordx4 v[42:43], off
	s_waitcnt lgkmcnt(1)
	v_mfma_f32_32x32x16_bf16 a[48:63], v[14:17], v[30:33], a[48:63]
	v_lshl_add_u64 v[42:43], v[2:3], 0, s[4:5]
	v_lshl_add_u64 v[44:45], v[42:43], 0, s[44:45]
	s_add_i32 m0, s98, 0x400
	s_nop 0
	global_load_lds_dwordx4 v[44:45], off
	ds_read_b128 v[14:17], v249 offset:8192
	s_waitcnt lgkmcnt(1)
	v_mfma_f32_32x32x16_bf16 a[224:239], v[48:51], v[18:21], a[224:239]
	v_lshl_add_u64 v[44:45], v[6:7], 0, s[4:5]
	v_lshl_add_u64 v[46:47], v[44:45], 0, s[64:65]
	s_add_i32 m0, s98, 0x8400
	s_nop 0
	global_load_lds_dwordx4 v[46:47], off
	v_mfma_f32_32x32x16_bf16 a[160:175], v[48:51], v[22:25], a[160:175]
	v_lshl_add_u64 v[46:47], v[38:39], 0, s[2:3]
	s_add_i32 m0, s98, 0x800
	s_nop 0
	global_load_lds_dwordx4 v[46:47], off
	v_mfma_f32_32x32x16_bf16 a[96:111], v[48:51], v[26:29], a[96:111]
	v_lshl_add_u64 v[46:47], v[40:41], 0, s[66:67]
	s_add_i32 m0, s98, 0x8800
	s_nop 0
	global_load_lds_dwordx4 v[46:47], off
	v_mfma_f32_32x32x16_bf16 a[32:47], v[48:51], v[30:33], a[32:47]
	v_lshl_add_u64 v[46:47], v[42:43], 0, s[46:47]
	s_add_i32 m0, s98, 0xc00
	s_nop 0
	global_load_lds_dwordx4 v[46:47], off
	ds_read_b128 v[48:51], v249 offset:12288
	s_waitcnt lgkmcnt(1)
	v_mfma_f32_32x32x16_bf16 a[208:223], v[14:17], v[18:21], a[208:223]
	v_lshl_add_u64 v[46:47], v[44:45], 0, s[68:69]
	s_add_i32 m0, s98, 0x8c00
	s_nop 0
	global_load_lds_dwordx4 v[46:47], off
	v_mfma_f32_32x32x16_bf16 a[144:159], v[14:17], v[22:25], a[144:159]
	v_lshl_add_u64 v[46:47], v[38:39], 0, s[50:51]
	s_add_i32 m0, s98, 0x1000
	v_lshl_add_u64 v[38:39], v[38:39], 0, s[54:55]
	global_load_lds_dwordx4 v[46:47], off
	v_mfma_f32_32x32x16_bf16 a[80:95], v[14:17], v[26:29], a[80:95]
	v_lshl_add_u64 v[46:47], v[40:41], 0, s[70:71]
	s_add_i32 m0, s98, 0x9000
	s_nop 0
	global_load_lds_dwordx4 v[46:47], off
	v_mfma_f32_32x32x16_bf16 a[16:31], v[14:17], v[30:33], a[16:31]
	v_lshl_add_u64 v[46:47], v[42:43], 0, s[52:53]
	s_add_i32 m0, s98, 0x1400
	s_nop 0
	global_load_lds_dwordx4 v[46:47], off
	v_lshl_or_b32 v250, v12, 1, s11
	v_add_u32_e32 v249, v250, v9
	v_add_u32_e32 v250, v250, v8
	ds_read_b128 v[14:17], v249
	s_waitcnt lgkmcnt(1)
	v_mfma_f32_32x32x16_bf16 a[192:207], v[48:51], v[18:21], a[192:207]
	v_lshl_add_u64 v[46:47], v[44:45], 0, s[76:77]
	s_add_i32 m0, s98, 0x9400
	s_nop 0
	global_load_lds_dwordx4 v[46:47], off
	ds_read_b128 v[18:21], v250 offset:32768
	v_mfma_f32_32x32x16_bf16 a[128:143], v[48:51], v[22:25], a[128:143]
	s_add_i32 m0, s98, 0x1800
	s_nop 0
	global_load_lds_dwordx4 v[38:39], off
	ds_read_b128 v[22:25], v250 offset:36864
	v_mfma_f32_32x32x16_bf16 a[64:79], v[48:51], v[26:29], a[64:79]
	v_lshl_add_u64 v[38:39], v[40:41], 0, s[78:79]
	s_add_i32 m0, s98, 0x9800
	s_nop 0
	global_load_lds_dwordx4 v[38:39], off
	ds_read_b128 v[26:29], v250 offset:40960
	v_mfma_f32_32x32x16_bf16 a[0:15], v[48:51], v[30:33], a[0:15]
	v_lshl_add_u64 v[38:39], v[42:43], 0, s[56:57]
	s_add_i32 m0, s98, 0x1c00
	s_nop 0
	global_load_lds_dwordx4 v[38:39], off
	ds_read_b128 v[30:33], v250 offset:45056
	ds_read_b128 v[48:51], v249 offset:4096
	s_waitcnt lgkmcnt(4)
	v_mfma_f32_32x32x16_bf16 a[240:255], v[14:17], v[18:21], a[240:255]
	v_lshl_add_u64 v[38:39], v[44:45], 0, s[80:81]
	s_add_i32 m0, s98, 0x9c00
	s_nop 0
	global_load_lds_dwordx4 v[38:39], off
	s_waitcnt lgkmcnt(3)
	v_mfma_f32_32x32x16_bf16 a[176:191], v[14:17], v[22:25], a[176:191]
	s_waitcnt lgkmcnt(2)
	v_mfma_f32_32x32x16_bf16 a[112:127], v[14:17], v[26:29], a[112:127]
	s_waitcnt lgkmcnt(1)
	v_mfma_f32_32x32x16_bf16 a[48:63], v[14:17], v[30:33], a[48:63]
	ds_read_b128 v[14:17], v249 offset:8192
	s_waitcnt lgkmcnt(1)
	v_mfma_f32_32x32x16_bf16 a[224:239], v[48:51], v[18:21], a[224:239]
	v_mfma_f32_32x32x16_bf16 a[160:175], v[48:51], v[22:25], a[160:175]
	v_mfma_f32_32x32x16_bf16 a[96:111], v[48:51], v[26:29], a[96:111]
	v_mfma_f32_32x32x16_bf16 a[32:47], v[48:51], v[30:33], a[32:47]
	ds_read_b128 v[48:51], v249 offset:12288
	s_waitcnt lgkmcnt(1)
	v_mfma_f32_32x32x16_bf16 a[208:223], v[14:17], v[18:21], a[208:223]
	v_mfma_f32_32x32x16_bf16 a[144:159], v[14:17], v[22:25], a[144:159]
	v_mfma_f32_32x32x16_bf16 a[80:95], v[14:17], v[26:29], a[80:95]
	v_mfma_f32_32x32x16_bf16 a[16:31], v[14:17], v[30:33], a[16:31]
	v_lshl_or_b32 v250, v11, 1, s11
	v_add_u32_e32 v249, v250, v9
	v_add_u32_e32 v250, v250, v8
	ds_read_b128 v[14:17], v249
	s_waitcnt lgkmcnt(1)
	v_mfma_f32_32x32x16_bf16 a[192:207], v[48:51], v[18:21], a[192:207]
	ds_read_b128 v[18:21], v250 offset:32768
	v_mfma_f32_32x32x16_bf16 a[128:143], v[48:51], v[22:25], a[128:143]
	ds_read_b128 v[22:25], v250 offset:36864
	v_mfma_f32_32x32x16_bf16 a[64:79], v[48:51], v[26:29], a[64:79]
	ds_read_b128 v[26:29], v250 offset:40960
	v_mfma_f32_32x32x16_bf16 a[0:15], v[48:51], v[30:33], a[0:15]
	ds_read_b128 v[30:33], v250 offset:45056
	ds_read_b128 v[48:51], v249 offset:4096
	s_waitcnt lgkmcnt(4)
	v_mfma_f32_32x32x16_bf16 a[240:255], v[14:17], v[18:21], a[240:255]
	s_waitcnt lgkmcnt(3)
	v_mfma_f32_32x32x16_bf16 a[176:191], v[14:17], v[22:25], a[176:191]
	s_waitcnt lgkmcnt(2)
	v_mfma_f32_32x32x16_bf16 a[112:127], v[14:17], v[26:29], a[112:127]
	s_waitcnt lgkmcnt(1)
	v_mfma_f32_32x32x16_bf16 a[48:63], v[14:17], v[30:33], a[48:63]
	ds_read_b128 v[14:17], v249 offset:8192
	s_waitcnt lgkmcnt(1)
	v_mfma_f32_32x32x16_bf16 a[224:239], v[48:51], v[18:21], a[224:239]
	v_mfma_f32_32x32x16_bf16 a[160:175], v[48:51], v[22:25], a[160:175]
	v_mfma_f32_32x32x16_bf16 a[96:111], v[48:51], v[26:29], a[96:111]
	v_mfma_f32_32x32x16_bf16 a[32:47], v[48:51], v[30:33], a[32:47]
	ds_read_b128 v[48:51], v249 offset:12288
	s_waitcnt lgkmcnt(1)
	v_mfma_f32_32x32x16_bf16 a[208:223], v[14:17], v[18:21], a[208:223]
	v_mfma_f32_32x32x16_bf16 a[144:159], v[14:17], v[22:25], a[144:159]
	v_mfma_f32_32x32x16_bf16 a[80:95], v[14:17], v[26:29], a[80:95]
	v_mfma_f32_32x32x16_bf16 a[16:31], v[14:17], v[30:33], a[16:31]
	v_lshl_or_b32 v250, v10, 1, s11
	v_add_u32_e32 v249, v250, v9
	v_add_u32_e32 v250, v250, v8
	ds_read_b128 v[14:17], v249
	s_waitcnt lgkmcnt(1)
	v_mfma_f32_32x32x16_bf16 a[192:207], v[48:51], v[18:21], a[192:207]
	ds_read_b128 v[18:21], v250 offset:32768
	v_mfma_f32_32x32x16_bf16 a[128:143], v[48:51], v[22:25], a[128:143]
	ds_read_b128 v[22:25], v250 offset:36864
	v_mfma_f32_32x32x16_bf16 a[64:79], v[48:51], v[26:29], a[64:79]
	ds_read_b128 v[26:29], v250 offset:40960
	v_mfma_f32_32x32x16_bf16 a[0:15], v[48:51], v[30:33], a[0:15]
	ds_read_b128 v[30:33], v250 offset:45056
	ds_read_b128 v[48:51], v249 offset:4096
	s_waitcnt lgkmcnt(4)
	v_mfma_f32_32x32x16_bf16 a[240:255], v[14:17], v[18:21], a[240:255]
	s_waitcnt lgkmcnt(3)
	v_mfma_f32_32x32x16_bf16 a[176:191], v[14:17], v[22:25], a[176:191]
	s_waitcnt lgkmcnt(2)
	v_mfma_f32_32x32x16_bf16 a[112:127], v[14:17], v[26:29], a[112:127]
	s_waitcnt lgkmcnt(1)
	v_mfma_f32_32x32x16_bf16 a[48:63], v[14:17], v[30:33], a[48:63]
	ds_read_b128 v[14:17], v249 offset:8192
	s_waitcnt lgkmcnt(1)
	v_mfma_f32_32x32x16_bf16 a[224:239], v[48:51], v[18:21], a[224:239]
	v_mfma_f32_32x32x16_bf16 a[160:175], v[48:51], v[22:25], a[160:175]
	v_mfma_f32_32x32x16_bf16 a[96:111], v[48:51], v[26:29], a[96:111]
	v_mfma_f32_32x32x16_bf16 a[32:47], v[48:51], v[30:33], a[32:47]
	ds_read_b128 v[48:51], v249 offset:12288
	s_waitcnt lgkmcnt(1)
	v_mfma_f32_32x32x16_bf16 a[208:223], v[14:17], v[18:21], a[208:223]
	v_mfma_f32_32x32x16_bf16 a[144:159], v[14:17], v[22:25], a[144:159]
	v_mfma_f32_32x32x16_bf16 a[80:95], v[14:17], v[26:29], a[80:95]
	v_mfma_f32_32x32x16_bf16 a[16:31], v[14:17], v[30:33], a[16:31]
	s_waitcnt vmcnt(0)
	s_waitcnt vmcnt(0) lgkmcnt(0)
	s_barrier
	s_add_u32 s4, s4, 0x80
	s_addc_u32 s5, s5, 0
	s_add_i32 s9, s9, 0x8000
	s_cmpk_lg_i32 s4, 0x780
	v_mfma_f32_32x32x16_bf16 a[192:207], v[48:51], v[18:21], a[192:207]
	v_mfma_f32_32x32x16_bf16 a[128:143], v[48:51], v[22:25], a[128:143]
	v_mfma_f32_32x32x16_bf16 a[64:79], v[48:51], v[26:29], a[64:79]
	v_mfma_f32_32x32x16_bf16 a[0:15], v[48:51], v[30:33], a[0:15]
	s_cbranch_scc1 .LBB0_85
	v_lshlrev_b32_e32 v13, 1, v13
	s_mov_b32 s4, 0x10000
	s_mov_b32 s5, 0x18000
	v_add3_u32 v18, v9, v13, s4
	v_add3_u32 v13, v8, v13, s5
	ds_read_b128 v[0:3], v18
	ds_read_b128 v[4:7], v18 offset:4096
	ds_read_b128 v[14:17], v18 offset:8192
	ds_read_b128 v[18:21], v18 offset:12288
	ds_read_b128 v[22:25], v13
	ds_read_b128 v[26:29], v13 offset:4096
	ds_read_b128 v[30:33], v13 offset:8192
	ds_read_b128 v[34:37], v13 offset:12288
	s_waitcnt lgkmcnt(3)
	v_mfma_f32_32x32x16_bf16 a[240:255], v[0:3], v[22:25], a[240:255]
	v_lshlrev_b32_e32 v11, 1, v11
	s_waitcnt lgkmcnt(2)
	v_mfma_f32_32x32x16_bf16 a[176:191], v[0:3], v[26:29], a[176:191]
	s_waitcnt lgkmcnt(1)
	v_mfma_f32_32x32x16_bf16 a[112:127], v[0:3], v[30:33], a[112:127]
	s_waitcnt lgkmcnt(0)
	v_mfma_f32_32x32x16_bf16 a[48:63], v[0:3], v[34:37], a[48:63]
	v_mfma_f32_32x32x16_bf16 a[192:207], v[18:21], v[22:25], a[192:207]
	v_mfma_f32_32x32x16_bf16 a[128:143], v[18:21], v[26:29], a[128:143]
	v_mfma_f32_32x32x16_bf16 a[64:79], v[18:21], v[30:33], a[64:79]
	v_mfma_f32_32x32x16_bf16 a[0:15], v[18:21], v[34:37], a[0:15]
	v_lshlrev_b32_e32 v20, 1, v12
	v_mfma_f32_32x32x16_bf16 a[96:111], v[4:7], v[30:33], a[96:111]
	v_mfma_f32_32x32x16_bf16 a[208:223], v[14:17], v[22:25], a[208:223]
	v_mfma_f32_32x32x16_bf16 a[144:159], v[14:17], v[26:29], a[144:159]
	v_mfma_f32_32x32x16_bf16 a[80:95], v[14:17], v[30:33], a[80:95]
	v_add3_u32 v32, v8, v20, s5
	v_mfma_f32_32x32x16_bf16 a[16:31], v[14:17], v[34:37], a[16:31]
	v_add3_u32 v16, v9, v20, s4
	v_mfma_f32_32x32x16_bf16 a[224:239], v[4:7], v[22:25], a[224:239]
	v_mfma_f32_32x32x16_bf16 a[160:175], v[4:7], v[26:29], a[160:175]
	v_mfma_f32_32x32x16_bf16 a[32:47], v[4:7], v[34:37], a[32:47]
	ds_read_b128 v[0:3], v16
	ds_read_b128 v[4:7], v16 offset:4096
	ds_read_b128 v[12:15], v16 offset:8192
	ds_read_b128 v[16:19], v16 offset:12288
	ds_read_b128 v[20:23], v32
	ds_read_b128 v[24:27], v32 offset:4096
	ds_read_b128 v[28:31], v32 offset:8192
	ds_read_b128 v[32:35], v32 offset:12288
	s_waitcnt lgkmcnt(3)
	v_mfma_f32_32x32x16_bf16 a[240:255], v[0:3], v[20:23], a[240:255]
	s_waitcnt lgkmcnt(2)
	v_mfma_f32_32x32x16_bf16 a[176:191], v[0:3], v[24:27], a[176:191]
	s_waitcnt lgkmcnt(1)
	v_mfma_f32_32x32x16_bf16 a[112:127], v[0:3], v[28:31], a[112:127]
	s_waitcnt lgkmcnt(0)
	v_mfma_f32_32x32x16_bf16 a[48:63], v[0:3], v[32:35], a[48:63]
	v_mfma_f32_32x32x16_bf16 a[192:207], v[16:19], v[20:23], a[192:207]
	v_mfma_f32_32x32x16_bf16 a[128:143], v[16:19], v[24:27], a[128:143]
	v_mfma_f32_32x32x16_bf16 a[64:79], v[16:19], v[28:31], a[64:79]
	v_mfma_f32_32x32x16_bf16 a[0:15], v[16:19], v[32:35], a[0:15]
	v_add3_u32 v16, v9, v11, s4
	v_add3_u32 v11, v8, v11, s5
	v_mfma_f32_32x32x16_bf16 a[224:239], v[4:7], v[20:23], a[224:239]
	v_mfma_f32_32x32x16_bf16 a[160:175], v[4:7], v[24:27], a[160:175]
	v_mfma_f32_32x32x16_bf16 a[96:111], v[4:7], v[28:31], a[96:111]
	v_mfma_f32_32x32x16_bf16 a[32:47], v[4:7], v[32:35], a[32:47]
	v_mfma_f32_32x32x16_bf16 a[208:223], v[12:15], v[20:23], a[208:223]
	v_mfma_f32_32x32x16_bf16 a[144:159], v[12:15], v[24:27], a[144:159]
	v_mfma_f32_32x32x16_bf16 a[80:95], v[12:15], v[28:31], a[80:95]
	v_mfma_f32_32x32x16_bf16 a[16:31], v[12:15], v[32:35], a[16:31]
	ds_read_b128 v[0:3], v16
	ds_read_b128 v[4:7], v16 offset:4096
	ds_read_b128 v[12:15], v16 offset:8192
	ds_read_b128 v[16:19], v16 offset:12288
	ds_read_b128 v[20:23], v11
	ds_read_b128 v[24:27], v11 offset:4096
	ds_read_b128 v[28:31], v11 offset:8192
	ds_read_b128 v[32:35], v11 offset:12288
	s_waitcnt lgkmcnt(3)
	v_mfma_f32_32x32x16_bf16 a[240:255], v[0:3], v[20:23], a[240:255]
	s_waitcnt lgkmcnt(2)
	v_mfma_f32_32x32x16_bf16 a[176:191], v[0:3], v[24:27], a[176:191]
	s_waitcnt lgkmcnt(1)
	v_mfma_f32_32x32x16_bf16 a[112:127], v[0:3], v[28:31], a[112:127]
	s_waitcnt lgkmcnt(0)
	v_mfma_f32_32x32x16_bf16 a[48:63], v[0:3], v[32:35], a[48:63]
	v_mfma_f32_32x32x16_bf16 a[192:207], v[16:19], v[20:23], a[192:207]
	v_mfma_f32_32x32x16_bf16 a[128:143], v[16:19], v[24:27], a[128:143]
	v_mfma_f32_32x32x16_bf16 a[64:79], v[16:19], v[28:31], a[64:79]
	v_mfma_f32_32x32x16_bf16 a[0:15], v[16:19], v[32:35], a[0:15]
	v_lshlrev_b32_e32 v18, 1, v10
	v_add3_u32 v9, v9, v18, s4
	v_add3_u32 v8, v8, v18, s5
	s_mov_b32 s5, 0
	s_mov_b32 s4, 0
	v_mfma_f32_32x32x16_bf16 a[224:239], v[4:7], v[20:23], a[224:239]
	v_mfma_f32_32x32x16_bf16 a[160:175], v[4:7], v[24:27], a[160:175]
	v_mfma_f32_32x32x16_bf16 a[96:111], v[4:7], v[28:31], a[96:111]
	v_mfma_f32_32x32x16_bf16 a[32:47], v[4:7], v[32:35], a[32:47]
	v_mfma_f32_32x32x16_bf16 a[208:223], v[12:15], v[20:23], a[208:223]
	v_mfma_f32_32x32x16_bf16 a[144:159], v[12:15], v[24:27], a[144:159]
	v_mfma_f32_32x32x16_bf16 a[80:95], v[12:15], v[28:31], a[80:95]
	v_mfma_f32_32x32x16_bf16 a[16:31], v[12:15], v[32:35], a[16:31]
	ds_read_b128 v[0:3], v9
	ds_read_b128 v[4:7], v9 offset:4096
	ds_read_b128 v[10:13], v9 offset:8192
	ds_read_b128 v[14:17], v9 offset:12288
	ds_read_b128 v[18:21], v8
	ds_read_b128 v[22:25], v8 offset:4096
	ds_read_b128 v[26:29], v8 offset:8192
	ds_read_b128 v[30:33], v8 offset:12288
	s_waitcnt vmcnt(0)
	s_waitcnt lgkmcnt(0)
	s_barrier
	v_mfma_f32_32x32x16_bf16 a[240:255], v[0:3], v[18:21], a[240:255]
	v_mfma_f32_32x32x16_bf16 a[176:191], v[0:3], v[22:25], a[176:191]
	v_mfma_f32_32x32x16_bf16 a[112:127], v[0:3], v[26:29], a[112:127]
	v_mfma_f32_32x32x16_bf16 a[48:63], v[0:3], v[30:33], a[48:63]
	v_mbcnt_lo_u32_b32 v0, -1, s5
	v_mbcnt_hi_u32_b32 v0, -1, v0
	v_or_b32_e32 v1, s34, v0
	v_and_b32_e32 v2, 31, v0
	v_lshlrev_b32_e32 v1, 1, v1
	v_and_or_b32 v1, v1, s14, v2
	v_mov_b32_e32 v2, s34
	s_mov_b32 s5, 0x7fffff80
	v_bitop3_b32 v2, v0, s5, v2 bitop3:0xc8
	v_lshrrev_b32_e32 v0, 2, v0
	v_and_b32_e32 v0, 8, v0
	v_lshl_or_b32 v0, v2, 1, v0
	v_mad_u32_u24 v0, v1, s25, v0
	v_accvgpr_read_b32 v1, a241
	v_accvgpr_read_b32 v2, a240
	v_cvt_pk_bf16_f32 v2, v2, v1
	v_accvgpr_read_b32 v1, a243
	v_accvgpr_read_b32 v3, a242
	v_mfma_f32_32x32x16_bf16 a[224:239], v[4:7], v[18:21], a[224:239]
	v_cvt_pk_bf16_f32 v3, v3, v1
	v_accvgpr_read_b32 v1, a245
	s_lshl_b32 s5, s62, 7
	s_and_b32 s5, s5, 0xfffffc00
	s_add_i32 s5, s8, s5
	s_add_i32 s12, s5, 0xfffffc00
	s_ashr_i32 s13, s12, 31
	v_mfma_f32_32x32x16_bf16 a[160:175], v[4:7], v[22:25], a[160:175]
	s_lshl_b64 s[12:13], s[12:13], 12
	s_add_u32 s5, s30, s12
	s_addc_u32 s9, s31, s13
	s_lshl_b32 s11, s21, 1
	s_add_u32 s12, s5, s11
	s_mov_b32 s5, 0
	s_addc_u32 s13, s9, 0
	v_mfma_f32_32x32x16_bf16 a[96:111], v[4:7], v[26:29], a[96:111]
	v_mfma_f32_32x32x16_bf16 a[32:47], v[4:7], v[30:33], a[32:47]
	v_accvgpr_read_b32 v4, a244
	v_cvt_pk_bf16_f32 v4, v4, v1
	v_accvgpr_read_b32 v1, a247
	v_accvgpr_read_b32 v5, a246
	v_cvt_pk_bf16_f32 v5, v5, v1
	ds_write2_b64 v0, v[2:3], v[4:5] offset1:2
	v_accvgpr_read_b32 v1, a249
	v_accvgpr_read_b32 v2, a248
	v_cvt_pk_bf16_f32 v2, v2, v1
	v_accvgpr_read_b32 v1, a251
	v_accvgpr_read_b32 v3, a250
	v_cvt_pk_bf16_f32 v3, v3, v1
	v_accvgpr_read_b32 v1, a253
	v_accvgpr_read_b32 v4, a252
	v_cvt_pk_bf16_f32 v4, v4, v1
	v_accvgpr_read_b32 v1, a255
	v_accvgpr_read_b32 v5, a254
	v_cvt_pk_bf16_f32 v5, v5, v1
	ds_write2_b64 v0, v[2:3], v[4:5] offset0:4 offset1:6
	v_accvgpr_read_b32 v1, a225
	v_accvgpr_read_b32 v2, a224
	v_cvt_pk_bf16_f32 v2, v2, v1
	v_accvgpr_read_b32 v1, a227
	v_accvgpr_read_b32 v3, a226
	v_mfma_f32_32x32x16_bf16 a[208:223], v[10:13], v[18:21], a[208:223]
	v_cvt_pk_bf16_f32 v3, v3, v1
	v_accvgpr_read_b32 v1, a229
	v_accvgpr_read_b32 v4, a228
	v_cvt_pk_bf16_f32 v4, v4, v1
	v_accvgpr_read_b32 v1, a231
	v_accvgpr_read_b32 v5, a230
	v_cvt_pk_bf16_f32 v5, v5, v1
	ds_write2_b64 v0, v[2:3], v[4:5] offset0:8 offset1:10
	v_accvgpr_read_b32 v1, a233
	v_accvgpr_read_b32 v2, a232
	v_cvt_pk_bf16_f32 v2, v2, v1
	v_accvgpr_read_b32 v1, a235
	v_accvgpr_read_b32 v3, a234
	v_cvt_pk_bf16_f32 v3, v3, v1
	v_accvgpr_read_b32 v1, a237
	v_accvgpr_read_b32 v4, a236
	v_cvt_pk_bf16_f32 v4, v4, v1
	v_accvgpr_read_b32 v1, a239
	v_accvgpr_read_b32 v5, a238
	v_cvt_pk_bf16_f32 v5, v5, v1
	ds_write2_b64 v0, v[2:3], v[4:5] offset0:12 offset1:14
	v_accvgpr_read_b32 v1, a209
	v_accvgpr_read_b32 v2, a208
	v_cvt_pk_bf16_f32 v2, v2, v1
	v_accvgpr_read_b32 v1, a211
	v_accvgpr_read_b32 v3, a210
	v_mfma_f32_32x32x16_bf16 a[192:207], v[14:17], v[18:21], a[192:207]
	v_cvt_pk_bf16_f32 v3, v3, v1
	v_accvgpr_read_b32 v1, a213
	v_accvgpr_read_b32 v4, a212
	v_cvt_pk_bf16_f32 v4, v4, v1
	v_accvgpr_read_b32 v1, a215
	v_accvgpr_read_b32 v5, a214
	v_cvt_pk_bf16_f32 v5, v5, v1
	ds_write2_b64 v0, v[2:3], v[4:5] offset0:16 offset1:18
	v_accvgpr_read_b32 v1, a217
	v_accvgpr_read_b32 v2, a216
	v_cvt_pk_bf16_f32 v2, v2, v1
	v_accvgpr_read_b32 v1, a219
	v_accvgpr_read_b32 v3, a218
	v_cvt_pk_bf16_f32 v3, v3, v1
	v_accvgpr_read_b32 v1, a221
	v_accvgpr_read_b32 v4, a220
	v_cvt_pk_bf16_f32 v4, v4, v1
	v_accvgpr_read_b32 v1, a223
	v_accvgpr_read_b32 v5, a222
	v_cvt_pk_bf16_f32 v5, v5, v1
	ds_write2_b64 v0, v[2:3], v[4:5] offset0:20 offset1:22
	v_accvgpr_read_b32 v1, a193
	v_accvgpr_read_b32 v2, a192
	v_cvt_pk_bf16_f32 v2, v2, v1
	v_accvgpr_read_b32 v1, a195
	v_accvgpr_read_b32 v3, a194
	v_cvt_pk_bf16_f32 v3, v3, v1
	v_accvgpr_read_b32 v1, a197
	v_accvgpr_read_b32 v4, a196
	v_cvt_pk_bf16_f32 v4, v4, v1
	v_accvgpr_read_b32 v1, a199
	v_accvgpr_read_b32 v5, a198
	v_cvt_pk_bf16_f32 v5, v5, v1
	ds_write2_b64 v0, v[2:3], v[4:5] offset0:24 offset1:26
	v_accvgpr_read_b32 v1, a201
	v_accvgpr_read_b32 v2, a200
	v_cvt_pk_bf16_f32 v2, v2, v1
	v_accvgpr_read_b32 v1, a203
	v_accvgpr_read_b32 v3, a202
	v_cvt_pk_bf16_f32 v3, v3, v1
	v_accvgpr_read_b32 v1, a205
	v_accvgpr_read_b32 v4, a204
	v_cvt_pk_bf16_f32 v4, v4, v1
	v_accvgpr_read_b32 v1, a207
	v_accvgpr_read_b32 v5, a206
	v_cvt_pk_bf16_f32 v5, v5, v1
	ds_write2_b64 v0, v[2:3], v[4:5] offset0:28 offset1:30
	v_accvgpr_read_b32 v1, a177
	v_accvgpr_read_b32 v2, a176
	v_cvt_pk_bf16_f32 v2, v2, v1
	v_accvgpr_read_b32 v1, a179
	v_accvgpr_read_b32 v3, a178
	v_cvt_pk_bf16_f32 v3, v3, v1
	v_accvgpr_read_b32 v1, a181
	v_accvgpr_read_b32 v4, a180
	v_cvt_pk_bf16_f32 v4, v4, v1
	v_accvgpr_read_b32 v1, a183
	v_accvgpr_read_b32 v5, a182
	v_cvt_pk_bf16_f32 v5, v5, v1
	v_add_u32_e32 v1, 0x4000, v0
	ds_write2_b64 v1, v[2:3], v[4:5] offset0:64 offset1:66
	v_accvgpr_read_b32 v2, a185
	v_accvgpr_read_b32 v3, a184
	v_cvt_pk_bf16_f32 v2, v3, v2
	v_accvgpr_read_b32 v3, a187
	v_accvgpr_read_b32 v4, a186
	v_cvt_pk_bf16_f32 v3, v4, v3
	v_accvgpr_read_b32 v4, a189
	v_accvgpr_read_b32 v5, a188
	v_cvt_pk_bf16_f32 v4, v5, v4
	v_accvgpr_read_b32 v5, a191
	v_accvgpr_read_b32 v6, a190
	v_cvt_pk_bf16_f32 v5, v6, v5
	ds_write2_b64 v1, v[2:3], v[4:5] offset0:68 offset1:70
	v_accvgpr_read_b32 v2, a161
	v_accvgpr_read_b32 v3, a160
	v_cvt_pk_bf16_f32 v2, v3, v2
	v_accvgpr_read_b32 v3, a163
	v_accvgpr_read_b32 v4, a162
	v_mfma_f32_32x32x16_bf16 a[144:159], v[10:13], v[22:25], a[144:159]
	v_cvt_pk_bf16_f32 v3, v4, v3
	v_accvgpr_read_b32 v4, a165
	v_accvgpr_read_b32 v5, a164
	v_cvt_pk_bf16_f32 v4, v5, v4
	v_accvgpr_read_b32 v5, a167
	v_accvgpr_read_b32 v6, a166
	v_cvt_pk_bf16_f32 v5, v6, v5
	ds_write2_b64 v1, v[2:3], v[4:5] offset0:72 offset1:74
	v_accvgpr_read_b32 v2, a169
	v_accvgpr_read_b32 v3, a168
	v_cvt_pk_bf16_f32 v2, v3, v2
	v_accvgpr_read_b32 v3, a171
	v_accvgpr_read_b32 v4, a170
	v_cvt_pk_bf16_f32 v3, v4, v3
	v_accvgpr_read_b32 v4, a173
	v_accvgpr_read_b32 v5, a172
	v_cvt_pk_bf16_f32 v4, v5, v4
	v_accvgpr_read_b32 v5, a175
	v_accvgpr_read_b32 v6, a174
	v_cvt_pk_bf16_f32 v5, v6, v5
	ds_write2_b64 v1, v[2:3], v[4:5] offset0:76 offset1:78
	v_accvgpr_read_b32 v2, a145
	v_accvgpr_read_b32 v3, a144
	v_cvt_pk_bf16_f32 v2, v3, v2
	v_accvgpr_read_b32 v3, a147
	v_accvgpr_read_b32 v4, a146
	v_mfma_f32_32x32x16_bf16 a[128:143], v[14:17], v[22:25], a[128:143]
	v_cvt_pk_bf16_f32 v3, v4, v3
	v_accvgpr_read_b32 v4, a149
	v_accvgpr_read_b32 v5, a148
	v_cvt_pk_bf16_f32 v4, v5, v4
	v_accvgpr_read_b32 v5, a151
	v_accvgpr_read_b32 v6, a150
	v_cvt_pk_bf16_f32 v5, v6, v5
	ds_write2_b64 v1, v[2:3], v[4:5] offset0:80 offset1:82
	v_accvgpr_read_b32 v2, a153
	v_accvgpr_read_b32 v3, a152
	v_cvt_pk_bf16_f32 v2, v3, v2
	v_accvgpr_read_b32 v3, a155
	v_accvgpr_read_b32 v4, a154
	v_cvt_pk_bf16_f32 v3, v4, v3
	v_accvgpr_read_b32 v4, a157
	v_accvgpr_read_b32 v5, a156
	v_cvt_pk_bf16_f32 v4, v5, v4
	v_accvgpr_read_b32 v5, a159
	v_accvgpr_read_b32 v6, a158
	v_cvt_pk_bf16_f32 v5, v6, v5
	ds_write2_b64 v1, v[2:3], v[4:5] offset0:84 offset1:86
	v_accvgpr_read_b32 v2, a129
	v_accvgpr_read_b32 v3, a128
	v_cvt_pk_bf16_f32 v2, v3, v2
	v_accvgpr_read_b32 v3, a131
	v_accvgpr_read_b32 v4, a130
	v_cvt_pk_bf16_f32 v3, v4, v3
	v_accvgpr_read_b32 v4, a133
	v_accvgpr_read_b32 v5, a132
	v_cvt_pk_bf16_f32 v4, v5, v4
	v_accvgpr_read_b32 v5, a135
	v_accvgpr_read_b32 v6, a134
	v_cvt_pk_bf16_f32 v5, v6, v5
	ds_write2_b64 v1, v[2:3], v[4:5] offset0:88 offset1:90
	v_accvgpr_read_b32 v2, a137
	v_accvgpr_read_b32 v3, a136
	v_cvt_pk_bf16_f32 v2, v3, v2
	v_accvgpr_read_b32 v3, a139
	v_accvgpr_read_b32 v4, a138
	v_cvt_pk_bf16_f32 v3, v4, v3
	v_accvgpr_read_b32 v4, a141
	v_accvgpr_read_b32 v5, a140
	v_cvt_pk_bf16_f32 v4, v5, v4
	v_accvgpr_read_b32 v5, a143
	v_accvgpr_read_b32 v6, a142
	v_cvt_pk_bf16_f32 v5, v6, v5
	ds_write2_b64 v1, v[2:3], v[4:5] offset0:92 offset1:94
	v_accvgpr_read_b32 v1, a113
	v_accvgpr_read_b32 v2, a112
	v_cvt_pk_bf16_f32 v2, v2, v1
	v_accvgpr_read_b32 v1, a115
	v_accvgpr_read_b32 v3, a114
	v_cvt_pk_bf16_f32 v3, v3, v1
	v_accvgpr_read_b32 v1, a117
	v_accvgpr_read_b32 v4, a116
	v_cvt_pk_bf16_f32 v4, v4, v1
	v_accvgpr_read_b32 v1, a119
	v_accvgpr_read_b32 v5, a118
	v_cvt_pk_bf16_f32 v5, v5, v1
	v_add_u32_e32 v1, 0x8000, v0
	ds_write2_b64 v1, v[2:3], v[4:5] offset0:128 offset1:130
	v_accvgpr_read_b32 v2, a121
	v_accvgpr_read_b32 v3, a120
	v_cvt_pk_bf16_f32 v2, v3, v2
	v_accvgpr_read_b32 v3, a123
	v_accvgpr_read_b32 v4, a122
	v_cvt_pk_bf16_f32 v3, v4, v3
	v_accvgpr_read_b32 v4, a125
	v_accvgpr_read_b32 v5, a124
	v_cvt_pk_bf16_f32 v4, v5, v4
	v_accvgpr_read_b32 v5, a127
	v_accvgpr_read_b32 v6, a126
	v_cvt_pk_bf16_f32 v5, v6, v5
	ds_write2_b64 v1, v[2:3], v[4:5] offset0:132 offset1:134
	v_accvgpr_read_b32 v2, a97
	v_accvgpr_read_b32 v3, a96
	v_cvt_pk_bf16_f32 v2, v3, v2
	v_accvgpr_read_b32 v3, a99
	v_accvgpr_read_b32 v4, a98
	v_mfma_f32_32x32x16_bf16 a[80:95], v[10:13], v[26:29], a[80:95]
	v_cvt_pk_bf16_f32 v3, v4, v3
	v_accvgpr_read_b32 v4, a101
	v_accvgpr_read_b32 v5, a100
	v_cvt_pk_bf16_f32 v4, v5, v4
	v_accvgpr_read_b32 v5, a103
	v_accvgpr_read_b32 v6, a102
	v_cvt_pk_bf16_f32 v5, v6, v5
	ds_write2_b64 v1, v[2:3], v[4:5] offset0:136 offset1:138
	v_accvgpr_read_b32 v2, a105
	v_accvgpr_read_b32 v3, a104
	v_cvt_pk_bf16_f32 v2, v3, v2
	v_accvgpr_read_b32 v3, a107
	v_accvgpr_read_b32 v4, a106
	v_cvt_pk_bf16_f32 v3, v4, v3
	v_accvgpr_read_b32 v4, a109
	v_accvgpr_read_b32 v5, a108
	v_cvt_pk_bf16_f32 v4, v5, v4
	v_accvgpr_read_b32 v5, a111
	v_accvgpr_read_b32 v6, a110
	v_cvt_pk_bf16_f32 v5, v6, v5
	ds_write2_b64 v1, v[2:3], v[4:5] offset0:140 offset1:142
	v_accvgpr_read_b32 v2, a81
	v_accvgpr_read_b32 v3, a80
	v_cvt_pk_bf16_f32 v2, v3, v2
	v_accvgpr_read_b32 v3, a83
	v_accvgpr_read_b32 v4, a82
	v_mfma_f32_32x32x16_bf16 a[64:79], v[14:17], v[26:29], a[64:79]
	v_cvt_pk_bf16_f32 v3, v4, v3
	v_accvgpr_read_b32 v4, a85
	v_accvgpr_read_b32 v5, a84
	v_cvt_pk_bf16_f32 v4, v5, v4
	v_accvgpr_read_b32 v5, a87
	v_accvgpr_read_b32 v6, a86
	v_cvt_pk_bf16_f32 v5, v6, v5
	ds_write2_b64 v1, v[2:3], v[4:5] offset0:144 offset1:146
	v_accvgpr_read_b32 v2, a89
	v_accvgpr_read_b32 v3, a88
	v_cvt_pk_bf16_f32 v2, v3, v2
	v_accvgpr_read_b32 v3, a91
	v_accvgpr_read_b32 v4, a90
	v_cvt_pk_bf16_f32 v3, v4, v3
	v_accvgpr_read_b32 v4, a93
	v_accvgpr_read_b32 v5, a92
	v_cvt_pk_bf16_f32 v4, v5, v4
	v_accvgpr_read_b32 v5, a95
	v_accvgpr_read_b32 v6, a94
	v_cvt_pk_bf16_f32 v5, v6, v5
	ds_write2_b64 v1, v[2:3], v[4:5] offset0:148 offset1:150
	v_accvgpr_read_b32 v2, a65
	v_accvgpr_read_b32 v3, a64
	v_cvt_pk_bf16_f32 v2, v3, v2
	v_accvgpr_read_b32 v3, a67
	v_accvgpr_read_b32 v4, a66
	v_cvt_pk_bf16_f32 v3, v4, v3
	v_accvgpr_read_b32 v4, a69
	v_accvgpr_read_b32 v5, a68
	v_cvt_pk_bf16_f32 v4, v5, v4
	v_accvgpr_read_b32 v5, a71
	v_accvgpr_read_b32 v6, a70
	v_cvt_pk_bf16_f32 v5, v6, v5
	ds_write2_b64 v1, v[2:3], v[4:5] offset0:152 offset1:154
	v_accvgpr_read_b32 v2, a73
	v_accvgpr_read_b32 v3, a72
	v_cvt_pk_bf16_f32 v2, v3, v2
	v_accvgpr_read_b32 v3, a75
	v_accvgpr_read_b32 v4, a74
	v_cvt_pk_bf16_f32 v3, v4, v3
	v_accvgpr_read_b32 v4, a77
	v_accvgpr_read_b32 v5, a76
	v_cvt_pk_bf16_f32 v4, v5, v4
	v_accvgpr_read_b32 v5, a79
	v_accvgpr_read_b32 v6, a78
	v_cvt_pk_bf16_f32 v5, v6, v5
	ds_write2_b64 v1, v[2:3], v[4:5] offset0:156 offset1:158
	v_accvgpr_read_b32 v1, a49
	v_accvgpr_read_b32 v2, a48
	v_cvt_pk_bf16_f32 v2, v2, v1
	v_accvgpr_read_b32 v1, a51
	v_accvgpr_read_b32 v3, a50
	v_cvt_pk_bf16_f32 v3, v3, v1
	v_accvgpr_read_b32 v1, a53
	v_accvgpr_read_b32 v4, a52
	v_cvt_pk_bf16_f32 v4, v4, v1
	v_accvgpr_read_b32 v1, a55
	v_accvgpr_read_b32 v5, a54
	v_cvt_pk_bf16_f32 v5, v5, v1
	v_add_u32_e32 v6, 0xc000, v0
	v_accvgpr_read_b32 v0, a57
	v_accvgpr_read_b32 v1, a56
	ds_write2_b64 v6, v[2:3], v[4:5] offset0:192 offset1:194
	v_cvt_pk_bf16_f32 v0, v1, v0
	v_accvgpr_read_b32 v1, a59
	v_accvgpr_read_b32 v2, a58
	v_cvt_pk_bf16_f32 v1, v2, v1
	v_accvgpr_read_b32 v2, a61
	v_accvgpr_read_b32 v3, a60
	v_cvt_pk_bf16_f32 v2, v3, v2
	v_accvgpr_read_b32 v3, a63
	v_accvgpr_read_b32 v4, a62
	v_cvt_pk_bf16_f32 v3, v4, v3
	ds_write2_b64 v6, v[0:1], v[2:3] offset0:196 offset1:198
	v_accvgpr_read_b32 v0, a33
	v_accvgpr_read_b32 v1, a32
	v_cvt_pk_bf16_f32 v0, v1, v0
	v_accvgpr_read_b32 v1, a35
	v_accvgpr_read_b32 v2, a34
	v_mfma_f32_32x32x16_bf16 a[16:31], v[10:13], v[30:33], a[16:31]
	v_cvt_pk_bf16_f32 v1, v2, v1
	v_accvgpr_read_b32 v2, a37
	v_accvgpr_read_b32 v3, a36
	v_cvt_pk_bf16_f32 v2, v3, v2
	v_accvgpr_read_b32 v3, a39
	v_accvgpr_read_b32 v4, a38
	v_cvt_pk_bf16_f32 v3, v4, v3
	ds_write2_b64 v6, v[0:1], v[2:3] offset0:200 offset1:202
	v_accvgpr_read_b32 v0, a41
	v_accvgpr_read_b32 v1, a40
	v_cvt_pk_bf16_f32 v0, v1, v0
	v_accvgpr_read_b32 v1, a43
	v_accvgpr_read_b32 v2, a42
	v_cvt_pk_bf16_f32 v1, v2, v1
	v_accvgpr_read_b32 v2, a45
	v_accvgpr_read_b32 v3, a44
	v_cvt_pk_bf16_f32 v2, v3, v2
	v_accvgpr_read_b32 v3, a47
	v_accvgpr_read_b32 v4, a46
	v_cvt_pk_bf16_f32 v3, v4, v3
	ds_write2_b64 v6, v[0:1], v[2:3] offset0:204 offset1:206
	v_accvgpr_read_b32 v0, a17
	v_accvgpr_read_b32 v1, a16
	v_cvt_pk_bf16_f32 v0, v1, v0
	v_accvgpr_read_b32 v1, a19
	v_accvgpr_read_b32 v2, a18
	v_mfma_f32_32x32x16_bf16 a[0:15], v[14:17], v[30:33], a[0:15]
	v_cvt_pk_bf16_f32 v1, v2, v1
	v_accvgpr_read_b32 v2, a21
	v_accvgpr_read_b32 v3, a20
	v_cvt_pk_bf16_f32 v2, v3, v2
	v_accvgpr_read_b32 v3, a23
	v_accvgpr_read_b32 v4, a22
	v_cvt_pk_bf16_f32 v3, v4, v3
	ds_write2_b64 v6, v[0:1], v[2:3] offset0:208 offset1:210
	v_accvgpr_read_b32 v0, a25
	v_accvgpr_read_b32 v1, a24
	v_cvt_pk_bf16_f32 v0, v1, v0
	v_accvgpr_read_b32 v1, a27
	v_accvgpr_read_b32 v2, a26
	v_cvt_pk_bf16_f32 v1, v2, v1
	v_accvgpr_read_b32 v2, a29
	v_accvgpr_read_b32 v3, a28
	v_cvt_pk_bf16_f32 v2, v3, v2
	v_accvgpr_read_b32 v3, a31
	v_accvgpr_read_b32 v4, a30
	v_cvt_pk_bf16_f32 v3, v4, v3
	ds_write2_b64 v6, v[0:1], v[2:3] offset0:212 offset1:214
	v_accvgpr_read_b32 v0, a1
	v_accvgpr_read_b32 v1, a0
	v_cvt_pk_bf16_f32 v0, v1, v0
	v_accvgpr_read_b32 v1, a3
	v_accvgpr_read_b32 v2, a2
	v_cvt_pk_bf16_f32 v1, v2, v1
	v_accvgpr_read_b32 v2, a5
	v_accvgpr_read_b32 v3, a4
	v_cvt_pk_bf16_f32 v2, v3, v2
	v_accvgpr_read_b32 v3, a7
	v_accvgpr_read_b32 v4, a6
	v_cvt_pk_bf16_f32 v3, v4, v3
	ds_write2_b64 v6, v[0:1], v[2:3] offset0:216 offset1:218
	v_accvgpr_read_b32 v0, a9
	v_accvgpr_read_b32 v1, a8
	v_cvt_pk_bf16_f32 v0, v1, v0
	v_accvgpr_read_b32 v1, a11
	v_accvgpr_read_b32 v2, a10
	v_cvt_pk_bf16_f32 v1, v2, v1
	v_accvgpr_read_b32 v2, a13
	v_accvgpr_read_b32 v3, a12
	v_cvt_pk_bf16_f32 v2, v3, v2
	v_accvgpr_read_b32 v3, a15
	v_accvgpr_read_b32 v4, a14
	v_cvt_pk_bf16_f32 v3, v4, v3
	ds_write2_b64 v6, v[0:1], v[2:3] offset0:220 offset1:222
	s_waitcnt lgkmcnt(0)
	s_barrier
	s_nop 0
	v_mbcnt_lo_u32_b32 v0, -1, s5
	v_mbcnt_hi_u32_b32 v0, -1, v0
	v_or_b32_e32 v2, s34, v0
	v_lshlrev_b32_e32 v0, 4, v0
	v_and_b32_e32 v252, 0x1f0, v0
	v_lshl_add_u64 v[0:1], s[12:13], 0, v[252:253]

.LBB0_91:
	s_add_i32 s12, s14, 0xffff8000
	s_and_b32 s12, s12, 0x8000
	s_lshl_b32 s12, s12, 1
	v_lshl_or_b32 v250, v13, 1, s12
	v_add_u32_e32 v249, v250, v9
	v_add_u32_e32 v250, v250, v8
	ds_read_b128 v[14:17], v249
	ds_read_b128 v[18:21], v250 offset:32768
	ds_read_b128 v[22:25], v250 offset:36864
	ds_read_b128 v[26:29], v250 offset:40960
	ds_read_b128 v[30:33], v250 offset:45056
	ds_read_b128 v[128:131], v249 offset:4096
	s_waitcnt lgkmcnt(4)
	v_mfma_f32_32x32x16_bf16 a[240:255], v[14:17], v[18:21], a[240:255]
	s_waitcnt lgkmcnt(3)
	v_mfma_f32_32x32x16_bf16 a[176:191], v[14:17], v[22:25], a[176:191]
	s_and_b32 s98, s14, 0x8000
	s_lshl_b32 s98, s98, 1
	s_add_i32 s98, s40, s98
	v_lshl_add_u64 v[118:119], v[0:1], 0, s[10:11]
	v_lshl_add_u64 v[120:121], v[118:119], 0, s[16:17]
	s_mov_b32 m0, s98
	s_add_i32 s99, s98, 0x8000
	global_load_lds_dwordx4 v[120:121], off
	s_waitcnt lgkmcnt(2)
	v_mfma_f32_32x32x16_bf16 a[112:127], v[14:17], v[26:29], a[112:127]
	v_lshl_add_u64 v[120:121], v[4:5], 0, s[10:11]
	v_lshl_add_u64 v[122:123], v[120:121], 0, s[38:39]
	s_mov_b32 m0, s99
	s_nop 0
	global_load_lds_dwordx4 v[122:123], off
	s_waitcnt lgkmcnt(1)
	v_mfma_f32_32x32x16_bf16 a[48:63], v[14:17], v[30:33], a[48:63]
	v_lshl_add_u64 v[122:123], v[2:3], 0, s[10:11]
	v_lshl_add_u64 v[124:125], v[122:123], 0, s[64:65]
	s_add_i32 m0, s98, 0x400
	s_nop 0
	global_load_lds_dwordx4 v[124:125], off
	ds_read_b128 v[14:17], v249 offset:8192
	s_waitcnt lgkmcnt(1)
	v_mfma_f32_32x32x16_bf16 a[224:239], v[128:131], v[18:21], a[224:239]
	v_lshl_add_u64 v[124:125], v[6:7], 0, s[10:11]
	v_lshl_add_u64 v[126:127], v[124:125], 0, s[44:45]
	s_add_i32 m0, s98, 0x8400
	s_nop 0
	global_load_lds_dwordx4 v[126:127], off
	v_mfma_f32_32x32x16_bf16 a[160:175], v[128:131], v[22:25], a[160:175]
	v_lshl_add_u64 v[126:127], v[118:119], 0, s[66:67]
	s_add_i32 m0, s98, 0x800
	s_nop 0
	global_load_lds_dwordx4 v[126:127], off
	v_mfma_f32_32x32x16_bf16 a[96:111], v[128:131], v[26:29], a[96:111]
	v_lshl_add_u64 v[126:127], v[120:121], 0, s[2:3]
	s_add_i32 m0, s98, 0x8800
	s_nop 0
	global_load_lds_dwordx4 v[126:127], off
	v_mfma_f32_32x32x16_bf16 a[32:47], v[128:131], v[30:33], a[32:47]
	v_lshl_add_u64 v[126:127], v[122:123], 0, s[68:69]
	s_add_i32 m0, s98, 0xc00
	s_nop 0
	global_load_lds_dwordx4 v[126:127], off
	ds_read_b128 v[128:131], v249 offset:12288
	s_waitcnt lgkmcnt(1)
	v_mfma_f32_32x32x16_bf16 a[208:223], v[14:17], v[18:21], a[208:223]
	v_lshl_add_u64 v[126:127], v[124:125], 0, s[46:47]
	s_add_i32 m0, s98, 0x8c00
	s_nop 0
	global_load_lds_dwordx4 v[126:127], off
	v_mfma_f32_32x32x16_bf16 a[144:159], v[14:17], v[22:25], a[144:159]
	v_lshl_add_u64 v[126:127], v[118:119], 0, s[70:71]
	s_add_i32 m0, s98, 0x1000
	v_lshl_add_u64 v[118:119], v[118:119], 0, s[78:79]
	global_load_lds_dwordx4 v[126:127], off
	v_mfma_f32_32x32x16_bf16 a[80:95], v[14:17], v[26:29], a[80:95]
	v_lshl_add_u64 v[126:127], v[120:121], 0, s[50:51]
	s_add_i32 m0, s98, 0x9000
	s_nop 0
	global_load_lds_dwordx4 v[126:127], off
	v_mfma_f32_32x32x16_bf16 a[16:31], v[14:17], v[30:33], a[16:31]
	v_lshl_add_u64 v[126:127], v[122:123], 0, s[76:77]
	s_add_i32 m0, s98, 0x1400
	s_nop 0
	global_load_lds_dwordx4 v[126:127], off
	v_lshl_or_b32 v250, v12, 1, s12
	v_add_u32_e32 v249, v250, v9
	v_add_u32_e32 v250, v250, v8
	ds_read_b128 v[14:17], v249
	s_waitcnt lgkmcnt(1)
	v_mfma_f32_32x32x16_bf16 a[192:207], v[128:131], v[18:21], a[192:207]
	v_lshl_add_u64 v[126:127], v[124:125], 0, s[52:53]
	s_add_i32 m0, s98, 0x9400
	s_nop 0
	global_load_lds_dwordx4 v[126:127], off
	ds_read_b128 v[18:21], v250 offset:32768
	v_mfma_f32_32x32x16_bf16 a[128:143], v[128:131], v[22:25], a[128:143]
	s_add_i32 m0, s98, 0x1800
	s_nop 0
	global_load_lds_dwordx4 v[118:119], off
	ds_read_b128 v[22:25], v250 offset:36864
	v_mfma_f32_32x32x16_bf16 a[64:79], v[128:131], v[26:29], a[64:79]
	v_lshl_add_u64 v[118:119], v[120:121], 0, s[54:55]
	s_add_i32 m0, s98, 0x9800
	s_nop 0
	global_load_lds_dwordx4 v[118:119], off
	ds_read_b128 v[26:29], v250 offset:40960
	v_mfma_f32_32x32x16_bf16 a[0:15], v[128:131], v[30:33], a[0:15]
	v_lshl_add_u64 v[118:119], v[122:123], 0, s[80:81]
	s_add_i32 m0, s98, 0x1c00
	s_nop 0
	global_load_lds_dwordx4 v[118:119], off
	ds_read_b128 v[30:33], v250 offset:45056
	ds_read_b128 v[128:131], v249 offset:4096
	s_waitcnt lgkmcnt(4)
	v_mfma_f32_32x32x16_bf16 a[240:255], v[14:17], v[18:21], a[240:255]
	v_lshl_add_u64 v[118:119], v[124:125], 0, s[56:57]
	s_add_i32 m0, s98, 0x9c00
	s_nop 0
	global_load_lds_dwordx4 v[118:119], off
	s_waitcnt lgkmcnt(3)
	v_mfma_f32_32x32x16_bf16 a[176:191], v[14:17], v[22:25], a[176:191]
	s_waitcnt lgkmcnt(2)
	v_mfma_f32_32x32x16_bf16 a[112:127], v[14:17], v[26:29], a[112:127]
	s_waitcnt lgkmcnt(1)
	v_mfma_f32_32x32x16_bf16 a[48:63], v[14:17], v[30:33], a[48:63]
	ds_read_b128 v[14:17], v249 offset:8192
	s_waitcnt lgkmcnt(1)
	v_mfma_f32_32x32x16_bf16 a[224:239], v[128:131], v[18:21], a[224:239]
	v_mfma_f32_32x32x16_bf16 a[160:175], v[128:131], v[22:25], a[160:175]
	v_mfma_f32_32x32x16_bf16 a[96:111], v[128:131], v[26:29], a[96:111]
	v_mfma_f32_32x32x16_bf16 a[32:47], v[128:131], v[30:33], a[32:47]
	ds_read_b128 v[128:131], v249 offset:12288
	s_waitcnt lgkmcnt(1)
	v_mfma_f32_32x32x16_bf16 a[208:223], v[14:17], v[18:21], a[208:223]
	v_mfma_f32_32x32x16_bf16 a[144:159], v[14:17], v[22:25], a[144:159]
	v_mfma_f32_32x32x16_bf16 a[80:95], v[14:17], v[26:29], a[80:95]
	v_mfma_f32_32x32x16_bf16 a[16:31], v[14:17], v[30:33], a[16:31]
	v_lshl_or_b32 v250, v11, 1, s12
	v_add_u32_e32 v249, v250, v9
	v_add_u32_e32 v250, v250, v8
	ds_read_b128 v[14:17], v249
	s_waitcnt lgkmcnt(1)
	v_mfma_f32_32x32x16_bf16 a[192:207], v[128:131], v[18:21], a[192:207]
	ds_read_b128 v[18:21], v250 offset:32768
	v_mfma_f32_32x32x16_bf16 a[128:143], v[128:131], v[22:25], a[128:143]
	ds_read_b128 v[22:25], v250 offset:36864
	v_mfma_f32_32x32x16_bf16 a[64:79], v[128:131], v[26:29], a[64:79]
	ds_read_b128 v[26:29], v250 offset:40960
	v_mfma_f32_32x32x16_bf16 a[0:15], v[128:131], v[30:33], a[0:15]
	ds_read_b128 v[30:33], v250 offset:45056
	ds_read_b128 v[128:131], v249 offset:4096
	s_waitcnt lgkmcnt(4)
	v_mfma_f32_32x32x16_bf16 a[240:255], v[14:17], v[18:21], a[240:255]
	s_waitcnt lgkmcnt(3)
	v_mfma_f32_32x32x16_bf16 a[176:191], v[14:17], v[22:25], a[176:191]
	s_waitcnt lgkmcnt(2)
	v_mfma_f32_32x32x16_bf16 a[112:127], v[14:17], v[26:29], a[112:127]
	s_waitcnt lgkmcnt(1)
	v_mfma_f32_32x32x16_bf16 a[48:63], v[14:17], v[30:33], a[48:63]
	ds_read_b128 v[14:17], v249 offset:8192
	s_waitcnt lgkmcnt(1)
	v_mfma_f32_32x32x16_bf16 a[224:239], v[128:131], v[18:21], a[224:239]
	v_mfma_f32_32x32x16_bf16 a[160:175], v[128:131], v[22:25], a[160:175]
	v_mfma_f32_32x32x16_bf16 a[96:111], v[128:131], v[26:29], a[96:111]
	v_mfma_f32_32x32x16_bf16 a[32:47], v[128:131], v[30:33], a[32:47]
	ds_read_b128 v[128:131], v249 offset:12288
	s_waitcnt lgkmcnt(1)
	v_mfma_f32_32x32x16_bf16 a[208:223], v[14:17], v[18:21], a[208:223]
	v_mfma_f32_32x32x16_bf16 a[144:159], v[14:17], v[22:25], a[144:159]
	v_mfma_f32_32x32x16_bf16 a[80:95], v[14:17], v[26:29], a[80:95]
	v_mfma_f32_32x32x16_bf16 a[16:31], v[14:17], v[30:33], a[16:31]
	v_lshl_or_b32 v250, v10, 1, s12
	v_add_u32_e32 v249, v250, v9
	v_add_u32_e32 v250, v250, v8
	ds_read_b128 v[14:17], v249
	s_waitcnt lgkmcnt(1)
	v_mfma_f32_32x32x16_bf16 a[192:207], v[128:131], v[18:21], a[192:207]
	ds_read_b128 v[18:21], v250 offset:32768
	v_mfma_f32_32x32x16_bf16 a[128:143], v[128:131], v[22:25], a[128:143]
	ds_read_b128 v[22:25], v250 offset:36864
	v_mfma_f32_32x32x16_bf16 a[64:79], v[128:131], v[26:29], a[64:79]
	ds_read_b128 v[26:29], v250 offset:40960
	v_mfma_f32_32x32x16_bf16 a[0:15], v[128:131], v[30:33], a[0:15]
	ds_read_b128 v[30:33], v250 offset:45056
	ds_read_b128 v[128:131], v249 offset:4096
	s_waitcnt lgkmcnt(4)
	v_mfma_f32_32x32x16_bf16 a[240:255], v[14:17], v[18:21], a[240:255]
	s_waitcnt lgkmcnt(3)
	v_mfma_f32_32x32x16_bf16 a[176:191], v[14:17], v[22:25], a[176:191]
	s_waitcnt lgkmcnt(2)
	v_mfma_f32_32x32x16_bf16 a[112:127], v[14:17], v[26:29], a[112:127]
	s_waitcnt lgkmcnt(1)
	v_mfma_f32_32x32x16_bf16 a[48:63], v[14:17], v[30:33], a[48:63]
	ds_read_b128 v[14:17], v249 offset:8192
	s_waitcnt lgkmcnt(1)
	v_mfma_f32_32x32x16_bf16 a[224:239], v[128:131], v[18:21], a[224:239]
	v_mfma_f32_32x32x16_bf16 a[160:175], v[128:131], v[22:25], a[160:175]
	v_mfma_f32_32x32x16_bf16 a[96:111], v[128:131], v[26:29], a[96:111]
	v_mfma_f32_32x32x16_bf16 a[32:47], v[128:131], v[30:33], a[32:47]
	ds_read_b128 v[128:131], v249 offset:12288
	s_waitcnt lgkmcnt(1)
	v_mfma_f32_32x32x16_bf16 a[208:223], v[14:17], v[18:21], a[208:223]
	v_mfma_f32_32x32x16_bf16 a[144:159], v[14:17], v[22:25], a[144:159]
	v_mfma_f32_32x32x16_bf16 a[80:95], v[14:17], v[26:29], a[80:95]
	v_mfma_f32_32x32x16_bf16 a[16:31], v[14:17], v[30:33], a[16:31]
	s_waitcnt vmcnt(0)
	s_waitcnt vmcnt(0) lgkmcnt(0)
	s_barrier
	s_add_u32 s10, s10, 0x80
	s_addc_u32 s11, s11, 0
	s_add_i32 s14, s14, 0x8000
	s_cmpk_lg_i32 s10, 0x780
	v_mfma_f32_32x32x16_bf16 a[192:207], v[128:131], v[18:21], a[192:207]
	v_mfma_f32_32x32x16_bf16 a[128:143], v[128:131], v[22:25], a[128:143]
	v_mfma_f32_32x32x16_bf16 a[64:79], v[128:131], v[26:29], a[64:79]
	v_mfma_f32_32x32x16_bf16 a[0:15], v[128:131], v[30:33], a[0:15]
	s_cbranch_scc1 .LBB0_91
	v_lshlrev_b32_e32 v4, 1, v13
	s_mov_b32 s10, 0x10000
	v_add3_u32 v13, v9, v4, s10
	ds_read_b128 v[0:3], v13
	s_mov_b32 s11, 0x18000
	v_add3_u32 v26, v8, v4, s11
	ds_read_b128 v[4:7], v26
	ds_read_b128 v[14:17], v13 offset:4096
	ds_read_b128 v[18:21], v26 offset:4096
	ds_read_b128 v[22:25], v26 offset:8192
	ds_read_b128 v[26:29], v26 offset:12288
	s_waitcnt lgkmcnt(3)
	v_mfma_f32_32x32x16_bf16 a[224:239], v[14:17], v[4:7], a[224:239]
	v_mfma_f32_32x32x16_bf16 a[240:255], v[0:3], v[4:7], a[240:255]
	s_waitcnt lgkmcnt(2)
	v_mfma_f32_32x32x16_bf16 a[176:191], v[0:3], v[18:21], a[176:191]
	s_waitcnt lgkmcnt(1)
	v_mfma_f32_32x32x16_bf16 a[112:127], v[0:3], v[22:25], a[112:127]
	s_waitcnt lgkmcnt(0)
	v_mfma_f32_32x32x16_bf16 a[48:63], v[0:3], v[26:29], a[48:63]
	v_mfma_f32_32x32x16_bf16 a[160:175], v[14:17], v[18:21], a[160:175]
	v_mfma_f32_32x32x16_bf16 a[96:111], v[14:17], v[22:25], a[96:111]
	v_mfma_f32_32x32x16_bf16 a[32:47], v[14:17], v[26:29], a[32:47]
	ds_read_b128 v[0:3], v13 offset:8192
	ds_read_b128 v[14:17], v13 offset:12288
	s_waitcnt lgkmcnt(1)
	v_mfma_f32_32x32x16_bf16 a[208:223], v[0:3], v[4:7], a[208:223]
	s_waitcnt lgkmcnt(0)
	v_mfma_f32_32x32x16_bf16 a[192:207], v[14:17], v[4:7], a[192:207]
	v_lshlrev_b32_e32 v4, 1, v12
	v_mfma_f32_32x32x16_bf16 a[80:95], v[0:3], v[22:25], a[80:95]
	v_mfma_f32_32x32x16_bf16 a[64:79], v[14:17], v[22:25], a[64:79]
	v_add3_u32 v24, v9, v4, s10
	v_add3_u32 v25, v8, v4, s11
	v_mfma_f32_32x32x16_bf16 a[144:159], v[0:3], v[18:21], a[144:159]
	v_mfma_f32_32x32x16_bf16 a[16:31], v[0:3], v[26:29], a[16:31]
	ds_read_b128 v[0:3], v24
	v_mfma_f32_32x32x16_bf16 a[128:143], v[14:17], v[18:21], a[128:143]
	v_mfma_f32_32x32x16_bf16 a[0:15], v[14:17], v[26:29], a[0:15]
	ds_read_b128 v[4:7], v25
	ds_read_b128 v[12:15], v24 offset:4096
	ds_read_b128 v[16:19], v25 offset:4096
	ds_read_b128 v[20:23], v25 offset:8192
	ds_read_b128 v[48:51], v25 offset:12288
	s_waitcnt lgkmcnt(4)
	v_mfma_f32_32x32x16_bf16 a[240:255], v[0:3], v[4:7], a[240:255]
	s_waitcnt lgkmcnt(2)
	v_mfma_f32_32x32x16_bf16 a[176:191], v[0:3], v[16:19], a[176:191]
	s_waitcnt lgkmcnt(1)
	v_mfma_f32_32x32x16_bf16 a[112:127], v[0:3], v[20:23], a[112:127]
	s_waitcnt lgkmcnt(0)
	v_mfma_f32_32x32x16_bf16 a[48:63], v[0:3], v[48:51], a[48:63]
	ds_read_b128 v[0:3], v24 offset:8192
	ds_read_b128 v[52:55], v24 offset:12288
	v_mfma_f32_32x32x16_bf16 a[224:239], v[12:15], v[4:7], a[224:239]
	s_waitcnt lgkmcnt(1)
	v_mfma_f32_32x32x16_bf16 a[208:223], v[0:3], v[4:7], a[208:223]
	s_waitcnt lgkmcnt(0)
	v_mfma_f32_32x32x16_bf16 a[192:207], v[52:55], v[4:7], a[192:207]
	v_lshlrev_b32_e32 v4, 1, v11
	v_add3_u32 v5, v9, v4, s10
	v_add3_u32 v4, v8, v4, s11
	v_mfma_f32_32x32x16_bf16 a[144:159], v[0:3], v[16:19], a[144:159]
	v_mfma_f32_32x32x16_bf16 a[80:95], v[0:3], v[20:23], a[80:95]
	v_mfma_f32_32x32x16_bf16 a[16:31], v[0:3], v[48:51], a[16:31]
	ds_read_b128 v[0:3], v5
	ds_read_b128 v[40:43], v4
	ds_read_b128 v[44:47], v5 offset:4096
	ds_read_b128 v[28:31], v4 offset:4096
	v_mfma_f32_32x32x16_bf16 a[96:111], v[12:15], v[20:23], a[96:111]
	v_mfma_f32_32x32x16_bf16 a[64:79], v[52:55], v[20:23], a[64:79]
	ds_read_b128 v[32:35], v4 offset:8192
	ds_read_b128 v[20:23], v4 offset:12288
	ds_read_b128 v[56:59], v5 offset:8192
	ds_read_b128 v[24:27], v5 offset:12288
	v_lshlrev_b32_e32 v4, 1, v10
	s_waitcnt lgkmcnt(6)
	v_mfma_f32_32x32x16_bf16 a[240:255], v[0:3], v[40:43], a[240:255]
	s_waitcnt lgkmcnt(4)
	v_mfma_f32_32x32x16_bf16 a[176:191], v[0:3], v[28:31], a[176:191]
	s_waitcnt lgkmcnt(3)
	v_mfma_f32_32x32x16_bf16 a[112:127], v[0:3], v[32:35], a[112:127]
	s_waitcnt lgkmcnt(2)
	v_mfma_f32_32x32x16_bf16 a[48:63], v[0:3], v[20:23], a[48:63]
	v_add3_u32 v0, v9, v4, s10
	v_add3_u32 v4, v8, v4, s11
	s_mov_b32 s10, 0
	s_mov_b32 s11, 0x7fffff80
	v_mfma_f32_32x32x16_bf16 a[160:175], v[12:15], v[16:19], a[160:175]
	v_mfma_f32_32x32x16_bf16 a[32:47], v[12:15], v[48:51], a[32:47]
	v_mfma_f32_32x32x16_bf16 a[128:143], v[52:55], v[16:19], a[128:143]
	ds_read_b128 v[64:67], v0
	ds_read_b128 v[16:19], v0 offset:4096
	ds_read_b128 v[72:75], v0 offset:8192
	ds_read_b128 v[0:3], v0 offset:12288
	ds_read_b128 v[36:39], v4
	ds_read_b128 v[12:15], v4 offset:4096
	ds_read_b128 v[8:11], v4 offset:8192
	ds_read_b128 v[4:7], v4 offset:12288
	s_waitcnt vmcnt(0)
	s_waitcnt lgkmcnt(0)
	s_barrier
	v_mfma_f32_32x32x16_bf16 a[208:223], v[56:59], v[40:43], a[208:223]
	v_mfma_f32_32x32x16_bf16 a[144:159], v[56:59], v[28:31], a[144:159]
	v_mfma_f32_32x32x16_bf16 a[80:95], v[56:59], v[32:35], a[80:95]
	v_mfma_f32_32x32x16_bf16 a[16:31], v[56:59], v[20:23], a[16:31]
	v_mbcnt_lo_u32_b32 v56, -1, s10
	v_mbcnt_hi_u32_b32 v56, -1, v56
	v_or_b32_e32 v114, s34, v56
	v_and_b32_e32 v57, 31, v56
	v_lshlrev_b32_e32 v58, 1, v114
	v_lshrrev_b32_e32 v56, 3, v56
	v_and_or_b32 v115, v58, s15, v57
	v_and_b32_e32 v116, 4, v56
	v_lshlrev_b32_e32 v252, 2, v116
	v_or_b32_e32 v56, s21, v115
	v_lshl_add_u64 v[62:63], s[0:1], 0, v[252:253]
	v_lshl_add_u64 v[60:61], s[6:7], 0, v[252:253]
	v_lshlrev_b32_e32 v252, 5, v56
	v_lshl_add_u64 v[58:59], v[60:61], 0, v[252:253]
	v_lshl_add_u64 v[56:57], v[62:63], 0, v[252:253]
	global_load_dwordx4 v[88:91], v[58:59], off
	global_load_dwordx4 v[92:95], v[56:57], off
	v_mfma_f32_32x32x16_bf16 a[240:255], v[64:67], v[36:39], a[240:255]
	s_mov_b32 s10, 0
	v_mfma_f32_32x32x16_bf16 a[224:239], v[44:47], v[40:43], a[224:239]
	s_nop 9
	v_accvgpr_read_b32 v97, a247
	v_accvgpr_read_b32 v96, a246
	v_accvgpr_read_b32 v101, a245
	v_accvgpr_read_b32 v100, a244
	v_mfma_f32_32x32x16_bf16 a[0:15], v[52:55], v[48:51], a[0:15]
	v_accvgpr_read_b32 v52, a240
	v_accvgpr_read_b32 v99, a243
	v_accvgpr_read_b32 v98, a242
	v_and_or_b32 v50, v114, s11, v116
	v_mul_u32_u24_e32 v51, 0x210, v115
	v_accvgpr_read_b32 v53, a241
	v_lshl_add_u32 v50, v50, 1, v51
	v_mfma_f32_32x32x16_bf16 a[224:239], v[16:19], v[36:39], a[224:239]
	v_accvgpr_read_b32 v51, a249
	s_waitcnt vmcnt(1)
	v_mul_f32_e64 v54, v100, v88
	v_mul_f32_e64 v55, v101, v89
	v_mul_f32_e64 v114, v96, v90
	v_mul_f32_e64 v115, v97, v91
	s_waitcnt vmcnt(0)
	v_pk_fma_f32 v[54:55], v[52:53], v[92:93], v[54:55] neg_lo:[0,0,1] neg_hi:[0,0,1]
	v_pk_fma_f32 v[114:115], v[98:99], v[94:95], v[114:115] neg_lo:[0,0,1] neg_hi:[0,0,1]
	v_pk_mul_f32 v[52:53], v[52:53], v[88:89]
	v_pk_mul_f32 v[98:99], v[98:99], v[90:91]
	v_pk_fma_f32 v[52:53], v[100:101], v[92:93], v[52:53]
	v_pk_fma_f32 v[96:97], v[96:97], v[94:95], v[98:99]
	v_cvt_pk_bf16_f32 v54, v54, v55
	v_cvt_pk_bf16_f32 v55, v114, v115
	v_cvt_pk_bf16_f32 v52, v52, v53
	v_cvt_pk_bf16_f32 v53, v96, v97
	v_mfma_f32_32x32x16_bf16 a[208:223], v[72:75], v[36:39], a[208:223]
	ds_write2_b64 v50, v[54:55], v[52:53] offset1:2
	v_accvgpr_read_b32 v52, a248
	v_cvt_pk_bf16_f32 v52, v52, v51
	v_accvgpr_read_b32 v51, a251
	v_accvgpr_read_b32 v53, a250
	v_cvt_pk_bf16_f32 v53, v53, v51
	v_accvgpr_read_b32 v51, a253
	v_accvgpr_read_b32 v54, a252
	v_mfma_f32_32x32x16_bf16 a[192:207], v[24:27], v[40:43], a[192:207]
	v_cvt_pk_bf16_f32 v54, v54, v51
	v_accvgpr_read_b32 v51, a255
	v_accvgpr_read_b32 v55, a254
	v_cvt_pk_bf16_f32 v55, v55, v51
	v_accvgpr_read_b32 v51, a225
	v_accvgpr_read_b32 v41, a231
	v_accvgpr_read_b32 v42, a230
	v_mfma_f32_32x32x16_bf16 a[160:175], v[44:47], v[28:31], a[160:175]
	v_cvt_pk_bf16_f32 v41, v42, v41
	v_accvgpr_read_b32 v109, a215
	v_accvgpr_read_b32 v108, a214
	v_accvgpr_read_b32 v111, a211
	v_accvgpr_read_b32 v110, a210
	v_accvgpr_read_b32 v113, a213
	v_accvgpr_read_b32 v112, a212
	v_mfma_f32_32x32x16_bf16 a[96:111], v[44:47], v[32:35], a[96:111]
	ds_write2_b64 v50, v[52:53], v[54:55] offset0:4 offset1:6
	v_mfma_f32_32x32x16_bf16 a[32:47], v[44:47], v[20:23], a[32:47]
	v_accvgpr_read_b32 v45, a227
	v_accvgpr_read_b32 v46, a226
	v_accvgpr_read_b32 v44, a224
	v_cvt_pk_bf16_f32 v45, v46, v45
	v_accvgpr_read_b32 v46, a229
	v_accvgpr_read_b32 v47, a228
	v_cvt_pk_bf16_f32 v44, v44, v51
	v_mfma_f32_32x32x16_bf16 a[128:143], v[24:27], v[28:31], a[128:143]
	v_accvgpr_read_b32 v29, a235
	v_accvgpr_read_b32 v30, a234
	v_cvt_pk_bf16_f32 v40, v47, v46
	v_cvt_pk_bf16_f32 v29, v30, v29
	v_accvgpr_read_b32 v30, a237
	v_accvgpr_read_b32 v31, a236
	ds_write2_b64 v50, v[44:45], v[40:41] offset0:8 offset1:10
	v_accvgpr_read_b32 v40, a233
	v_accvgpr_read_b32 v41, a232
	v_cvt_pk_bf16_f32 v30, v31, v30
	v_mfma_f32_32x32x16_bf16 a[64:79], v[24:27], v[32:35], a[64:79]
	v_accvgpr_read_b32 v31, a239
	v_accvgpr_read_b32 v32, a238
	v_cvt_pk_bf16_f32 v28, v41, v40
	v_cvt_pk_bf16_f32 v31, v32, v31
	ds_write2_b64 v50, v[28:29], v[30:31] offset0:12 offset1:14
	v_accvgpr_read_b32 v28, a208
	v_accvgpr_read_b32 v29, a209
	v_pk_mul_f32 v[30:31], v[112:113], v[88:89]
	v_mfma_f32_32x32x16_bf16 a[0:15], v[24:27], v[20:23], a[0:15]
	v_mul_f32_e64 v20, v108, v90
	v_mul_f32_e64 v21, v109, v91
	v_mul_f32_e64 v22, v28, v88
	v_mul_f32_e64 v23, v29, v89
	v_mul_f32_e64 v24, v110, v90
	v_mul_f32_e64 v25, v111, v91
	v_pk_fma_f32 v[30:31], v[28:29], v[92:93], v[30:31] neg_lo:[0,0,1] neg_hi:[0,0,1]
	v_pk_fma_f32 v[20:21], v[110:111], v[94:95], v[20:21] neg_lo:[0,0,1] neg_hi:[0,0,1]
	v_pk_fma_f32 v[22:23], v[112:113], v[92:93], v[22:23]
	v_pk_fma_f32 v[24:25], v[108:109], v[94:95], v[24:25]
	v_mfma_f32_32x32x16_bf16 a[192:207], v[0:3], v[36:39], a[192:207]
	v_cvt_pk_bf16_f32 v26, v30, v31
	v_cvt_pk_bf16_f32 v27, v20, v21
	v_cvt_pk_bf16_f32 v20, v22, v23
	v_cvt_pk_bf16_f32 v21, v24, v25
	ds_write2_b64 v50, v[26:27], v[20:21] offset0:16 offset1:18
	v_accvgpr_read_b32 v20, a217
	v_accvgpr_read_b32 v21, a216
	v_cvt_pk_bf16_f32 v20, v21, v20
	v_accvgpr_read_b32 v21, a219
	v_accvgpr_read_b32 v22, a218
	v_mfma_f32_32x32x16_bf16 a[176:191], v[64:67], v[12:15], a[176:191]
	v_cvt_pk_bf16_f32 v21, v22, v21
	v_accvgpr_read_b32 v22, a221
	v_accvgpr_read_b32 v23, a220
	v_cvt_pk_bf16_f32 v22, v23, v22
	v_accvgpr_read_b32 v23, a223
	v_accvgpr_read_b32 v24, a222
	v_cvt_pk_bf16_f32 v23, v24, v23
	v_mfma_f32_32x32x16_bf16 a[112:127], v[64:67], v[8:11], a[112:127]
	ds_write2_b64 v50, v[20:21], v[22:23] offset0:20 offset1:22
	v_accvgpr_read_b32 v20, a193
	v_accvgpr_read_b32 v21, a192
	v_cvt_pk_bf16_f32 v20, v21, v20
	v_accvgpr_read_b32 v21, a195
	v_accvgpr_read_b32 v103, a183
	v_accvgpr_read_b32 v102, a182
	v_mfma_f32_32x32x16_bf16 a[48:63], v[64:67], v[4:7], a[48:63]
	v_accvgpr_read_b32 v105, a179
	v_accvgpr_read_b32 v104, a178
	v_accvgpr_read_b32 v107, a181
	v_accvgpr_read_b32 v106, a180
	v_accvgpr_read_b32 v77, a119
	v_accvgpr_read_b32 v76, a118
	v_accvgpr_read_b32 v79, a115
	v_mfma_f32_32x32x16_bf16 a[144:159], v[72:75], v[12:15], a[144:159]
	v_accvgpr_read_b32 v78, a114
	v_accvgpr_read_b32 v81, a117
	v_accvgpr_read_b32 v80, a116
	s_nop 0
	v_accvgpr_read_b32 v65, a55
	v_accvgpr_read_b32 v64, a54
	v_accvgpr_read_b32 v67, a51
	v_mfma_f32_32x32x16_bf16 a[80:95], v[72:75], v[8:11], a[80:95]
	v_accvgpr_read_b32 v66, a50
	v_accvgpr_read_b32 v69, a53
	v_accvgpr_read_b32 v68, a52
	s_nop 0
	v_accvgpr_read_b32 v83, a151
	v_accvgpr_read_b32 v82, a150
	v_accvgpr_read_b32 v85, a147
	v_mfma_f32_32x32x16_bf16 a[16:31], v[72:75], v[4:7], a[16:31]
	v_accvgpr_read_b32 v84, a146
	v_accvgpr_read_b32 v87, a149
	v_accvgpr_read_b32 v86, a148
	s_nop 0
	v_accvgpr_read_b32 v71, a87
	v_accvgpr_read_b32 v70, a86
	v_accvgpr_read_b32 v73, a83
	v_mfma_f32_32x32x16_bf16 a[160:175], v[16:19], v[12:15], a[160:175]
	v_accvgpr_read_b32 v72, a82
	v_accvgpr_read_b32 v75, a85
	v_accvgpr_read_b32 v74, a84
	s_nop 0
	v_accvgpr_read_b32 v57, a23
	v_accvgpr_read_b32 v56, a22
	v_accvgpr_read_b32 v59, a19
	v_mfma_f32_32x32x16_bf16 a[96:111], v[16:19], v[8:11], a[96:111]
	v_accvgpr_read_b32 v58, a18
	v_accvgpr_read_b32 v49, a21
	v_accvgpr_read_b32 v48, a20
	v_mfma_f32_32x32x16_bf16 a[32:47], v[16:19], v[4:7], a[32:47]
	v_accvgpr_read_b32 v16, a194
	v_cvt_pk_bf16_f32 v21, v16, v21
	v_accvgpr_read_b32 v16, a197
	v_accvgpr_read_b32 v17, a196
	v_cvt_pk_bf16_f32 v16, v17, v16
	v_accvgpr_read_b32 v17, a199
	v_accvgpr_read_b32 v18, a198
	v_mfma_f32_32x32x16_bf16 a[128:143], v[0:3], v[12:15], a[128:143]
	v_accvgpr_read_b32 v12, a201
	v_accvgpr_read_b32 v13, a200
	v_cvt_pk_bf16_f32 v12, v13, v12
	v_accvgpr_read_b32 v13, a203
	v_accvgpr_read_b32 v14, a202
	v_cvt_pk_bf16_f32 v17, v18, v17
	v_cvt_pk_bf16_f32 v13, v14, v13
	v_mfma_f32_32x32x16_bf16 a[64:79], v[0:3], v[8:11], a[64:79]
	v_accvgpr_read_b32 v8, a205
	v_accvgpr_read_b32 v9, a204
	v_cvt_pk_bf16_f32 v8, v9, v8
	v_accvgpr_read_b32 v9, a207
	v_accvgpr_read_b32 v10, a206
	v_cvt_pk_bf16_f32 v9, v10, v9
	ds_write2_b64 v50, v[20:21], v[16:17] offset0:24 offset1:26
	ds_write2_b64 v50, v[12:13], v[8:9] offset0:28 offset1:30
	v_mfma_f32_32x32x16_bf16 a[0:15], v[0:3], v[4:7], a[0:15]
	v_or_b32_e32 v0, 0x400, v252
	v_mov_b32_e32 v1, v253
	v_lshl_add_u64 v[2:3], v[62:63], 0, v[0:1]
	v_lshl_add_u64 v[4:5], v[60:61], 0, v[0:1]
	global_load_dwordx4 v[0:3], v[2:3], off
	s_nop 0
	global_load_dwordx4 v[4:7], v[4:5], off
	v_accvgpr_read_b32 v8, a176
	v_accvgpr_read_b32 v9, a177
	s_waitcnt vmcnt(0)
	v_pk_mul_f32 v[10:11], v[106:107], v[4:5]
	s_nop 0
	v_pk_fma_f32 v[10:11], v[8:9], v[0:1], v[10:11] neg_lo:[0,0,1] neg_hi:[0,0,1]
	v_pk_mul_f32 v[12:13], v[102:103], v[6:7]
	v_pk_mul_f32 v[8:9], v[8:9], v[4:5]
	v_pk_mul_f32 v[14:15], v[104:105], v[6:7]
	v_pk_fma_f32 v[12:13], v[104:105], v[2:3], v[12:13] neg_lo:[0,0,1] neg_hi:[0,0,1]
	v_pk_fma_f32 v[8:9], v[106:107], v[0:1], v[8:9]
	v_pk_fma_f32 v[14:15], v[102:103], v[2:3], v[14:15]
	v_cvt_pk_bf16_f32 v10, v10, v11
	v_cvt_pk_bf16_f32 v11, v12, v13
	v_cvt_pk_bf16_f32 v8, v8, v9
	v_cvt_pk_bf16_f32 v9, v14, v15
	v_add_u32_e32 v14, 0x4000, v50
	ds_write2_b64 v14, v[10:11], v[8:9] offset0:64 offset1:66
	v_accvgpr_read_b32 v8, a185
	v_accvgpr_read_b32 v9, a184
	v_cvt_pk_bf16_f32 v8, v9, v8
	v_accvgpr_read_b32 v9, a187
	v_accvgpr_read_b32 v10, a186
	v_cvt_pk_bf16_f32 v9, v10, v9
	v_accvgpr_read_b32 v10, a189
	v_accvgpr_read_b32 v11, a188
	v_cvt_pk_bf16_f32 v10, v11, v10
	v_accvgpr_read_b32 v11, a191
	v_accvgpr_read_b32 v12, a190
	v_cvt_pk_bf16_f32 v11, v12, v11
	ds_write2_b64 v14, v[8:9], v[10:11] offset0:68 offset1:70
	v_accvgpr_read_b32 v8, a161
	v_accvgpr_read_b32 v9, a160
	v_cvt_pk_bf16_f32 v8, v9, v8
	v_accvgpr_read_b32 v9, a163
	v_accvgpr_read_b32 v10, a162
	v_cvt_pk_bf16_f32 v9, v10, v9
	v_accvgpr_read_b32 v10, a165
	v_accvgpr_read_b32 v11, a164
	v_cvt_pk_bf16_f32 v10, v11, v10
	v_accvgpr_read_b32 v11, a167
	v_accvgpr_read_b32 v12, a166
	v_cvt_pk_bf16_f32 v11, v12, v11
	ds_write2_b64 v14, v[8:9], v[10:11] offset0:72 offset1:74
	v_accvgpr_read_b32 v8, a169
	v_accvgpr_read_b32 v9, a168
	v_cvt_pk_bf16_f32 v8, v9, v8
	v_accvgpr_read_b32 v9, a171
	v_accvgpr_read_b32 v10, a170
	v_cvt_pk_bf16_f32 v9, v10, v9
	v_accvgpr_read_b32 v10, a173
	v_accvgpr_read_b32 v11, a172
	v_cvt_pk_bf16_f32 v10, v11, v10
	v_accvgpr_read_b32 v11, a175
	v_accvgpr_read_b32 v12, a174
	v_cvt_pk_bf16_f32 v11, v12, v11
	ds_write2_b64 v14, v[8:9], v[10:11] offset0:76 offset1:78
	v_accvgpr_read_b32 v8, a144
	v_accvgpr_read_b32 v9, a145
	v_pk_mul_f32 v[10:11], v[86:87], v[4:5]
	v_pk_mul_f32 v[4:5], v[8:9], v[4:5]
	v_pk_fma_f32 v[10:11], v[8:9], v[0:1], v[10:11] neg_lo:[0,0,1] neg_hi:[0,0,1]
	v_pk_mul_f32 v[12:13], v[82:83], v[6:7]
	v_pk_fma_f32 v[0:1], v[86:87], v[0:1], v[4:5]
	v_pk_mul_f32 v[4:5], v[84:85], v[6:7]
	v_pk_fma_f32 v[12:13], v[84:85], v[2:3], v[12:13] neg_lo:[0,0,1] neg_hi:[0,0,1]
	v_pk_fma_f32 v[2:3], v[82:83], v[2:3], v[4:5]
	v_cvt_pk_bf16_f32 v4, v10, v11
	v_cvt_pk_bf16_f32 v5, v12, v13
	v_cvt_pk_bf16_f32 v0, v0, v1
	v_cvt_pk_bf16_f32 v1, v2, v3
	ds_write2_b64 v14, v[4:5], v[0:1] offset0:80 offset1:82
	v_accvgpr_read_b32 v0, a153
	v_accvgpr_read_b32 v1, a152
	v_cvt_pk_bf16_f32 v0, v1, v0
	v_accvgpr_read_b32 v1, a155
	v_accvgpr_read_b32 v2, a154
	v_cvt_pk_bf16_f32 v1, v2, v1
	v_accvgpr_read_b32 v2, a157
	v_accvgpr_read_b32 v3, a156
	v_cvt_pk_bf16_f32 v2, v3, v2
	v_accvgpr_read_b32 v3, a159
	v_accvgpr_read_b32 v4, a158
	v_cvt_pk_bf16_f32 v3, v4, v3
	ds_write2_b64 v14, v[0:1], v[2:3] offset0:84 offset1:86
	v_accvgpr_read_b32 v0, a129
	v_accvgpr_read_b32 v1, a128
	v_cvt_pk_bf16_f32 v0, v1, v0
	v_accvgpr_read_b32 v1, a131
	v_accvgpr_read_b32 v2, a130
	v_cvt_pk_bf16_f32 v1, v2, v1
	v_accvgpr_read_b32 v2, a133
	v_accvgpr_read_b32 v3, a132
	v_cvt_pk_bf16_f32 v2, v3, v2
	v_accvgpr_read_b32 v3, a135
	v_accvgpr_read_b32 v4, a134
	v_cvt_pk_bf16_f32 v3, v4, v3
	ds_write2_b64 v14, v[0:1], v[2:3] offset0:88 offset1:90
	v_accvgpr_read_b32 v0, a137
	v_accvgpr_read_b32 v1, a136
	v_cvt_pk_bf16_f32 v0, v1, v0
	v_accvgpr_read_b32 v1, a139
	v_accvgpr_read_b32 v2, a138
	v_cvt_pk_bf16_f32 v1, v2, v1
	v_accvgpr_read_b32 v2, a141
	v_accvgpr_read_b32 v3, a140
	v_cvt_pk_bf16_f32 v2, v3, v2
	v_accvgpr_read_b32 v3, a143
	v_accvgpr_read_b32 v4, a142
	v_cvt_pk_bf16_f32 v3, v4, v3
	ds_write2_b64 v14, v[0:1], v[2:3] offset0:92 offset1:94
	v_or_b32_e32 v0, 0x800, v252
	v_mov_b32_e32 v1, v253
	v_lshl_add_u64 v[2:3], v[62:63], 0, v[0:1]
	v_lshl_add_u64 v[4:5], v[60:61], 0, v[0:1]
	global_load_dwordx4 v[0:3], v[2:3], off
	s_nop 0
	global_load_dwordx4 v[4:7], v[4:5], off
	v_accvgpr_read_b32 v8, a112
	v_accvgpr_read_b32 v9, a113
	s_waitcnt vmcnt(0)
	v_pk_mul_f32 v[10:11], v[80:81], v[4:5]
	s_nop 0
	v_pk_fma_f32 v[10:11], v[8:9], v[0:1], v[10:11] neg_lo:[0,0,1] neg_hi:[0,0,1]
	v_pk_mul_f32 v[12:13], v[76:77], v[6:7]
	v_pk_mul_f32 v[8:9], v[8:9], v[4:5]
	v_pk_mul_f32 v[14:15], v[78:79], v[6:7]
	v_pk_fma_f32 v[12:13], v[78:79], v[2:3], v[12:13] neg_lo:[0,0,1] neg_hi:[0,0,1]
	v_pk_fma_f32 v[8:9], v[80:81], v[0:1], v[8:9]
	v_pk_fma_f32 v[14:15], v[76:77], v[2:3], v[14:15]
	v_cvt_pk_bf16_f32 v10, v10, v11
	v_cvt_pk_bf16_f32 v11, v12, v13
	v_cvt_pk_bf16_f32 v8, v8, v9
	v_cvt_pk_bf16_f32 v9, v14, v15
	v_add_u32_e32 v14, 0x8000, v50
	ds_write2_b64 v14, v[10:11], v[8:9] offset0:128 offset1:130
	v_accvgpr_read_b32 v8, a121
	v_accvgpr_read_b32 v9, a120
	v_cvt_pk_bf16_f32 v8, v9, v8
	v_accvgpr_read_b32 v9, a123
	v_accvgpr_read_b32 v10, a122
	v_cvt_pk_bf16_f32 v9, v10, v9
	v_accvgpr_read_b32 v10, a125
	v_accvgpr_read_b32 v11, a124
	v_cvt_pk_bf16_f32 v10, v11, v10
	v_accvgpr_read_b32 v11, a127
	v_accvgpr_read_b32 v12, a126
	v_cvt_pk_bf16_f32 v11, v12, v11
	ds_write2_b64 v14, v[8:9], v[10:11] offset0:132 offset1:134
	v_accvgpr_read_b32 v8, a97
	v_accvgpr_read_b32 v9, a96
	v_cvt_pk_bf16_f32 v8, v9, v8
	v_accvgpr_read_b32 v9, a99
	v_accvgpr_read_b32 v10, a98
	v_cvt_pk_bf16_f32 v9, v10, v9
	v_accvgpr_read_b32 v10, a101
	v_accvgpr_read_b32 v11, a100
	v_cvt_pk_bf16_f32 v10, v11, v10
	v_accvgpr_read_b32 v11, a103
	v_accvgpr_read_b32 v12, a102
	v_cvt_pk_bf16_f32 v11, v12, v11
	ds_write2_b64 v14, v[8:9], v[10:11] offset0:136 offset1:138
	v_accvgpr_read_b32 v8, a105
	v_accvgpr_read_b32 v9, a104
	v_cvt_pk_bf16_f32 v8, v9, v8
	v_accvgpr_read_b32 v9, a107
	v_accvgpr_read_b32 v10, a106
	v_cvt_pk_bf16_f32 v9, v10, v9
	v_accvgpr_read_b32 v10, a109
	v_accvgpr_read_b32 v11, a108
	v_cvt_pk_bf16_f32 v10, v11, v10
	v_accvgpr_read_b32 v11, a111
	v_accvgpr_read_b32 v12, a110
	v_cvt_pk_bf16_f32 v11, v12, v11
	ds_write2_b64 v14, v[8:9], v[10:11] offset0:140 offset1:142
	v_accvgpr_read_b32 v8, a80
	v_accvgpr_read_b32 v9, a81
	v_pk_mul_f32 v[10:11], v[74:75], v[4:5]
	v_pk_mul_f32 v[4:5], v[8:9], v[4:5]
	v_pk_fma_f32 v[10:11], v[8:9], v[0:1], v[10:11] neg_lo:[0,0,1] neg_hi:[0,0,1]
	v_pk_mul_f32 v[12:13], v[70:71], v[6:7]
	v_pk_fma_f32 v[0:1], v[74:75], v[0:1], v[4:5]
	v_pk_mul_f32 v[4:5], v[72:73], v[6:7]
	v_pk_fma_f32 v[12:13], v[72:73], v[2:3], v[12:13] neg_lo:[0,0,1] neg_hi:[0,0,1]
	v_pk_fma_f32 v[2:3], v[70:71], v[2:3], v[4:5]
	v_cvt_pk_bf16_f32 v4, v10, v11
	v_cvt_pk_bf16_f32 v5, v12, v13
	v_cvt_pk_bf16_f32 v0, v0, v1
	v_cvt_pk_bf16_f32 v1, v2, v3
	ds_write2_b64 v14, v[4:5], v[0:1] offset0:144 offset1:146
	v_accvgpr_read_b32 v0, a89
	v_accvgpr_read_b32 v1, a88
	v_cvt_pk_bf16_f32 v0, v1, v0
	v_accvgpr_read_b32 v1, a91
	v_accvgpr_read_b32 v2, a90
	v_cvt_pk_bf16_f32 v1, v2, v1
	v_accvgpr_read_b32 v2, a93
	v_accvgpr_read_b32 v3, a92
	v_cvt_pk_bf16_f32 v2, v3, v2
	v_accvgpr_read_b32 v3, a95
	v_accvgpr_read_b32 v4, a94
	v_cvt_pk_bf16_f32 v3, v4, v3
	ds_write2_b64 v14, v[0:1], v[2:3] offset0:148 offset1:150
	v_accvgpr_read_b32 v0, a65
	v_accvgpr_read_b32 v1, a64
	v_cvt_pk_bf16_f32 v0, v1, v0
	v_accvgpr_read_b32 v1, a67
	v_accvgpr_read_b32 v2, a66
	v_cvt_pk_bf16_f32 v1, v2, v1
	v_accvgpr_read_b32 v2, a69
	v_accvgpr_read_b32 v3, a68
	v_cvt_pk_bf16_f32 v2, v3, v2
	v_accvgpr_read_b32 v3, a71
	v_accvgpr_read_b32 v4, a70
	v_cvt_pk_bf16_f32 v3, v4, v3
	ds_write2_b64 v14, v[0:1], v[2:3] offset0:152 offset1:154
	v_accvgpr_read_b32 v0, a73
	v_accvgpr_read_b32 v1, a72
	v_cvt_pk_bf16_f32 v0, v1, v0
	v_accvgpr_read_b32 v1, a75
	v_accvgpr_read_b32 v2, a74
	v_cvt_pk_bf16_f32 v1, v2, v1
	v_accvgpr_read_b32 v2, a77
	v_accvgpr_read_b32 v3, a76
	v_cvt_pk_bf16_f32 v2, v3, v2
	v_accvgpr_read_b32 v3, a79
	v_accvgpr_read_b32 v4, a78
	v_cvt_pk_bf16_f32 v3, v4, v3
	ds_write2_b64 v14, v[0:1], v[2:3] offset0:156 offset1:158
	v_or_b32_e32 v252, 0xc00, v252
	v_lshl_add_u64 v[0:1], v[62:63], 0, v[252:253]
	v_lshl_add_u64 v[4:5], v[60:61], 0, v[252:253]
	global_load_dwordx4 v[0:3], v[0:1], off
	s_nop 0
	global_load_dwordx4 v[4:7], v[4:5], off
	v_accvgpr_read_b32 v8, a48
	v_accvgpr_read_b32 v9, a49
	s_waitcnt vmcnt(0)
	v_pk_mul_f32 v[10:11], v[68:69], v[4:5]
	s_nop 0
	v_pk_fma_f32 v[10:11], v[8:9], v[0:1], v[10:11] neg_lo:[0,0,1] neg_hi:[0,0,1]
	v_pk_mul_f32 v[12:13], v[64:65], v[6:7]
	v_pk_mul_f32 v[8:9], v[8:9], v[4:5]
	v_pk_mul_f32 v[14:15], v[66:67], v[6:7]
	v_pk_fma_f32 v[12:13], v[66:67], v[2:3], v[12:13] neg_lo:[0,0,1] neg_hi:[0,0,1]
	v_pk_fma_f32 v[8:9], v[68:69], v[0:1], v[8:9]
	v_pk_fma_f32 v[14:15], v[64:65], v[2:3], v[14:15]
	v_cvt_pk_bf16_f32 v10, v10, v11
	v_cvt_pk_bf16_f32 v11, v12, v13
	v_cvt_pk_bf16_f32 v8, v8, v9
	v_cvt_pk_bf16_f32 v9, v14, v15
	v_add_u32_e32 v14, 0xc000, v50
	ds_write2_b64 v14, v[10:11], v[8:9] offset0:192 offset1:194
	v_accvgpr_read_b32 v8, a57
	v_accvgpr_read_b32 v9, a56
	v_cvt_pk_bf16_f32 v8, v9, v8
	v_accvgpr_read_b32 v9, a59
	v_accvgpr_read_b32 v10, a58
	v_cvt_pk_bf16_f32 v9, v10, v9
	v_accvgpr_read_b32 v10, a61
	v_accvgpr_read_b32 v11, a60
	v_cvt_pk_bf16_f32 v10, v11, v10
	v_accvgpr_read_b32 v11, a63
	v_accvgpr_read_b32 v12, a62
	v_cvt_pk_bf16_f32 v11, v12, v11
	ds_write2_b64 v14, v[8:9], v[10:11] offset0:196 offset1:198
	v_accvgpr_read_b32 v8, a33
	v_accvgpr_read_b32 v9, a32
	v_cvt_pk_bf16_f32 v8, v9, v8
	v_accvgpr_read_b32 v9, a35
	v_accvgpr_read_b32 v10, a34
	v_cvt_pk_bf16_f32 v9, v10, v9
	v_accvgpr_read_b32 v10, a37
	v_accvgpr_read_b32 v11, a36
	v_cvt_pk_bf16_f32 v10, v11, v10
	v_accvgpr_read_b32 v11, a39
	v_accvgpr_read_b32 v12, a38
	v_cvt_pk_bf16_f32 v11, v12, v11
	ds_write2_b64 v14, v[8:9], v[10:11] offset0:200 offset1:202
	v_accvgpr_read_b32 v8, a41
	v_accvgpr_read_b32 v9, a40
	v_cvt_pk_bf16_f32 v8, v9, v8
	v_accvgpr_read_b32 v9, a43
	v_accvgpr_read_b32 v10, a42
	v_cvt_pk_bf16_f32 v9, v10, v9
	v_accvgpr_read_b32 v10, a45
	v_accvgpr_read_b32 v11, a44
	v_cvt_pk_bf16_f32 v10, v11, v10
	v_accvgpr_read_b32 v11, a47
	v_accvgpr_read_b32 v12, a46
	v_cvt_pk_bf16_f32 v11, v12, v11
	ds_write2_b64 v14, v[8:9], v[10:11] offset0:204 offset1:206
	v_accvgpr_read_b32 v8, a16
	v_accvgpr_read_b32 v9, a17
	v_pk_mul_f32 v[10:11], v[48:49], v[4:5]
	v_pk_mul_f32 v[4:5], v[8:9], v[4:5]
	v_pk_fma_f32 v[10:11], v[8:9], v[0:1], v[10:11] neg_lo:[0,0,1] neg_hi:[0,0,1]
	v_pk_mul_f32 v[12:13], v[56:57], v[6:7]
	v_pk_fma_f32 v[0:1], v[48:49], v[0:1], v[4:5]
	v_pk_mul_f32 v[4:5], v[58:59], v[6:7]
	v_pk_fma_f32 v[12:13], v[58:59], v[2:3], v[12:13] neg_lo:[0,0,1] neg_hi:[0,0,1]
	v_pk_fma_f32 v[2:3], v[56:57], v[2:3], v[4:5]
	v_cvt_pk_bf16_f32 v4, v10, v11
	v_cvt_pk_bf16_f32 v5, v12, v13
	v_cvt_pk_bf16_f32 v0, v0, v1
	v_cvt_pk_bf16_f32 v1, v2, v3
	ds_write2_b64 v14, v[4:5], v[0:1] offset0:208 offset1:210
	v_accvgpr_read_b32 v0, a25
	v_accvgpr_read_b32 v1, a24
	v_cvt_pk_bf16_f32 v0, v1, v0
	v_accvgpr_read_b32 v1, a27
	v_accvgpr_read_b32 v2, a26
	v_cvt_pk_bf16_f32 v1, v2, v1
	v_accvgpr_read_b32 v2, a29
	v_accvgpr_read_b32 v3, a28
	v_cvt_pk_bf16_f32 v2, v3, v2
	v_accvgpr_read_b32 v3, a31
	v_accvgpr_read_b32 v4, a30
	v_cvt_pk_bf16_f32 v3, v4, v3
	ds_write2_b64 v14, v[0:1], v[2:3] offset0:212 offset1:214
	v_accvgpr_read_b32 v0, a1
	v_accvgpr_read_b32 v1, a0
	v_cvt_pk_bf16_f32 v0, v1, v0
	v_accvgpr_read_b32 v1, a3
	v_accvgpr_read_b32 v2, a2
	v_cvt_pk_bf16_f32 v1, v2, v1
	v_accvgpr_read_b32 v2, a5
	v_accvgpr_read_b32 v3, a4
	v_cvt_pk_bf16_f32 v2, v3, v2
	v_accvgpr_read_b32 v3, a7
	v_accvgpr_read_b32 v4, a6
	v_cvt_pk_bf16_f32 v3, v4, v3
	ds_write2_b64 v14, v[0:1], v[2:3] offset0:216 offset1:218
	v_accvgpr_read_b32 v0, a9
	v_accvgpr_read_b32 v1, a8
	v_cvt_pk_bf16_f32 v0, v1, v0
	v_accvgpr_read_b32 v1, a11
	v_accvgpr_read_b32 v2, a10
	v_cvt_pk_bf16_f32 v1, v2, v1
	v_accvgpr_read_b32 v2, a13
	v_accvgpr_read_b32 v3, a12
	v_cvt_pk_bf16_f32 v2, v3, v2
	v_accvgpr_read_b32 v3, a15
	v_accvgpr_read_b32 v4, a14
	v_cvt_pk_bf16_f32 v3, v4, v3
	ds_write2_b64 v14, v[0:1], v[2:3] offset0:220 offset1:222
	s_lshl_b64 s[4:5], s[4:5], 1
	s_add_u32 s11, s41, s4
	s_addc_u32 s12, s42, s5
	s_lshl_b64 s[4:5], s[8:9], 1
	s_mov_b32 s8, 0
	s_waitcnt lgkmcnt(0)
	s_barrier
	s_add_u32 s4, s11, s4
	v_mbcnt_lo_u32_b32 v0, -1, s8
	v_mbcnt_hi_u32_b32 v0, -1, v0
	v_or_b32_e32 v2, s34, v0
	v_lshlrev_b32_e32 v0, 4, v0
	s_addc_u32 s5, s12, s5
	v_and_b32_e32 v252, 0x1f0, v0
	v_lshl_add_u64 v[0:1], s[4:5], 0, v[252:253]

.LBB0_97:
	s_add_i32 s14, s11, 0xffff8000
	s_and_b32 s14, s14, 0x8000
	s_lshl_b32 s14, s14, 1
	v_lshl_or_b32 v185, v10, 1, s14
	v_add_u32_e32 v184, v185, v21
	v_add_u32_e32 v185, v185, v20
	ds_read_b128 v[12:15], v184
	ds_read_b128 v[24:27], v185 offset:32768
	ds_read_b128 v[28:31], v185 offset:36864
	ds_read_b128 v[32:35], v185 offset:40960
	ds_read_b128 v[36:39], v185 offset:45056
	ds_read_b128 v[112:115], v184 offset:4096
	s_waitcnt lgkmcnt(4)
	v_mfma_f32_32x32x16_bf16 a[240:255], v[12:15], v[24:27], a[240:255]
	s_waitcnt lgkmcnt(3)
	v_mfma_f32_32x32x16_bf16 a[176:191], v[12:15], v[28:31], a[176:191]
	s_and_b32 s98, s11, 0x8000
	s_lshl_b32 s98, s98, 1
	s_add_i32 s98, s34, s98
	v_lshl_add_u64 v[88:89], v[0:1], 0, s[12:13]
	v_lshl_add_u64 v[90:91], v[88:89], 0, s[64:65]
	s_mov_b32 m0, s98
	s_add_i32 s99, s98, 0x8000
	global_load_lds_dwordx4 v[90:91], off
	s_waitcnt lgkmcnt(2)
	v_mfma_f32_32x32x16_bf16 a[112:127], v[12:15], v[32:35], a[112:127]
	v_lshl_add_u64 v[90:91], v[4:5], 0, s[12:13]
	v_lshl_add_u64 v[92:93], v[90:91], 0, s[38:39]
	s_mov_b32 m0, s99
	s_nop 0
	global_load_lds_dwordx4 v[92:93], off
	s_waitcnt lgkmcnt(1)
	v_mfma_f32_32x32x16_bf16 a[48:63], v[12:15], v[36:39], a[48:63]
	v_lshl_add_u64 v[92:93], v[2:3], 0, s[12:13]
	v_lshl_add_u64 v[98:99], v[92:93], 0, s[66:67]
	s_add_i32 m0, s98, 0x400
	s_nop 0
	global_load_lds_dwordx4 v[98:99], off
	ds_read_b128 v[12:15], v184 offset:8192
	s_waitcnt lgkmcnt(1)
	v_mfma_f32_32x32x16_bf16 a[224:239], v[112:115], v[24:27], a[224:239]
	v_lshl_add_u64 v[98:99], v[6:7], 0, s[12:13]
	v_lshl_add_u64 v[106:107], v[98:99], 0, s[44:45]
	s_add_i32 m0, s98, 0x8400
	s_nop 0
	global_load_lds_dwordx4 v[106:107], off
	v_mfma_f32_32x32x16_bf16 a[160:175], v[112:115], v[28:31], a[160:175]
	v_lshl_add_u64 v[106:107], v[88:89], 0, s[68:69]
	s_add_i32 m0, s98, 0x800
	s_nop 0
	global_load_lds_dwordx4 v[106:107], off
	v_mfma_f32_32x32x16_bf16 a[96:111], v[112:115], v[32:35], a[96:111]
	v_lshl_add_u64 v[106:107], v[90:91], 0, s[2:3]
	s_add_i32 m0, s98, 0x8800
	s_nop 0
	global_load_lds_dwordx4 v[106:107], off
	v_mfma_f32_32x32x16_bf16 a[32:47], v[112:115], v[36:39], a[32:47]
	v_lshl_add_u64 v[106:107], v[92:93], 0, s[70:71]
	s_add_i32 m0, s98, 0xc00
	s_nop 0
	global_load_lds_dwordx4 v[106:107], off
	ds_read_b128 v[112:115], v184 offset:12288
	s_waitcnt lgkmcnt(1)
	v_mfma_f32_32x32x16_bf16 a[208:223], v[12:15], v[24:27], a[208:223]
	v_lshl_add_u64 v[106:107], v[98:99], 0, s[46:47]
	s_add_i32 m0, s98, 0x8c00
	s_nop 0
	global_load_lds_dwordx4 v[106:107], off
	v_mfma_f32_32x32x16_bf16 a[144:159], v[12:15], v[28:31], a[144:159]
	v_lshl_add_u64 v[106:107], v[88:89], 0, s[76:77]
	s_add_i32 m0, s98, 0x1000
	v_lshl_add_u64 v[88:89], v[88:89], 0, s[48:49]
	global_load_lds_dwordx4 v[106:107], off
	v_mfma_f32_32x32x16_bf16 a[80:95], v[12:15], v[32:35], a[80:95]
	v_lshl_add_u64 v[106:107], v[90:91], 0, s[50:51]
	s_add_i32 m0, s98, 0x9000
	s_nop 0
	global_load_lds_dwordx4 v[106:107], off
	v_mfma_f32_32x32x16_bf16 a[16:31], v[12:15], v[36:39], a[16:31]
	v_lshl_add_u64 v[106:107], v[92:93], 0, s[78:79]
	s_add_i32 m0, s98, 0x1400
	s_nop 0
	global_load_lds_dwordx4 v[106:107], off
	v_lshl_or_b32 v185, v9, 1, s14
	v_add_u32_e32 v184, v185, v21
	v_add_u32_e32 v185, v185, v20
	ds_read_b128 v[12:15], v184
	s_waitcnt lgkmcnt(1)
	v_mfma_f32_32x32x16_bf16 a[192:207], v[112:115], v[24:27], a[192:207]
	v_lshl_add_u64 v[106:107], v[98:99], 0, s[52:53]
	s_add_i32 m0, s98, 0x9400
	s_nop 0
	global_load_lds_dwordx4 v[106:107], off
	ds_read_b128 v[24:27], v185 offset:32768
	v_mfma_f32_32x32x16_bf16 a[128:143], v[112:115], v[28:31], a[128:143]
	s_add_i32 m0, s98, 0x1800
	s_nop 0
	global_load_lds_dwordx4 v[88:89], off
	ds_read_b128 v[28:31], v185 offset:36864
	v_mfma_f32_32x32x16_bf16 a[64:79], v[112:115], v[32:35], a[64:79]
	v_lshl_add_u64 v[88:89], v[90:91], 0, s[54:55]
	s_add_i32 m0, s98, 0x9800
	s_nop 0
	global_load_lds_dwordx4 v[88:89], off
	ds_read_b128 v[32:35], v185 offset:40960
	v_mfma_f32_32x32x16_bf16 a[0:15], v[112:115], v[36:39], a[0:15]
	v_lshl_add_u64 v[88:89], v[92:93], 0, s[28:29]
	s_add_i32 m0, s98, 0x1c00
	s_nop 0
	global_load_lds_dwordx4 v[88:89], off
	ds_read_b128 v[36:39], v185 offset:45056
	ds_read_b128 v[112:115], v184 offset:4096
	s_waitcnt lgkmcnt(4)
	v_mfma_f32_32x32x16_bf16 a[240:255], v[12:15], v[24:27], a[240:255]
	v_lshl_add_u64 v[88:89], v[98:99], 0, s[56:57]
	s_add_i32 m0, s98, 0x9c00
	s_nop 0
	global_load_lds_dwordx4 v[88:89], off
	s_waitcnt lgkmcnt(3)
	v_mfma_f32_32x32x16_bf16 a[176:191], v[12:15], v[28:31], a[176:191]
	s_waitcnt lgkmcnt(2)
	v_mfma_f32_32x32x16_bf16 a[112:127], v[12:15], v[32:35], a[112:127]
	s_waitcnt lgkmcnt(1)
	v_mfma_f32_32x32x16_bf16 a[48:63], v[12:15], v[36:39], a[48:63]
	ds_read_b128 v[12:15], v184 offset:8192
	s_waitcnt lgkmcnt(1)
	v_mfma_f32_32x32x16_bf16 a[224:239], v[112:115], v[24:27], a[224:239]
	v_mfma_f32_32x32x16_bf16 a[160:175], v[112:115], v[28:31], a[160:175]
	v_mfma_f32_32x32x16_bf16 a[96:111], v[112:115], v[32:35], a[96:111]
	v_mfma_f32_32x32x16_bf16 a[32:47], v[112:115], v[36:39], a[32:47]
	ds_read_b128 v[112:115], v184 offset:12288
	s_waitcnt lgkmcnt(1)
	v_mfma_f32_32x32x16_bf16 a[208:223], v[12:15], v[24:27], a[208:223]
	v_mfma_f32_32x32x16_bf16 a[144:159], v[12:15], v[28:31], a[144:159]
	v_mfma_f32_32x32x16_bf16 a[80:95], v[12:15], v[32:35], a[80:95]
	v_mfma_f32_32x32x16_bf16 a[16:31], v[12:15], v[36:39], a[16:31]
	v_lshl_or_b32 v185, v16, 1, s14
	v_add_u32_e32 v184, v185, v21
	v_add_u32_e32 v185, v185, v20
	ds_read_b128 v[12:15], v184
	s_waitcnt lgkmcnt(1)
	v_mfma_f32_32x32x16_bf16 a[192:207], v[112:115], v[24:27], a[192:207]
	ds_read_b128 v[24:27], v185 offset:32768
	v_mfma_f32_32x32x16_bf16 a[128:143], v[112:115], v[28:31], a[128:143]
	ds_read_b128 v[28:31], v185 offset:36864
	v_mfma_f32_32x32x16_bf16 a[64:79], v[112:115], v[32:35], a[64:79]
	ds_read_b128 v[32:35], v185 offset:40960
	v_mfma_f32_32x32x16_bf16 a[0:15], v[112:115], v[36:39], a[0:15]
	ds_read_b128 v[36:39], v185 offset:45056
	ds_read_b128 v[112:115], v184 offset:4096
	s_waitcnt lgkmcnt(4)
	v_mfma_f32_32x32x16_bf16 a[240:255], v[12:15], v[24:27], a[240:255]
	s_waitcnt lgkmcnt(3)
	v_mfma_f32_32x32x16_bf16 a[176:191], v[12:15], v[28:31], a[176:191]
	s_waitcnt lgkmcnt(2)
	v_mfma_f32_32x32x16_bf16 a[112:127], v[12:15], v[32:35], a[112:127]
	s_waitcnt lgkmcnt(1)
	v_mfma_f32_32x32x16_bf16 a[48:63], v[12:15], v[36:39], a[48:63]
	ds_read_b128 v[12:15], v184 offset:8192
	s_waitcnt lgkmcnt(1)
	v_mfma_f32_32x32x16_bf16 a[224:239], v[112:115], v[24:27], a[224:239]
	v_mfma_f32_32x32x16_bf16 a[160:175], v[112:115], v[28:31], a[160:175]
	v_mfma_f32_32x32x16_bf16 a[96:111], v[112:115], v[32:35], a[96:111]
	v_mfma_f32_32x32x16_bf16 a[32:47], v[112:115], v[36:39], a[32:47]
	ds_read_b128 v[112:115], v184 offset:12288
	s_waitcnt lgkmcnt(1)
	v_mfma_f32_32x32x16_bf16 a[208:223], v[12:15], v[24:27], a[208:223]
	v_mfma_f32_32x32x16_bf16 a[144:159], v[12:15], v[28:31], a[144:159]
	v_mfma_f32_32x32x16_bf16 a[80:95], v[12:15], v[32:35], a[80:95]
	v_mfma_f32_32x32x16_bf16 a[16:31], v[12:15], v[36:39], a[16:31]
	v_lshl_or_b32 v185, v22, 1, s14
	v_add_u32_e32 v184, v185, v21
	v_add_u32_e32 v185, v185, v20
	ds_read_b128 v[12:15], v184
	s_waitcnt lgkmcnt(1)
	v_mfma_f32_32x32x16_bf16 a[192:207], v[112:115], v[24:27], a[192:207]
	ds_read_b128 v[24:27], v185 offset:32768
	v_mfma_f32_32x32x16_bf16 a[128:143], v[112:115], v[28:31], a[128:143]
	ds_read_b128 v[28:31], v185 offset:36864
	v_mfma_f32_32x32x16_bf16 a[64:79], v[112:115], v[32:35], a[64:79]
	ds_read_b128 v[32:35], v185 offset:40960
	v_mfma_f32_32x32x16_bf16 a[0:15], v[112:115], v[36:39], a[0:15]
	ds_read_b128 v[36:39], v185 offset:45056
	ds_read_b128 v[112:115], v184 offset:4096
	s_waitcnt lgkmcnt(4)
	v_mfma_f32_32x32x16_bf16 a[240:255], v[12:15], v[24:27], a[240:255]
	s_waitcnt lgkmcnt(3)
	v_mfma_f32_32x32x16_bf16 a[176:191], v[12:15], v[28:31], a[176:191]
	s_waitcnt lgkmcnt(2)
	v_mfma_f32_32x32x16_bf16 a[112:127], v[12:15], v[32:35], a[112:127]
	s_waitcnt lgkmcnt(1)
	v_mfma_f32_32x32x16_bf16 a[48:63], v[12:15], v[36:39], a[48:63]
	ds_read_b128 v[12:15], v184 offset:8192
	s_waitcnt lgkmcnt(1)
	v_mfma_f32_32x32x16_bf16 a[224:239], v[112:115], v[24:27], a[224:239]
	v_mfma_f32_32x32x16_bf16 a[160:175], v[112:115], v[28:31], a[160:175]
	v_mfma_f32_32x32x16_bf16 a[96:111], v[112:115], v[32:35], a[96:111]
	v_mfma_f32_32x32x16_bf16 a[32:47], v[112:115], v[36:39], a[32:47]
	ds_read_b128 v[112:115], v184 offset:12288
	s_waitcnt lgkmcnt(1)
	v_mfma_f32_32x32x16_bf16 a[208:223], v[12:15], v[24:27], a[208:223]
	v_mfma_f32_32x32x16_bf16 a[144:159], v[12:15], v[28:31], a[144:159]
	v_mfma_f32_32x32x16_bf16 a[80:95], v[12:15], v[32:35], a[80:95]
	v_mfma_f32_32x32x16_bf16 a[16:31], v[12:15], v[36:39], a[16:31]
	s_waitcnt vmcnt(0)
	s_waitcnt vmcnt(0) lgkmcnt(0)
	s_barrier
	s_add_u32 s12, s12, 0x80
	s_addc_u32 s13, s13, 0
	s_add_i32 s11, s11, 0x8000
	s_cmpk_lg_i32 s12, 0x780
	v_mfma_f32_32x32x16_bf16 a[192:207], v[112:115], v[24:27], a[192:207]
	v_mfma_f32_32x32x16_bf16 a[128:143], v[112:115], v[28:31], a[128:143]
	v_mfma_f32_32x32x16_bf16 a[64:79], v[112:115], v[32:35], a[64:79]
	v_mfma_f32_32x32x16_bf16 a[0:15], v[112:115], v[36:39], a[0:15]
	s_cbranch_scc1 .LBB0_97
	s_and_b32 s10, s10, 0x700
	v_lshlrev_b32_e32 v4, 1, v10
	s_mov_b32 s11, 0x10000
	v_add3_u32 v8, v21, v4, s11
	ds_read_b128 v[0:3], v8
	s_mov_b32 s12, 0x18000
	v_add3_u32 v10, v20, v4, s12
	ds_read_b128 v[4:7], v10
	ds_read_b128 v[24:27], v8 offset:4096
	ds_read_b128 v[28:31], v10 offset:4096
	ds_read_b128 v[32:35], v10 offset:8192
	ds_read_b128 v[12:15], v10 offset:12288
	s_waitcnt lgkmcnt(3)
	v_mfma_f32_32x32x16_bf16 a[224:239], v[24:27], v[4:7], a[224:239]
	v_lshlrev_b32_e32 v16, 1, v16
	v_lshlrev_b32_e32 v22, 1, v22
	v_add3_u32 v23, v21, v16, s11
	v_mfma_f32_32x32x16_bf16 a[240:255], v[0:3], v[4:7], a[240:255]
	s_waitcnt lgkmcnt(2)
	v_mfma_f32_32x32x16_bf16 a[176:191], v[0:3], v[28:31], a[176:191]
	s_waitcnt lgkmcnt(1)
	v_mfma_f32_32x32x16_bf16 a[112:127], v[0:3], v[32:35], a[112:127]
	s_waitcnt lgkmcnt(0)
	v_mfma_f32_32x32x16_bf16 a[48:63], v[0:3], v[12:15], a[48:63]
	v_mfma_f32_32x32x16_bf16 a[160:175], v[24:27], v[28:31], a[160:175]
	v_mfma_f32_32x32x16_bf16 a[96:111], v[24:27], v[32:35], a[96:111]
	v_mfma_f32_32x32x16_bf16 a[32:47], v[24:27], v[12:15], a[32:47]
	ds_read_b128 v[0:3], v8 offset:8192
	ds_read_b128 v[24:27], v8 offset:12288
	s_waitcnt lgkmcnt(1)
	v_mfma_f32_32x32x16_bf16 a[208:223], v[0:3], v[4:7], a[208:223]
	v_mfma_f32_32x32x16_bf16 a[144:159], v[0:3], v[28:31], a[144:159]
	v_mfma_f32_32x32x16_bf16 a[80:95], v[0:3], v[32:35], a[80:95]
	v_mfma_f32_32x32x16_bf16 a[16:31], v[0:3], v[12:15], a[16:31]
	v_lshlrev_b32_e32 v0, 1, v9
	v_add3_u32 v17, v21, v0, s11
	ds_read_b128 v[8:11], v17
	v_add3_u32 v0, v20, v0, s12
	s_waitcnt lgkmcnt(1)
	v_mfma_f32_32x32x16_bf16 a[192:207], v[24:27], v[4:7], a[192:207]
	v_mfma_f32_32x32x16_bf16 a[128:143], v[24:27], v[28:31], a[128:143]
	v_mfma_f32_32x32x16_bf16 a[64:79], v[24:27], v[32:35], a[64:79]
	ds_read_b128 v[28:31], v0
	ds_read_b128 v[32:35], v17 offset:4096
	ds_read_b128 v[40:43], v0 offset:4096
	ds_read_b128 v[4:7], v0 offset:8192
	ds_read_b128 v[0:3], v0 offset:12288
	s_waitcnt lgkmcnt(4)
	v_mfma_f32_32x32x16_bf16 a[240:255], v[8:11], v[28:31], a[240:255]
	s_waitcnt lgkmcnt(2)
	v_mfma_f32_32x32x16_bf16 a[176:191], v[8:11], v[40:43], a[176:191]
	s_waitcnt lgkmcnt(1)
	v_mfma_f32_32x32x16_bf16 a[112:127], v[8:11], v[4:7], a[112:127]
	s_waitcnt lgkmcnt(0)
	v_mfma_f32_32x32x16_bf16 a[48:63], v[8:11], v[0:3], a[48:63]
	v_mfma_f32_32x32x16_bf16 a[224:239], v[32:35], v[28:31], a[224:239]
	v_mfma_f32_32x32x16_bf16 a[160:175], v[32:35], v[40:43], a[160:175]
	v_mfma_f32_32x32x16_bf16 a[96:111], v[32:35], v[4:7], a[96:111]
	v_mfma_f32_32x32x16_bf16 a[32:47], v[32:35], v[0:3], a[32:47]
	ds_read_b128 v[32:35], v17 offset:8192
	ds_read_b128 v[8:11], v17 offset:12288
	ds_read_b128 v[72:75], v23
	v_mfma_f32_32x32x16_bf16 a[0:15], v[24:27], v[12:15], a[0:15]
	s_waitcnt lgkmcnt(2)
	v_mfma_f32_32x32x16_bf16 a[208:223], v[32:35], v[28:31], a[208:223]
	v_mfma_f32_32x32x16_bf16 a[144:159], v[32:35], v[40:43], a[144:159]
	v_mfma_f32_32x32x16_bf16 a[80:95], v[32:35], v[4:7], a[80:95]
	v_mfma_f32_32x32x16_bf16 a[16:31], v[32:35], v[0:3], a[16:31]
	v_add3_u32 v32, v20, v22, s12
	s_waitcnt lgkmcnt(1)
	v_mfma_f32_32x32x16_bf16 a[192:207], v[8:11], v[28:31], a[192:207]
	v_add3_u32 v28, v20, v16, s12
	v_add3_u32 v29, v21, v22, s11
	s_mov_b32 s11, 0
	ds_read_b128 v[56:59], v28
	ds_read_b128 v[80:83], v23 offset:4096
	ds_read_b128 v[16:19], v28 offset:4096
	ds_read_b128 v[76:79], v29
	ds_read_b128 v[60:63], v32
	ds_read_b128 v[64:67], v23 offset:8192
	ds_read_b128 v[20:23], v23 offset:12288
	ds_read_b128 v[84:87], v29 offset:4096
	ds_read_b128 v[52:55], v32 offset:4096
	ds_read_b128 v[48:51], v28 offset:8192
	ds_read_b128 v[36:39], v28 offset:12288
	ds_read_b128 v[68:71], v29 offset:8192
	ds_read_b128 v[28:31], v29 offset:12288
	ds_read_b128 v[44:47], v32 offset:8192
	ds_read_b128 v[32:35], v32 offset:12288
	s_waitcnt vmcnt(0)
	s_waitcnt lgkmcnt(0)
	s_barrier
	v_mfma_f32_32x32x16_bf16 a[64:79], v[8:11], v[4:7], a[64:79]
	v_mbcnt_lo_u32_b32 v12, -1, s11
	v_mbcnt_hi_u32_b32 v4, -1, v12
	v_or_b32_e32 v250, s26, v4
	v_and_b32_e32 v5, 31, v4
	v_lshlrev_b32_e32 v6, 1, v250
	v_lshrrev_b32_e32 v4, 3, v4
	v_and_or_b32 v251, v6, s19, v5
	v_and_b32_e32 v4, 4, v4
	v_mfma_f32_32x32x16_bf16 a[0:15], v[8:11], v[0:3], a[0:15]
	v_lshlrev_b32_e32 v252, 2, v4
	v_or_b32_e32 v0, s10, v251
	v_lshl_add_u64 v[24:25], s[0:1], 0, v[252:253]
	v_lshl_add_u64 v[14:15], s[6:7], 0, v[252:253]
	v_lshlrev_b32_e32 v252, 5, v0
	v_lshl_add_u64 v[0:1], v[24:25], 0, v[252:253]
	v_lshl_add_u64 v[2:3], v[14:15], 0, v[252:253]
	global_load_dwordx4 v[236:239], v[0:1], off
	global_load_dwordx4 v[240:243], v[2:3], off
	v_mfma_f32_32x32x16_bf16 a[240:255], v[72:75], v[56:59], a[240:255]
	s_mov_b32 s11, 0x7fffff80
	s_mov_b32 s10, 0
	v_mfma_f32_32x32x16_bf16 a[128:143], v[8:11], v[40:43], a[128:143]
	v_mfma_f32_32x32x16_bf16 a[240:255], v[76:79], v[60:63], a[240:255]
	v_mfma_f32_32x32x16_bf16 a[192:207], v[20:23], v[56:59], a[192:207]
	s_nop 10
	v_accvgpr_read_b32 v195, a247
	v_accvgpr_read_b32 v194, a246
	v_accvgpr_read_b32 v199, a245
	v_mfma_f32_32x32x16_bf16 a[128:143], v[20:23], v[16:19], a[128:143]
	v_accvgpr_read_b32 v198, a244
	v_accvgpr_read_b32 v197, a243
	v_accvgpr_read_b32 v196, a242
	v_accvgpr_read_b32 v191, a251
	v_accvgpr_read_b32 v190, a250
	v_accvgpr_read_b32 v193, a249
	v_accvgpr_read_b32 v192, a248
	v_mfma_f32_32x32x16_bf16 a[64:79], v[20:23], v[48:51], a[64:79]
	v_accvgpr_read_b32 v187, a255
	v_accvgpr_read_b32 v186, a254
	v_accvgpr_read_b32 v189, a253
	v_accvgpr_read_b32 v188, a252
	v_mfma_f32_32x32x16_bf16 a[0:15], v[20:23], v[36:39], a[0:15]
	v_mfma_f32_32x32x16_bf16 a[48:63], v[72:75], v[36:39], a[48:63]
	v_mfma_f32_32x32x16_bf16 a[32:47], v[80:83], v[36:39], a[32:47]
	v_mfma_f32_32x32x16_bf16 a[16:31], v[64:67], v[36:39], a[16:31]
	v_mfma_f32_32x32x16_bf16 a[224:239], v[80:83], v[56:59], a[224:239]
	v_mfma_f32_32x32x16_bf16 a[192:207], v[28:31], v[60:63], a[192:207]
	v_mfma_f32_32x32x16_bf16 a[128:143], v[28:31], v[52:55], a[128:143]
	s_nop 10
	v_accvgpr_read_b32 v249, a195
	v_accvgpr_read_b32 v248, a194
	v_accvgpr_read_b32 v245, a199
	v_mfma_f32_32x32x16_bf16 a[64:79], v[28:31], v[44:47], a[64:79]
	v_accvgpr_read_b32 v244, a198
	v_accvgpr_read_b32 v247, a197
	v_accvgpr_read_b32 v246, a196
	v_accvgpr_read_b32 v233, a203
	v_accvgpr_read_b32 v232, a202
	v_accvgpr_read_b32 v235, a201
	v_accvgpr_read_b32 v234, a200
	v_mfma_f32_32x32x16_bf16 a[0:15], v[28:31], v[32:35], a[0:15]
	v_accvgpr_read_b32 v30, a240
	v_accvgpr_read_b32 v31, a241
	v_and_or_b32 v28, v250, s11, v4
	v_mul_u32_u24_e32 v29, 0x210, v251
	v_lshl_add_u32 v28, v28, 1, v29
	v_accvgpr_read_b32 v229, a207
	v_accvgpr_read_b32 v228, a206
	v_mfma_f32_32x32x16_bf16 a[48:63], v[76:79], v[32:35], a[48:63]
	v_accvgpr_read_b32 v231, a205
	v_accvgpr_read_b32 v230, a204
	v_accvgpr_read_b32 v43, a143
	v_accvgpr_read_b32 v42, a142
	v_accvgpr_read_b32 v1, a15
	v_accvgpr_read_b32 v0, a14
	v_accvgpr_write_b32 a15, v1
	v_mfma_f32_32x32x16_bf16 a[32:47], v[84:87], v[32:35], a[32:47]
	v_accvgpr_write_b32 a14, v0
	v_accvgpr_read_b32 v2, a12
	v_accvgpr_read_b32 v1, a11
	v_accvgpr_read_b32 v0, a10
	v_accvgpr_read_b32 v95, a55
	v_accvgpr_read_b32 v94, a54
	v_accvgpr_read_b32 v97, a51
	v_mfma_f32_32x32x16_bf16 a[16:31], v[68:71], v[32:35], a[16:31]
	s_waitcnt vmcnt(0)
	v_mul_f32_e64 v32, v198, v240
	v_mul_f32_e64 v33, v199, v241
	v_mul_f32_e64 v34, v194, v242
	v_mul_f32_e64 v35, v195, v243
	v_pk_fma_f32 v[32:33], v[30:31], v[236:237], v[32:33] neg_lo:[0,0,1] neg_hi:[0,0,1]
	v_pk_fma_f32 v[34:35], v[196:197], v[238:239], v[34:35] neg_lo:[0,0,1] neg_hi:[0,0,1]
	v_pk_mul_f32 v[32:33], v[32:33], s[58:59] op_sel_hi:[1,0]
	v_pk_mul_f32 v[34:35], v[34:35], s[58:59] op_sel_hi:[1,0]
	v_cvt_pk_bf16_f32 v32, v32, v33
	v_mfma_f32_32x32x16_bf16 a[224:239], v[84:87], v[60:63], a[224:239]
	v_cvt_pk_bf16_f32 v33, v34, v35
	v_mul_f32_e64 v30, v30, v240
	v_mul_f32_e64 v31, v31, v241
	v_mul_f32_e64 v34, v196, v242
	v_mul_f32_e64 v35, v197, v243
	v_pk_fma_f32 v[30:31], v[198:199], v[236:237], v[30:31]
	v_pk_fma_f32 v[34:35], v[194:195], v[238:239], v[34:35]
	v_pk_mul_f32 v[30:31], v[30:31], s[58:59] op_sel_hi:[1,0]
	v_pk_mul_f32 v[34:35], v[34:35], s[58:59] op_sel_hi:[1,0]
	v_mfma_f32_32x32x16_bf16 a[208:223], v[64:67], v[56:59], a[208:223]
	v_cvt_pk_bf16_f32 v30, v30, v31
	v_cvt_pk_bf16_f32 v31, v34, v35
	ds_write2_b64 v28, v[32:33], v[30:31] offset1:2
	v_mul_f32_e64 v30, v192, s58
	v_mul_f32_e64 v31, v193, s58
	v_pk_mul_f32 v[32:33], v[190:191], s[58:59] op_sel_hi:[1,0]
	v_cvt_pk_bf16_f32 v30, v30, v31
	v_cvt_pk_bf16_f32 v31, v32, v33
	v_pk_mul_f32 v[32:33], v[188:189], s[58:59] op_sel_hi:[1,0]
	v_pk_mul_f32 v[34:35], v[186:187], s[58:59] op_sel_hi:[1,0]
	v_cvt_pk_bf16_f32 v32, v32, v33
	v_cvt_pk_bf16_f32 v33, v34, v35
	v_mfma_f32_32x32x16_bf16 a[208:223], v[68:71], v[60:63], a[208:223]
	ds_write2_b64 v28, v[30:31], v[32:33] offset0:4 offset1:6
	v_accvgpr_read_b32 v30, a224
	v_accvgpr_read_b32 v213, a227
	v_accvgpr_read_b32 v212, a226
	v_accvgpr_read_b32 v31, a225
	v_accvgpr_read_b32 v209, a231
	v_accvgpr_read_b32 v208, a230
	v_accvgpr_read_b32 v211, a229
	v_accvgpr_read_b32 v210, a228
	v_pk_mul_f32 v[30:31], v[30:31], s[58:59] op_sel_hi:[1,0]
	v_pk_mul_f32 v[32:33], v[212:213], s[58:59] op_sel_hi:[1,0]
	v_cvt_pk_bf16_f32 v30, v30, v31
	v_cvt_pk_bf16_f32 v31, v32, v33
	v_pk_mul_f32 v[32:33], v[210:211], s[58:59] op_sel_hi:[1,0]
	v_pk_mul_f32 v[34:35], v[208:209], s[58:59] op_sel_hi:[1,0]
	v_accvgpr_read_b32 v205, a235
	v_accvgpr_read_b32 v204, a234
	v_accvgpr_read_b32 v207, a233
	v_accvgpr_read_b32 v206, a232
	v_cvt_pk_bf16_f32 v32, v32, v33
	v_cvt_pk_bf16_f32 v33, v34, v35
	v_accvgpr_read_b32 v201, a239
	v_accvgpr_read_b32 v200, a238
	v_accvgpr_read_b32 v203, a237
	v_accvgpr_read_b32 v202, a236
	ds_write2_b64 v28, v[30:31], v[32:33] offset0:8 offset1:10
	v_pk_mul_f32 v[30:31], v[206:207], s[58:59] op_sel_hi:[1,0]
	v_pk_mul_f32 v[32:33], v[204:205], s[58:59] op_sel_hi:[1,0]
	v_cvt_pk_bf16_f32 v30, v30, v31
	v_cvt_pk_bf16_f32 v31, v32, v33
	v_pk_mul_f32 v[32:33], v[202:203], s[58:59] op_sel_hi:[1,0]
	v_pk_mul_f32 v[34:35], v[200:201], s[58:59] op_sel_hi:[1,0]
	v_cvt_pk_bf16_f32 v32, v32, v33
	v_cvt_pk_bf16_f32 v33, v34, v35
	v_accvgpr_read_b32 v223, a215
	v_accvgpr_read_b32 v222, a214
	v_accvgpr_read_b32 v227, a213
	v_accvgpr_read_b32 v226, a212
	ds_write2_b64 v28, v[30:31], v[32:33] offset0:12 offset1:14
	v_accvgpr_read_b32 v30, a208
	v_accvgpr_read_b32 v225, a211
	v_accvgpr_read_b32 v224, a210
	v_accvgpr_read_b32 v31, a209
	v_pk_mul_f32 v[32:33], v[226:227], v[240:241]
	v_pk_mul_f32 v[34:35], v[222:223], v[242:243]
	v_pk_fma_f32 v[32:33], v[30:31], v[236:237], v[32:33] neg_lo:[0,0,1] neg_hi:[0,0,1]
	v_pk_fma_f32 v[34:35], v[224:225], v[238:239], v[34:35] neg_lo:[0,0,1] neg_hi:[0,0,1]
	v_mfma_f32_32x32x16_bf16 a[176:191], v[72:75], v[16:19], a[176:191]
	v_mul_f32_e64 v32, v32, s58
	v_mul_f32_e64 v33, v33, s58
	v_mul_f32_e64 v34, v34, s58
	v_mul_f32_e64 v35, v35, s58
	v_cvt_pk_bf16_f32 v32, v32, v33
	v_cvt_pk_bf16_f32 v33, v34, v35
	v_pk_mul_f32 v[30:31], v[30:31], v[240:241]
	v_pk_mul_f32 v[34:35], v[224:225], v[242:243]
	v_pk_fma_f32 v[30:31], v[226:227], v[236:237], v[30:31]
	v_mfma_f32_32x32x16_bf16 a[112:127], v[72:75], v[48:51], a[112:127]
	v_fma_f32 v34, v222, v238, v34
	v_fma_f32 v35, v223, v239, v35
	v_mul_f32_e64 v30, v30, s58
	v_mul_f32_e64 v31, v31, s58
	v_mul_f32_e64 v34, v34, s58
	v_mul_f32_e64 v35, v35, s58
	v_accvgpr_read_b32 v219, a219
	v_accvgpr_read_b32 v218, a218
	v_accvgpr_read_b32 v221, a217
	v_accvgpr_read_b32 v220, a216
	v_mfma_f32_32x32x16_bf16 a[160:175], v[80:83], v[16:19], a[160:175]
	v_cvt_pk_bf16_f32 v30, v30, v31
	v_cvt_pk_bf16_f32 v31, v34, v35
	v_accvgpr_read_b32 v215, a223
	v_accvgpr_read_b32 v214, a222
	v_accvgpr_read_b32 v217, a221
	v_accvgpr_read_b32 v216, a220
	ds_write2_b64 v28, v[32:33], v[30:31] offset0:16 offset1:18
	v_mfma_f32_32x32x16_bf16 a[96:111], v[80:83], v[48:51], a[96:111]
	v_mul_f32_e64 v30, v220, s58
	v_mul_f32_e64 v31, v221, s58
	v_mul_f32_e64 v32, v218, s58
	v_mul_f32_e64 v33, v219, s58
	v_cvt_pk_bf16_f32 v30, v30, v31
	v_cvt_pk_bf16_f32 v31, v32, v33
	v_pk_mul_f32 v[32:33], v[216:217], s[58:59] op_sel_hi:[1,0]
	v_pk_mul_f32 v[34:35], v[214:215], s[58:59] op_sel_hi:[1,0]
	v_cvt_pk_bf16_f32 v32, v32, v33
	v_mfma_f32_32x32x16_bf16 a[144:159], v[64:67], v[16:19], a[144:159]
	v_cvt_pk_bf16_f32 v33, v34, v35
	ds_write2_b64 v28, v[30:31], v[32:33] offset0:20 offset1:22
	v_accvgpr_read_b32 v30, a192
	v_accvgpr_read_b32 v31, a193
	v_mul_f32_e64 v30, v30, s58
	v_mul_f32_e64 v31, v31, s58
	v_pk_mul_f32 v[32:33], v[248:249], s[58:59] op_sel_hi:[1,0]
	v_cvt_pk_bf16_f32 v30, v30, v31
	v_mfma_f32_32x32x16_bf16 a[80:95], v[64:67], v[48:51], a[80:95]
	v_cvt_pk_bf16_f32 v31, v32, v33
	v_mul_f32_e64 v32, v246, s58
	v_mul_f32_e64 v33, v247, s58
	v_mul_f32_e64 v34, v244, s58
	v_mul_f32_e64 v35, v245, s58
	v_cvt_pk_bf16_f32 v32, v32, v33
	v_cvt_pk_bf16_f32 v33, v34, v35
	ds_write2_b64 v28, v[30:31], v[32:33] offset0:24 offset1:26
	v_pk_mul_f32 v[30:31], v[234:235], s[58:59] op_sel_hi:[1,0]
	v_mfma_f32_32x32x16_bf16 a[176:191], v[76:79], v[52:55], a[176:191]
	v_mul_f32_e64 v32, v232, s58
	v_mul_f32_e64 v33, v233, s58
	v_cvt_pk_bf16_f32 v30, v30, v31
	v_cvt_pk_bf16_f32 v31, v32, v33
	v_mul_f32_e64 v32, v230, s58
	v_mul_f32_e64 v33, v231, s58
	v_pk_mul_f32 v[34:35], v[228:229], s[58:59] op_sel_hi:[1,0]
	v_cvt_pk_bf16_f32 v32, v32, v33
	v_cvt_pk_bf16_f32 v33, v34, v35
	v_mfma_f32_32x32x16_bf16 a[112:127], v[76:79], v[44:47], a[112:127]
	v_accvgpr_read_b32 v73, a63
	v_accvgpr_read_b32 v72, a62
	v_accvgpr_read_b32 v75, a61
	v_accvgpr_read_b32 v74, a60
	v_accvgpr_read_b32 v141, a191
	v_accvgpr_read_b32 v140, a190
	v_accvgpr_read_b32 v143, a189
	v_mfma_f32_32x32x16_bf16 a[160:175], v[84:87], v[52:55], a[160:175]
	v_accvgpr_read_b32 v142, a188
	v_accvgpr_read_b32 v147, a187
	v_accvgpr_read_b32 v146, a186
	v_accvgpr_read_b32 v151, a185
	v_accvgpr_read_b32 v150, a184
	v_accvgpr_read_b32 v173, a183
	v_accvgpr_read_b32 v172, a182
	v_mfma_f32_32x32x16_bf16 a[96:111], v[84:87], v[44:47], a[96:111]
	v_accvgpr_read_b32 v175, a179
	v_accvgpr_read_b32 v174, a178
	v_accvgpr_read_b32 v177, a181
	v_accvgpr_read_b32 v176, a180
	v_accvgpr_read_b32 v101, a127
	v_accvgpr_read_b32 v100, a126
	v_accvgpr_read_b32 v103, a125
	v_mfma_f32_32x32x16_bf16 a[144:159], v[68:71], v[52:55], a[144:159]
	v_accvgpr_read_b32 v102, a124
	v_accvgpr_read_b32 v105, a123
	v_accvgpr_read_b32 v104, a122
	v_accvgpr_read_b32 v109, a121
	v_accvgpr_read_b32 v108, a120
	v_accvgpr_read_b32 v131, a119
	v_accvgpr_read_b32 v130, a118
	v_mfma_f32_32x32x16_bf16 a[80:95], v[68:71], v[44:47], a[80:95]
	v_accvgpr_read_b32 v133, a115
	v_accvgpr_read_b32 v132, a114
	v_accvgpr_read_b32 v135, a117
	v_accvgpr_read_b32 v134, a116
	v_accvgpr_read_b32 v77, a59
	v_accvgpr_read_b32 v76, a58
	v_accvgpr_read_b32 v79, a57
	v_accvgpr_read_b32 v78, a56
	v_accvgpr_read_b32 v96, a50
	v_accvgpr_read_b32 v99, a53
	v_accvgpr_read_b32 v98, a52
	v_accvgpr_read_b32 v153, a175
	v_accvgpr_read_b32 v152, a174
	v_accvgpr_read_b32 v157, a173
	v_accvgpr_read_b32 v156, a172
	v_accvgpr_read_b32 v161, a171
	v_accvgpr_read_b32 v160, a170
	v_accvgpr_read_b32 v165, a169
	v_accvgpr_read_b32 v164, a168
	v_accvgpr_read_b32 v167, a167
	v_accvgpr_read_b32 v166, a166
	v_accvgpr_read_b32 v169, a165
	v_accvgpr_read_b32 v168, a164
	v_accvgpr_read_b32 v171, a163
	v_accvgpr_read_b32 v170, a162
	v_accvgpr_read_b32 v111, a111
	v_accvgpr_read_b32 v110, a110
	v_accvgpr_read_b32 v115, a109
	v_accvgpr_read_b32 v114, a108
	v_accvgpr_read_b32 v119, a107
	v_accvgpr_read_b32 v118, a106
	v_accvgpr_read_b32 v123, a105
	v_accvgpr_read_b32 v122, a104
	v_accvgpr_read_b32 v125, a103
	v_accvgpr_read_b32 v124, a102
	v_accvgpr_read_b32 v127, a101
	v_accvgpr_read_b32 v126, a100
	v_accvgpr_read_b32 v129, a99
	v_accvgpr_read_b32 v128, a98
	v_accvgpr_read_b32 v81, a47
	v_accvgpr_read_b32 v80, a46
	v_accvgpr_read_b32 v83, a45
	v_accvgpr_read_b32 v82, a44
	v_accvgpr_read_b32 v85, a43
	v_accvgpr_read_b32 v84, a42
	v_accvgpr_read_b32 v87, a41
	v_accvgpr_read_b32 v86, a40
	v_accvgpr_read_b32 v89, a39
	v_accvgpr_read_b32 v88, a38
	v_accvgpr_read_b32 v91, a37
	v_accvgpr_read_b32 v90, a36
	v_accvgpr_read_b32 v93, a35
	v_accvgpr_read_b32 v92, a34
	v_accvgpr_read_b32 v149, a159
	v_accvgpr_read_b32 v148, a158
	v_accvgpr_read_b32 v155, a157
	v_accvgpr_read_b32 v154, a156
	v_accvgpr_read_b32 v159, a155
	v_accvgpr_read_b32 v158, a154
	v_accvgpr_read_b32 v163, a153
	v_accvgpr_read_b32 v162, a152
	v_accvgpr_read_b32 v179, a151
	v_accvgpr_read_b32 v178, a150
	v_accvgpr_read_b32 v181, a147
	v_accvgpr_read_b32 v180, a146
	v_accvgpr_read_b32 v183, a149
	v_accvgpr_read_b32 v182, a148
	v_accvgpr_read_b32 v107, a95
	v_accvgpr_read_b32 v106, a94
	v_accvgpr_read_b32 v113, a93
	v_accvgpr_read_b32 v112, a92
	v_accvgpr_read_b32 v117, a91
	v_accvgpr_read_b32 v116, a90
	v_accvgpr_read_b32 v121, a89
	v_accvgpr_read_b32 v120, a88
	v_accvgpr_read_b32 v71, a87
	v_accvgpr_read_b32 v70, a86
	v_accvgpr_read_b32 v137, a83
	v_accvgpr_read_b32 v136, a82
	v_accvgpr_read_b32 v139, a85
	v_accvgpr_read_b32 v138, a84
	v_accvgpr_read_b32 v65, a31
	v_accvgpr_read_b32 v64, a30
	v_accvgpr_read_b32 v57, a29
	v_accvgpr_read_b32 v56, a28
	v_accvgpr_read_b32 v59, a27
	v_accvgpr_read_b32 v58, a26
	v_accvgpr_read_b32 v67, a25
	v_accvgpr_read_b32 v66, a24
	v_accvgpr_read_b32 v61, a23
	v_accvgpr_read_b32 v60, a22
	v_accvgpr_read_b32 v63, a19
	v_accvgpr_read_b32 v62, a18
	v_accvgpr_read_b32 v69, a21
	v_accvgpr_read_b32 v68, a20
	v_accvgpr_read_b32 v53, a141
	v_accvgpr_read_b32 v52, a140
	v_accvgpr_read_b32 v55, a139
	v_accvgpr_read_b32 v54, a138
	v_accvgpr_read_b32 v145, a137
	v_accvgpr_read_b32 v144, a136
	v_accvgpr_read_b32 v49, a135
	v_accvgpr_read_b32 v48, a134
	v_accvgpr_read_b32 v51, a133
	v_accvgpr_read_b32 v50, a132
	v_accvgpr_read_b32 v185, a131
	v_accvgpr_read_b32 v184, a130
	v_accvgpr_read_b32 v17, a79
	v_accvgpr_read_b32 v16, a78
	v_accvgpr_read_b32 v19, a77
	v_accvgpr_read_b32 v18, a76
	v_accvgpr_read_b32 v27, a75
	v_accvgpr_read_b32 v26, a74
	v_accvgpr_read_b32 v41, a73
	v_accvgpr_read_b32 v40, a72
	v_accvgpr_read_b32 v21, a71
	v_accvgpr_read_b32 v20, a70
	v_accvgpr_read_b32 v23, a69
	v_accvgpr_read_b32 v22, a68
	v_accvgpr_read_b32 v37, a67
	v_accvgpr_read_b32 v36, a66
	v_accvgpr_read_b32 v3, a13
	v_accvgpr_read_b32 v7, a9
	v_accvgpr_read_b32 v6, a8
	v_accvgpr_read_b32 v9, a7
	v_accvgpr_read_b32 v8, a6
	v_accvgpr_read_b32 v11, a5
	v_accvgpr_read_b32 v10, a4
	v_accvgpr_read_b32 v13, a3
	v_accvgpr_read_b32 v12, a2
	ds_write2_b64 v28, v[30:31], v[32:33] offset0:28 offset1:30
	v_or_b32_e32 v30, 0x400, v252
	v_mov_b32_e32 v31, v253
	v_lshl_add_u64 v[32:33], v[24:25], 0, v[30:31]
	v_lshl_add_u64 v[34:35], v[14:15], 0, v[30:31]
	global_load_dwordx4 v[30:33], v[32:33], off
	s_nop 0
	global_load_dwordx4 v[44:47], v[34:35], off
	v_accvgpr_read_b32 v34, a176
	v_accvgpr_read_b32 v35, a177
	v_add_u32_e32 v29, 0x4000, v28
	v_pk_mul_f32 v[140:141], v[140:141], s[58:59] op_sel_hi:[1,0]
	s_waitcnt vmcnt(0)
	v_pk_mul_f32 v[38:39], v[176:177], v[44:45]
	v_pk_mul_f32 v[186:187], v[172:173], v[46:47]
	v_pk_fma_f32 v[38:39], v[34:35], v[30:31], v[38:39] neg_lo:[0,0,1] neg_hi:[0,0,1]
	v_pk_fma_f32 v[186:187], v[174:175], v[32:33], v[186:187] neg_lo:[0,0,1] neg_hi:[0,0,1]
	v_pk_mul_f32 v[34:35], v[34:35], v[44:45]
	v_pk_mul_f32 v[174:175], v[174:175], v[46:47]
	v_pk_fma_f32 v[34:35], v[176:177], v[30:31], v[34:35]
	v_pk_fma_f32 v[172:173], v[172:173], v[32:33], v[174:175]
	v_pk_mul_f32 v[38:39], v[38:39], s[58:59] op_sel_hi:[1,0]
	v_pk_mul_f32 v[186:187], v[186:187], s[58:59] op_sel_hi:[1,0]
	v_pk_mul_f32 v[34:35], v[34:35], s[58:59] op_sel_hi:[1,0]
	v_pk_mul_f32 v[172:173], v[172:173], s[58:59] op_sel_hi:[1,0]
	v_cvt_pk_bf16_f32 v38, v38, v39
	v_cvt_pk_bf16_f32 v39, v186, v187
	v_cvt_pk_bf16_f32 v34, v34, v35
	v_cvt_pk_bf16_f32 v35, v172, v173
	ds_write2_b64 v29, v[38:39], v[34:35] offset0:64 offset1:66
	v_pk_mul_f32 v[34:35], v[150:151], s[58:59] op_sel_hi:[1,0]
	v_pk_mul_f32 v[38:39], v[146:147], s[58:59] op_sel_hi:[1,0]
	v_cvt_pk_bf16_f32 v34, v34, v35
	v_cvt_pk_bf16_f32 v35, v38, v39
	v_pk_mul_f32 v[38:39], v[142:143], s[58:59] op_sel_hi:[1,0]
	s_nop 0
	v_cvt_pk_bf16_f32 v38, v38, v39
	v_cvt_pk_bf16_f32 v39, v140, v141
	ds_write2_b64 v29, v[34:35], v[38:39] offset0:68 offset1:70
	v_accvgpr_read_b32 v34, a160
	v_accvgpr_read_b32 v35, a161
	v_pk_mul_f32 v[34:35], v[34:35], s[58:59] op_sel_hi:[1,0]
	v_pk_mul_f32 v[38:39], v[170:171], s[58:59] op_sel_hi:[1,0]
	v_cvt_pk_bf16_f32 v34, v34, v35
	v_cvt_pk_bf16_f32 v35, v38, v39
	v_pk_mul_f32 v[38:39], v[168:169], s[58:59] op_sel_hi:[1,0]
	v_pk_mul_f32 v[140:141], v[166:167], s[58:59] op_sel_hi:[1,0]
	v_cvt_pk_bf16_f32 v38, v38, v39
	v_cvt_pk_bf16_f32 v39, v140, v141
	ds_write2_b64 v29, v[34:35], v[38:39] offset0:72 offset1:74
	v_pk_mul_f32 v[34:35], v[164:165], s[58:59] op_sel_hi:[1,0]
	v_pk_mul_f32 v[38:39], v[160:161], s[58:59] op_sel_hi:[1,0]
	v_cvt_pk_bf16_f32 v34, v34, v35
	v_cvt_pk_bf16_f32 v35, v38, v39
	v_pk_mul_f32 v[38:39], v[156:157], s[58:59] op_sel_hi:[1,0]
	v_pk_mul_f32 v[140:141], v[152:153], s[58:59] op_sel_hi:[1,0]
	v_cvt_pk_bf16_f32 v38, v38, v39
	v_cvt_pk_bf16_f32 v39, v140, v141
	ds_write2_b64 v29, v[34:35], v[38:39] offset0:76 offset1:78
	v_accvgpr_read_b32 v34, a144
	v_accvgpr_read_b32 v35, a145
	v_pk_mul_f32 v[38:39], v[182:183], v[44:45]
	v_pk_mul_f32 v[140:141], v[178:179], v[46:47]
	v_pk_fma_f32 v[38:39], v[34:35], v[30:31], v[38:39] neg_lo:[0,0,1] neg_hi:[0,0,1]
	v_pk_mul_f32 v[34:35], v[34:35], v[44:45]
	v_pk_fma_f32 v[140:141], v[180:181], v[32:33], v[140:141] neg_lo:[0,0,1] neg_hi:[0,0,1]
	v_pk_fma_f32 v[30:31], v[182:183], v[30:31], v[34:35]
	v_pk_mul_f32 v[34:35], v[180:181], v[46:47]
	v_pk_mul_f32 v[38:39], v[38:39], s[58:59] op_sel_hi:[1,0]
	v_pk_fma_f32 v[32:33], v[178:179], v[32:33], v[34:35]
	v_pk_mul_f32 v[140:141], v[140:141], s[58:59] op_sel_hi:[1,0]
	v_pk_mul_f32 v[30:31], v[30:31], s[58:59] op_sel_hi:[1,0]
	v_pk_mul_f32 v[32:33], v[32:33], s[58:59] op_sel_hi:[1,0]
	v_cvt_pk_bf16_f32 v38, v38, v39
	v_cvt_pk_bf16_f32 v39, v140, v141
	v_cvt_pk_bf16_f32 v30, v30, v31
	v_cvt_pk_bf16_f32 v31, v32, v33
	ds_write2_b64 v29, v[38:39], v[30:31] offset0:80 offset1:82
	v_pk_mul_f32 v[30:31], v[162:163], s[58:59] op_sel_hi:[1,0]
	v_pk_mul_f32 v[32:33], v[158:159], s[58:59] op_sel_hi:[1,0]
	v_cvt_pk_bf16_f32 v30, v30, v31
	v_cvt_pk_bf16_f32 v31, v32, v33
	v_pk_mul_f32 v[32:33], v[154:155], s[58:59] op_sel_hi:[1,0]
	v_pk_mul_f32 v[34:35], v[148:149], s[58:59] op_sel_hi:[1,0]
	v_cvt_pk_bf16_f32 v32, v32, v33
	v_cvt_pk_bf16_f32 v33, v34, v35
	ds_write2_b64 v29, v[30:31], v[32:33] offset0:84 offset1:86
	v_accvgpr_read_b32 v30, a128
	v_accvgpr_read_b32 v31, a129
	v_pk_mul_f32 v[30:31], v[30:31], s[58:59] op_sel_hi:[1,0]
	v_pk_mul_f32 v[32:33], v[184:185], s[58:59] op_sel_hi:[1,0]
	v_cvt_pk_bf16_f32 v30, v30, v31
	v_cvt_pk_bf16_f32 v31, v32, v33
	v_pk_mul_f32 v[32:33], v[50:51], s[58:59] op_sel_hi:[1,0]
	v_pk_mul_f32 v[34:35], v[48:49], s[58:59] op_sel_hi:[1,0]
	v_cvt_pk_bf16_f32 v32, v32, v33
	v_cvt_pk_bf16_f32 v33, v34, v35
	ds_write2_b64 v29, v[30:31], v[32:33] offset0:88 offset1:90
	v_pk_mul_f32 v[30:31], v[144:145], s[58:59] op_sel_hi:[1,0]
	v_pk_mul_f32 v[32:33], v[54:55], s[58:59] op_sel_hi:[1,0]
	v_cvt_pk_bf16_f32 v30, v30, v31
	v_cvt_pk_bf16_f32 v31, v32, v33
	v_pk_mul_f32 v[32:33], v[52:53], s[58:59] op_sel_hi:[1,0]
	v_pk_mul_f32 v[34:35], v[42:43], s[58:59] op_sel_hi:[1,0]
	v_cvt_pk_bf16_f32 v32, v32, v33
	v_cvt_pk_bf16_f32 v33, v34, v35
	ds_write2_b64 v29, v[30:31], v[32:33] offset0:92 offset1:94
	v_or_b32_e32 v30, 0x800, v252
	v_mov_b32_e32 v31, v253
	v_lshl_add_u64 v[32:33], v[24:25], 0, v[30:31]
	v_lshl_add_u64 v[34:35], v[14:15], 0, v[30:31]
	global_load_dwordx4 v[30:33], v[32:33], off
	s_nop 0
	global_load_dwordx4 v[42:45], v[34:35], off
	v_accvgpr_read_b32 v34, a112
	v_accvgpr_read_b32 v35, a113
	v_add_u32_e32 v29, 0x8000, v28
	v_pk_mul_f32 v[22:23], v[22:23], s[58:59] op_sel_hi:[1,0]
	v_pk_mul_f32 v[20:21], v[20:21], s[58:59] op_sel_hi:[1,0]
	v_cvt_pk_bf16_f32 v22, v22, v23
	v_cvt_pk_bf16_f32 v23, v20, v21
	v_pk_mul_f32 v[20:21], v[40:41], s[58:59] op_sel_hi:[1,0]
	v_pk_mul_f32 v[18:19], v[18:19], s[58:59] op_sel_hi:[1,0]
	v_pk_mul_f32 v[16:17], v[16:17], s[58:59] op_sel_hi:[1,0]
	v_cvt_pk_bf16_f32 v20, v20, v21
	v_cvt_pk_bf16_f32 v18, v18, v19
	v_cvt_pk_bf16_f32 v19, v16, v17
	s_waitcnt vmcnt(0)
	v_pk_mul_f32 v[38:39], v[134:135], v[42:43]
	v_pk_mul_f32 v[46:47], v[130:131], v[44:45]
	v_pk_fma_f32 v[38:39], v[34:35], v[30:31], v[38:39] neg_lo:[0,0,1] neg_hi:[0,0,1]
	v_pk_fma_f32 v[46:47], v[132:133], v[32:33], v[46:47] neg_lo:[0,0,1] neg_hi:[0,0,1]
	v_pk_mul_f32 v[38:39], v[38:39], s[58:59] op_sel_hi:[1,0]
	v_pk_mul_f32 v[46:47], v[46:47], s[58:59] op_sel_hi:[1,0]
	v_cvt_pk_bf16_f32 v38, v38, v39
	v_cvt_pk_bf16_f32 v39, v46, v47
	v_pk_mul_f32 v[34:35], v[34:35], v[42:43]
	v_pk_mul_f32 v[46:47], v[132:133], v[44:45]
	v_pk_fma_f32 v[34:35], v[134:135], v[30:31], v[34:35]
	v_pk_fma_f32 v[46:47], v[130:131], v[32:33], v[46:47]
	v_pk_mul_f32 v[34:35], v[34:35], s[58:59] op_sel_hi:[1,0]
	v_pk_mul_f32 v[46:47], v[46:47], s[58:59] op_sel_hi:[1,0]
	v_cvt_pk_bf16_f32 v34, v34, v35
	v_cvt_pk_bf16_f32 v35, v46, v47
	ds_write2_b64 v29, v[38:39], v[34:35] offset0:128 offset1:130
	v_pk_mul_f32 v[34:35], v[108:109], s[58:59] op_sel_hi:[1,0]
	v_pk_mul_f32 v[38:39], v[104:105], s[58:59] op_sel_hi:[1,0]
	v_cvt_pk_bf16_f32 v34, v34, v35
	v_cvt_pk_bf16_f32 v35, v38, v39
	v_pk_mul_f32 v[38:39], v[102:103], s[58:59] op_sel_hi:[1,0]
	v_pk_mul_f32 v[46:47], v[100:101], s[58:59] op_sel_hi:[1,0]
	v_cvt_pk_bf16_f32 v38, v38, v39
	v_cvt_pk_bf16_f32 v39, v46, v47
	ds_write2_b64 v29, v[34:35], v[38:39] offset0:132 offset1:134
	v_accvgpr_read_b32 v34, a96
	v_accvgpr_read_b32 v35, a97
	v_pk_mul_f32 v[34:35], v[34:35], s[58:59] op_sel_hi:[1,0]
	v_pk_mul_f32 v[38:39], v[128:129], s[58:59] op_sel_hi:[1,0]
	v_cvt_pk_bf16_f32 v34, v34, v35
	v_cvt_pk_bf16_f32 v35, v38, v39
	v_pk_mul_f32 v[38:39], v[126:127], s[58:59] op_sel_hi:[1,0]
	v_pk_mul_f32 v[46:47], v[124:125], s[58:59] op_sel_hi:[1,0]
	v_cvt_pk_bf16_f32 v38, v38, v39
	v_cvt_pk_bf16_f32 v39, v46, v47
	ds_write2_b64 v29, v[34:35], v[38:39] offset0:136 offset1:138
	v_pk_mul_f32 v[34:35], v[122:123], s[58:59] op_sel_hi:[1,0]
	v_pk_mul_f32 v[38:39], v[118:119], s[58:59] op_sel_hi:[1,0]
	v_cvt_pk_bf16_f32 v34, v34, v35
	v_cvt_pk_bf16_f32 v35, v38, v39
	v_pk_mul_f32 v[38:39], v[114:115], s[58:59] op_sel_hi:[1,0]
	v_pk_mul_f32 v[46:47], v[110:111], s[58:59] op_sel_hi:[1,0]
	v_cvt_pk_bf16_f32 v38, v38, v39
	v_cvt_pk_bf16_f32 v39, v46, v47
	ds_write2_b64 v29, v[34:35], v[38:39] offset0:140 offset1:142
	v_accvgpr_read_b32 v34, a80
	v_accvgpr_read_b32 v35, a81
	v_pk_mul_f32 v[38:39], v[138:139], v[42:43]
	v_pk_mul_f32 v[46:47], v[70:71], v[44:45]
	v_pk_fma_f32 v[38:39], v[34:35], v[30:31], v[38:39] neg_lo:[0,0,1] neg_hi:[0,0,1]
	v_pk_mul_f32 v[34:35], v[34:35], v[42:43]
	v_pk_fma_f32 v[46:47], v[136:137], v[32:33], v[46:47] neg_lo:[0,0,1] neg_hi:[0,0,1]
	v_pk_fma_f32 v[30:31], v[138:139], v[30:31], v[34:35]
	v_pk_mul_f32 v[34:35], v[136:137], v[44:45]
	v_pk_mul_f32 v[38:39], v[38:39], s[58:59] op_sel_hi:[1,0]
	v_pk_fma_f32 v[32:33], v[70:71], v[32:33], v[34:35]
	v_pk_mul_f32 v[46:47], v[46:47], s[58:59] op_sel_hi:[1,0]
	v_pk_mul_f32 v[30:31], v[30:31], s[58:59] op_sel_hi:[1,0]
	v_pk_mul_f32 v[32:33], v[32:33], s[58:59] op_sel_hi:[1,0]
	v_cvt_pk_bf16_f32 v38, v38, v39
	v_cvt_pk_bf16_f32 v39, v46, v47
	v_cvt_pk_bf16_f32 v30, v30, v31
	v_cvt_pk_bf16_f32 v31, v32, v33
	ds_write2_b64 v29, v[38:39], v[30:31] offset0:144 offset1:146
	v_pk_mul_f32 v[30:31], v[120:121], s[58:59] op_sel_hi:[1,0]
	v_pk_mul_f32 v[32:33], v[116:117], s[58:59] op_sel_hi:[1,0]
	v_cvt_pk_bf16_f32 v30, v30, v31
	v_cvt_pk_bf16_f32 v31, v32, v33
	v_pk_mul_f32 v[32:33], v[112:113], s[58:59] op_sel_hi:[1,0]
	v_pk_mul_f32 v[34:35], v[106:107], s[58:59] op_sel_hi:[1,0]
	v_cvt_pk_bf16_f32 v32, v32, v33
	v_cvt_pk_bf16_f32 v33, v34, v35
	ds_write2_b64 v29, v[30:31], v[32:33] offset0:148 offset1:150
	v_accvgpr_read_b32 v30, a64
	v_accvgpr_read_b32 v31, a65
	v_pk_mul_f32 v[30:31], v[30:31], s[58:59] op_sel_hi:[1,0]
	v_pk_mul_f32 v[32:33], v[36:37], s[58:59] op_sel_hi:[1,0]
	v_cvt_pk_bf16_f32 v30, v30, v31
	v_cvt_pk_bf16_f32 v31, v32, v33
	ds_write2_b64 v29, v[30:31], v[22:23] offset0:152 offset1:154
	v_pk_mul_f32 v[22:23], v[26:27], s[58:59] op_sel_hi:[1,0]
	s_nop 0
	v_cvt_pk_bf16_f32 v21, v22, v23
	ds_write2_b64 v29, v[20:21], v[18:19] offset0:156 offset1:158
	v_or_b32_e32 v252, 0xc00, v252
	v_lshl_add_u64 v[16:17], v[24:25], 0, v[252:253]
	v_lshl_add_u64 v[18:19], v[14:15], 0, v[252:253]
	global_load_dwordx4 v[14:17], v[16:17], off
	s_nop 0
	global_load_dwordx4 v[18:21], v[18:19], off
	v_accvgpr_read_b32 v22, a48
	v_accvgpr_read_b32 v23, a49
	v_add_u32_e32 v28, 0xc000, v28
	v_pk_mul_f32 v[4:5], v[0:1], s[58:59] op_sel_hi:[1,0]
	v_accvgpr_read_b32 v0, a14
	v_accvgpr_read_b32 v1, a15
	v_pk_mul_f32 v[12:13], v[12:13], s[58:59] op_sel_hi:[1,0]
	v_pk_mul_f32 v[10:11], v[10:11], s[58:59] op_sel_hi:[1,0]
	v_pk_mul_f32 v[8:9], v[8:9], s[58:59] op_sel_hi:[1,0]
	v_pk_mul_f32 v[6:7], v[6:7], s[58:59] op_sel_hi:[1,0]
	v_pk_mul_f32 v[2:3], v[2:3], s[58:59] op_sel_hi:[1,0]
	v_pk_mul_f32 v[0:1], v[0:1], s[58:59] op_sel_hi:[1,0]
	v_cvt_pk_bf16_f32 v10, v10, v11
	v_cvt_pk_bf16_f32 v11, v8, v9
	v_cvt_pk_bf16_f32 v6, v6, v7
	v_cvt_pk_bf16_f32 v7, v4, v5
	v_cvt_pk_bf16_f32 v2, v2, v3
	v_cvt_pk_bf16_f32 v3, v0, v1
	ds_write2_b64 v28, v[6:7], v[2:3] offset0:220 offset1:222
	s_waitcnt vmcnt(0)
	v_pk_mul_f32 v[24:25], v[98:99], v[18:19]
	v_pk_mul_f32 v[26:27], v[94:95], v[20:21]
	v_pk_fma_f32 v[24:25], v[22:23], v[14:15], v[24:25] neg_lo:[0,0,1] neg_hi:[0,0,1]
	v_pk_fma_f32 v[26:27], v[96:97], v[16:17], v[26:27] neg_lo:[0,0,1] neg_hi:[0,0,1]
	v_pk_mul_f32 v[24:25], v[24:25], s[58:59] op_sel_hi:[1,0]
	v_pk_mul_f32 v[26:27], v[26:27], s[58:59] op_sel_hi:[1,0]
	v_cvt_pk_bf16_f32 v24, v24, v25
	v_cvt_pk_bf16_f32 v25, v26, v27
	v_pk_mul_f32 v[22:23], v[22:23], v[18:19]
	v_pk_mul_f32 v[26:27], v[96:97], v[20:21]
	v_pk_fma_f32 v[22:23], v[98:99], v[14:15], v[22:23]
	v_pk_fma_f32 v[26:27], v[94:95], v[16:17], v[26:27]
	v_pk_mul_f32 v[22:23], v[22:23], s[58:59] op_sel_hi:[1,0]
	v_pk_mul_f32 v[26:27], v[26:27], s[58:59] op_sel_hi:[1,0]
	v_cvt_pk_bf16_f32 v22, v22, v23
	v_cvt_pk_bf16_f32 v23, v26, v27
	ds_write2_b64 v28, v[24:25], v[22:23] offset0:192 offset1:194
	v_pk_mul_f32 v[22:23], v[78:79], s[58:59] op_sel_hi:[1,0]
	v_pk_mul_f32 v[24:25], v[76:77], s[58:59] op_sel_hi:[1,0]
	v_cvt_pk_bf16_f32 v22, v22, v23
	v_cvt_pk_bf16_f32 v23, v24, v25
	v_pk_mul_f32 v[24:25], v[74:75], s[58:59] op_sel_hi:[1,0]
	v_pk_mul_f32 v[26:27], v[72:73], s[58:59] op_sel_hi:[1,0]
	v_cvt_pk_bf16_f32 v24, v24, v25
	v_cvt_pk_bf16_f32 v25, v26, v27
	ds_write2_b64 v28, v[22:23], v[24:25] offset0:196 offset1:198
	v_accvgpr_read_b32 v22, a32
	v_accvgpr_read_b32 v23, a33
	v_pk_mul_f32 v[22:23], v[22:23], s[58:59] op_sel_hi:[1,0]
	v_pk_mul_f32 v[24:25], v[92:93], s[58:59] op_sel_hi:[1,0]
	v_cvt_pk_bf16_f32 v22, v22, v23
	v_cvt_pk_bf16_f32 v23, v24, v25
	v_pk_mul_f32 v[24:25], v[90:91], s[58:59] op_sel_hi:[1,0]
	v_pk_mul_f32 v[26:27], v[88:89], s[58:59] op_sel_hi:[1,0]
	v_cvt_pk_bf16_f32 v24, v24, v25
	v_cvt_pk_bf16_f32 v25, v26, v27
	ds_write2_b64 v28, v[22:23], v[24:25] offset0:200 offset1:202
	v_pk_mul_f32 v[22:23], v[86:87], s[58:59] op_sel_hi:[1,0]
	v_pk_mul_f32 v[24:25], v[84:85], s[58:59] op_sel_hi:[1,0]
	v_cvt_pk_bf16_f32 v22, v22, v23
	v_cvt_pk_bf16_f32 v23, v24, v25
	v_pk_mul_f32 v[24:25], v[82:83], s[58:59] op_sel_hi:[1,0]
	v_pk_mul_f32 v[26:27], v[80:81], s[58:59] op_sel_hi:[1,0]
	v_cvt_pk_bf16_f32 v24, v24, v25
	v_cvt_pk_bf16_f32 v25, v26, v27
	ds_write2_b64 v28, v[22:23], v[24:25] offset0:204 offset1:206
	v_accvgpr_read_b32 v23, a17
	v_accvgpr_read_b32 v22, a16
	v_pk_mul_f32 v[24:25], v[68:69], v[18:19]
	v_pk_mul_f32 v[18:19], v[22:23], v[18:19]
	v_pk_fma_f32 v[24:25], v[22:23], v[14:15], v[24:25] neg_lo:[0,0,1] neg_hi:[0,0,1]
	v_pk_mul_f32 v[26:27], v[60:61], v[20:21]
	v_pk_fma_f32 v[14:15], v[68:69], v[14:15], v[18:19]
	v_pk_mul_f32 v[18:19], v[62:63], v[20:21]
	v_pk_fma_f32 v[26:27], v[62:63], v[16:17], v[26:27] neg_lo:[0,0,1] neg_hi:[0,0,1]
	v_pk_fma_f32 v[16:17], v[60:61], v[16:17], v[18:19]
	v_pk_mul_f32 v[24:25], v[24:25], s[58:59] op_sel_hi:[1,0]
	v_pk_mul_f32 v[26:27], v[26:27], s[58:59] op_sel_hi:[1,0]
	v_pk_mul_f32 v[14:15], v[14:15], s[58:59] op_sel_hi:[1,0]
	v_pk_mul_f32 v[16:17], v[16:17], s[58:59] op_sel_hi:[1,0]
	v_cvt_pk_bf16_f32 v24, v24, v25
	v_cvt_pk_bf16_f32 v25, v26, v27
	v_cvt_pk_bf16_f32 v14, v14, v15
	v_cvt_pk_bf16_f32 v15, v16, v17
	ds_write2_b64 v28, v[24:25], v[14:15] offset0:208 offset1:210
	v_pk_mul_f32 v[14:15], v[66:67], s[58:59] op_sel_hi:[1,0]
	v_pk_mul_f32 v[16:17], v[58:59], s[58:59] op_sel_hi:[1,0]
	v_cvt_pk_bf16_f32 v14, v14, v15
	v_cvt_pk_bf16_f32 v15, v16, v17
	v_pk_mul_f32 v[16:17], v[56:57], s[58:59] op_sel_hi:[1,0]
	v_pk_mul_f32 v[18:19], v[64:65], s[58:59] op_sel_hi:[1,0]
	v_cvt_pk_bf16_f32 v16, v16, v17
	v_cvt_pk_bf16_f32 v17, v18, v19
	ds_write2_b64 v28, v[14:15], v[16:17] offset0:212 offset1:214
	v_accvgpr_read_b32 v15, a1
	v_accvgpr_read_b32 v14, a0
	v_pk_mul_f32 v[14:15], v[14:15], s[58:59] op_sel_hi:[1,0]
	s_nop 0
	v_cvt_pk_bf16_f32 v14, v14, v15
	v_cvt_pk_bf16_f32 v15, v12, v13
	ds_write2_b64 v28, v[14:15], v[10:11] offset0:216 offset1:218
	s_lshl_b64 s[8:9], s[8:9], 1
	s_add_u32 s8, s40, s8
	s_addc_u32 s9, s41, s9
	s_lshl_b64 s[4:5], s[4:5], 1
	s_add_u32 s4, s8, s4
	s_mov_b32 s8, 0
	s_waitcnt lgkmcnt(0)
	s_barrier
	s_addc_u32 s5, s9, s5
	v_mbcnt_lo_u32_b32 v0, -1, s8
	v_mbcnt_hi_u32_b32 v0, -1, v0
	v_or_b32_e32 v2, s26, v0
	v_lshlrev_b32_e32 v0, 4, v0
	v_and_b32_e32 v252, 0x1f0, v0
	v_lshl_add_u64 v[0:1], s[4:5], 0, v[252:253]

.LBB0_123:
	s_and_b64 vcc, exec, s[0:1]
	s_cbranch_vccz .LBB0_142
	v_readlane_b32 s0, v255, 63
	s_cmp_eq_u32 s0, 0
	s_cbranch_scc1 .Lgu_entry
	s_cmp_eq_u32 s0, 1
	s_cbranch_scc1 .Lga_entry
	s_cmp_eq_u32 s0, 2
	s_cbranch_scc1 .Lgv_entry
	s_branch .Lgl2_entry
.Lgl1_entry:
	s_mov_b64 s[82:83], exec
	v_readlane_b32 s4, v254, 40
	v_readlane_b32 s5, v254, 41
	v_readlane_b32 s6, v255, 15
	v_readlane_b32 s7, v254, 21
	s_nop 4
	s_load_dword s8, s[4:5], 0x0
	v_mbcnt_lo_u32_b32 v0, -1, 0
	v_mbcnt_hi_u32_b32 v0, -1, v0
	v_readlane_b32 s9, v255, 48
	v_readlane_b32 s10, v255, 52
	v_readlane_b32 s11, v255, 53
	v_readlane_b32 s12, v255, 54
	v_readlane_b32 s13, v255, 55
	v_readlane_b32 s14, v255, 50
	v_readlane_b32 s15, v255, 51
	v_lshlrev_b32_e32 v1, 6, v0
	v_lshlrev_b32_e32 v2, 5, v0
	v_lshlrev_b32_e32 v3, 2, v0
	v_xor_b32_e32 v4, 0x4, v3
	v_xor_b32_e32 v5, 0x8, v3
	v_xor_b32_e32 v6, 0x10, v3
	v_xor_b32_e32 v7, 0x20, v3
	v_xor_b32_e32 v8, 0x40, v3
	v_xor_b32_e32 v9, 0x80, v3
	v_mov_b32_e32 v10, 0x3727c5ac
	s_and_b32 s9, s9, 0xff
	s_lshl_b32 s9, s9, 13
	s_add_u32 s10, s10, s9
	s_addc_u32 s11, s11, 0
	s_add_u32 s12, s12, s9
	s_addc_u32 s13, s13, 0
	global_load_dwordx4 v[16:19], v1, s[10:11]
	global_load_dwordx4 v[20:23], v1, s[10:11] offset:16
	global_load_dwordx4 v[24:27], v1, s[10:11] offset:32
	global_load_dwordx4 v[28:31], v1, s[10:11] offset:48
	global_load_dwordx4 v[32:35], v1, s[12:13]
	global_load_dwordx4 v[36:39], v1, s[12:13] offset:16
	global_load_dwordx4 v[40:43], v1, s[12:13] offset:32
	global_load_dwordx4 v[44:47], v1, s[12:13] offset:48
	v_add_u32_e32 v49, 0x1000, v1
	v_add_u32_e32 v53, 0x800, v2
	v_add_u32_e32 v50, 0x2000, v1
	v_add_u32_e32 v54, 0x1000, v2
	v_add_u32_e32 v51, 0x3000, v1
	v_add_u32_e32 v55, 0x1800, v2
	v_mov_b32_e32 v48, v1
	v_mov_b32_e32 v52, v2
	s_lshl_b32 s6, s6, 2
	s_lshr_b32 s7, s7, 6
	s_add_u32 s6, s6, s7
	s_lshl_b32 s22, s6, 2
	s_waitcnt lgkmcnt(0)
	s_lshl_b32 s26, s8, 4
	s_add_u32 s16, s92, 0xc100000
	s_addc_u32 s17, s93, 0
	s_add_u32 s18, s92, 0x8100000
	s_addc_u32 s19, s93, 0
	s_add_u32 s14, s92, 0x2a100000
	s_addc_u32 s15, s93, 0
	s_cmp_ge_u32 s22, 0x8000
	s_cbranch_scc1 .Lgl1_done
.Lgl1_loop:
	s_lshl_b32 s30, s22, 12
	s_add_u32 s40, s16, s30
	s_addc_u32 s41, s17, 0
	s_add_u32 s64, s14, s30
	s_addc_u32 s65, s15, 0
	s_lshl_b32 s30, s22, 11
	s_add_u32 s66, s18, s30
	s_addc_u32 s67, s19, 0
	global_load_dwordx4 v[64:67], v48, s[40:41]
	global_load_dwordx4 v[68:71], v48, s[40:41] offset:16
	global_load_dwordx4 v[72:75], v48, s[40:41] offset:32
	global_load_dwordx4 v[76:79], v48, s[40:41] offset:48
	global_load_dwordx4 v[80:83], v49, s[40:41]
	global_load_dwordx4 v[84:87], v49, s[40:41] offset:16
	global_load_dwordx4 v[88:91], v49, s[40:41] offset:32
	global_load_dwordx4 v[92:95], v49, s[40:41] offset:48
	global_load_dwordx4 v[96:99], v50, s[40:41]
	global_load_dwordx4 v[100:103], v50, s[40:41] offset:16
	global_load_dwordx4 v[104:107], v50, s[40:41] offset:32
	global_load_dwordx4 v[108:111], v50, s[40:41] offset:48
	global_load_dwordx4 v[112:115], v51, s[40:41]
	global_load_dwordx4 v[116:119], v51, s[40:41] offset:16
	global_load_dwordx4 v[120:123], v51, s[40:41] offset:32
	global_load_dwordx4 v[124:127], v51, s[40:41] offset:48
	s_waitcnt vmcnt(12)
	v_add_f32_e32 v56, v64, v65
	v_add_f32_e32 v56, v66, v56
	v_add_f32_e32 v56, v67, v56
	v_add_f32_e32 v56, v68, v56
	v_add_f32_e32 v56, v69, v56
	v_add_f32_e32 v56, v70, v56
	v_add_f32_e32 v56, v71, v56
	v_add_f32_e32 v56, v72, v56
	v_add_f32_e32 v56, v73, v56
	v_add_f32_e32 v56, v74, v56
	v_add_f32_e32 v56, v75, v56
	v_add_f32_e32 v56, v76, v56
	v_add_f32_e32 v56, v77, v56
	v_add_f32_e32 v56, v78, v56
	v_add_f32_e32 v56, v79, v56
	s_waitcnt vmcnt(8)
	v_add_f32_e32 v57, v80, v81
	v_add_f32_e32 v57, v82, v57
	v_add_f32_e32 v57, v83, v57
	v_add_f32_e32 v57, v84, v57
	v_add_f32_e32 v57, v85, v57
	v_add_f32_e32 v57, v86, v57
	v_add_f32_e32 v57, v87, v57
	v_add_f32_e32 v57, v88, v57
	v_add_f32_e32 v57, v89, v57
	v_add_f32_e32 v57, v90, v57
	v_add_f32_e32 v57, v91, v57
	v_add_f32_e32 v57, v92, v57
	v_add_f32_e32 v57, v93, v57
	v_add_f32_e32 v57, v94, v57
	v_add_f32_e32 v57, v95, v57
	s_waitcnt vmcnt(4)
	v_add_f32_e32 v58, v96, v97
	v_add_f32_e32 v58, v98, v58
	v_add_f32_e32 v58, v99, v58
	v_add_f32_e32 v58, v100, v58
	v_add_f32_e32 v58, v101, v58
	v_add_f32_e32 v58, v102, v58
	v_add_f32_e32 v58, v103, v58
	v_add_f32_e32 v58, v104, v58
	v_add_f32_e32 v58, v105, v58
	v_add_f32_e32 v58, v106, v58
	v_add_f32_e32 v58, v107, v58
	v_add_f32_e32 v58, v108, v58
	v_add_f32_e32 v58, v109, v58
	v_add_f32_e32 v58, v110, v58
	v_add_f32_e32 v58, v111, v58
	s_waitcnt vmcnt(0)
	v_add_f32_e32 v59, v112, v113
	v_add_f32_e32 v59, v114, v59
	v_add_f32_e32 v59, v115, v59
	v_add_f32_e32 v59, v116, v59
	v_add_f32_e32 v59, v117, v59
	v_add_f32_e32 v59, v118, v59
	v_add_f32_e32 v59, v119, v59
	v_add_f32_e32 v59, v120, v59
	v_add_f32_e32 v59, v121, v59
	v_add_f32_e32 v59, v122, v59
	v_add_f32_e32 v59, v123, v59
	v_add_f32_e32 v59, v124, v59
	v_add_f32_e32 v59, v125, v59
	v_add_f32_e32 v59, v126, v59
	v_add_f32_e32 v59, v127, v59
	ds_bpermute_b32 v60, v4, v56
	ds_bpermute_b32 v61, v4, v57
	ds_bpermute_b32 v62, v4, v58
	ds_bpermute_b32 v63, v4, v59
	s_waitcnt lgkmcnt(3)
	v_add_f32_e32 v56, v56, v60
	s_waitcnt lgkmcnt(2)
	v_add_f32_e32 v57, v57, v61
	s_waitcnt lgkmcnt(1)
	v_add_f32_e32 v58, v58, v62
	s_waitcnt lgkmcnt(0)
	v_add_f32_e32 v59, v59, v63
	ds_bpermute_b32 v60, v5, v56
	ds_bpermute_b32 v61, v5, v57
	ds_bpermute_b32 v62, v5, v58
	ds_bpermute_b32 v63, v5, v59
	s_waitcnt lgkmcnt(3)
	v_add_f32_e32 v56, v56, v60
	s_waitcnt lgkmcnt(2)
	v_add_f32_e32 v57, v57, v61
	s_waitcnt lgkmcnt(1)
	v_add_f32_e32 v58, v58, v62
	s_waitcnt lgkmcnt(0)
	v_add_f32_e32 v59, v59, v63
	ds_bpermute_b32 v60, v6, v56
	ds_bpermute_b32 v61, v6, v57
	ds_bpermute_b32 v62, v6, v58
	ds_bpermute_b32 v63, v6, v59
	s_waitcnt lgkmcnt(3)
	v_add_f32_e32 v56, v56, v60
	s_waitcnt lgkmcnt(2)
	v_add_f32_e32 v57, v57, v61
	s_waitcnt lgkmcnt(1)
	v_add_f32_e32 v58, v58, v62
	s_waitcnt lgkmcnt(0)
	v_add_f32_e32 v59, v59, v63
	ds_bpermute_b32 v60, v7, v56
	ds_bpermute_b32 v61, v7, v57
	ds_bpermute_b32 v62, v7, v58
	ds_bpermute_b32 v63, v7, v59
	s_waitcnt lgkmcnt(3)
	v_add_f32_e32 v56, v56, v60
	s_waitcnt lgkmcnt(2)
	v_add_f32_e32 v57, v57, v61
	s_waitcnt lgkmcnt(1)
	v_add_f32_e32 v58, v58, v62
	s_waitcnt lgkmcnt(0)
	v_add_f32_e32 v59, v59, v63
	ds_bpermute_b32 v60, v8, v56
	ds_bpermute_b32 v61, v8, v57
	ds_bpermute_b32 v62, v8, v58
	ds_bpermute_b32 v63, v8, v59
	s_waitcnt lgkmcnt(3)
	v_add_f32_e32 v56, v56, v60
	s_waitcnt lgkmcnt(2)
	v_add_f32_e32 v57, v57, v61
	s_waitcnt lgkmcnt(1)
	v_add_f32_e32 v58, v58, v62
	s_waitcnt lgkmcnt(0)
	v_add_f32_e32 v59, v59, v63
	ds_bpermute_b32 v60, v9, v56
	ds_bpermute_b32 v61, v9, v57
	ds_bpermute_b32 v62, v9, v58
	ds_bpermute_b32 v63, v9, v59
	s_waitcnt lgkmcnt(3)
	v_add_f32_e32 v56, v56, v60
	s_waitcnt lgkmcnt(2)
	v_add_f32_e32 v57, v57, v61
	s_waitcnt lgkmcnt(1)
	v_add_f32_e32 v58, v58, v62
	s_waitcnt lgkmcnt(0)
	v_add_f32_e32 v59, v59, v63
	v_mul_f32_e32 v60, 0x3a800000, v56
	v_sub_f32_e32 v64, v64, v60
	v_sub_f32_e32 v65, v65, v60
	v_sub_f32_e32 v66, v66, v60
	v_sub_f32_e32 v67, v67, v60
	v_sub_f32_e32 v68, v68, v60
	v_sub_f32_e32 v69, v69, v60
	v_sub_f32_e32 v70, v70, v60
	v_sub_f32_e32 v71, v71, v60
	v_sub_f32_e32 v72, v72, v60
	v_sub_f32_e32 v73, v73, v60
	v_sub_f32_e32 v74, v74, v60
	v_sub_f32_e32 v75, v75, v60
	v_sub_f32_e32 v76, v76, v60
	v_sub_f32_e32 v77, v77, v60
	v_sub_f32_e32 v78, v78, v60
	v_sub_f32_e32 v79, v79, v60
	v_mul_f32_e32 v56, v64, v64
	v_fmac_f32_e32 v56, v65, v65
	v_fmac_f32_e32 v56, v66, v66
	v_fmac_f32_e32 v56, v67, v67
	v_fmac_f32_e32 v56, v68, v68
	v_fmac_f32_e32 v56, v69, v69
	v_fmac_f32_e32 v56, v70, v70
	v_fmac_f32_e32 v56, v71, v71
	v_fmac_f32_e32 v56, v72, v72
	v_fmac_f32_e32 v56, v73, v73
	v_fmac_f32_e32 v56, v74, v74
	v_fmac_f32_e32 v56, v75, v75
	v_fmac_f32_e32 v56, v76, v76
	v_fmac_f32_e32 v56, v77, v77
	v_fmac_f32_e32 v56, v78, v78
	v_fmac_f32_e32 v56, v79, v79
	v_mul_f32_e32 v61, 0x3a800000, v57
	v_sub_f32_e32 v80, v80, v61
	v_sub_f32_e32 v81, v81, v61
	v_sub_f32_e32 v82, v82, v61
	v_sub_f32_e32 v83, v83, v61
	v_sub_f32_e32 v84, v84, v61
	v_sub_f32_e32 v85, v85, v61
	v_sub_f32_e32 v86, v86, v61
	v_sub_f32_e32 v87, v87, v61
	v_sub_f32_e32 v88, v88, v61
	v_sub_f32_e32 v89, v89, v61
	v_sub_f32_e32 v90, v90, v61
	v_sub_f32_e32 v91, v91, v61
	v_sub_f32_e32 v92, v92, v61
	v_sub_f32_e32 v93, v93, v61
	v_sub_f32_e32 v94, v94, v61
	v_sub_f32_e32 v95, v95, v61
	v_mul_f32_e32 v57, v80, v80
	v_fmac_f32_e32 v57, v81, v81
	v_fmac_f32_e32 v57, v82, v82
	v_fmac_f32_e32 v57, v83, v83
	v_fmac_f32_e32 v57, v84, v84
	v_fmac_f32_e32 v57, v85, v85
	v_fmac_f32_e32 v57, v86, v86
	v_fmac_f32_e32 v57, v87, v87
	v_fmac_f32_e32 v57, v88, v88
	v_fmac_f32_e32 v57, v89, v89
	v_fmac_f32_e32 v57, v90, v90
	v_fmac_f32_e32 v57, v91, v91
	v_fmac_f32_e32 v57, v92, v92
	v_fmac_f32_e32 v57, v93, v93
	v_fmac_f32_e32 v57, v94, v94
	v_fmac_f32_e32 v57, v95, v95
	v_mul_f32_e32 v62, 0x3a800000, v58
	v_sub_f32_e32 v96, v96, v62
	v_sub_f32_e32 v97, v97, v62
	v_sub_f32_e32 v98, v98, v62
	v_sub_f32_e32 v99, v99, v62
	v_sub_f32_e32 v100, v100, v62
	v_sub_f32_e32 v101, v101, v62
	v_sub_f32_e32 v102, v102, v62
	v_sub_f32_e32 v103, v103, v62
	v_sub_f32_e32 v104, v104, v62
	v_sub_f32_e32 v105, v105, v62
	v_sub_f32_e32 v106, v106, v62
	v_sub_f32_e32 v107, v107, v62
	v_sub_f32_e32 v108, v108, v62
	v_sub_f32_e32 v109, v109, v62
	v_sub_f32_e32 v110, v110, v62
	v_sub_f32_e32 v111, v111, v62
	v_mul_f32_e32 v58, v96, v96
	v_fmac_f32_e32 v58, v97, v97
	v_fmac_f32_e32 v58, v98, v98
	v_fmac_f32_e32 v58, v99, v99
	v_fmac_f32_e32 v58, v100, v100
	v_fmac_f32_e32 v58, v101, v101
	v_fmac_f32_e32 v58, v102, v102
	v_fmac_f32_e32 v58, v103, v103
	v_fmac_f32_e32 v58, v104, v104
	v_fmac_f32_e32 v58, v105, v105
	v_fmac_f32_e32 v58, v106, v106
	v_fmac_f32_e32 v58, v107, v107
	v_fmac_f32_e32 v58, v108, v108
	v_fmac_f32_e32 v58, v109, v109
	v_fmac_f32_e32 v58, v110, v110
	v_fmac_f32_e32 v58, v111, v111
	v_mul_f32_e32 v63, 0x3a800000, v59
	v_sub_f32_e32 v112, v112, v63
	v_sub_f32_e32 v113, v113, v63
	v_sub_f32_e32 v114, v114, v63
	v_sub_f32_e32 v115, v115, v63
	v_sub_f32_e32 v116, v116, v63
	v_sub_f32_e32 v117, v117, v63
	v_sub_f32_e32 v118, v118, v63
	v_sub_f32_e32 v119, v119, v63
	v_sub_f32_e32 v120, v120, v63
	v_sub_f32_e32 v121, v121, v63
	v_sub_f32_e32 v122, v122, v63
	v_sub_f32_e32 v123, v123, v63
	v_sub_f32_e32 v124, v124, v63
	v_sub_f32_e32 v125, v125, v63
	v_sub_f32_e32 v126, v126, v63
	v_sub_f32_e32 v127, v127, v63
	v_mul_f32_e32 v59, v112, v112
	v_fmac_f32_e32 v59, v113, v113
	v_fmac_f32_e32 v59, v114, v114
	v_fmac_f32_e32 v59, v115, v115
	v_fmac_f32_e32 v59, v116, v116
	v_fmac_f32_e32 v59, v117, v117
	v_fmac_f32_e32 v59, v118, v118
	v_fmac_f32_e32 v59, v119, v119
	v_fmac_f32_e32 v59, v120, v120
	v_fmac_f32_e32 v59, v121, v121
	v_fmac_f32_e32 v59, v122, v122
	v_fmac_f32_e32 v59, v123, v123
	v_fmac_f32_e32 v59, v124, v124
	v_fmac_f32_e32 v59, v125, v125
	v_fmac_f32_e32 v59, v126, v126
	v_fmac_f32_e32 v59, v127, v127
	ds_bpermute_b32 v60, v4, v56
	ds_bpermute_b32 v61, v4, v57
	ds_bpermute_b32 v62, v4, v58
	ds_bpermute_b32 v63, v4, v59
	s_waitcnt lgkmcnt(3)
	v_add_f32_e32 v56, v56, v60
	s_waitcnt lgkmcnt(2)
	v_add_f32_e32 v57, v57, v61
	s_waitcnt lgkmcnt(1)
	v_add_f32_e32 v58, v58, v62
	s_waitcnt lgkmcnt(0)
	v_add_f32_e32 v59, v59, v63
	ds_bpermute_b32 v60, v5, v56
	ds_bpermute_b32 v61, v5, v57
	ds_bpermute_b32 v62, v5, v58
	ds_bpermute_b32 v63, v5, v59
	s_waitcnt lgkmcnt(3)
	v_add_f32_e32 v56, v56, v60
	s_waitcnt lgkmcnt(2)
	v_add_f32_e32 v57, v57, v61
	s_waitcnt lgkmcnt(1)
	v_add_f32_e32 v58, v58, v62
	s_waitcnt lgkmcnt(0)
	v_add_f32_e32 v59, v59, v63
	ds_bpermute_b32 v60, v6, v56
	ds_bpermute_b32 v61, v6, v57
	ds_bpermute_b32 v62, v6, v58
	ds_bpermute_b32 v63, v6, v59
	s_waitcnt lgkmcnt(3)
	v_add_f32_e32 v56, v56, v60
	s_waitcnt lgkmcnt(2)
	v_add_f32_e32 v57, v57, v61
	s_waitcnt lgkmcnt(1)
	v_add_f32_e32 v58, v58, v62
	s_waitcnt lgkmcnt(0)
	v_add_f32_e32 v59, v59, v63
	ds_bpermute_b32 v60, v7, v56
	ds_bpermute_b32 v61, v7, v57
	ds_bpermute_b32 v62, v7, v58
	ds_bpermute_b32 v63, v7, v59
	s_waitcnt lgkmcnt(3)
	v_add_f32_e32 v56, v56, v60
	s_waitcnt lgkmcnt(2)
	v_add_f32_e32 v57, v57, v61
	s_waitcnt lgkmcnt(1)
	v_add_f32_e32 v58, v58, v62
	s_waitcnt lgkmcnt(0)
	v_add_f32_e32 v59, v59, v63
	ds_bpermute_b32 v60, v8, v56
	ds_bpermute_b32 v61, v8, v57
	ds_bpermute_b32 v62, v8, v58
	ds_bpermute_b32 v63, v8, v59
	s_waitcnt lgkmcnt(3)
	v_add_f32_e32 v56, v56, v60
	s_waitcnt lgkmcnt(2)
	v_add_f32_e32 v57, v57, v61
	s_waitcnt lgkmcnt(1)
	v_add_f32_e32 v58, v58, v62
	s_waitcnt lgkmcnt(0)
	v_add_f32_e32 v59, v59, v63
	ds_bpermute_b32 v60, v9, v56
	ds_bpermute_b32 v61, v9, v57
	ds_bpermute_b32 v62, v9, v58
	ds_bpermute_b32 v63, v9, v59
	s_waitcnt lgkmcnt(3)
	v_add_f32_e32 v56, v56, v60
	s_waitcnt lgkmcnt(2)
	v_add_f32_e32 v57, v57, v61
	s_waitcnt lgkmcnt(1)
	v_add_f32_e32 v58, v58, v62
	s_waitcnt lgkmcnt(0)
	v_add_f32_e32 v59, v59, v63
	v_fmamk_f32 v56, v56, 0x3a800000, v10
	v_fmamk_f32 v57, v57, 0x3a800000, v10
	v_fmamk_f32 v58, v58, 0x3a800000, v10
	v_fmamk_f32 v59, v59, 0x3a800000, v10
	v_rsq_f32_e32 v56, v56
	v_rsq_f32_e32 v57, v57
	v_rsq_f32_e32 v58, v58
	v_rsq_f32_e32 v59, v59
	s_nop 1
	s_waitcnt vmcnt(0)
	v_mul_f32_e32 v64, v64, v56
	v_mul_f32_e32 v65, v65, v56
	v_mul_f32_e32 v66, v66, v56
	v_mul_f32_e32 v67, v67, v56
	v_mul_f32_e32 v68, v68, v56
	v_mul_f32_e32 v69, v69, v56
	v_mul_f32_e32 v70, v70, v56
	v_mul_f32_e32 v71, v71, v56
	v_mul_f32_e32 v72, v72, v56
	v_mul_f32_e32 v73, v73, v56
	v_mul_f32_e32 v74, v74, v56
	v_mul_f32_e32 v75, v75, v56
	v_mul_f32_e32 v76, v76, v56
	v_mul_f32_e32 v77, v77, v56
	v_mul_f32_e32 v78, v78, v56
	v_mul_f32_e32 v79, v79, v56
	v_fma_f32 v64, v64, v16, v32
	v_fma_f32 v65, v65, v17, v33
	v_fma_f32 v66, v66, v18, v34
	v_fma_f32 v67, v67, v19, v35
	v_fma_f32 v68, v68, v20, v36
	v_fma_f32 v69, v69, v21, v37
	v_fma_f32 v70, v70, v22, v38
	v_fma_f32 v71, v71, v23, v39
	v_fma_f32 v72, v72, v24, v40
	v_fma_f32 v73, v73, v25, v41
	v_fma_f32 v74, v74, v26, v42
	v_fma_f32 v75, v75, v27, v43
	v_fma_f32 v76, v76, v28, v44
	v_fma_f32 v77, v77, v29, v45
	v_fma_f32 v78, v78, v30, v46
	v_fma_f32 v79, v79, v31, v47
	global_store_dwordx4 v48, v[64:67], s[64:65]
	global_store_dwordx4 v48, v[68:71], s[64:65] offset:16
	global_store_dwordx4 v48, v[72:75], s[64:65] offset:32
	global_store_dwordx4 v48, v[76:79], s[64:65] offset:48
	v_mul_f32_e32 v80, v80, v57
	v_mul_f32_e32 v81, v81, v57
	v_mul_f32_e32 v82, v82, v57
	v_mul_f32_e32 v83, v83, v57
	v_mul_f32_e32 v84, v84, v57
	v_mul_f32_e32 v85, v85, v57
	v_mul_f32_e32 v86, v86, v57
	v_mul_f32_e32 v87, v87, v57
	v_mul_f32_e32 v88, v88, v57
	v_mul_f32_e32 v89, v89, v57
	v_mul_f32_e32 v90, v90, v57
	v_mul_f32_e32 v91, v91, v57
	v_mul_f32_e32 v92, v92, v57
	v_mul_f32_e32 v93, v93, v57
	v_mul_f32_e32 v94, v94, v57
	v_mul_f32_e32 v95, v95, v57
	v_fma_f32 v80, v80, v16, v32
	v_fma_f32 v81, v81, v17, v33
	v_fma_f32 v82, v82, v18, v34
	v_fma_f32 v83, v83, v19, v35
	v_fma_f32 v84, v84, v20, v36
	v_fma_f32 v85, v85, v21, v37
	v_fma_f32 v86, v86, v22, v38
	v_fma_f32 v87, v87, v23, v39
	v_fma_f32 v88, v88, v24, v40
	v_fma_f32 v89, v89, v25, v41
	v_fma_f32 v90, v90, v26, v42
	v_fma_f32 v91, v91, v27, v43
	v_fma_f32 v92, v92, v28, v44
	v_fma_f32 v93, v93, v29, v45
	v_fma_f32 v94, v94, v30, v46
	v_fma_f32 v95, v95, v31, v47
	global_store_dwordx4 v49, v[80:83], s[64:65]
	global_store_dwordx4 v49, v[84:87], s[64:65] offset:16
	global_store_dwordx4 v49, v[88:91], s[64:65] offset:32
	global_store_dwordx4 v49, v[92:95], s[64:65] offset:48
	v_mul_f32_e32 v96, v96, v58
	v_mul_f32_e32 v97, v97, v58
	v_mul_f32_e32 v98, v98, v58
	v_mul_f32_e32 v99, v99, v58
	v_mul_f32_e32 v100, v100, v58
	v_mul_f32_e32 v101, v101, v58
	v_mul_f32_e32 v102, v102, v58
	v_mul_f32_e32 v103, v103, v58
	v_mul_f32_e32 v104, v104, v58
	v_mul_f32_e32 v105, v105, v58
	v_mul_f32_e32 v106, v106, v58
	v_mul_f32_e32 v107, v107, v58
	v_mul_f32_e32 v108, v108, v58
	v_mul_f32_e32 v109, v109, v58
	v_mul_f32_e32 v110, v110, v58
	v_mul_f32_e32 v111, v111, v58
	v_fma_f32 v96, v96, v16, v32
	v_fma_f32 v97, v97, v17, v33
	v_fma_f32 v98, v98, v18, v34
	v_fma_f32 v99, v99, v19, v35
	v_fma_f32 v100, v100, v20, v36
	v_fma_f32 v101, v101, v21, v37
	v_fma_f32 v102, v102, v22, v38
	v_fma_f32 v103, v103, v23, v39
	v_fma_f32 v104, v104, v24, v40
	v_fma_f32 v105, v105, v25, v41
	v_fma_f32 v106, v106, v26, v42
	v_fma_f32 v107, v107, v27, v43
	v_fma_f32 v108, v108, v28, v44
	v_fma_f32 v109, v109, v29, v45
	v_fma_f32 v110, v110, v30, v46
	v_fma_f32 v111, v111, v31, v47
	global_store_dwordx4 v50, v[96:99], s[64:65]
	global_store_dwordx4 v50, v[100:103], s[64:65] offset:16
	global_store_dwordx4 v50, v[104:107], s[64:65] offset:32
	global_store_dwordx4 v50, v[108:111], s[64:65] offset:48
	v_mul_f32_e32 v112, v112, v59
	v_mul_f32_e32 v113, v113, v59
	v_mul_f32_e32 v114, v114, v59
	v_mul_f32_e32 v115, v115, v59
	v_mul_f32_e32 v116, v116, v59
	v_mul_f32_e32 v117, v117, v59
	v_mul_f32_e32 v118, v118, v59
	v_mul_f32_e32 v119, v119, v59
	v_mul_f32_e32 v120, v120, v59
	v_mul_f32_e32 v121, v121, v59
	v_mul_f32_e32 v122, v122, v59
	v_mul_f32_e32 v123, v123, v59
	v_mul_f32_e32 v124, v124, v59
	v_mul_f32_e32 v125, v125, v59
	v_mul_f32_e32 v126, v126, v59
	v_mul_f32_e32 v127, v127, v59
	v_fma_f32 v112, v112, v16, v32
	v_fma_f32 v113, v113, v17, v33
	v_fma_f32 v114, v114, v18, v34
	v_fma_f32 v115, v115, v19, v35
	v_fma_f32 v116, v116, v20, v36
	v_fma_f32 v117, v117, v21, v37
	v_fma_f32 v118, v118, v22, v38
	v_fma_f32 v119, v119, v23, v39
	v_fma_f32 v120, v120, v24, v40
	v_fma_f32 v121, v121, v25, v41
	v_fma_f32 v122, v122, v26, v42
	v_fma_f32 v123, v123, v27, v43
	v_fma_f32 v124, v124, v28, v44
	v_fma_f32 v125, v125, v29, v45
	v_fma_f32 v126, v126, v30, v46
	v_fma_f32 v127, v127, v31, v47
	global_store_dwordx4 v51, v[112:115], s[64:65]
	global_store_dwordx4 v51, v[116:119], s[64:65] offset:16
	global_store_dwordx4 v51, v[120:123], s[64:65] offset:32
	global_store_dwordx4 v51, v[124:127], s[64:65] offset:48
	s_nop 1
	v_cvt_pk_bf16_f32 v128, v64, v65
	v_cvt_pk_bf16_f32 v129, v66, v67
	v_cvt_pk_bf16_f32 v130, v68, v69
	v_cvt_pk_bf16_f32 v131, v70, v71
	v_cvt_pk_bf16_f32 v132, v72, v73
	v_cvt_pk_bf16_f32 v133, v74, v75
	v_cvt_pk_bf16_f32 v134, v76, v77
	v_cvt_pk_bf16_f32 v135, v78, v79
	global_store_dwordx4 v52, v[128:131], s[66:67]
	global_store_dwordx4 v52, v[132:135], s[66:67] offset:16
	v_cvt_pk_bf16_f32 v136, v80, v81
	v_cvt_pk_bf16_f32 v137, v82, v83
	v_cvt_pk_bf16_f32 v138, v84, v85
	v_cvt_pk_bf16_f32 v139, v86, v87
	v_cvt_pk_bf16_f32 v140, v88, v89
	v_cvt_pk_bf16_f32 v141, v90, v91
	v_cvt_pk_bf16_f32 v142, v92, v93
	v_cvt_pk_bf16_f32 v143, v94, v95
	global_store_dwordx4 v53, v[136:139], s[66:67]
	global_store_dwordx4 v53, v[140:143], s[66:67] offset:16
	v_cvt_pk_bf16_f32 v144, v96, v97
	v_cvt_pk_bf16_f32 v145, v98, v99
	v_cvt_pk_bf16_f32 v146, v100, v101
	v_cvt_pk_bf16_f32 v147, v102, v103
	v_cvt_pk_bf16_f32 v148, v104, v105
	v_cvt_pk_bf16_f32 v149, v106, v107
	v_cvt_pk_bf16_f32 v150, v108, v109
	v_cvt_pk_bf16_f32 v151, v110, v111
	global_store_dwordx4 v54, v[144:147], s[66:67]
	global_store_dwordx4 v54, v[148:151], s[66:67] offset:16
	v_cvt_pk_bf16_f32 v152, v112, v113
	v_cvt_pk_bf16_f32 v153, v114, v115
	v_cvt_pk_bf16_f32 v154, v116, v117
	v_cvt_pk_bf16_f32 v155, v118, v119
	v_cvt_pk_bf16_f32 v156, v120, v121
	v_cvt_pk_bf16_f32 v157, v122, v123
	v_cvt_pk_bf16_f32 v158, v124, v125
	v_cvt_pk_bf16_f32 v159, v126, v127
	global_store_dwordx4 v55, v[152:155], s[66:67]
	global_store_dwordx4 v55, v[156:159], s[66:67] offset:16
	s_add_u32 s22, s22, s26
	s_cmp_lt_u32 s22, 0x8000
	s_cbranch_scc1 .Lgl1_loop

.LBB0_148:
	s_add_i32 s12, s11, 0xffff8000
	s_and_b32 s12, s12, 0x8000
	s_lshl_b32 s12, s12, 1
	v_lshl_or_b32 v250, v13, 1, s12
	v_add_u32_e32 v249, v250, v10
	v_add_u32_e32 v250, v250, v9
	ds_read_b128 v[14:17], v249
	ds_read_b128 v[18:21], v250 offset:32768
	ds_read_b128 v[22:25], v250 offset:36864
	ds_read_b128 v[26:29], v250 offset:40960
	ds_read_b128 v[30:33], v250 offset:45056
	ds_read_b128 v[244:247], v249 offset:4096
	s_waitcnt lgkmcnt(4)
	v_mfma_f32_32x32x16_bf16 a[128:143], v[14:17], v[18:21], a[128:143]
	s_waitcnt lgkmcnt(3)
	v_mfma_f32_32x32x16_bf16 a[64:79], v[14:17], v[22:25], a[64:79]
	s_and_b32 s98, s11, 0x8000
	s_lshl_b32 s98, s98, 1
	s_add_i32 s14, s31, s98
	v_lshl_add_u64 v[234:235], v[0:1], 0, s[4:5]
	s_mov_b64 s[98:99], 0x2c00080
	v_lshl_add_u64 v[236:237], v[234:235], 0, s[98:99]
	s_mov_b32 m0, s14
	s_add_i32 s15, s14, 0x8000
	global_load_lds_dwordx4 v[236:237], off
	s_waitcnt lgkmcnt(2)
	v_mfma_f32_32x32x16_bf16 a[144:159], v[14:17], v[26:29], a[144:159]
	v_lshl_add_u64 v[236:237], v[4:5], 0, s[4:5]
	v_lshl_add_u64 v[238:239], v[236:237], 0, s[38:39]
	s_mov_b32 m0, s15
	s_mov_b64 s[98:99], 0x2c04080
	global_load_lds_dwordx4 v[238:239], off
	s_waitcnt lgkmcnt(1)
	v_mfma_f32_32x32x16_bf16 a[0:15], v[14:17], v[30:33], a[0:15]
	v_lshl_add_u64 v[238:239], v[2:3], 0, s[4:5]
	v_lshl_add_u64 v[240:241], v[238:239], 0, s[98:99]
	s_add_i32 m0, s14, 0x400
	s_mov_b64 s[98:99], 0x2c08080
	global_load_lds_dwordx4 v[240:241], off
	ds_read_b128 v[14:17], v249 offset:8192
	s_waitcnt lgkmcnt(1)
	v_mfma_f32_32x32x16_bf16 a[160:175], v[244:247], v[18:21], a[160:175]
	v_lshl_add_u64 v[240:241], v[6:7], 0, s[4:5]
	v_lshl_add_u64 v[242:243], v[240:241], 0, s[44:45]
	s_add_i32 m0, s14, 0x8400
	s_nop 0
	global_load_lds_dwordx4 v[242:243], off
	v_mfma_f32_32x32x16_bf16 a[80:95], v[244:247], v[22:25], a[80:95]
	v_lshl_add_u64 v[242:243], v[234:235], 0, s[98:99]
	s_add_i32 m0, s14, 0x800
	s_mov_b64 s[98:99], 0x2c0c080
	global_load_lds_dwordx4 v[242:243], off
	v_mfma_f32_32x32x16_bf16 a[176:191], v[244:247], v[26:29], a[176:191]
	v_lshl_add_u64 v[242:243], v[236:237], 0, s[2:3]
	s_add_i32 m0, s14, 0x8800
	s_nop 0
	global_load_lds_dwordx4 v[242:243], off
	v_mfma_f32_32x32x16_bf16 a[16:31], v[244:247], v[30:33], a[16:31]
	v_lshl_add_u64 v[242:243], v[238:239], 0, s[98:99]
	s_add_i32 m0, s14, 0xc00
	s_mov_b64 s[98:99], 0x2c10080
	global_load_lds_dwordx4 v[242:243], off
	ds_read_b128 v[244:247], v249 offset:12288
	s_waitcnt lgkmcnt(1)
	v_mfma_f32_32x32x16_bf16 a[192:207], v[14:17], v[18:21], a[192:207]
	v_lshl_add_u64 v[242:243], v[240:241], 0, s[46:47]
	s_add_i32 m0, s14, 0x8c00
	s_nop 0
	global_load_lds_dwordx4 v[242:243], off
	v_mfma_f32_32x32x16_bf16 a[96:111], v[14:17], v[22:25], a[96:111]
	v_lshl_add_u64 v[242:243], v[234:235], 0, s[98:99]
	s_add_i32 m0, s14, 0x1000
	s_mov_b64 s[98:99], 0x2c14080
	global_load_lds_dwordx4 v[242:243], off
	v_mfma_f32_32x32x16_bf16 a[208:223], v[14:17], v[26:29], a[208:223]
	v_lshl_add_u64 v[242:243], v[236:237], 0, s[50:51]
	s_add_i32 m0, s14, 0x9000
	s_nop 0
	global_load_lds_dwordx4 v[242:243], off
	v_mfma_f32_32x32x16_bf16 a[32:47], v[14:17], v[30:33], a[32:47]
	v_lshl_add_u64 v[242:243], v[238:239], 0, s[98:99]
	s_add_i32 m0, s14, 0x1400
	s_mov_b64 s[98:99], 0x2c18080
	global_load_lds_dwordx4 v[242:243], off
	v_lshl_or_b32 v250, v12, 1, s12
	v_add_u32_e32 v249, v250, v10
	v_add_u32_e32 v250, v250, v9
	ds_read_b128 v[14:17], v249
	s_waitcnt lgkmcnt(1)
	v_mfma_f32_32x32x16_bf16 a[224:239], v[244:247], v[18:21], a[224:239]
	v_lshl_add_u64 v[242:243], v[240:241], 0, s[52:53]
	s_add_i32 m0, s14, 0x9400
	v_lshl_add_u64 v[234:235], v[234:235], 0, s[98:99]
	global_load_lds_dwordx4 v[242:243], off
	ds_read_b128 v[18:21], v250 offset:32768
	v_mfma_f32_32x32x16_bf16 a[112:127], v[244:247], v[22:25], a[112:127]
	s_add_i32 m0, s14, 0x1800
	s_mov_b64 s[98:99], 0x2c1c080
	global_load_lds_dwordx4 v[234:235], off
	ds_read_b128 v[22:25], v250 offset:36864
	v_mfma_f32_32x32x16_bf16 a[240:255], v[244:247], v[26:29], a[240:255]
	v_lshl_add_u64 v[234:235], v[236:237], 0, s[54:55]
	s_add_i32 m0, s14, 0x9800
	s_nop 0
	global_load_lds_dwordx4 v[234:235], off
	ds_read_b128 v[26:29], v250 offset:40960
	v_mfma_f32_32x32x16_bf16 a[48:63], v[244:247], v[30:33], a[48:63]
	v_lshl_add_u64 v[234:235], v[238:239], 0, s[98:99]
	s_add_i32 m0, s14, 0x1c00
	s_nop 0
	global_load_lds_dwordx4 v[234:235], off
	ds_read_b128 v[30:33], v250 offset:45056
	ds_read_b128 v[244:247], v249 offset:4096
	s_waitcnt lgkmcnt(4)
	v_mfma_f32_32x32x16_bf16 a[128:143], v[14:17], v[18:21], a[128:143]
	v_lshl_add_u64 v[234:235], v[240:241], 0, s[56:57]
	s_add_i32 m0, s14, 0x9c00
	s_nop 0
	global_load_lds_dwordx4 v[234:235], off
	s_waitcnt lgkmcnt(3)
	v_mfma_f32_32x32x16_bf16 a[64:79], v[14:17], v[22:25], a[64:79]
	s_waitcnt lgkmcnt(2)
	v_mfma_f32_32x32x16_bf16 a[144:159], v[14:17], v[26:29], a[144:159]
	s_waitcnt lgkmcnt(1)
	v_mfma_f32_32x32x16_bf16 a[0:15], v[14:17], v[30:33], a[0:15]
	ds_read_b128 v[14:17], v249 offset:8192
	s_waitcnt lgkmcnt(1)
	v_mfma_f32_32x32x16_bf16 a[160:175], v[244:247], v[18:21], a[160:175]
	v_mfma_f32_32x32x16_bf16 a[80:95], v[244:247], v[22:25], a[80:95]
	v_mfma_f32_32x32x16_bf16 a[176:191], v[244:247], v[26:29], a[176:191]
	v_mfma_f32_32x32x16_bf16 a[16:31], v[244:247], v[30:33], a[16:31]
	ds_read_b128 v[244:247], v249 offset:12288
	s_waitcnt lgkmcnt(1)
	v_mfma_f32_32x32x16_bf16 a[192:207], v[14:17], v[18:21], a[192:207]
	v_mfma_f32_32x32x16_bf16 a[96:111], v[14:17], v[22:25], a[96:111]
	v_mfma_f32_32x32x16_bf16 a[208:223], v[14:17], v[26:29], a[208:223]
	v_mfma_f32_32x32x16_bf16 a[32:47], v[14:17], v[30:33], a[32:47]
	v_lshl_or_b32 v250, v11, 1, s12
	v_add_u32_e32 v249, v250, v10
	v_add_u32_e32 v250, v250, v9
	ds_read_b128 v[14:17], v249
	s_waitcnt lgkmcnt(1)
	v_mfma_f32_32x32x16_bf16 a[224:239], v[244:247], v[18:21], a[224:239]
	ds_read_b128 v[18:21], v250 offset:32768
	v_mfma_f32_32x32x16_bf16 a[112:127], v[244:247], v[22:25], a[112:127]
	ds_read_b128 v[22:25], v250 offset:36864
	v_mfma_f32_32x32x16_bf16 a[240:255], v[244:247], v[26:29], a[240:255]
	ds_read_b128 v[26:29], v250 offset:40960
	v_mfma_f32_32x32x16_bf16 a[48:63], v[244:247], v[30:33], a[48:63]
	ds_read_b128 v[30:33], v250 offset:45056
	ds_read_b128 v[244:247], v249 offset:4096
	s_waitcnt lgkmcnt(4)
	v_mfma_f32_32x32x16_bf16 a[128:143], v[14:17], v[18:21], a[128:143]
	s_waitcnt lgkmcnt(3)
	v_mfma_f32_32x32x16_bf16 a[64:79], v[14:17], v[22:25], a[64:79]
	s_waitcnt lgkmcnt(2)
	v_mfma_f32_32x32x16_bf16 a[144:159], v[14:17], v[26:29], a[144:159]
	s_waitcnt lgkmcnt(1)
	v_mfma_f32_32x32x16_bf16 a[0:15], v[14:17], v[30:33], a[0:15]
	ds_read_b128 v[14:17], v249 offset:8192
	s_waitcnt lgkmcnt(1)
	v_mfma_f32_32x32x16_bf16 a[160:175], v[244:247], v[18:21], a[160:175]
	v_mfma_f32_32x32x16_bf16 a[80:95], v[244:247], v[22:25], a[80:95]
	v_mfma_f32_32x32x16_bf16 a[176:191], v[244:247], v[26:29], a[176:191]
	v_mfma_f32_32x32x16_bf16 a[16:31], v[244:247], v[30:33], a[16:31]
	ds_read_b128 v[244:247], v249 offset:12288
	s_waitcnt lgkmcnt(1)
	v_mfma_f32_32x32x16_bf16 a[192:207], v[14:17], v[18:21], a[192:207]
	v_mfma_f32_32x32x16_bf16 a[96:111], v[14:17], v[22:25], a[96:111]
	v_mfma_f32_32x32x16_bf16 a[208:223], v[14:17], v[26:29], a[208:223]
	v_mfma_f32_32x32x16_bf16 a[32:47], v[14:17], v[30:33], a[32:47]
	v_lshl_or_b32 v250, v8, 1, s12
	v_add_u32_e32 v249, v250, v10
	v_add_u32_e32 v250, v250, v9
	ds_read_b128 v[14:17], v249
	s_waitcnt lgkmcnt(1)
	v_mfma_f32_32x32x16_bf16 a[224:239], v[244:247], v[18:21], a[224:239]
	ds_read_b128 v[18:21], v250 offset:32768
	v_mfma_f32_32x32x16_bf16 a[112:127], v[244:247], v[22:25], a[112:127]
	ds_read_b128 v[22:25], v250 offset:36864
	v_mfma_f32_32x32x16_bf16 a[240:255], v[244:247], v[26:29], a[240:255]
	ds_read_b128 v[26:29], v250 offset:40960
	v_mfma_f32_32x32x16_bf16 a[48:63], v[244:247], v[30:33], a[48:63]
	ds_read_b128 v[30:33], v250 offset:45056
	ds_read_b128 v[244:247], v249 offset:4096
	s_waitcnt lgkmcnt(4)
	v_mfma_f32_32x32x16_bf16 a[128:143], v[14:17], v[18:21], a[128:143]
	s_waitcnt lgkmcnt(3)
	v_mfma_f32_32x32x16_bf16 a[64:79], v[14:17], v[22:25], a[64:79]
	s_waitcnt lgkmcnt(2)
	v_mfma_f32_32x32x16_bf16 a[144:159], v[14:17], v[26:29], a[144:159]
	s_waitcnt lgkmcnt(1)
	v_mfma_f32_32x32x16_bf16 a[0:15], v[14:17], v[30:33], a[0:15]
	ds_read_b128 v[14:17], v249 offset:8192
	s_waitcnt lgkmcnt(1)
	v_mfma_f32_32x32x16_bf16 a[160:175], v[244:247], v[18:21], a[160:175]
	v_mfma_f32_32x32x16_bf16 a[80:95], v[244:247], v[22:25], a[80:95]
	v_mfma_f32_32x32x16_bf16 a[176:191], v[244:247], v[26:29], a[176:191]
	v_mfma_f32_32x32x16_bf16 a[16:31], v[244:247], v[30:33], a[16:31]
	ds_read_b128 v[244:247], v249 offset:12288
	s_waitcnt lgkmcnt(1)
	v_mfma_f32_32x32x16_bf16 a[192:207], v[14:17], v[18:21], a[192:207]
	v_mfma_f32_32x32x16_bf16 a[96:111], v[14:17], v[22:25], a[96:111]
	v_mfma_f32_32x32x16_bf16 a[208:223], v[14:17], v[26:29], a[208:223]
	v_mfma_f32_32x32x16_bf16 a[32:47], v[14:17], v[30:33], a[32:47]
	s_waitcnt vmcnt(0)
	s_waitcnt vmcnt(0) lgkmcnt(0)
	s_barrier
	s_add_u32 s4, s4, 0x80
	s_addc_u32 s5, s5, 0
	s_add_i32 s11, s11, 0x8000
	s_cmpk_lg_i32 s4, 0x780
	v_mfma_f32_32x32x16_bf16 a[224:239], v[244:247], v[18:21], a[224:239]
	v_mfma_f32_32x32x16_bf16 a[112:127], v[244:247], v[22:25], a[112:127]
	v_mfma_f32_32x32x16_bf16 a[240:255], v[244:247], v[26:29], a[240:255]
	v_mfma_f32_32x32x16_bf16 a[48:63], v[244:247], v[30:33], a[48:63]
	s_cbranch_scc1 .LBB0_148
	v_lshlrev_b32_e32 v0, 1, v13
	s_mov_b32 s4, 0x10000
	v_add3_u32 v13, v10, v0, s4
	ds_read_b128 v[128:131], v13
	s_mov_b32 s5, 0x18000
	v_add3_u32 v14, v9, v0, s5
	ds_read_b128 v[0:3], v14
	ds_read_b128 v[136:139], v13 offset:4096
	ds_read_b128 v[132:135], v14 offset:4096
	ds_read_b128 v[4:7], v14 offset:8192
	ds_read_b128 v[140:143], v14 offset:12288
	ds_read_b128 v[148:151], v13 offset:8192
	ds_read_b128 v[144:147], v13 offset:12288
	s_waitcnt lgkmcnt(5)
	v_mfma_f32_32x32x16_bf16 a[160:175], v[136:139], v[0:3], a[160:175]
	v_mfma_f32_32x32x16_bf16 a[128:143], v[128:131], v[0:3], a[128:143]
	s_waitcnt lgkmcnt(1)
	v_mfma_f32_32x32x16_bf16 a[192:207], v[148:151], v[0:3], a[192:207]
	s_waitcnt lgkmcnt(0)
	v_mfma_f32_32x32x16_bf16 a[224:239], v[144:147], v[0:3], a[224:239]
	v_lshlrev_b32_e32 v0, 1, v12
	v_add3_u32 v12, v10, v0, s4
	ds_read_b128 v[152:155], v12
	v_add3_u32 v13, v9, v0, s5
	ds_read_b128 v[0:3], v13
	ds_read_b128 v[160:163], v12 offset:4096
	ds_read_b128 v[156:159], v13 offset:4096
	v_mfma_f32_32x32x16_bf16 a[144:159], v[128:131], v[4:7], a[144:159]
	v_mfma_f32_32x32x16_bf16 a[176:191], v[136:139], v[4:7], a[176:191]
	v_mfma_f32_32x32x16_bf16 a[208:223], v[148:151], v[4:7], a[208:223]
	v_mfma_f32_32x32x16_bf16 a[240:255], v[144:147], v[4:7], a[240:255]
	ds_read_b128 v[4:7], v13 offset:8192
	ds_read_b128 v[164:167], v13 offset:12288
	ds_read_b128 v[172:175], v12 offset:8192
	ds_read_b128 v[168:171], v12 offset:12288
	s_waitcnt lgkmcnt(6)
	v_mfma_f32_32x32x16_bf16 a[128:143], v[152:155], v[0:3], a[128:143]
	s_waitcnt lgkmcnt(5)
	v_mfma_f32_32x32x16_bf16 a[160:175], v[160:163], v[0:3], a[160:175]
	s_waitcnt lgkmcnt(1)
	v_mfma_f32_32x32x16_bf16 a[192:207], v[172:175], v[0:3], a[192:207]
	s_waitcnt lgkmcnt(0)
	v_mfma_f32_32x32x16_bf16 a[224:239], v[168:171], v[0:3], a[224:239]
	v_lshlrev_b32_e32 v0, 1, v11
	v_add3_u32 v11, v10, v0, s4
	ds_read_b128 v[176:179], v11
	v_add3_u32 v12, v9, v0, s5
	ds_read_b128 v[0:3], v12
	ds_read_b128 v[184:187], v11 offset:4096
	ds_read_b128 v[180:183], v12 offset:4096
	v_mfma_f32_32x32x16_bf16 a[144:159], v[152:155], v[4:7], a[144:159]
	v_mfma_f32_32x32x16_bf16 a[176:191], v[160:163], v[4:7], a[176:191]
	v_mfma_f32_32x32x16_bf16 a[208:223], v[172:175], v[4:7], a[208:223]
	v_mfma_f32_32x32x16_bf16 a[240:255], v[168:171], v[4:7], a[240:255]
	ds_read_b128 v[4:7], v12 offset:8192
	ds_read_b128 v[188:191], v12 offset:12288
	ds_read_b128 v[196:199], v11 offset:8192
	ds_read_b128 v[192:195], v11 offset:12288
	s_waitcnt lgkmcnt(6)
	v_mfma_f32_32x32x16_bf16 a[128:143], v[176:179], v[0:3], a[128:143]
	s_waitcnt lgkmcnt(5)
	v_mfma_f32_32x32x16_bf16 a[160:175], v[184:187], v[0:3], a[160:175]
	s_waitcnt lgkmcnt(1)
	v_mfma_f32_32x32x16_bf16 a[192:207], v[196:199], v[0:3], a[192:207]
	s_waitcnt lgkmcnt(0)
	v_mfma_f32_32x32x16_bf16 a[224:239], v[192:195], v[0:3], a[224:239]
	v_lshlrev_b32_e32 v0, 1, v8
	v_add3_u32 v8, v10, v0, s4
	ds_read_b128 v[200:203], v8
	v_add3_u32 v9, v9, v0, s5
	ds_read_b128 v[0:3], v9
	ds_read_b128 v[208:211], v8 offset:4096
	ds_read_b128 v[204:207], v9 offset:4096
	s_mov_b32 s5, 0
	s_mov_b32 s4, 0
	v_mfma_f32_32x32x16_bf16 a[144:159], v[176:179], v[4:7], a[144:159]
	v_mfma_f32_32x32x16_bf16 a[176:191], v[184:187], v[4:7], a[176:191]
	v_mfma_f32_32x32x16_bf16 a[208:223], v[196:199], v[4:7], a[208:223]
	v_mfma_f32_32x32x16_bf16 a[240:255], v[192:195], v[4:7], a[240:255]
	ds_read_b128 v[4:7], v9 offset:8192
	ds_read_b128 v[212:215], v9 offset:12288
	ds_read_b128 v[220:223], v8 offset:8192
	ds_read_b128 v[216:219], v8 offset:12288
	s_waitcnt vmcnt(0)
	s_waitcnt lgkmcnt(0)
	s_barrier
	v_mfma_f32_32x32x16_bf16 a[128:143], v[200:203], v[0:3], a[128:143]
	v_mbcnt_lo_u32_b32 v224, -1, s5
	v_mbcnt_hi_u32_b32 v224, -1, v224
	s_lshl_b32 s5, s41, 16
	v_or_b32_e32 v226, s30, v224
	s_add_u32 s12, s22, s5
	v_lshlrev_b32_e32 v224, 4, v224
	s_addc_u32 s13, s26, 0
	v_mfma_f32_32x32x16_bf16 a[144:159], v[200:203], v[4:7], a[144:159]
	v_and_b32_e32 v252, 0xf0, v224
	v_lshl_add_u64 v[224:225], s[12:13], 0, v[252:253]
	s_nop 1
	v_accvgpr_read_b32 v112, a128
	v_accvgpr_read_b32 v113, a129
	v_accvgpr_read_b32 v114, a130
	v_mfma_f32_32x32x16_bf16 a[160:175], v[208:211], v[0:3], a[160:175]
	v_accvgpr_read_b32 v115, a131
	v_accvgpr_read_b32 v116, a132
	v_accvgpr_read_b32 v117, a133
	v_accvgpr_read_b32 v118, a134
	v_accvgpr_read_b32 v48, a144
	v_accvgpr_read_b32 v119, a135
	v_accvgpr_read_b32 v120, a136
	v_mfma_f32_32x32x16_bf16 a[176:191], v[208:211], v[4:7], a[176:191]
	v_accvgpr_read_b32 v121, a137
	v_accvgpr_read_b32 v122, a138
	v_accvgpr_read_b32 v123, a139
	v_accvgpr_read_b32 v124, a140
	v_accvgpr_read_b32 v96, a160
	v_accvgpr_read_b32 v125, a141
	v_accvgpr_read_b32 v126, a142
	v_mfma_f32_32x32x16_bf16 a[192:207], v[220:223], v[0:3], a[192:207]
	v_accvgpr_read_b32 v127, a143
	v_accvgpr_read_b32 v49, a145
	v_accvgpr_read_b32 v50, a146
	v_accvgpr_read_b32 v51, a147
	v_accvgpr_read_b32 v32, a176
	v_accvgpr_read_b32 v52, a148
	v_accvgpr_read_b32 v53, a149
	v_mfma_f32_32x32x16_bf16 a[208:223], v[220:223], v[4:7], a[208:223]
	v_accvgpr_read_b32 v54, a150
	v_accvgpr_read_b32 v55, a151
	v_accvgpr_read_b32 v56, a152
	v_accvgpr_read_b32 v57, a153
	v_accvgpr_read_b32 v80, a192
	v_accvgpr_read_b32 v58, a154
	v_accvgpr_read_b32 v59, a155
	v_mfma_f32_32x32x16_bf16 a[224:239], v[216:219], v[0:3], a[224:239]
	v_accvgpr_read_b32 v60, a156
	v_accvgpr_read_b32 v61, a157
	v_accvgpr_read_b32 v62, a158
	v_accvgpr_read_b32 v63, a159
	v_accvgpr_read_b32 v16, a208
	v_accvgpr_read_b32 v97, a161
	v_accvgpr_read_b32 v98, a162
	v_mfma_f32_32x32x16_bf16 a[240:255], v[216:219], v[4:7], a[240:255]
	v_accvgpr_read_b32 v99, a163
	v_accvgpr_read_b32 v100, a164
	v_accvgpr_read_b32 v101, a165
	v_accvgpr_read_b32 v102, a166
	v_accvgpr_read_b32 v64, a224
	v_accvgpr_read_b32 v103, a167
	v_accvgpr_read_b32 v104, a168
	v_accvgpr_read_b32 v105, a169
	v_accvgpr_read_b32 v106, a170
	v_accvgpr_read_b32 v107, a171
	v_accvgpr_read_b32 v108, a172
	v_accvgpr_read_b32 v109, a173
	v_accvgpr_read_b32 v0, a240
	v_accvgpr_read_b32 v110, a174
	v_accvgpr_read_b32 v111, a175
	v_accvgpr_read_b32 v33, a177
	v_accvgpr_read_b32 v34, a178
	v_accvgpr_read_b32 v35, a179
	v_accvgpr_read_b32 v36, a180
	v_accvgpr_read_b32 v37, a181
	v_accvgpr_read_b32 v38, a182
	v_accvgpr_read_b32 v39, a183
	v_accvgpr_read_b32 v40, a184
	v_accvgpr_read_b32 v41, a185
	v_accvgpr_read_b32 v42, a186
	v_accvgpr_read_b32 v43, a187
	v_accvgpr_read_b32 v44, a188
	v_accvgpr_read_b32 v45, a189
	v_accvgpr_read_b32 v46, a190
	v_accvgpr_read_b32 v47, a191
	v_accvgpr_read_b32 v81, a193
	v_accvgpr_read_b32 v82, a194
	v_accvgpr_read_b32 v83, a195
	v_accvgpr_read_b32 v84, a196
	v_accvgpr_read_b32 v85, a197
	v_accvgpr_read_b32 v86, a198
	v_accvgpr_read_b32 v87, a199
	v_accvgpr_read_b32 v88, a200
	v_accvgpr_read_b32 v89, a201
	v_accvgpr_read_b32 v90, a202
	v_accvgpr_read_b32 v91, a203
	v_accvgpr_read_b32 v92, a204
	v_accvgpr_read_b32 v93, a205
	v_accvgpr_read_b32 v94, a206
	v_accvgpr_read_b32 v95, a207
	v_accvgpr_read_b32 v17, a209
	v_accvgpr_read_b32 v18, a210
	v_accvgpr_read_b32 v19, a211
	v_accvgpr_read_b32 v20, a212
	v_accvgpr_read_b32 v21, a213
	v_accvgpr_read_b32 v22, a214
	v_accvgpr_read_b32 v23, a215
	v_accvgpr_read_b32 v24, a216
	v_accvgpr_read_b32 v25, a217
	v_accvgpr_read_b32 v26, a218
	v_accvgpr_read_b32 v27, a219
	v_accvgpr_read_b32 v28, a220
	v_accvgpr_read_b32 v29, a221
	v_accvgpr_read_b32 v30, a222
	v_accvgpr_read_b32 v31, a223
	v_accvgpr_read_b32 v65, a225
	v_accvgpr_read_b32 v66, a226
	v_accvgpr_read_b32 v67, a227
	v_accvgpr_read_b32 v68, a228
	v_accvgpr_read_b32 v69, a229
	v_accvgpr_read_b32 v70, a230
	v_accvgpr_read_b32 v71, a231
	v_accvgpr_read_b32 v72, a232
	v_accvgpr_read_b32 v73, a233
	v_accvgpr_read_b32 v74, a234
	v_accvgpr_read_b32 v75, a235
	v_accvgpr_read_b32 v76, a236
	v_accvgpr_read_b32 v77, a237
	v_accvgpr_read_b32 v78, a238
	v_accvgpr_read_b32 v79, a239
	v_accvgpr_read_b32 v1, a241
	v_accvgpr_read_b32 v2, a242
	v_accvgpr_read_b32 v3, a243
	v_accvgpr_read_b32 v4, a244
	v_accvgpr_read_b32 v5, a245
	v_accvgpr_read_b32 v6, a246
	v_accvgpr_read_b32 v7, a247
	v_accvgpr_read_b32 v8, a248
	v_accvgpr_read_b32 v9, a249
	v_accvgpr_read_b32 v10, a250
	v_accvgpr_read_b32 v11, a251
	v_accvgpr_read_b32 v12, a252
	v_accvgpr_read_b32 v13, a253
	v_accvgpr_read_b32 v14, a254
	v_accvgpr_read_b32 v15, a255

.LBB0_160:
	s_andn2_b64 vcc, exec, s[0:1]
	s_cbranch_vccnz .LBB0_249
	v_readlane_b32 s0, v255, 47
	s_and_b32 s14, 0xffff, s0
	s_cmp_lt_i32 s14, 3
	s_mov_b64 s[0:1], -1
	s_cbranch_scc1 .LBB0_189
	s_cmp_lt_i32 s14, 4
	s_cbranch_scc1 .LBB0_183
	s_cmp_gt_i32 s14, 4
	s_cbranch_scc0 .LBB0_168
	s_branch .Lgl1_entry

.LBB0_172:
	s_add_i32 s10, s7, 0xffff8000
	s_and_b32 s10, s10, 0x8000
	s_lshl_b32 s10, s10, 1
	v_lshl_or_b32 v250, v13, 1, s10
	v_add_u32_e32 v249, v250, v9
	v_add_u32_e32 v250, v250, v8
	ds_read_b128 v[14:17], v249
	ds_read_b128 v[18:21], v250 offset:32768
	ds_read_b128 v[22:25], v250 offset:36864
	ds_read_b128 v[26:29], v250 offset:40960
	ds_read_b128 v[30:33], v250 offset:45056
	ds_read_b128 v[48:51], v249 offset:4096
	s_waitcnt lgkmcnt(4)
	v_mfma_f32_32x32x16_bf16 a[192:207], v[14:17], v[18:21], a[192:207]
	s_waitcnt lgkmcnt(3)
	v_mfma_f32_32x32x16_bf16 a[128:143], v[14:17], v[22:25], a[128:143]
	s_and_b32 s98, s7, 0x8000
	s_lshl_b32 s98, s98, 1
	s_add_i32 s31, s22, s98
	v_lshl_add_u64 v[38:39], v[0:1], 0, s[0:1]
	s_mov_b64 s[98:99], 0x1800080
	v_lshl_add_u64 v[40:41], v[38:39], 0, s[98:99]
	s_mov_b32 m0, s31
	s_add_i32 s34, s31, 0x8000
	global_load_lds_dwordx4 v[40:41], off
	s_waitcnt lgkmcnt(2)
	v_mfma_f32_32x32x16_bf16 a[64:79], v[14:17], v[26:29], a[64:79]
	v_lshl_add_u64 v[40:41], v[4:5], 0, s[0:1]
	s_mov_b64 s[98:99], 0x32100080
	v_lshl_add_u64 v[42:43], v[40:41], 0, s[98:99]
	s_mov_b32 m0, s34
	s_mov_b64 s[98:99], 0x1808080
	global_load_lds_dwordx4 v[42:43], off
	s_waitcnt lgkmcnt(1)
	v_mfma_f32_32x32x16_bf16 a[0:15], v[14:17], v[30:33], a[0:15]
	v_lshl_add_u64 v[42:43], v[2:3], 0, s[0:1]
	v_lshl_add_u64 v[44:45], v[42:43], 0, s[98:99]
	s_add_i32 m0, s31, 0x400
	s_mov_b64 s[98:99], 0x32108080
	global_load_lds_dwordx4 v[44:45], off
	ds_read_b128 v[14:17], v249 offset:8192
	s_waitcnt lgkmcnt(1)
	v_mfma_f32_32x32x16_bf16 a[208:223], v[48:51], v[18:21], a[208:223]
	v_lshl_add_u64 v[44:45], v[6:7], 0, s[0:1]
	v_lshl_add_u64 v[46:47], v[44:45], 0, s[98:99]
	s_add_i32 m0, s31, 0x8400
	s_mov_b64 s[98:99], 0x1810080
	global_load_lds_dwordx4 v[46:47], off
	v_mfma_f32_32x32x16_bf16 a[144:159], v[48:51], v[22:25], a[144:159]
	v_lshl_add_u64 v[46:47], v[38:39], 0, s[98:99]
	s_add_i32 m0, s31, 0x800
	s_mov_b64 s[98:99], 0x32110080
	global_load_lds_dwordx4 v[46:47], off
	v_mfma_f32_32x32x16_bf16 a[80:95], v[48:51], v[26:29], a[80:95]
	v_lshl_add_u64 v[46:47], v[40:41], 0, s[98:99]
	s_add_i32 m0, s31, 0x8800
	s_mov_b64 s[98:99], 0x1818080
	global_load_lds_dwordx4 v[46:47], off
	v_mfma_f32_32x32x16_bf16 a[16:31], v[48:51], v[30:33], a[16:31]
	v_lshl_add_u64 v[46:47], v[42:43], 0, s[98:99]
	s_add_i32 m0, s31, 0xc00
	s_mov_b64 s[98:99], 0x32118080
	global_load_lds_dwordx4 v[46:47], off
	ds_read_b128 v[48:51], v249 offset:12288
	s_waitcnt lgkmcnt(1)
	v_mfma_f32_32x32x16_bf16 a[224:239], v[14:17], v[18:21], a[224:239]
	v_lshl_add_u64 v[46:47], v[44:45], 0, s[98:99]
	s_add_i32 m0, s31, 0x8c00
	s_mov_b64 s[98:99], 0x1820080
	global_load_lds_dwordx4 v[46:47], off
	v_mfma_f32_32x32x16_bf16 a[160:175], v[14:17], v[22:25], a[160:175]
	v_lshl_add_u64 v[46:47], v[38:39], 0, s[98:99]
	s_add_i32 m0, s31, 0x1000
	s_mov_b64 s[98:99], 0x32120080
	global_load_lds_dwordx4 v[46:47], off
	v_mfma_f32_32x32x16_bf16 a[96:111], v[14:17], v[26:29], a[96:111]
	v_lshl_add_u64 v[46:47], v[40:41], 0, s[98:99]
	s_add_i32 m0, s31, 0x9000
	s_mov_b64 s[98:99], 0x1828080
	global_load_lds_dwordx4 v[46:47], off
	v_mfma_f32_32x32x16_bf16 a[32:47], v[14:17], v[30:33], a[32:47]
	v_lshl_add_u64 v[46:47], v[42:43], 0, s[98:99]
	s_add_i32 m0, s31, 0x1400
	s_mov_b64 s[98:99], 0x32128080
	global_load_lds_dwordx4 v[46:47], off
	v_lshl_or_b32 v250, v12, 1, s10
	v_add_u32_e32 v249, v250, v9
	v_add_u32_e32 v250, v250, v8
	ds_read_b128 v[14:17], v249
	s_waitcnt lgkmcnt(1)
	v_mfma_f32_32x32x16_bf16 a[240:255], v[48:51], v[18:21], a[240:255]
	v_lshl_add_u64 v[46:47], v[44:45], 0, s[98:99]
	s_add_i32 m0, s31, 0x9400
	s_mov_b64 s[98:99], 0x1830080
	global_load_lds_dwordx4 v[46:47], off
	ds_read_b128 v[18:21], v250 offset:32768
	v_mfma_f32_32x32x16_bf16 a[176:191], v[48:51], v[22:25], a[176:191]
	v_lshl_add_u64 v[38:39], v[38:39], 0, s[98:99]
	s_add_i32 m0, s31, 0x1800
	s_mov_b64 s[98:99], 0x32130080
	global_load_lds_dwordx4 v[38:39], off
	ds_read_b128 v[22:25], v250 offset:36864
	v_mfma_f32_32x32x16_bf16 a[112:127], v[48:51], v[26:29], a[112:127]
	v_lshl_add_u64 v[38:39], v[40:41], 0, s[98:99]
	s_add_i32 m0, s31, 0x9800
	s_mov_b64 s[98:99], 0x1838080
	global_load_lds_dwordx4 v[38:39], off
	ds_read_b128 v[26:29], v250 offset:40960
	v_mfma_f32_32x32x16_bf16 a[48:63], v[48:51], v[30:33], a[48:63]
	v_lshl_add_u64 v[38:39], v[42:43], 0, s[98:99]
	s_add_i32 m0, s31, 0x1c00
	s_mov_b64 s[98:99], 0x32138080
	global_load_lds_dwordx4 v[38:39], off
	ds_read_b128 v[30:33], v250 offset:45056
	ds_read_b128 v[48:51], v249 offset:4096
	s_waitcnt lgkmcnt(4)
	v_mfma_f32_32x32x16_bf16 a[192:207], v[14:17], v[18:21], a[192:207]
	v_lshl_add_u64 v[38:39], v[44:45], 0, s[98:99]
	s_add_i32 m0, s31, 0x9c00
	s_nop 0
	global_load_lds_dwordx4 v[38:39], off
	s_waitcnt lgkmcnt(3)
	v_mfma_f32_32x32x16_bf16 a[128:143], v[14:17], v[22:25], a[128:143]
	s_waitcnt lgkmcnt(2)
	v_mfma_f32_32x32x16_bf16 a[64:79], v[14:17], v[26:29], a[64:79]
	s_waitcnt lgkmcnt(1)
	v_mfma_f32_32x32x16_bf16 a[0:15], v[14:17], v[30:33], a[0:15]
	ds_read_b128 v[14:17], v249 offset:8192
	s_waitcnt lgkmcnt(1)
	v_mfma_f32_32x32x16_bf16 a[208:223], v[48:51], v[18:21], a[208:223]
	v_mfma_f32_32x32x16_bf16 a[144:159], v[48:51], v[22:25], a[144:159]
	v_mfma_f32_32x32x16_bf16 a[80:95], v[48:51], v[26:29], a[80:95]
	v_mfma_f32_32x32x16_bf16 a[16:31], v[48:51], v[30:33], a[16:31]
	ds_read_b128 v[48:51], v249 offset:12288
	s_waitcnt lgkmcnt(1)
	v_mfma_f32_32x32x16_bf16 a[224:239], v[14:17], v[18:21], a[224:239]
	v_mfma_f32_32x32x16_bf16 a[160:175], v[14:17], v[22:25], a[160:175]
	v_mfma_f32_32x32x16_bf16 a[96:111], v[14:17], v[26:29], a[96:111]
	v_mfma_f32_32x32x16_bf16 a[32:47], v[14:17], v[30:33], a[32:47]
	v_lshl_or_b32 v250, v11, 1, s10
	v_add_u32_e32 v249, v250, v9
	v_add_u32_e32 v250, v250, v8
	ds_read_b128 v[14:17], v249
	s_waitcnt lgkmcnt(1)
	v_mfma_f32_32x32x16_bf16 a[240:255], v[48:51], v[18:21], a[240:255]
	ds_read_b128 v[18:21], v250 offset:32768
	v_mfma_f32_32x32x16_bf16 a[176:191], v[48:51], v[22:25], a[176:191]
	ds_read_b128 v[22:25], v250 offset:36864
	v_mfma_f32_32x32x16_bf16 a[112:127], v[48:51], v[26:29], a[112:127]
	ds_read_b128 v[26:29], v250 offset:40960
	v_mfma_f32_32x32x16_bf16 a[48:63], v[48:51], v[30:33], a[48:63]
	ds_read_b128 v[30:33], v250 offset:45056
	ds_read_b128 v[48:51], v249 offset:4096
	s_waitcnt lgkmcnt(4)
	v_mfma_f32_32x32x16_bf16 a[192:207], v[14:17], v[18:21], a[192:207]
	s_waitcnt lgkmcnt(3)
	v_mfma_f32_32x32x16_bf16 a[128:143], v[14:17], v[22:25], a[128:143]
	s_waitcnt lgkmcnt(2)
	v_mfma_f32_32x32x16_bf16 a[64:79], v[14:17], v[26:29], a[64:79]
	s_waitcnt lgkmcnt(1)
	v_mfma_f32_32x32x16_bf16 a[0:15], v[14:17], v[30:33], a[0:15]
	ds_read_b128 v[14:17], v249 offset:8192
	s_waitcnt lgkmcnt(1)
	v_mfma_f32_32x32x16_bf16 a[208:223], v[48:51], v[18:21], a[208:223]
	v_mfma_f32_32x32x16_bf16 a[144:159], v[48:51], v[22:25], a[144:159]
	v_mfma_f32_32x32x16_bf16 a[80:95], v[48:51], v[26:29], a[80:95]
	v_mfma_f32_32x32x16_bf16 a[16:31], v[48:51], v[30:33], a[16:31]
	ds_read_b128 v[48:51], v249 offset:12288
	s_waitcnt lgkmcnt(1)
	v_mfma_f32_32x32x16_bf16 a[224:239], v[14:17], v[18:21], a[224:239]
	v_mfma_f32_32x32x16_bf16 a[160:175], v[14:17], v[22:25], a[160:175]
	v_mfma_f32_32x32x16_bf16 a[96:111], v[14:17], v[26:29], a[96:111]
	v_mfma_f32_32x32x16_bf16 a[32:47], v[14:17], v[30:33], a[32:47]
	v_lshl_or_b32 v250, v10, 1, s10
	v_add_u32_e32 v249, v250, v9
	v_add_u32_e32 v250, v250, v8
	ds_read_b128 v[14:17], v249
	s_waitcnt lgkmcnt(1)
	v_mfma_f32_32x32x16_bf16 a[240:255], v[48:51], v[18:21], a[240:255]
	ds_read_b128 v[18:21], v250 offset:32768
	v_mfma_f32_32x32x16_bf16 a[176:191], v[48:51], v[22:25], a[176:191]
	ds_read_b128 v[22:25], v250 offset:36864
	v_mfma_f32_32x32x16_bf16 a[112:127], v[48:51], v[26:29], a[112:127]
	ds_read_b128 v[26:29], v250 offset:40960
	v_mfma_f32_32x32x16_bf16 a[48:63], v[48:51], v[30:33], a[48:63]
	ds_read_b128 v[30:33], v250 offset:45056
	ds_read_b128 v[48:51], v249 offset:4096
	s_waitcnt lgkmcnt(4)
	v_mfma_f32_32x32x16_bf16 a[192:207], v[14:17], v[18:21], a[192:207]
	s_waitcnt lgkmcnt(3)
	v_mfma_f32_32x32x16_bf16 a[128:143], v[14:17], v[22:25], a[128:143]
	s_waitcnt lgkmcnt(2)
	v_mfma_f32_32x32x16_bf16 a[64:79], v[14:17], v[26:29], a[64:79]
	s_waitcnt lgkmcnt(1)
	v_mfma_f32_32x32x16_bf16 a[0:15], v[14:17], v[30:33], a[0:15]
	ds_read_b128 v[14:17], v249 offset:8192
	s_waitcnt lgkmcnt(1)
	v_mfma_f32_32x32x16_bf16 a[208:223], v[48:51], v[18:21], a[208:223]
	v_mfma_f32_32x32x16_bf16 a[144:159], v[48:51], v[22:25], a[144:159]
	v_mfma_f32_32x32x16_bf16 a[80:95], v[48:51], v[26:29], a[80:95]
	v_mfma_f32_32x32x16_bf16 a[16:31], v[48:51], v[30:33], a[16:31]
	ds_read_b128 v[48:51], v249 offset:12288
	s_waitcnt lgkmcnt(1)
	v_mfma_f32_32x32x16_bf16 a[224:239], v[14:17], v[18:21], a[224:239]
	v_mfma_f32_32x32x16_bf16 a[160:175], v[14:17], v[22:25], a[160:175]
	v_mfma_f32_32x32x16_bf16 a[96:111], v[14:17], v[26:29], a[96:111]
	v_mfma_f32_32x32x16_bf16 a[32:47], v[14:17], v[30:33], a[32:47]
	s_waitcnt vmcnt(0)
	s_waitcnt vmcnt(0) lgkmcnt(0)
	s_barrier
	s_add_u32 s0, s0, 0x80
	s_addc_u32 s1, s1, 0
	s_add_i32 s7, s7, 0x8000
	s_cmpk_lg_i32 s0, 0xf80
	v_mfma_f32_32x32x16_bf16 a[240:255], v[48:51], v[18:21], a[240:255]
	v_mfma_f32_32x32x16_bf16 a[176:191], v[48:51], v[22:25], a[176:191]
	v_mfma_f32_32x32x16_bf16 a[112:127], v[48:51], v[26:29], a[112:127]
	v_mfma_f32_32x32x16_bf16 a[48:63], v[48:51], v[30:33], a[48:63]
	s_cbranch_scc1 .LBB0_172
	v_lshlrev_b32_e32 v13, 1, v13
	s_mov_b32 s0, 0x10000
	s_mov_b32 s1, 0x18000
	v_add3_u32 v18, v9, v13, s0
	v_add3_u32 v13, v8, v13, s1
	ds_read_b128 v[0:3], v18
	ds_read_b128 v[4:7], v18 offset:4096
	ds_read_b128 v[14:17], v18 offset:8192
	ds_read_b128 v[18:21], v18 offset:12288
	ds_read_b128 v[22:25], v13
	ds_read_b128 v[26:29], v13 offset:4096
	ds_read_b128 v[30:33], v13 offset:8192
	ds_read_b128 v[34:37], v13 offset:12288
	s_waitcnt lgkmcnt(3)
	v_mfma_f32_32x32x16_bf16 a[192:207], v[0:3], v[22:25], a[192:207]
	v_lshlrev_b32_e32 v11, 1, v11
	s_waitcnt lgkmcnt(2)
	v_mfma_f32_32x32x16_bf16 a[128:143], v[0:3], v[26:29], a[128:143]
	s_waitcnt lgkmcnt(1)
	v_mfma_f32_32x32x16_bf16 a[64:79], v[0:3], v[30:33], a[64:79]
	s_waitcnt lgkmcnt(0)
	v_mfma_f32_32x32x16_bf16 a[0:15], v[0:3], v[34:37], a[0:15]
	v_mfma_f32_32x32x16_bf16 a[208:223], v[4:7], v[22:25], a[208:223]
	v_mfma_f32_32x32x16_bf16 a[144:159], v[4:7], v[26:29], a[144:159]
	v_mfma_f32_32x32x16_bf16 a[80:95], v[4:7], v[30:33], a[80:95]
	v_mfma_f32_32x32x16_bf16 a[16:31], v[4:7], v[34:37], a[16:31]
	v_mfma_f32_32x32x16_bf16 a[224:239], v[14:17], v[22:25], a[224:239]
	v_mfma_f32_32x32x16_bf16 a[160:175], v[14:17], v[26:29], a[160:175]
	v_mfma_f32_32x32x16_bf16 a[96:111], v[14:17], v[30:33], a[96:111]
	v_mfma_f32_32x32x16_bf16 a[32:47], v[14:17], v[34:37], a[32:47]
	v_mfma_f32_32x32x16_bf16 a[240:255], v[18:21], v[22:25], a[240:255]
	v_mfma_f32_32x32x16_bf16 a[176:191], v[18:21], v[26:29], a[176:191]
	v_mfma_f32_32x32x16_bf16 a[112:127], v[18:21], v[30:33], a[112:127]
	v_mfma_f32_32x32x16_bf16 a[48:63], v[18:21], v[34:37], a[48:63]
	v_lshlrev_b32_e32 v20, 1, v12
	v_add3_u32 v16, v9, v20, s0
	v_add3_u32 v32, v8, v20, s1
	ds_read_b128 v[0:3], v16
	ds_read_b128 v[4:7], v16 offset:4096
	ds_read_b128 v[12:15], v16 offset:8192
	ds_read_b128 v[16:19], v16 offset:12288
	ds_read_b128 v[20:23], v32
	ds_read_b128 v[24:27], v32 offset:4096
	ds_read_b128 v[28:31], v32 offset:8192
	ds_read_b128 v[32:35], v32 offset:12288
	s_waitcnt lgkmcnt(3)
	v_mfma_f32_32x32x16_bf16 a[192:207], v[0:3], v[20:23], a[192:207]
	s_waitcnt lgkmcnt(2)
	v_mfma_f32_32x32x16_bf16 a[128:143], v[0:3], v[24:27], a[128:143]
	s_waitcnt lgkmcnt(1)
	v_mfma_f32_32x32x16_bf16 a[64:79], v[0:3], v[28:31], a[64:79]
	s_waitcnt lgkmcnt(0)
	v_mfma_f32_32x32x16_bf16 a[0:15], v[0:3], v[32:35], a[0:15]
	v_mfma_f32_32x32x16_bf16 a[208:223], v[4:7], v[20:23], a[208:223]
	v_mfma_f32_32x32x16_bf16 a[144:159], v[4:7], v[24:27], a[144:159]
	v_mfma_f32_32x32x16_bf16 a[80:95], v[4:7], v[28:31], a[80:95]
	v_mfma_f32_32x32x16_bf16 a[16:31], v[4:7], v[32:35], a[16:31]
	v_mfma_f32_32x32x16_bf16 a[224:239], v[12:15], v[20:23], a[224:239]
	v_mfma_f32_32x32x16_bf16 a[160:175], v[12:15], v[24:27], a[160:175]
	v_mfma_f32_32x32x16_bf16 a[96:111], v[12:15], v[28:31], a[96:111]
	v_mfma_f32_32x32x16_bf16 a[32:47], v[12:15], v[32:35], a[32:47]
	v_mfma_f32_32x32x16_bf16 a[240:255], v[16:19], v[20:23], a[240:255]
	v_mfma_f32_32x32x16_bf16 a[176:191], v[16:19], v[24:27], a[176:191]
	v_mfma_f32_32x32x16_bf16 a[112:127], v[16:19], v[28:31], a[112:127]
	v_mfma_f32_32x32x16_bf16 a[48:63], v[16:19], v[32:35], a[48:63]
	v_add3_u32 v16, v9, v11, s0
	v_add3_u32 v11, v8, v11, s1
	ds_read_b128 v[0:3], v16
	ds_read_b128 v[4:7], v16 offset:4096
	ds_read_b128 v[12:15], v16 offset:8192
	ds_read_b128 v[16:19], v16 offset:12288
	ds_read_b128 v[20:23], v11
	ds_read_b128 v[24:27], v11 offset:4096
	ds_read_b128 v[28:31], v11 offset:8192
	ds_read_b128 v[32:35], v11 offset:12288
	s_waitcnt lgkmcnt(3)
	v_mfma_f32_32x32x16_bf16 a[192:207], v[0:3], v[20:23], a[192:207]
	s_waitcnt lgkmcnt(2)
	v_mfma_f32_32x32x16_bf16 a[128:143], v[0:3], v[24:27], a[128:143]
	s_waitcnt lgkmcnt(1)
	v_mfma_f32_32x32x16_bf16 a[64:79], v[0:3], v[28:31], a[64:79]
	s_waitcnt lgkmcnt(0)
	v_mfma_f32_32x32x16_bf16 a[0:15], v[0:3], v[32:35], a[0:15]
	v_mfma_f32_32x32x16_bf16 a[208:223], v[4:7], v[20:23], a[208:223]
	v_mfma_f32_32x32x16_bf16 a[144:159], v[4:7], v[24:27], a[144:159]
	v_mfma_f32_32x32x16_bf16 a[80:95], v[4:7], v[28:31], a[80:95]
	v_mfma_f32_32x32x16_bf16 a[16:31], v[4:7], v[32:35], a[16:31]
	v_mfma_f32_32x32x16_bf16 a[224:239], v[12:15], v[20:23], a[224:239]
	v_mfma_f32_32x32x16_bf16 a[160:175], v[12:15], v[24:27], a[160:175]
	v_mfma_f32_32x32x16_bf16 a[96:111], v[12:15], v[28:31], a[96:111]
	v_mfma_f32_32x32x16_bf16 a[32:47], v[12:15], v[32:35], a[32:47]
	v_mfma_f32_32x32x16_bf16 a[240:255], v[16:19], v[20:23], a[240:255]
	v_mfma_f32_32x32x16_bf16 a[176:191], v[16:19], v[24:27], a[176:191]
	v_mfma_f32_32x32x16_bf16 a[112:127], v[16:19], v[28:31], a[112:127]
	v_mfma_f32_32x32x16_bf16 a[48:63], v[16:19], v[32:35], a[48:63]
	v_lshlrev_b32_e32 v18, 1, v10
	v_add3_u32 v9, v9, v18, s0
	v_add3_u32 v8, v8, v18, s1
	ds_read_b128 v[0:3], v9
	ds_read_b128 v[4:7], v9 offset:4096
	ds_read_b128 v[10:13], v9 offset:8192
	ds_read_b128 v[14:17], v9 offset:12288
	ds_read_b128 v[18:21], v8
	ds_read_b128 v[22:25], v8 offset:4096
	ds_read_b128 v[26:29], v8 offset:8192
	ds_read_b128 v[30:33], v8 offset:12288
	s_mov_b32 s0, s35
	s_waitcnt vmcnt(0)
	s_waitcnt lgkmcnt(3)
	v_mfma_f32_32x32x16_bf16 a[192:207], v[0:3], v[18:21], a[192:207]
	s_waitcnt lgkmcnt(0)
	s_barrier
	v_mfma_f32_32x32x16_bf16 a[128:143], v[0:3], v[22:25], a[128:143]
	v_mfma_f32_32x32x16_bf16 a[64:79], v[0:3], v[26:29], a[64:79]
	v_mfma_f32_32x32x16_bf16 a[0:15], v[0:3], v[30:33], a[0:15]
	v_mbcnt_lo_u32_b32 v0, -1, s0
	v_mbcnt_hi_u32_b32 v0, -1, v0
	v_mov_b32_e32 v3, s21
	s_mov_b32 s0, 0x3fffff80
	v_bitop3_b32 v3, v0, s0, v3 bitop3:0xc8
	v_or_b32_e32 v1, s21, v0
	v_and_b32_e32 v2, 31, v0
	v_mfma_f32_32x32x16_bf16 a[208:223], v[4:7], v[18:21], a[208:223]
	v_and_b32_e32 v1, 64, v1
	v_cmp_ne_u32_e32 vcc, 0, v1
	v_mfma_f32_32x32x16_bf16 a[144:159], v[4:7], v[22:25], a[144:159]
	v_mfma_f32_32x32x16_bf16 a[80:95], v[4:7], v[26:29], a[80:95]
	v_mfma_f32_32x32x16_bf16 a[16:31], v[4:7], v[30:33], a[16:31]
	v_lshrrev_b32_e32 v4, 1, v0
	v_and_b32_e32 v4, 16, v4
	v_lshl_or_b32 v3, v3, 2, v4
	v_bitop3_b32 v0, v0, 64, s21 bitop3:0xc8
	v_mad_u32_u24 v36, v2, s95, v3
	v_cmp_eq_u32_e64 s[0:1], 0, v0
	v_add_u32_e32 v35, 0x10400, v36
	v_mfma_f32_32x32x16_bf16 a[224:239], v[10:13], v[18:21], a[224:239]
	v_add_u32_e32 v34, 0x10420, v36
	v_add_u32_e32 v9, 0x18740, v36
	v_add_u32_e32 v8, 0x18760, v36
	v_add_u32_e32 v7, 0x18780, v36
	v_add_u32_e32 v6, 0x187a0, v36
	v_add_u32_e32 v5, 0x187c0, v36
	v_add_u32_e32 v4, 0x187e0, v36
	v_mfma_f32_32x32x16_bf16 a[160:175], v[10:13], v[22:25], a[160:175]
	v_mfma_f32_32x32x16_bf16 a[96:111], v[10:13], v[26:29], a[96:111]
	v_mfma_f32_32x32x16_bf16 a[32:47], v[10:13], v[30:33], a[32:47]
	v_add_u32_e32 v13, 0x186c0, v36
	v_add_u32_e32 v12, 0x186e0, v36
	v_add_u32_e32 v11, 0x18700, v36
	v_add_u32_e32 v10, 0x18720, v36
	v_mfma_f32_32x32x16_bf16 a[240:255], v[14:17], v[18:21], a[240:255]
	v_add_u32_e32 v21, 0x105c0, v36
	v_add_u32_e32 v20, 0x105e0, v36
	v_add_u32_e32 v19, 0x18600, v36
	v_add_u32_e32 v18, 0x18620, v36
	v_mfma_f32_32x32x16_bf16 a[176:191], v[14:17], v[22:25], a[176:191]
	v_add_u32_e32 v25, 0x10540, v36
	v_add_u32_e32 v24, 0x10560, v36
	v_add_u32_e32 v23, 0x10580, v36
	v_add_u32_e32 v22, 0x105a0, v36
	v_mfma_f32_32x32x16_bf16 a[112:127], v[14:17], v[26:29], a[112:127]
	v_add_u32_e32 v29, 0x104c0, v36
	v_add_u32_e32 v28, 0x104e0, v36
	v_add_u32_e32 v27, 0x10500, v36
	v_add_u32_e32 v26, 0x10520, v36
	v_mfma_f32_32x32x16_bf16 a[48:63], v[14:17], v[30:33], a[48:63]
	v_add_u32_e32 v33, 0x10440, v36
	v_add_u32_e32 v32, 0x10460, v36
	v_add_u32_e32 v31, 0x10480, v36
	v_add_u32_e32 v30, 0x104a0, v36
	v_add_u32_e32 v17, 0x18640, v36
	v_add_u32_e32 v16, 0x18660, v36
	v_add_u32_e32 v15, 0x18680, v36
	v_add_u32_e32 v14, 0x186a0, v36
	s_and_saveexec_b64 s[10:11], s[0:1]
	s_cbranch_execz .LBB0_175
	ds_write_b128 v36, a[192:195]
	ds_write_b128 v36, a[196:199] offset:32
	ds_write_b128 v36, a[200:203] offset:64
	ds_write_b128 v36, a[204:207] offset:96
	ds_write_b128 v36, a[208:211] offset:128
	ds_write_b128 v36, a[212:215] offset:160
	ds_write_b128 v36, a[216:219] offset:192
	ds_write_b128 v36, a[220:223] offset:224
	ds_write_b128 v36, a[224:227] offset:256
	ds_write_b128 v36, a[228:231] offset:288
	ds_write_b128 v36, a[232:235] offset:320
	ds_write_b128 v36, a[236:239] offset:352
	ds_write_b128 v36, a[240:243] offset:384
	ds_write_b128 v36, a[244:247] offset:416
	ds_write_b128 v36, a[248:251] offset:448
	ds_write_b128 v36, a[252:255] offset:480
	ds_write_b128 v36, a[128:131] offset:33280
	ds_write_b128 v36, a[132:135] offset:33312
	ds_write_b128 v36, a[136:139] offset:33344
	ds_write_b128 v36, a[140:143] offset:33376
	ds_write_b128 v36, a[144:147] offset:33408
	ds_write_b128 v36, a[148:151] offset:33440
	ds_write_b128 v36, a[152:155] offset:33472
	ds_write_b128 v36, a[156:159] offset:33504
	ds_write_b128 v36, a[160:163] offset:33536
	ds_write_b128 v36, a[164:167] offset:33568
	ds_write_b128 v36, a[168:171] offset:33600
	ds_write_b128 v36, a[172:175] offset:33632
	ds_write_b128 v36, a[176:179] offset:33664
	ds_write_b128 v36, a[180:183] offset:33696
	ds_write_b128 v36, a[184:187] offset:33728
	ds_write_b128 v36, a[188:191] offset:33760
	ds_write_b128 v35, a[64:67]
	ds_write_b128 v34, a[68:71]
	ds_write_b128 v33, a[72:75]
	ds_write_b128 v32, a[76:79]
	ds_write_b128 v31, a[80:83]
	ds_write_b128 v30, a[84:87]
	ds_write_b128 v29, a[88:91]
	ds_write_b128 v28, a[92:95]
	ds_write_b128 v27, a[96:99]
	ds_write_b128 v26, a[100:103]
	ds_write_b128 v25, a[104:107]
	ds_write_b128 v24, a[108:111]
	ds_write_b128 v23, a[112:115]
	ds_write_b128 v22, a[116:119]
	ds_write_b128 v21, a[120:123]
	ds_write_b128 v20, a[124:127]
	ds_write_b128 v19, a[0:3]
	ds_write_b128 v18, a[4:7]
	ds_write_b128 v17, a[8:11]
	ds_write_b128 v16, a[12:15]
	ds_write_b128 v15, a[16:19]
	ds_write_b128 v14, a[20:23]
	ds_write_b128 v13, a[24:27]
	ds_write_b128 v12, a[28:31]
	ds_write_b128 v11, a[32:35]
	ds_write_b128 v10, a[36:39]
	ds_write_b128 v9, a[40:43]
	ds_write_b128 v8, a[44:47]
	ds_write_b128 v7, a[48:51]
	ds_write_b128 v6, a[52:55]
	ds_write_b128 v5, a[56:59]
	ds_write_b128 v4, a[60:63]

.LBB0_208:
	s_add_i32 s14, s11, 0xffff8000
	s_and_b32 s14, s14, 0x8000
	s_lshl_b32 s14, s14, 1
	v_lshl_or_b32 v250, v13, 1, s14
	v_add_u32_e32 v249, v250, v9
	v_add_u32_e32 v250, v250, v8
	ds_read_b128 v[14:17], v249
	ds_read_b128 v[18:21], v250 offset:32768
	ds_read_b128 v[22:25], v250 offset:36864
	ds_read_b128 v[26:29], v250 offset:40960
	ds_read_b128 v[30:33], v250 offset:45056
	ds_read_b128 v[48:51], v249 offset:4096
	s_waitcnt lgkmcnt(4)
	v_mfma_f32_32x32x16_bf16 a[240:255], v[14:17], v[18:21], a[240:255]
	s_waitcnt lgkmcnt(3)
	v_mfma_f32_32x32x16_bf16 a[176:191], v[14:17], v[22:25], a[176:191]
	s_and_b32 s98, s11, 0x8000
	s_lshl_b32 s98, s98, 1
	s_add_i32 s98, s62, s98
	v_lshl_add_u64 v[38:39], v[0:1], 0, s[4:5]
	v_lshl_add_u64 v[40:41], v[38:39], 0, s[30:31]
	s_mov_b32 m0, s98
	s_add_i32 s99, s98, 0x8000
	global_load_lds_dwordx4 v[40:41], off
	s_waitcnt lgkmcnt(2)
	v_mfma_f32_32x32x16_bf16 a[112:127], v[14:17], v[26:29], a[112:127]
	v_lshl_add_u64 v[40:41], v[4:5], 0, s[4:5]
	v_lshl_add_u64 v[42:43], v[40:41], 0, s[38:39]
	s_mov_b32 m0, s99
	s_nop 0
	global_load_lds_dwordx4 v[42:43], off
	s_waitcnt lgkmcnt(1)
	v_mfma_f32_32x32x16_bf16 a[48:63], v[14:17], v[30:33], a[48:63]
	v_lshl_add_u64 v[42:43], v[2:3], 0, s[4:5]
	v_lshl_add_u64 v[44:45], v[42:43], 0, s[40:41]
	s_add_i32 m0, s98, 0x400
	s_nop 0
	global_load_lds_dwordx4 v[44:45], off
	ds_read_b128 v[14:17], v249 offset:8192
	s_waitcnt lgkmcnt(1)
	v_mfma_f32_32x32x16_bf16 a[224:239], v[48:51], v[18:21], a[224:239]
	v_lshl_add_u64 v[44:45], v[6:7], 0, s[4:5]
	v_lshl_add_u64 v[46:47], v[44:45], 0, s[44:45]
	s_add_i32 m0, s98, 0x8400
	s_nop 0
	global_load_lds_dwordx4 v[46:47], off
	v_mfma_f32_32x32x16_bf16 a[160:175], v[48:51], v[22:25], a[160:175]
	v_lshl_add_u64 v[46:47], v[38:39], 0, s[68:69]
	s_add_i32 m0, s98, 0x800
	s_nop 0
	global_load_lds_dwordx4 v[46:47], off
	v_mfma_f32_32x32x16_bf16 a[96:111], v[48:51], v[26:29], a[96:111]
	v_lshl_add_u64 v[46:47], v[40:41], 0, s[2:3]
	s_add_i32 m0, s98, 0x8800
	s_nop 0
	global_load_lds_dwordx4 v[46:47], off
	v_mfma_f32_32x32x16_bf16 a[32:47], v[48:51], v[30:33], a[32:47]
	v_lshl_add_u64 v[46:47], v[42:43], 0, s[70:71]
	s_add_i32 m0, s98, 0xc00
	s_nop 0
	global_load_lds_dwordx4 v[46:47], off
	ds_read_b128 v[48:51], v249 offset:12288
	s_waitcnt lgkmcnt(1)
	v_mfma_f32_32x32x16_bf16 a[208:223], v[14:17], v[18:21], a[208:223]
	v_lshl_add_u64 v[46:47], v[44:45], 0, s[46:47]
	s_add_i32 m0, s98, 0x8c00
	s_nop 0
	global_load_lds_dwordx4 v[46:47], off
	v_mfma_f32_32x32x16_bf16 a[144:159], v[14:17], v[22:25], a[144:159]
	v_lshl_add_u64 v[46:47], v[38:39], 0, s[76:77]
	s_add_i32 m0, s98, 0x1000
	v_lshl_add_u64 v[38:39], v[38:39], 0, s[80:81]
	global_load_lds_dwordx4 v[46:47], off
	v_mfma_f32_32x32x16_bf16 a[80:95], v[14:17], v[26:29], a[80:95]
	v_lshl_add_u64 v[46:47], v[40:41], 0, s[50:51]
	s_add_i32 m0, s98, 0x9000
	s_nop 0
	global_load_lds_dwordx4 v[46:47], off
	v_mfma_f32_32x32x16_bf16 a[16:31], v[14:17], v[30:33], a[16:31]
	v_lshl_add_u64 v[46:47], v[42:43], 0, s[78:79]
	s_add_i32 m0, s98, 0x1400
	s_nop 0
	global_load_lds_dwordx4 v[46:47], off
	v_lshl_or_b32 v250, v12, 1, s14
	v_add_u32_e32 v249, v250, v9
	v_add_u32_e32 v250, v250, v8
	ds_read_b128 v[14:17], v249
	s_waitcnt lgkmcnt(1)
	v_mfma_f32_32x32x16_bf16 a[192:207], v[48:51], v[18:21], a[192:207]
	v_lshl_add_u64 v[46:47], v[44:45], 0, s[52:53]
	s_add_i32 m0, s98, 0x9400
	s_nop 0
	global_load_lds_dwordx4 v[46:47], off
	ds_read_b128 v[18:21], v250 offset:32768
	v_mfma_f32_32x32x16_bf16 a[128:143], v[48:51], v[22:25], a[128:143]
	s_add_i32 m0, s98, 0x1800
	s_nop 0
	global_load_lds_dwordx4 v[38:39], off
	ds_read_b128 v[22:25], v250 offset:36864
	v_mfma_f32_32x32x16_bf16 a[64:79], v[48:51], v[26:29], a[64:79]
	v_lshl_add_u64 v[38:39], v[40:41], 0, s[54:55]
	s_add_i32 m0, s98, 0x9800
	s_nop 0
	global_load_lds_dwordx4 v[38:39], off
	ds_read_b128 v[26:29], v250 offset:40960
	v_mfma_f32_32x32x16_bf16 a[0:15], v[48:51], v[30:33], a[0:15]
	v_lshl_add_u64 v[38:39], v[42:43], 0, s[82:83]
	s_add_i32 m0, s98, 0x1c00
	s_nop 0
	global_load_lds_dwordx4 v[38:39], off
	ds_read_b128 v[30:33], v250 offset:45056
	ds_read_b128 v[48:51], v249 offset:4096
	s_waitcnt lgkmcnt(4)
	v_mfma_f32_32x32x16_bf16 a[240:255], v[14:17], v[18:21], a[240:255]
	v_lshl_add_u64 v[38:39], v[44:45], 0, s[56:57]
	s_add_i32 m0, s98, 0x9c00
	s_nop 0
	global_load_lds_dwordx4 v[38:39], off
	s_waitcnt lgkmcnt(3)
	v_mfma_f32_32x32x16_bf16 a[176:191], v[14:17], v[22:25], a[176:191]
	s_waitcnt lgkmcnt(2)
	v_mfma_f32_32x32x16_bf16 a[112:127], v[14:17], v[26:29], a[112:127]
	s_waitcnt lgkmcnt(1)
	v_mfma_f32_32x32x16_bf16 a[48:63], v[14:17], v[30:33], a[48:63]
	ds_read_b128 v[14:17], v249 offset:8192
	s_waitcnt lgkmcnt(1)
	v_mfma_f32_32x32x16_bf16 a[224:239], v[48:51], v[18:21], a[224:239]
	v_mfma_f32_32x32x16_bf16 a[160:175], v[48:51], v[22:25], a[160:175]
	v_mfma_f32_32x32x16_bf16 a[96:111], v[48:51], v[26:29], a[96:111]
	v_mfma_f32_32x32x16_bf16 a[32:47], v[48:51], v[30:33], a[32:47]
	ds_read_b128 v[48:51], v249 offset:12288
	s_waitcnt lgkmcnt(1)
	v_mfma_f32_32x32x16_bf16 a[208:223], v[14:17], v[18:21], a[208:223]
	v_mfma_f32_32x32x16_bf16 a[144:159], v[14:17], v[22:25], a[144:159]
	v_mfma_f32_32x32x16_bf16 a[80:95], v[14:17], v[26:29], a[80:95]
	v_mfma_f32_32x32x16_bf16 a[16:31], v[14:17], v[30:33], a[16:31]
	v_lshl_or_b32 v250, v11, 1, s14
	v_add_u32_e32 v249, v250, v9
	v_add_u32_e32 v250, v250, v8
	ds_read_b128 v[14:17], v249
	s_waitcnt lgkmcnt(1)
	v_mfma_f32_32x32x16_bf16 a[192:207], v[48:51], v[18:21], a[192:207]
	ds_read_b128 v[18:21], v250 offset:32768
	v_mfma_f32_32x32x16_bf16 a[128:143], v[48:51], v[22:25], a[128:143]
	ds_read_b128 v[22:25], v250 offset:36864
	v_mfma_f32_32x32x16_bf16 a[64:79], v[48:51], v[26:29], a[64:79]
	ds_read_b128 v[26:29], v250 offset:40960
	v_mfma_f32_32x32x16_bf16 a[0:15], v[48:51], v[30:33], a[0:15]
	ds_read_b128 v[30:33], v250 offset:45056
	ds_read_b128 v[48:51], v249 offset:4096
	s_waitcnt lgkmcnt(4)
	v_mfma_f32_32x32x16_bf16 a[240:255], v[14:17], v[18:21], a[240:255]
	s_waitcnt lgkmcnt(3)
	v_mfma_f32_32x32x16_bf16 a[176:191], v[14:17], v[22:25], a[176:191]
	s_waitcnt lgkmcnt(2)
	v_mfma_f32_32x32x16_bf16 a[112:127], v[14:17], v[26:29], a[112:127]
	s_waitcnt lgkmcnt(1)
	v_mfma_f32_32x32x16_bf16 a[48:63], v[14:17], v[30:33], a[48:63]
	ds_read_b128 v[14:17], v249 offset:8192
	s_waitcnt lgkmcnt(1)
	v_mfma_f32_32x32x16_bf16 a[224:239], v[48:51], v[18:21], a[224:239]
	v_mfma_f32_32x32x16_bf16 a[160:175], v[48:51], v[22:25], a[160:175]
	v_mfma_f32_32x32x16_bf16 a[96:111], v[48:51], v[26:29], a[96:111]
	v_mfma_f32_32x32x16_bf16 a[32:47], v[48:51], v[30:33], a[32:47]
	ds_read_b128 v[48:51], v249 offset:12288
	s_waitcnt lgkmcnt(1)
	v_mfma_f32_32x32x16_bf16 a[208:223], v[14:17], v[18:21], a[208:223]
	v_mfma_f32_32x32x16_bf16 a[144:159], v[14:17], v[22:25], a[144:159]
	v_mfma_f32_32x32x16_bf16 a[80:95], v[14:17], v[26:29], a[80:95]
	v_mfma_f32_32x32x16_bf16 a[16:31], v[14:17], v[30:33], a[16:31]
	v_lshl_or_b32 v250, v10, 1, s14
	v_add_u32_e32 v249, v250, v9
	v_add_u32_e32 v250, v250, v8
	ds_read_b128 v[14:17], v249
	s_waitcnt lgkmcnt(1)
	v_mfma_f32_32x32x16_bf16 a[192:207], v[48:51], v[18:21], a[192:207]
	ds_read_b128 v[18:21], v250 offset:32768
	v_mfma_f32_32x32x16_bf16 a[128:143], v[48:51], v[22:25], a[128:143]
	ds_read_b128 v[22:25], v250 offset:36864
	v_mfma_f32_32x32x16_bf16 a[64:79], v[48:51], v[26:29], a[64:79]
	ds_read_b128 v[26:29], v250 offset:40960
	v_mfma_f32_32x32x16_bf16 a[0:15], v[48:51], v[30:33], a[0:15]
	ds_read_b128 v[30:33], v250 offset:45056
	ds_read_b128 v[48:51], v249 offset:4096
	s_waitcnt lgkmcnt(4)
	v_mfma_f32_32x32x16_bf16 a[240:255], v[14:17], v[18:21], a[240:255]
	s_waitcnt lgkmcnt(3)
	v_mfma_f32_32x32x16_bf16 a[176:191], v[14:17], v[22:25], a[176:191]
	s_waitcnt lgkmcnt(2)
	v_mfma_f32_32x32x16_bf16 a[112:127], v[14:17], v[26:29], a[112:127]
	s_waitcnt lgkmcnt(1)
	v_mfma_f32_32x32x16_bf16 a[48:63], v[14:17], v[30:33], a[48:63]
	ds_read_b128 v[14:17], v249 offset:8192
	s_waitcnt lgkmcnt(1)
	v_mfma_f32_32x32x16_bf16 a[224:239], v[48:51], v[18:21], a[224:239]
	v_mfma_f32_32x32x16_bf16 a[160:175], v[48:51], v[22:25], a[160:175]
	v_mfma_f32_32x32x16_bf16 a[96:111], v[48:51], v[26:29], a[96:111]
	v_mfma_f32_32x32x16_bf16 a[32:47], v[48:51], v[30:33], a[32:47]
	ds_read_b128 v[48:51], v249 offset:12288
	s_waitcnt lgkmcnt(1)
	v_mfma_f32_32x32x16_bf16 a[208:223], v[14:17], v[18:21], a[208:223]
	v_mfma_f32_32x32x16_bf16 a[144:159], v[14:17], v[22:25], a[144:159]
	v_mfma_f32_32x32x16_bf16 a[80:95], v[14:17], v[26:29], a[80:95]
	v_mfma_f32_32x32x16_bf16 a[16:31], v[14:17], v[30:33], a[16:31]
	s_waitcnt vmcnt(0)
	s_waitcnt vmcnt(0) lgkmcnt(0)
	s_barrier
	s_add_u32 s4, s4, 0x80
	s_addc_u32 s5, s5, 0
	s_add_i32 s11, s11, 0x8000
	s_cmpk_lg_i32 s4, 0x780
	v_mfma_f32_32x32x16_bf16 a[192:207], v[48:51], v[18:21], a[192:207]
	v_mfma_f32_32x32x16_bf16 a[128:143], v[48:51], v[22:25], a[128:143]
	v_mfma_f32_32x32x16_bf16 a[64:79], v[48:51], v[26:29], a[64:79]
	v_mfma_f32_32x32x16_bf16 a[0:15], v[48:51], v[30:33], a[0:15]
	s_cbranch_scc1 .LBB0_208
	v_lshlrev_b32_e32 v13, 1, v13
	s_mov_b32 s4, 0x10000
	s_mov_b32 s5, 0x18000
	v_add3_u32 v18, v9, v13, s4
	v_add3_u32 v13, v8, v13, s5
	ds_read_b128 v[0:3], v18
	ds_read_b128 v[4:7], v18 offset:4096
	ds_read_b128 v[14:17], v18 offset:8192
	ds_read_b128 v[18:21], v18 offset:12288
	ds_read_b128 v[22:25], v13
	ds_read_b128 v[26:29], v13 offset:4096
	ds_read_b128 v[30:33], v13 offset:8192
	ds_read_b128 v[34:37], v13 offset:12288
	s_waitcnt lgkmcnt(3)
	v_mfma_f32_32x32x16_bf16 a[240:255], v[0:3], v[22:25], a[240:255]
	v_lshlrev_b32_e32 v11, 1, v11
	s_waitcnt lgkmcnt(2)
	v_mfma_f32_32x32x16_bf16 a[176:191], v[0:3], v[26:29], a[176:191]
	s_waitcnt lgkmcnt(1)
	v_mfma_f32_32x32x16_bf16 a[112:127], v[0:3], v[30:33], a[112:127]
	s_waitcnt lgkmcnt(0)
	v_mfma_f32_32x32x16_bf16 a[48:63], v[0:3], v[34:37], a[48:63]
	v_mfma_f32_32x32x16_bf16 a[192:207], v[18:21], v[22:25], a[192:207]
	v_mfma_f32_32x32x16_bf16 a[128:143], v[18:21], v[26:29], a[128:143]
	v_mfma_f32_32x32x16_bf16 a[64:79], v[18:21], v[30:33], a[64:79]
	v_mfma_f32_32x32x16_bf16 a[0:15], v[18:21], v[34:37], a[0:15]
	v_lshlrev_b32_e32 v20, 1, v12
	v_mfma_f32_32x32x16_bf16 a[96:111], v[4:7], v[30:33], a[96:111]
	v_mfma_f32_32x32x16_bf16 a[208:223], v[14:17], v[22:25], a[208:223]
	v_mfma_f32_32x32x16_bf16 a[144:159], v[14:17], v[26:29], a[144:159]
	v_mfma_f32_32x32x16_bf16 a[80:95], v[14:17], v[30:33], a[80:95]
	v_add3_u32 v32, v8, v20, s5
	v_mfma_f32_32x32x16_bf16 a[16:31], v[14:17], v[34:37], a[16:31]
	v_add3_u32 v16, v9, v20, s4
	v_mfma_f32_32x32x16_bf16 a[224:239], v[4:7], v[22:25], a[224:239]
	v_mfma_f32_32x32x16_bf16 a[160:175], v[4:7], v[26:29], a[160:175]
	v_mfma_f32_32x32x16_bf16 a[32:47], v[4:7], v[34:37], a[32:47]
	ds_read_b128 v[0:3], v16
	ds_read_b128 v[4:7], v16 offset:4096
	ds_read_b128 v[12:15], v16 offset:8192
	ds_read_b128 v[16:19], v16 offset:12288
	ds_read_b128 v[20:23], v32
	ds_read_b128 v[24:27], v32 offset:4096
	ds_read_b128 v[28:31], v32 offset:8192
	ds_read_b128 v[32:35], v32 offset:12288
	s_waitcnt lgkmcnt(3)
	v_mfma_f32_32x32x16_bf16 a[240:255], v[0:3], v[20:23], a[240:255]
	s_waitcnt lgkmcnt(2)
	v_mfma_f32_32x32x16_bf16 a[176:191], v[0:3], v[24:27], a[176:191]
	s_waitcnt lgkmcnt(1)
	v_mfma_f32_32x32x16_bf16 a[112:127], v[0:3], v[28:31], a[112:127]
	s_waitcnt lgkmcnt(0)
	v_mfma_f32_32x32x16_bf16 a[48:63], v[0:3], v[32:35], a[48:63]
	v_mfma_f32_32x32x16_bf16 a[192:207], v[16:19], v[20:23], a[192:207]
	v_mfma_f32_32x32x16_bf16 a[128:143], v[16:19], v[24:27], a[128:143]
	v_mfma_f32_32x32x16_bf16 a[64:79], v[16:19], v[28:31], a[64:79]
	v_mfma_f32_32x32x16_bf16 a[0:15], v[16:19], v[32:35], a[0:15]
	v_add3_u32 v16, v9, v11, s4
	v_add3_u32 v11, v8, v11, s5
	v_mfma_f32_32x32x16_bf16 a[224:239], v[4:7], v[20:23], a[224:239]
	v_mfma_f32_32x32x16_bf16 a[160:175], v[4:7], v[24:27], a[160:175]
	v_mfma_f32_32x32x16_bf16 a[96:111], v[4:7], v[28:31], a[96:111]
	v_mfma_f32_32x32x16_bf16 a[32:47], v[4:7], v[32:35], a[32:47]
	v_mfma_f32_32x32x16_bf16 a[208:223], v[12:15], v[20:23], a[208:223]
	v_mfma_f32_32x32x16_bf16 a[144:159], v[12:15], v[24:27], a[144:159]
	v_mfma_f32_32x32x16_bf16 a[80:95], v[12:15], v[28:31], a[80:95]
	v_mfma_f32_32x32x16_bf16 a[16:31], v[12:15], v[32:35], a[16:31]
	ds_read_b128 v[0:3], v16
	ds_read_b128 v[4:7], v16 offset:4096
	ds_read_b128 v[12:15], v16 offset:8192
	ds_read_b128 v[16:19], v16 offset:12288
	ds_read_b128 v[20:23], v11
	ds_read_b128 v[24:27], v11 offset:4096
	ds_read_b128 v[28:31], v11 offset:8192
	ds_read_b128 v[32:35], v11 offset:12288
	s_waitcnt lgkmcnt(3)
	v_mfma_f32_32x32x16_bf16 a[240:255], v[0:3], v[20:23], a[240:255]
	s_waitcnt lgkmcnt(2)
	v_mfma_f32_32x32x16_bf16 a[176:191], v[0:3], v[24:27], a[176:191]
	s_waitcnt lgkmcnt(1)
	v_mfma_f32_32x32x16_bf16 a[112:127], v[0:3], v[28:31], a[112:127]
	s_waitcnt lgkmcnt(0)
	v_mfma_f32_32x32x16_bf16 a[48:63], v[0:3], v[32:35], a[48:63]
	v_mfma_f32_32x32x16_bf16 a[192:207], v[16:19], v[20:23], a[192:207]
	v_mfma_f32_32x32x16_bf16 a[128:143], v[16:19], v[24:27], a[128:143]
	v_mfma_f32_32x32x16_bf16 a[64:79], v[16:19], v[28:31], a[64:79]
	v_mfma_f32_32x32x16_bf16 a[0:15], v[16:19], v[32:35], a[0:15]
	v_lshlrev_b32_e32 v18, 1, v10
	v_add3_u32 v9, v9, v18, s4
	v_add3_u32 v8, v8, v18, s5
	s_mov_b32 s5, 0
	s_mov_b32 s4, 0
	v_mfma_f32_32x32x16_bf16 a[224:239], v[4:7], v[20:23], a[224:239]
	v_mfma_f32_32x32x16_bf16 a[160:175], v[4:7], v[24:27], a[160:175]
	v_mfma_f32_32x32x16_bf16 a[96:111], v[4:7], v[28:31], a[96:111]
	v_mfma_f32_32x32x16_bf16 a[32:47], v[4:7], v[32:35], a[32:47]
	v_mfma_f32_32x32x16_bf16 a[208:223], v[12:15], v[20:23], a[208:223]
	v_mfma_f32_32x32x16_bf16 a[144:159], v[12:15], v[24:27], a[144:159]
	v_mfma_f32_32x32x16_bf16 a[80:95], v[12:15], v[28:31], a[80:95]
	v_mfma_f32_32x32x16_bf16 a[16:31], v[12:15], v[32:35], a[16:31]
	ds_read_b128 v[0:3], v9
	ds_read_b128 v[4:7], v9 offset:4096
	ds_read_b128 v[10:13], v9 offset:8192
	ds_read_b128 v[14:17], v9 offset:12288
	ds_read_b128 v[18:21], v8
	ds_read_b128 v[22:25], v8 offset:4096
	ds_read_b128 v[26:29], v8 offset:8192
	ds_read_b128 v[30:33], v8 offset:12288
	s_waitcnt vmcnt(0)
	s_waitcnt lgkmcnt(0)
	s_barrier
	v_mfma_f32_32x32x16_bf16 a[240:255], v[0:3], v[18:21], a[240:255]
	v_mfma_f32_32x32x16_bf16 a[176:191], v[0:3], v[22:25], a[176:191]
	v_mfma_f32_32x32x16_bf16 a[112:127], v[0:3], v[26:29], a[112:127]
	v_mfma_f32_32x32x16_bf16 a[48:63], v[0:3], v[30:33], a[48:63]
	v_mbcnt_lo_u32_b32 v0, -1, s5
	v_mbcnt_hi_u32_b32 v0, -1, v0
	v_or_b32_e32 v1, s60, v0
	v_and_b32_e32 v2, 31, v0
	v_lshlrev_b32_e32 v1, 1, v1
	v_and_or_b32 v1, v1, s16, v2
	v_mov_b32_e32 v2, s60
	s_mov_b32 s5, 0x7fffff80
	v_bitop3_b32 v2, v0, s5, v2 bitop3:0xc8
	v_lshrrev_b32_e32 v0, 2, v0
	v_and_b32_e32 v0, 8, v0
	v_lshl_or_b32 v0, v2, 1, v0
	v_mad_u32_u24 v0, v1, s25, v0
	v_accvgpr_read_b32 v1, a240
	v_mul_f32_e32 v1, 0xbfb8aa3b, v1
	v_exp_f32_e32 v1, v1
	v_mfma_f32_32x32x16_bf16 a[224:239], v[4:7], v[18:21], a[224:239]
	v_add_f32_e32 v1, 1.0, v1
	v_rcp_f32_e32 v2, v1
	v_accvgpr_read_b32 v1, a241
	v_mul_f32_e32 v1, 0xbfb8aa3b, v1
	v_exp_f32_e32 v1, v1
	v_mfma_f32_32x32x16_bf16 a[160:175], v[4:7], v[22:25], a[160:175]
	v_add_f32_e32 v1, 1.0, v1
	v_rcp_f32_e32 v3, v1
	v_mfma_f32_32x32x16_bf16 a[96:111], v[4:7], v[26:29], a[96:111]
	v_mfma_f32_32x32x16_bf16 a[32:47], v[4:7], v[30:33], a[32:47]
	v_accvgpr_read_b32 v4, a240
	v_accvgpr_read_b32 v5, a241
	v_mul_f32_e64 v2, v4, v2
	v_mul_f32_e64 v3, v5, v3
	v_accvgpr_read_b32 v4, a242
	v_mul_f32_e32 v1, 0xbfb8aa3b, v4
	v_exp_f32_e32 v1, v1
	v_accvgpr_read_b32 v5, a243
	v_cvt_pk_bf16_f32 v2, v2, v3
	v_mfma_f32_32x32x16_bf16 a[208:223], v[10:13], v[18:21], a[208:223]
	v_add_f32_e32 v1, 1.0, v1
	v_rcp_f32_e32 v6, v1
	v_mul_f32_e32 v1, 0xbfb8aa3b, v5
	v_exp_f32_e32 v1, v1
	s_nop 0
	v_add_f32_e32 v1, 1.0, v1
	v_rcp_f32_e32 v7, v1
	v_mfma_f32_32x32x16_bf16 a[192:207], v[14:17], v[18:21], a[192:207]
	v_mul_f32_e64 v4, v4, v6
	v_mul_f32_e64 v5, v5, v7
	v_cvt_pk_bf16_f32 v3, v4, v5
	v_accvgpr_read_b32 v4, a244
	v_mul_f32_e32 v1, 0xbfb8aa3b, v4
	v_exp_f32_e32 v1, v1
	v_accvgpr_read_b32 v5, a245
	v_mfma_f32_32x32x16_bf16 a[144:159], v[10:13], v[22:25], a[144:159]
	v_add_f32_e32 v1, 1.0, v1
	v_rcp_f32_e32 v6, v1
	v_mul_f32_e32 v1, 0xbfb8aa3b, v5
	v_exp_f32_e32 v1, v1
	s_nop 0
	v_add_f32_e32 v1, 1.0, v1
	v_rcp_f32_e32 v7, v1
	v_mfma_f32_32x32x16_bf16 a[80:95], v[10:13], v[26:29], a[80:95]
	v_mul_f32_e64 v4, v4, v6
	v_mul_f32_e64 v5, v5, v7
	v_accvgpr_read_b32 v6, a246
	v_mul_f32_e32 v1, 0xbfb8aa3b, v6
	v_exp_f32_e32 v1, v1
	v_accvgpr_read_b32 v7, a247
	v_cvt_pk_bf16_f32 v4, v4, v5
	v_mfma_f32_32x32x16_bf16 a[16:31], v[10:13], v[30:33], a[16:31]
	v_add_f32_e32 v1, 1.0, v1
	v_rcp_f32_e32 v8, v1
	v_mul_f32_e32 v1, 0xbfb8aa3b, v7
	v_exp_f32_e32 v1, v1
	s_nop 0
	v_add_f32_e32 v1, 1.0, v1
	v_rcp_f32_e32 v9, v1
	v_mfma_f32_32x32x16_bf16 a[128:143], v[14:17], v[22:25], a[128:143]
	v_mul_f32_e64 v6, v6, v8
	v_mul_f32_e64 v7, v7, v9
	v_cvt_pk_bf16_f32 v5, v6, v7
	ds_write2_b64 v0, v[2:3], v[4:5] offset1:2
	v_accvgpr_read_b32 v2, a248
	v_mul_f32_e32 v1, 0xbfb8aa3b, v2
	v_exp_f32_e32 v1, v1
	v_accvgpr_read_b32 v3, a249
	v_mfma_f32_32x32x16_bf16 a[64:79], v[14:17], v[26:29], a[64:79]
	v_add_f32_e32 v1, 1.0, v1
	v_rcp_f32_e32 v4, v1
	v_mul_f32_e32 v1, 0xbfb8aa3b, v3
	v_exp_f32_e32 v1, v1
	s_nop 0
	v_add_f32_e32 v1, 1.0, v1
	v_rcp_f32_e32 v5, v1
	v_mfma_f32_32x32x16_bf16 a[0:15], v[14:17], v[30:33], a[0:15]
	v_mul_f32_e64 v2, v2, v4
	v_mul_f32_e64 v3, v3, v5
	v_accvgpr_read_b32 v4, a250
	v_mul_f32_e32 v1, 0xbfb8aa3b, v4
	v_exp_f32_e32 v1, v1
	v_accvgpr_read_b32 v5, a251
	v_cvt_pk_bf16_f32 v2, v2, v3
	v_add_f32_e32 v1, 1.0, v1
	v_rcp_f32_e32 v6, v1
	v_mul_f32_e32 v1, 0xbfb8aa3b, v5
	v_exp_f32_e32 v1, v1
	s_nop 0
	v_add_f32_e32 v1, 1.0, v1
	v_rcp_f32_e32 v7, v1
	s_nop 0
	v_pk_mul_f32 v[4:5], v[4:5], v[6:7]
	s_nop 0
	v_cvt_pk_bf16_f32 v3, v4, v5
	v_accvgpr_read_b32 v4, a252
	v_mul_f32_e32 v1, 0xbfb8aa3b, v4
	v_exp_f32_e32 v1, v1
	v_accvgpr_read_b32 v5, a253
	v_add_f32_e32 v1, 1.0, v1
	v_rcp_f32_e32 v6, v1
	v_mul_f32_e32 v1, 0xbfb8aa3b, v5
	v_exp_f32_e32 v1, v1
	s_nop 0
	v_add_f32_e32 v1, 1.0, v1
	v_rcp_f32_e32 v7, v1
	s_nop 0
	v_pk_mul_f32 v[4:5], v[4:5], v[6:7]
	v_accvgpr_read_b32 v6, a254
	v_mul_f32_e32 v1, 0xbfb8aa3b, v6
	v_exp_f32_e32 v1, v1
	v_accvgpr_read_b32 v7, a255
	v_cvt_pk_bf16_f32 v4, v4, v5
	v_add_f32_e32 v1, 1.0, v1
	v_rcp_f32_e32 v8, v1
	v_mul_f32_e32 v1, 0xbfb8aa3b, v7
	v_exp_f32_e32 v1, v1
	s_nop 0
	v_add_f32_e32 v1, 1.0, v1
	v_rcp_f32_e32 v9, v1
	v_accvgpr_read_b32 v1, a224
	v_mul_f32_e32 v1, 0xbfb8aa3b, v1
	v_exp_f32_e32 v1, v1
	v_pk_mul_f32 v[6:7], v[6:7], v[8:9]
	v_add_f32_e32 v1, 1.0, v1
	v_cvt_pk_bf16_f32 v5, v6, v7
	ds_write2_b64 v0, v[2:3], v[4:5] offset0:4 offset1:6
	v_rcp_f32_e32 v2, v1
	v_accvgpr_read_b32 v1, a225
	v_mul_f32_e32 v1, 0xbfb8aa3b, v1
	v_exp_f32_e32 v1, v1
	v_accvgpr_read_b32 v4, a224
	v_accvgpr_read_b32 v5, a225
	v_add_f32_e32 v1, 1.0, v1
	v_rcp_f32_e32 v3, v1
	s_nop 0
	v_pk_mul_f32 v[2:3], v[4:5], v[2:3]
	v_accvgpr_read_b32 v4, a226
	v_mul_f32_e32 v1, 0xbfb8aa3b, v4
	v_exp_f32_e32 v1, v1
	v_accvgpr_read_b32 v5, a227
	v_cvt_pk_bf16_f32 v2, v2, v3
	v_add_f32_e32 v1, 1.0, v1
	v_rcp_f32_e32 v6, v1
	v_mul_f32_e32 v1, 0xbfb8aa3b, v5
	v_exp_f32_e32 v1, v1
	s_nop 0
	v_add_f32_e32 v1, 1.0, v1
	v_rcp_f32_e32 v7, v1
	s_nop 0
	v_pk_mul_f32 v[4:5], v[4:5], v[6:7]
	s_nop 0
	v_cvt_pk_bf16_f32 v3, v4, v5
	v_accvgpr_read_b32 v4, a228
	v_mul_f32_e32 v1, 0xbfb8aa3b, v4
	v_exp_f32_e32 v1, v1
	v_accvgpr_read_b32 v5, a229
	v_add_f32_e32 v1, 1.0, v1
	v_rcp_f32_e32 v6, v1
	v_mul_f32_e32 v1, 0xbfb8aa3b, v5
	v_exp_f32_e32 v1, v1
	s_nop 0
	v_add_f32_e32 v1, 1.0, v1
	v_rcp_f32_e32 v7, v1
	s_nop 0
	v_pk_mul_f32 v[4:5], v[4:5], v[6:7]
	v_accvgpr_read_b32 v6, a230
	v_mul_f32_e32 v1, 0xbfb8aa3b, v6
	v_exp_f32_e32 v1, v1
	v_accvgpr_read_b32 v7, a231
	v_cvt_pk_bf16_f32 v4, v4, v5
	v_add_f32_e32 v1, 1.0, v1
	v_rcp_f32_e32 v8, v1
	v_mul_f32_e32 v1, 0xbfb8aa3b, v7
	v_exp_f32_e32 v1, v1
	s_nop 0
	v_add_f32_e32 v1, 1.0, v1
	v_rcp_f32_e32 v9, v1
	s_nop 0
	v_pk_mul_f32 v[6:7], v[6:7], v[8:9]
	s_nop 0
	v_cvt_pk_bf16_f32 v5, v6, v7
	ds_write2_b64 v0, v[2:3], v[4:5] offset0:8 offset1:10
	v_accvgpr_read_b32 v2, a232
	v_mul_f32_e32 v1, 0xbfb8aa3b, v2
	v_exp_f32_e32 v1, v1
	v_accvgpr_read_b32 v3, a233
	v_add_f32_e32 v1, 1.0, v1
	v_rcp_f32_e32 v4, v1
	v_mul_f32_e32 v1, 0xbfb8aa3b, v3
	v_exp_f32_e32 v1, v1
	s_nop 0
	v_add_f32_e32 v1, 1.0, v1
	v_rcp_f32_e32 v5, v1
	s_nop 0
	v_pk_mul_f32 v[2:3], v[2:3], v[4:5]
	v_accvgpr_read_b32 v4, a234
	v_mul_f32_e32 v1, 0xbfb8aa3b, v4
	v_exp_f32_e32 v1, v1
	v_accvgpr_read_b32 v5, a235
	v_cvt_pk_bf16_f32 v2, v2, v3
	v_add_f32_e32 v1, 1.0, v1
	v_rcp_f32_e32 v6, v1
	v_mul_f32_e32 v1, 0xbfb8aa3b, v5
	v_exp_f32_e32 v1, v1
	s_nop 0
	v_add_f32_e32 v1, 1.0, v1
	v_rcp_f32_e32 v7, v1
	s_nop 0
	v_pk_mul_f32 v[4:5], v[4:5], v[6:7]
	s_nop 0
	v_cvt_pk_bf16_f32 v3, v4, v5
	v_accvgpr_read_b32 v4, a236
	v_mul_f32_e32 v1, 0xbfb8aa3b, v4
	v_exp_f32_e32 v1, v1
	v_accvgpr_read_b32 v5, a237
	v_add_f32_e32 v1, 1.0, v1
	v_rcp_f32_e32 v6, v1
	v_mul_f32_e32 v1, 0xbfb8aa3b, v5
	v_exp_f32_e32 v1, v1
	s_nop 0
	v_add_f32_e32 v1, 1.0, v1
	v_rcp_f32_e32 v7, v1
	s_nop 0
	v_pk_mul_f32 v[4:5], v[4:5], v[6:7]
	v_accvgpr_read_b32 v6, a238
	v_mul_f32_e32 v1, 0xbfb8aa3b, v6
	v_exp_f32_e32 v1, v1
	v_accvgpr_read_b32 v7, a239
	v_cvt_pk_bf16_f32 v4, v4, v5
	v_add_f32_e32 v1, 1.0, v1
	v_rcp_f32_e32 v8, v1
	v_mul_f32_e32 v1, 0xbfb8aa3b, v7
	v_exp_f32_e32 v1, v1
	s_nop 0
	v_add_f32_e32 v1, 1.0, v1
	v_rcp_f32_e32 v9, v1
	v_accvgpr_read_b32 v1, a208
	v_mul_f32_e32 v1, 0xbfb8aa3b, v1
	v_exp_f32_e32 v1, v1
	v_pk_mul_f32 v[6:7], v[6:7], v[8:9]
	v_add_f32_e32 v1, 1.0, v1
	v_cvt_pk_bf16_f32 v5, v6, v7
	ds_write2_b64 v0, v[2:3], v[4:5] offset0:12 offset1:14
	v_rcp_f32_e32 v2, v1
	v_accvgpr_read_b32 v1, a209
	v_mul_f32_e32 v1, 0xbfb8aa3b, v1
	v_exp_f32_e32 v1, v1
	v_accvgpr_read_b32 v4, a208
	v_accvgpr_read_b32 v5, a209
	v_add_f32_e32 v1, 1.0, v1
	v_rcp_f32_e32 v3, v1
	s_nop 0
	v_pk_mul_f32 v[2:3], v[4:5], v[2:3]
	v_accvgpr_read_b32 v4, a210
	v_mul_f32_e32 v1, 0xbfb8aa3b, v4
	v_exp_f32_e32 v1, v1
	v_accvgpr_read_b32 v5, a211
	v_cvt_pk_bf16_f32 v2, v2, v3
	v_add_f32_e32 v1, 1.0, v1
	v_rcp_f32_e32 v6, v1
	v_mul_f32_e32 v1, 0xbfb8aa3b, v5
	v_exp_f32_e32 v1, v1
	s_nop 0
	v_add_f32_e32 v1, 1.0, v1
	v_rcp_f32_e32 v7, v1
	s_nop 0
	v_pk_mul_f32 v[4:5], v[4:5], v[6:7]
	s_nop 0
	v_cvt_pk_bf16_f32 v3, v4, v5
	v_accvgpr_read_b32 v4, a212
	v_mul_f32_e32 v1, 0xbfb8aa3b, v4
	v_exp_f32_e32 v1, v1
	v_accvgpr_read_b32 v5, a213
	v_add_f32_e32 v1, 1.0, v1
	v_rcp_f32_e32 v6, v1
	v_mul_f32_e32 v1, 0xbfb8aa3b, v5
	v_exp_f32_e32 v1, v1
	s_nop 0
	v_add_f32_e32 v1, 1.0, v1
	v_rcp_f32_e32 v7, v1
	s_nop 0
	v_pk_mul_f32 v[4:5], v[4:5], v[6:7]
	v_accvgpr_read_b32 v6, a214
	v_mul_f32_e32 v1, 0xbfb8aa3b, v6
	v_exp_f32_e32 v1, v1
	v_accvgpr_read_b32 v7, a215
	v_cvt_pk_bf16_f32 v4, v4, v5
	v_add_f32_e32 v1, 1.0, v1
	v_rcp_f32_e32 v8, v1
	v_mul_f32_e32 v1, 0xbfb8aa3b, v7
	v_exp_f32_e32 v1, v1
	s_nop 0
	v_add_f32_e32 v1, 1.0, v1
	v_rcp_f32_e32 v9, v1
	s_nop 0
	v_pk_mul_f32 v[6:7], v[6:7], v[8:9]
	s_nop 0
	v_cvt_pk_bf16_f32 v5, v6, v7
	ds_write2_b64 v0, v[2:3], v[4:5] offset0:16 offset1:18
	v_accvgpr_read_b32 v2, a216
	v_mul_f32_e32 v1, 0xbfb8aa3b, v2
	v_exp_f32_e32 v1, v1
	v_accvgpr_read_b32 v3, a217
	v_add_f32_e32 v1, 1.0, v1
	v_rcp_f32_e32 v4, v1
	v_mul_f32_e32 v1, 0xbfb8aa3b, v3
	v_exp_f32_e32 v1, v1
	s_nop 0
	v_add_f32_e32 v1, 1.0, v1
	v_rcp_f32_e32 v5, v1
	s_nop 0
	v_pk_mul_f32 v[2:3], v[2:3], v[4:5]
	v_accvgpr_read_b32 v4, a218
	v_mul_f32_e32 v1, 0xbfb8aa3b, v4
	v_exp_f32_e32 v1, v1
	v_accvgpr_read_b32 v5, a219
	v_cvt_pk_bf16_f32 v2, v2, v3
	v_add_f32_e32 v1, 1.0, v1
	v_rcp_f32_e32 v6, v1
	v_mul_f32_e32 v1, 0xbfb8aa3b, v5
	v_exp_f32_e32 v1, v1
	s_nop 0
	v_add_f32_e32 v1, 1.0, v1
	v_rcp_f32_e32 v7, v1
	s_nop 0
	v_pk_mul_f32 v[4:5], v[4:5], v[6:7]
	s_nop 0
	v_cvt_pk_bf16_f32 v3, v4, v5
	v_accvgpr_read_b32 v4, a220
	v_mul_f32_e32 v1, 0xbfb8aa3b, v4
	v_exp_f32_e32 v1, v1
	v_accvgpr_read_b32 v5, a221
	v_add_f32_e32 v1, 1.0, v1
	v_rcp_f32_e32 v6, v1
	v_mul_f32_e32 v1, 0xbfb8aa3b, v5
	v_exp_f32_e32 v1, v1
	s_nop 0
	v_add_f32_e32 v1, 1.0, v1
	v_rcp_f32_e32 v7, v1
	s_nop 0
	v_pk_mul_f32 v[4:5], v[4:5], v[6:7]
	v_accvgpr_read_b32 v6, a222
	v_mul_f32_e32 v1, 0xbfb8aa3b, v6
	v_exp_f32_e32 v1, v1
	v_accvgpr_read_b32 v7, a223
	v_cvt_pk_bf16_f32 v4, v4, v5
	v_add_f32_e32 v1, 1.0, v1
	v_rcp_f32_e32 v8, v1
	v_mul_f32_e32 v1, 0xbfb8aa3b, v7
	v_exp_f32_e32 v1, v1
	s_nop 0
	v_add_f32_e32 v1, 1.0, v1
	v_rcp_f32_e32 v9, v1
	v_accvgpr_read_b32 v1, a192
	v_mul_f32_e32 v1, 0xbfb8aa3b, v1
	v_exp_f32_e32 v1, v1
	v_pk_mul_f32 v[6:7], v[6:7], v[8:9]
	v_add_f32_e32 v1, 1.0, v1
	v_cvt_pk_bf16_f32 v5, v6, v7
	ds_write2_b64 v0, v[2:3], v[4:5] offset0:20 offset1:22
	v_rcp_f32_e32 v2, v1
	v_accvgpr_read_b32 v1, a193
	v_mul_f32_e32 v1, 0xbfb8aa3b, v1
	v_exp_f32_e32 v1, v1
	v_accvgpr_read_b32 v4, a192
	v_accvgpr_read_b32 v5, a193
	v_add_f32_e32 v1, 1.0, v1
	v_rcp_f32_e32 v3, v1
	s_nop 0
	v_pk_mul_f32 v[2:3], v[4:5], v[2:3]
	v_accvgpr_read_b32 v4, a194
	v_mul_f32_e32 v1, 0xbfb8aa3b, v4
	v_exp_f32_e32 v1, v1
	v_accvgpr_read_b32 v5, a195
	v_cvt_pk_bf16_f32 v2, v2, v3
	v_add_f32_e32 v1, 1.0, v1
	v_rcp_f32_e32 v6, v1
	v_mul_f32_e32 v1, 0xbfb8aa3b, v5
	v_exp_f32_e32 v1, v1
	s_nop 0
	v_add_f32_e32 v1, 1.0, v1
	v_rcp_f32_e32 v7, v1
	s_nop 0
	v_pk_mul_f32 v[4:5], v[4:5], v[6:7]
	s_nop 0
	v_cvt_pk_bf16_f32 v3, v4, v5
	v_accvgpr_read_b32 v4, a196
	v_mul_f32_e32 v1, 0xbfb8aa3b, v4
	v_exp_f32_e32 v1, v1
	v_accvgpr_read_b32 v5, a197
	v_add_f32_e32 v1, 1.0, v1
	v_rcp_f32_e32 v6, v1
	v_mul_f32_e32 v1, 0xbfb8aa3b, v5
	v_exp_f32_e32 v1, v1
	s_nop 0
	v_add_f32_e32 v1, 1.0, v1
	v_rcp_f32_e32 v7, v1
	s_nop 0
	v_pk_mul_f32 v[4:5], v[4:5], v[6:7]
	v_accvgpr_read_b32 v6, a198
	v_mul_f32_e32 v1, 0xbfb8aa3b, v6
	v_exp_f32_e32 v1, v1
	v_accvgpr_read_b32 v7, a199
	v_cvt_pk_bf16_f32 v4, v4, v5
	v_add_f32_e32 v1, 1.0, v1
	v_rcp_f32_e32 v8, v1
	v_mul_f32_e32 v1, 0xbfb8aa3b, v7
	v_exp_f32_e32 v1, v1
	s_nop 0
	v_add_f32_e32 v1, 1.0, v1
	v_rcp_f32_e32 v9, v1
	s_nop 0
	v_pk_mul_f32 v[6:7], v[6:7], v[8:9]
	s_nop 0
	v_cvt_pk_bf16_f32 v5, v6, v7
	ds_write2_b64 v0, v[2:3], v[4:5] offset0:24 offset1:26
	v_accvgpr_read_b32 v2, a200
	v_mul_f32_e32 v1, 0xbfb8aa3b, v2
	v_exp_f32_e32 v1, v1
	v_accvgpr_read_b32 v3, a201
	v_add_f32_e32 v1, 1.0, v1
	v_rcp_f32_e32 v4, v1
	v_mul_f32_e32 v1, 0xbfb8aa3b, v3
	v_exp_f32_e32 v1, v1
	s_nop 0
	v_add_f32_e32 v1, 1.0, v1
	v_rcp_f32_e32 v5, v1
	s_nop 0
	v_pk_mul_f32 v[2:3], v[2:3], v[4:5]
	v_accvgpr_read_b32 v4, a202
	v_mul_f32_e32 v1, 0xbfb8aa3b, v4
	v_exp_f32_e32 v1, v1
	v_accvgpr_read_b32 v5, a203
	v_cvt_pk_bf16_f32 v2, v2, v3
	v_add_f32_e32 v1, 1.0, v1
	v_rcp_f32_e32 v6, v1
	v_mul_f32_e32 v1, 0xbfb8aa3b, v5
	v_exp_f32_e32 v1, v1
	s_nop 0
	v_add_f32_e32 v1, 1.0, v1
	v_rcp_f32_e32 v7, v1
	s_nop 0
	v_pk_mul_f32 v[4:5], v[4:5], v[6:7]
	s_nop 0
	v_cvt_pk_bf16_f32 v3, v4, v5
	v_accvgpr_read_b32 v4, a204
	v_mul_f32_e32 v1, 0xbfb8aa3b, v4
	v_exp_f32_e32 v1, v1
	v_accvgpr_read_b32 v5, a205
	v_add_f32_e32 v1, 1.0, v1
	v_rcp_f32_e32 v6, v1
	v_mul_f32_e32 v1, 0xbfb8aa3b, v5
	v_exp_f32_e32 v1, v1
	s_nop 0
	v_add_f32_e32 v1, 1.0, v1
	v_rcp_f32_e32 v7, v1
	s_nop 0
	v_pk_mul_f32 v[4:5], v[4:5], v[6:7]
	v_accvgpr_read_b32 v6, a206
	v_mul_f32_e32 v1, 0xbfb8aa3b, v6
	v_exp_f32_e32 v1, v1
	v_accvgpr_read_b32 v7, a207
	v_cvt_pk_bf16_f32 v4, v4, v5
	v_add_f32_e32 v1, 1.0, v1
	v_rcp_f32_e32 v8, v1
	v_mul_f32_e32 v1, 0xbfb8aa3b, v7
	v_exp_f32_e32 v1, v1
	s_nop 0
	v_add_f32_e32 v1, 1.0, v1
	v_rcp_f32_e32 v9, v1
	s_nop 0
	v_pk_mul_f32 v[6:7], v[6:7], v[8:9]
	s_nop 0
	v_cvt_pk_bf16_f32 v5, v6, v7
	ds_write2_b64 v0, v[2:3], v[4:5] offset0:28 offset1:30
	v_accvgpr_read_b32 v1, a176
	v_mul_f32_e32 v1, 0xbfb8aa3b, v1
	v_exp_f32_e32 v1, v1
	v_accvgpr_read_b32 v4, a176
	v_accvgpr_read_b32 v5, a177
	v_add_f32_e32 v1, 1.0, v1
	v_rcp_f32_e32 v2, v1
	v_accvgpr_read_b32 v1, a177
	v_mul_f32_e32 v1, 0xbfb8aa3b, v1
	v_exp_f32_e32 v1, v1
	s_nop 0
	v_add_f32_e32 v1, 1.0, v1
	v_rcp_f32_e32 v3, v1
	s_nop 0
	v_pk_mul_f32 v[2:3], v[4:5], v[2:3]
	v_accvgpr_read_b32 v4, a178
	v_mul_f32_e32 v1, 0xbfb8aa3b, v4
	v_exp_f32_e32 v1, v1
	v_accvgpr_read_b32 v5, a179
	v_cvt_pk_bf16_f32 v2, v2, v3
	v_add_f32_e32 v1, 1.0, v1
	v_rcp_f32_e32 v6, v1
	v_mul_f32_e32 v1, 0xbfb8aa3b, v5
	v_exp_f32_e32 v1, v1
	s_nop 0
	v_add_f32_e32 v1, 1.0, v1
	v_rcp_f32_e32 v7, v1
	s_nop 0
	v_pk_mul_f32 v[4:5], v[4:5], v[6:7]
	s_nop 0
	v_cvt_pk_bf16_f32 v3, v4, v5
	v_accvgpr_read_b32 v4, a180
	v_mul_f32_e32 v1, 0xbfb8aa3b, v4
	v_exp_f32_e32 v1, v1
	v_accvgpr_read_b32 v5, a181
	v_add_f32_e32 v1, 1.0, v1
	v_rcp_f32_e32 v6, v1
	v_mul_f32_e32 v1, 0xbfb8aa3b, v5
	v_exp_f32_e32 v1, v1
	s_nop 0
	v_add_f32_e32 v1, 1.0, v1
	v_rcp_f32_e32 v7, v1
	s_nop 0
	v_pk_mul_f32 v[4:5], v[4:5], v[6:7]
	v_accvgpr_read_b32 v6, a182
	v_mul_f32_e32 v1, 0xbfb8aa3b, v6
	v_exp_f32_e32 v1, v1
	v_accvgpr_read_b32 v7, a183
	v_cvt_pk_bf16_f32 v4, v4, v5
	v_add_f32_e32 v1, 1.0, v1
	v_rcp_f32_e32 v8, v1
	v_mul_f32_e32 v1, 0xbfb8aa3b, v7
	v_exp_f32_e32 v1, v1
	s_nop 0
	v_add_f32_e32 v1, 1.0, v1
	v_rcp_f32_e32 v9, v1
	v_add_u32_e32 v1, 0x4000, v0
	v_pk_mul_f32 v[6:7], v[6:7], v[8:9]
	s_nop 0
	v_cvt_pk_bf16_f32 v5, v6, v7
	ds_write2_b64 v1, v[2:3], v[4:5] offset0:64 offset1:66
	v_accvgpr_read_b32 v2, a184
	v_mul_f32_e32 v3, 0xbfb8aa3b, v2
	v_exp_f32_e32 v3, v3
	s_nop 0
	v_add_f32_e32 v3, 1.0, v3
	v_rcp_f32_e32 v4, v3
	v_accvgpr_read_b32 v3, a185
	v_mul_f32_e32 v5, 0xbfb8aa3b, v3
	v_exp_f32_e32 v5, v5
	s_nop 0
	v_add_f32_e32 v5, 1.0, v5
	v_rcp_f32_e32 v5, v5
	s_nop 0
	v_pk_mul_f32 v[2:3], v[2:3], v[4:5]
	v_accvgpr_read_b32 v4, a186
	v_mul_f32_e32 v5, 0xbfb8aa3b, v4
	v_exp_f32_e32 v5, v5
	v_cvt_pk_bf16_f32 v2, v2, v3
	v_add_f32_e32 v5, 1.0, v5
	v_rcp_f32_e32 v6, v5
	v_accvgpr_read_b32 v5, a187
	v_mul_f32_e32 v7, 0xbfb8aa3b, v5
	v_exp_f32_e32 v7, v7
	s_nop 0
	v_add_f32_e32 v7, 1.0, v7
	v_rcp_f32_e32 v7, v7
	s_nop 0
	v_pk_mul_f32 v[4:5], v[4:5], v[6:7]
	s_nop 0
	v_cvt_pk_bf16_f32 v3, v4, v5
	v_accvgpr_read_b32 v4, a188
	v_mul_f32_e32 v5, 0xbfb8aa3b, v4
	v_exp_f32_e32 v5, v5
	s_nop 0
	v_add_f32_e32 v5, 1.0, v5
	v_rcp_f32_e32 v6, v5
	v_accvgpr_read_b32 v5, a189
	v_mul_f32_e32 v7, 0xbfb8aa3b, v5
	v_exp_f32_e32 v7, v7
	s_nop 0
	v_add_f32_e32 v7, 1.0, v7
	v_rcp_f32_e32 v7, v7
	s_nop 0
	v_pk_mul_f32 v[4:5], v[4:5], v[6:7]
	v_accvgpr_read_b32 v6, a190
	v_mul_f32_e32 v7, 0xbfb8aa3b, v6
	v_exp_f32_e32 v7, v7
	v_cvt_pk_bf16_f32 v4, v4, v5
	v_add_f32_e32 v7, 1.0, v7
	v_rcp_f32_e32 v8, v7
	v_accvgpr_read_b32 v7, a191
	v_mul_f32_e32 v9, 0xbfb8aa3b, v7
	v_exp_f32_e32 v9, v9
	s_nop 0
	v_add_f32_e32 v9, 1.0, v9
	v_rcp_f32_e32 v9, v9
	s_nop 0
	v_pk_mul_f32 v[6:7], v[6:7], v[8:9]
	s_nop 0
	v_cvt_pk_bf16_f32 v5, v6, v7
	ds_write2_b64 v1, v[2:3], v[4:5] offset0:68 offset1:70
	v_accvgpr_read_b32 v2, a160
	v_accvgpr_read_b32 v3, a161
	v_mul_f32_e32 v2, 0xbfb8aa3b, v2
	v_mul_f32_e32 v3, 0xbfb8aa3b, v3
	v_exp_f32_e32 v2, v2
	v_exp_f32_e32 v3, v3
	v_accvgpr_read_b32 v4, a160
	v_accvgpr_read_b32 v5, a161
	v_add_f32_e32 v2, 1.0, v2
	v_add_f32_e32 v3, 1.0, v3
	v_rcp_f32_e32 v2, v2
	v_rcp_f32_e32 v3, v3
	s_nop 0
	v_pk_mul_f32 v[2:3], v[4:5], v[2:3]
	v_accvgpr_read_b32 v4, a162
	v_mul_f32_e32 v5, 0xbfb8aa3b, v4
	v_exp_f32_e32 v5, v5
	v_cvt_pk_bf16_f32 v2, v2, v3
	v_add_f32_e32 v5, 1.0, v5
	v_rcp_f32_e32 v6, v5
	v_accvgpr_read_b32 v5, a163
	v_mul_f32_e32 v7, 0xbfb8aa3b, v5
	v_exp_f32_e32 v7, v7
	s_nop 0
	v_add_f32_e32 v7, 1.0, v7
	v_rcp_f32_e32 v7, v7
	s_nop 0
	v_pk_mul_f32 v[4:5], v[4:5], v[6:7]
	s_nop 0
	v_cvt_pk_bf16_f32 v3, v4, v5
	v_accvgpr_read_b32 v4, a164
	v_mul_f32_e32 v5, 0xbfb8aa3b, v4
	v_exp_f32_e32 v5, v5
	s_nop 0
	v_add_f32_e32 v5, 1.0, v5
	v_rcp_f32_e32 v6, v5
	v_accvgpr_read_b32 v5, a165
	v_mul_f32_e32 v7, 0xbfb8aa3b, v5
	v_exp_f32_e32 v7, v7
	s_nop 0
	v_add_f32_e32 v7, 1.0, v7
	v_rcp_f32_e32 v7, v7
	s_nop 0
	v_pk_mul_f32 v[4:5], v[4:5], v[6:7]
	v_accvgpr_read_b32 v6, a166
	v_mul_f32_e32 v7, 0xbfb8aa3b, v6
	v_exp_f32_e32 v7, v7
	v_cvt_pk_bf16_f32 v4, v4, v5
	v_add_f32_e32 v7, 1.0, v7
	v_rcp_f32_e32 v8, v7
	v_accvgpr_read_b32 v7, a167
	v_mul_f32_e32 v9, 0xbfb8aa3b, v7
	v_exp_f32_e32 v9, v9
	s_nop 0
	v_add_f32_e32 v9, 1.0, v9
	v_rcp_f32_e32 v9, v9
	s_nop 0
	v_pk_mul_f32 v[6:7], v[6:7], v[8:9]
	s_nop 0
	v_cvt_pk_bf16_f32 v5, v6, v7
	ds_write2_b64 v1, v[2:3], v[4:5] offset0:72 offset1:74
	v_accvgpr_read_b32 v2, a168
	v_mul_f32_e32 v3, 0xbfb8aa3b, v2
	v_exp_f32_e32 v3, v3
	s_nop 0
	v_add_f32_e32 v3, 1.0, v3
	v_rcp_f32_e32 v4, v3
	v_accvgpr_read_b32 v3, a169
	v_mul_f32_e32 v5, 0xbfb8aa3b, v3
	v_exp_f32_e32 v5, v5
	s_nop 0
	v_add_f32_e32 v5, 1.0, v5
	v_rcp_f32_e32 v5, v5
	s_nop 0
	v_pk_mul_f32 v[2:3], v[2:3], v[4:5]
	v_accvgpr_read_b32 v4, a170
	v_mul_f32_e32 v5, 0xbfb8aa3b, v4
	v_exp_f32_e32 v5, v5
	v_cvt_pk_bf16_f32 v2, v2, v3
	v_add_f32_e32 v5, 1.0, v5
	v_rcp_f32_e32 v6, v5
	v_accvgpr_read_b32 v5, a171
	v_mul_f32_e32 v7, 0xbfb8aa3b, v5
	v_exp_f32_e32 v7, v7
	s_nop 0
	v_add_f32_e32 v7, 1.0, v7
	v_rcp_f32_e32 v7, v7
	s_nop 0
	v_pk_mul_f32 v[4:5], v[4:5], v[6:7]
	s_nop 0
	v_cvt_pk_bf16_f32 v3, v4, v5
	v_accvgpr_read_b32 v4, a172
	v_mul_f32_e32 v5, 0xbfb8aa3b, v4
	v_exp_f32_e32 v5, v5
	s_nop 0
	v_add_f32_e32 v5, 1.0, v5
	v_rcp_f32_e32 v6, v5
	v_accvgpr_read_b32 v5, a173
	v_mul_f32_e32 v7, 0xbfb8aa3b, v5
	v_exp_f32_e32 v7, v7
	s_nop 0
	v_add_f32_e32 v7, 1.0, v7
	v_rcp_f32_e32 v7, v7
	s_nop 0
	v_pk_mul_f32 v[4:5], v[4:5], v[6:7]
	v_accvgpr_read_b32 v6, a174
	v_mul_f32_e32 v7, 0xbfb8aa3b, v6
	v_exp_f32_e32 v7, v7
	v_cvt_pk_bf16_f32 v4, v4, v5
	v_add_f32_e32 v7, 1.0, v7
	v_rcp_f32_e32 v8, v7
	v_accvgpr_read_b32 v7, a175
	v_mul_f32_e32 v9, 0xbfb8aa3b, v7
	v_exp_f32_e32 v9, v9
	s_nop 0
	v_add_f32_e32 v9, 1.0, v9
	v_rcp_f32_e32 v9, v9
	s_nop 0
	v_pk_mul_f32 v[6:7], v[6:7], v[8:9]
	s_nop 0
	v_cvt_pk_bf16_f32 v5, v6, v7
	ds_write2_b64 v1, v[2:3], v[4:5] offset0:76 offset1:78
	v_accvgpr_read_b32 v2, a144
	v_accvgpr_read_b32 v3, a145
	v_mul_f32_e32 v2, 0xbfb8aa3b, v2
	v_mul_f32_e32 v3, 0xbfb8aa3b, v3
	v_exp_f32_e32 v2, v2
	v_exp_f32_e32 v3, v3
	v_accvgpr_read_b32 v4, a144
	v_accvgpr_read_b32 v5, a145
	v_add_f32_e32 v2, 1.0, v2
	v_add_f32_e32 v3, 1.0, v3
	v_rcp_f32_e32 v2, v2
	v_rcp_f32_e32 v3, v3
	s_nop 0
	v_pk_mul_f32 v[2:3], v[4:5], v[2:3]
	v_accvgpr_read_b32 v4, a146
	v_mul_f32_e32 v5, 0xbfb8aa3b, v4
	v_exp_f32_e32 v5, v5
	v_cvt_pk_bf16_f32 v2, v2, v3
	v_add_f32_e32 v5, 1.0, v5
	v_rcp_f32_e32 v6, v5
	v_accvgpr_read_b32 v5, a147
	v_mul_f32_e32 v7, 0xbfb8aa3b, v5
	v_exp_f32_e32 v7, v7
	s_nop 0
	v_add_f32_e32 v7, 1.0, v7
	v_rcp_f32_e32 v7, v7
	s_nop 0
	v_pk_mul_f32 v[4:5], v[4:5], v[6:7]
	s_nop 0
	v_cvt_pk_bf16_f32 v3, v4, v5
	v_accvgpr_read_b32 v4, a148
	v_mul_f32_e32 v5, 0xbfb8aa3b, v4
	v_exp_f32_e32 v5, v5
	s_nop 0
	v_add_f32_e32 v5, 1.0, v5
	v_rcp_f32_e32 v6, v5
	v_accvgpr_read_b32 v5, a149
	v_mul_f32_e32 v7, 0xbfb8aa3b, v5
	v_exp_f32_e32 v7, v7
	s_nop 0
	v_add_f32_e32 v7, 1.0, v7
	v_rcp_f32_e32 v7, v7
	s_nop 0
	v_pk_mul_f32 v[4:5], v[4:5], v[6:7]
	v_accvgpr_read_b32 v6, a150
	v_mul_f32_e32 v7, 0xbfb8aa3b, v6
	v_exp_f32_e32 v7, v7
	v_cvt_pk_bf16_f32 v4, v4, v5
	v_add_f32_e32 v7, 1.0, v7
	v_rcp_f32_e32 v8, v7
	v_accvgpr_read_b32 v7, a151
	v_mul_f32_e32 v9, 0xbfb8aa3b, v7
	v_exp_f32_e32 v9, v9
	s_nop 0
	v_add_f32_e32 v9, 1.0, v9
	v_rcp_f32_e32 v9, v9
	s_nop 0
	v_pk_mul_f32 v[6:7], v[6:7], v[8:9]
	s_nop 0
	v_cvt_pk_bf16_f32 v5, v6, v7
	ds_write2_b64 v1, v[2:3], v[4:5] offset0:80 offset1:82
	v_accvgpr_read_b32 v2, a152
	v_mul_f32_e32 v3, 0xbfb8aa3b, v2
	v_exp_f32_e32 v3, v3
	s_nop 0
	v_add_f32_e32 v3, 1.0, v3
	v_rcp_f32_e32 v4, v3
	v_accvgpr_read_b32 v3, a153
	v_mul_f32_e32 v5, 0xbfb8aa3b, v3
	v_exp_f32_e32 v5, v5
	s_nop 0
	v_add_f32_e32 v5, 1.0, v5
	v_rcp_f32_e32 v5, v5
	s_nop 0
	v_pk_mul_f32 v[2:3], v[2:3], v[4:5]
	v_accvgpr_read_b32 v4, a154
	v_mul_f32_e32 v5, 0xbfb8aa3b, v4
	v_exp_f32_e32 v5, v5
	v_cvt_pk_bf16_f32 v2, v2, v3
	v_add_f32_e32 v5, 1.0, v5
	v_rcp_f32_e32 v6, v5
	v_accvgpr_read_b32 v5, a155
	v_mul_f32_e32 v7, 0xbfb8aa3b, v5
	v_exp_f32_e32 v7, v7
	s_nop 0
	v_add_f32_e32 v7, 1.0, v7
	v_rcp_f32_e32 v7, v7
	s_nop 0
	v_pk_mul_f32 v[4:5], v[4:5], v[6:7]
	s_nop 0
	v_cvt_pk_bf16_f32 v3, v4, v5
	v_accvgpr_read_b32 v4, a156
	v_mul_f32_e32 v5, 0xbfb8aa3b, v4
	v_exp_f32_e32 v5, v5
	s_nop 0
	v_add_f32_e32 v5, 1.0, v5
	v_rcp_f32_e32 v6, v5
	v_accvgpr_read_b32 v5, a157
	v_mul_f32_e32 v7, 0xbfb8aa3b, v5
	v_exp_f32_e32 v7, v7
	s_nop 0
	v_add_f32_e32 v7, 1.0, v7
	v_rcp_f32_e32 v7, v7
	s_nop 0
	v_pk_mul_f32 v[4:5], v[4:5], v[6:7]
	v_accvgpr_read_b32 v6, a158
	v_mul_f32_e32 v7, 0xbfb8aa3b, v6
	v_exp_f32_e32 v7, v7
	v_cvt_pk_bf16_f32 v4, v4, v5
	v_add_f32_e32 v7, 1.0, v7
	v_rcp_f32_e32 v8, v7
	v_accvgpr_read_b32 v7, a159
	v_mul_f32_e32 v9, 0xbfb8aa3b, v7
	v_exp_f32_e32 v9, v9
	s_nop 0
	v_add_f32_e32 v9, 1.0, v9
	v_rcp_f32_e32 v9, v9
	s_nop 0
	v_pk_mul_f32 v[6:7], v[6:7], v[8:9]
	s_nop 0
	v_cvt_pk_bf16_f32 v5, v6, v7
	ds_write2_b64 v1, v[2:3], v[4:5] offset0:84 offset1:86
	v_accvgpr_read_b32 v2, a128
	v_accvgpr_read_b32 v3, a129
	v_mul_f32_e32 v2, 0xbfb8aa3b, v2
	v_mul_f32_e32 v3, 0xbfb8aa3b, v3
	v_exp_f32_e32 v2, v2
	v_exp_f32_e32 v3, v3
	v_accvgpr_read_b32 v4, a128
	v_accvgpr_read_b32 v5, a129
	v_add_f32_e32 v2, 1.0, v2
	v_add_f32_e32 v3, 1.0, v3
	v_rcp_f32_e32 v2, v2
	v_rcp_f32_e32 v3, v3
	s_nop 0
	v_pk_mul_f32 v[2:3], v[4:5], v[2:3]
	v_accvgpr_read_b32 v4, a130
	v_mul_f32_e32 v5, 0xbfb8aa3b, v4
	v_exp_f32_e32 v5, v5
	v_cvt_pk_bf16_f32 v2, v2, v3
	v_add_f32_e32 v5, 1.0, v5
	v_rcp_f32_e32 v6, v5
	v_accvgpr_read_b32 v5, a131
	v_mul_f32_e32 v7, 0xbfb8aa3b, v5
	v_exp_f32_e32 v7, v7
	s_nop 0
	v_add_f32_e32 v7, 1.0, v7
	v_rcp_f32_e32 v7, v7
	s_nop 0
	v_pk_mul_f32 v[4:5], v[4:5], v[6:7]
	s_nop 0
	v_cvt_pk_bf16_f32 v3, v4, v5
	v_accvgpr_read_b32 v4, a132
	v_mul_f32_e32 v5, 0xbfb8aa3b, v4
	v_exp_f32_e32 v5, v5
	s_nop 0
	v_add_f32_e32 v5, 1.0, v5
	v_rcp_f32_e32 v6, v5
	v_accvgpr_read_b32 v5, a133
	v_mul_f32_e32 v7, 0xbfb8aa3b, v5
	v_exp_f32_e32 v7, v7
	s_nop 0
	v_add_f32_e32 v7, 1.0, v7
	v_rcp_f32_e32 v7, v7
	s_nop 0
	v_pk_mul_f32 v[4:5], v[4:5], v[6:7]
	v_accvgpr_read_b32 v6, a134
	v_mul_f32_e32 v7, 0xbfb8aa3b, v6
	v_exp_f32_e32 v7, v7
	v_cvt_pk_bf16_f32 v4, v4, v5
	v_add_f32_e32 v7, 1.0, v7
	v_rcp_f32_e32 v8, v7
	v_accvgpr_read_b32 v7, a135
	v_mul_f32_e32 v9, 0xbfb8aa3b, v7
	v_exp_f32_e32 v9, v9
	s_nop 0
	v_add_f32_e32 v9, 1.0, v9
	v_rcp_f32_e32 v9, v9
	s_nop 0
	v_pk_mul_f32 v[6:7], v[6:7], v[8:9]
	s_nop 0
	v_cvt_pk_bf16_f32 v5, v6, v7
	ds_write2_b64 v1, v[2:3], v[4:5] offset0:88 offset1:90
	v_accvgpr_read_b32 v2, a136
	v_mul_f32_e32 v3, 0xbfb8aa3b, v2
	v_exp_f32_e32 v3, v3
	s_nop 0
	v_add_f32_e32 v3, 1.0, v3
	v_rcp_f32_e32 v4, v3
	v_accvgpr_read_b32 v3, a137
	v_mul_f32_e32 v5, 0xbfb8aa3b, v3
	v_exp_f32_e32 v5, v5
	s_nop 0
	v_add_f32_e32 v5, 1.0, v5
	v_rcp_f32_e32 v5, v5
	s_nop 0
	v_pk_mul_f32 v[2:3], v[2:3], v[4:5]
	v_accvgpr_read_b32 v4, a138
	v_mul_f32_e32 v5, 0xbfb8aa3b, v4
	v_exp_f32_e32 v5, v5
	v_cvt_pk_bf16_f32 v2, v2, v3
	v_add_f32_e32 v5, 1.0, v5
	v_rcp_f32_e32 v6, v5
	v_accvgpr_read_b32 v5, a139
	v_mul_f32_e32 v7, 0xbfb8aa3b, v5
	v_exp_f32_e32 v7, v7
	s_nop 0
	v_add_f32_e32 v7, 1.0, v7
	v_rcp_f32_e32 v7, v7
	s_nop 0
	v_pk_mul_f32 v[4:5], v[4:5], v[6:7]
	s_nop 0
	v_cvt_pk_bf16_f32 v3, v4, v5
	v_accvgpr_read_b32 v4, a140
	v_mul_f32_e32 v5, 0xbfb8aa3b, v4
	v_exp_f32_e32 v5, v5
	s_nop 0
	v_add_f32_e32 v5, 1.0, v5
	v_rcp_f32_e32 v6, v5
	v_accvgpr_read_b32 v5, a141
	v_mul_f32_e32 v7, 0xbfb8aa3b, v5
	v_exp_f32_e32 v7, v7
	s_nop 0
	v_add_f32_e32 v7, 1.0, v7
	v_rcp_f32_e32 v7, v7
	s_nop 0
	v_pk_mul_f32 v[4:5], v[4:5], v[6:7]
	v_accvgpr_read_b32 v6, a142
	v_mul_f32_e32 v7, 0xbfb8aa3b, v6
	v_exp_f32_e32 v7, v7
	v_cvt_pk_bf16_f32 v4, v4, v5
	v_add_f32_e32 v7, 1.0, v7
	v_rcp_f32_e32 v8, v7
	v_accvgpr_read_b32 v7, a143
	v_mul_f32_e32 v9, 0xbfb8aa3b, v7
	v_exp_f32_e32 v9, v9
	s_nop 0
	v_add_f32_e32 v9, 1.0, v9
	v_rcp_f32_e32 v9, v9
	s_nop 0
	v_pk_mul_f32 v[6:7], v[6:7], v[8:9]
	s_nop 0
	v_cvt_pk_bf16_f32 v5, v6, v7
	ds_write2_b64 v1, v[2:3], v[4:5] offset0:92 offset1:94
	v_accvgpr_read_b32 v1, a112
	v_mul_f32_e32 v1, 0xbfb8aa3b, v1
	v_exp_f32_e32 v1, v1
	v_accvgpr_read_b32 v4, a112
	v_accvgpr_read_b32 v5, a113
	v_add_f32_e32 v1, 1.0, v1
	v_rcp_f32_e32 v2, v1
	v_accvgpr_read_b32 v1, a113
	v_mul_f32_e32 v1, 0xbfb8aa3b, v1
	v_exp_f32_e32 v1, v1
	s_nop 0
	v_add_f32_e32 v1, 1.0, v1
	v_rcp_f32_e32 v3, v1
	s_nop 0
	v_pk_mul_f32 v[2:3], v[4:5], v[2:3]
	v_accvgpr_read_b32 v4, a114
	v_mul_f32_e32 v1, 0xbfb8aa3b, v4
	v_exp_f32_e32 v1, v1
	v_accvgpr_read_b32 v5, a115
	v_cvt_pk_bf16_f32 v2, v2, v3
	v_add_f32_e32 v1, 1.0, v1
	v_rcp_f32_e32 v6, v1
	v_mul_f32_e32 v1, 0xbfb8aa3b, v5
	v_exp_f32_e32 v1, v1
	s_nop 0
	v_add_f32_e32 v1, 1.0, v1
	v_rcp_f32_e32 v7, v1
	s_nop 0
	v_pk_mul_f32 v[4:5], v[4:5], v[6:7]
	s_nop 0
	v_cvt_pk_bf16_f32 v3, v4, v5
	v_accvgpr_read_b32 v4, a116
	v_mul_f32_e32 v1, 0xbfb8aa3b, v4
	v_exp_f32_e32 v1, v1
	v_accvgpr_read_b32 v5, a117
	v_add_f32_e32 v1, 1.0, v1
	v_rcp_f32_e32 v6, v1
	v_mul_f32_e32 v1, 0xbfb8aa3b, v5
	v_exp_f32_e32 v1, v1
	s_nop 0
	v_add_f32_e32 v1, 1.0, v1
	v_rcp_f32_e32 v7, v1
	s_nop 0
	v_pk_mul_f32 v[4:5], v[4:5], v[6:7]
	v_accvgpr_read_b32 v6, a118
	v_mul_f32_e32 v1, 0xbfb8aa3b, v6
	v_exp_f32_e32 v1, v1
	v_accvgpr_read_b32 v7, a119
	v_cvt_pk_bf16_f32 v4, v4, v5
	v_add_f32_e32 v1, 1.0, v1
	v_rcp_f32_e32 v8, v1
	v_mul_f32_e32 v1, 0xbfb8aa3b, v7
	v_exp_f32_e32 v1, v1
	s_nop 0
	v_add_f32_e32 v1, 1.0, v1
	v_rcp_f32_e32 v9, v1
	v_add_u32_e32 v1, 0x8000, v0
	v_pk_mul_f32 v[6:7], v[6:7], v[8:9]
	s_nop 0
	v_cvt_pk_bf16_f32 v5, v6, v7
	ds_write2_b64 v1, v[2:3], v[4:5] offset0:128 offset1:130
	v_accvgpr_read_b32 v2, a120
	v_mul_f32_e32 v3, 0xbfb8aa3b, v2
	v_exp_f32_e32 v3, v3
	s_nop 0
	v_add_f32_e32 v3, 1.0, v3
	v_rcp_f32_e32 v4, v3
	v_accvgpr_read_b32 v3, a121
	v_mul_f32_e32 v5, 0xbfb8aa3b, v3
	v_exp_f32_e32 v5, v5
	s_nop 0
	v_add_f32_e32 v5, 1.0, v5
	v_rcp_f32_e32 v5, v5
	s_nop 0
	v_pk_mul_f32 v[2:3], v[2:3], v[4:5]
	v_accvgpr_read_b32 v4, a122
	v_mul_f32_e32 v5, 0xbfb8aa3b, v4
	v_exp_f32_e32 v5, v5
	v_cvt_pk_bf16_f32 v2, v2, v3
	v_add_f32_e32 v5, 1.0, v5
	v_rcp_f32_e32 v6, v5
	v_accvgpr_read_b32 v5, a123
	v_mul_f32_e32 v7, 0xbfb8aa3b, v5
	v_exp_f32_e32 v7, v7
	s_nop 0
	v_add_f32_e32 v7, 1.0, v7
	v_rcp_f32_e32 v7, v7
	s_nop 0
	v_pk_mul_f32 v[4:5], v[4:5], v[6:7]
	s_nop 0
	v_cvt_pk_bf16_f32 v3, v4, v5
	v_accvgpr_read_b32 v4, a124
	v_mul_f32_e32 v5, 0xbfb8aa3b, v4
	v_exp_f32_e32 v5, v5
	s_nop 0
	v_add_f32_e32 v5, 1.0, v5
	v_rcp_f32_e32 v6, v5
	v_accvgpr_read_b32 v5, a125
	v_mul_f32_e32 v7, 0xbfb8aa3b, v5
	v_exp_f32_e32 v7, v7
	s_nop 0
	v_add_f32_e32 v7, 1.0, v7
	v_rcp_f32_e32 v7, v7
	s_nop 0
	v_pk_mul_f32 v[4:5], v[4:5], v[6:7]
	v_accvgpr_read_b32 v6, a126
	v_mul_f32_e32 v7, 0xbfb8aa3b, v6
	v_exp_f32_e32 v7, v7
	v_cvt_pk_bf16_f32 v4, v4, v5
	v_add_f32_e32 v7, 1.0, v7
	v_rcp_f32_e32 v8, v7
	v_accvgpr_read_b32 v7, a127
	v_mul_f32_e32 v9, 0xbfb8aa3b, v7
	v_exp_f32_e32 v9, v9
	s_nop 0
	v_add_f32_e32 v9, 1.0, v9
	v_rcp_f32_e32 v9, v9
	s_nop 0
	v_pk_mul_f32 v[6:7], v[6:7], v[8:9]
	s_nop 0
	v_cvt_pk_bf16_f32 v5, v6, v7
	ds_write2_b64 v1, v[2:3], v[4:5] offset0:132 offset1:134
	v_accvgpr_read_b32 v2, a96
	v_accvgpr_read_b32 v3, a97
	v_mul_f32_e32 v2, 0xbfb8aa3b, v2
	v_mul_f32_e32 v3, 0xbfb8aa3b, v3
	v_exp_f32_e32 v2, v2
	v_exp_f32_e32 v3, v3
	v_accvgpr_read_b32 v4, a96
	v_accvgpr_read_b32 v5, a97
	v_add_f32_e32 v2, 1.0, v2
	v_add_f32_e32 v3, 1.0, v3
	v_rcp_f32_e32 v2, v2
	v_rcp_f32_e32 v3, v3
	s_nop 0
	v_pk_mul_f32 v[2:3], v[4:5], v[2:3]
	v_accvgpr_read_b32 v4, a98
	v_mul_f32_e32 v5, 0xbfb8aa3b, v4
	v_exp_f32_e32 v5, v5
	v_cvt_pk_bf16_f32 v2, v2, v3
	v_add_f32_e32 v5, 1.0, v5
	v_rcp_f32_e32 v6, v5
	v_accvgpr_read_b32 v5, a99
	v_mul_f32_e32 v7, 0xbfb8aa3b, v5
	v_exp_f32_e32 v7, v7
	s_nop 0
	v_add_f32_e32 v7, 1.0, v7
	v_rcp_f32_e32 v7, v7
	s_nop 0
	v_pk_mul_f32 v[4:5], v[4:5], v[6:7]
	s_nop 0
	v_cvt_pk_bf16_f32 v3, v4, v5
	v_accvgpr_read_b32 v4, a100
	v_mul_f32_e32 v5, 0xbfb8aa3b, v4
	v_exp_f32_e32 v5, v5
	s_nop 0
	v_add_f32_e32 v5, 1.0, v5
	v_rcp_f32_e32 v6, v5
	v_accvgpr_read_b32 v5, a101
	v_mul_f32_e32 v7, 0xbfb8aa3b, v5
	v_exp_f32_e32 v7, v7
	s_nop 0
	v_add_f32_e32 v7, 1.0, v7
	v_rcp_f32_e32 v7, v7
	s_nop 0
	v_pk_mul_f32 v[4:5], v[4:5], v[6:7]
	v_accvgpr_read_b32 v6, a102
	v_mul_f32_e32 v7, 0xbfb8aa3b, v6
	v_exp_f32_e32 v7, v7
	v_cvt_pk_bf16_f32 v4, v4, v5
	v_add_f32_e32 v7, 1.0, v7
	v_rcp_f32_e32 v8, v7
	v_accvgpr_read_b32 v7, a103
	v_mul_f32_e32 v9, 0xbfb8aa3b, v7
	v_exp_f32_e32 v9, v9
	s_nop 0
	v_add_f32_e32 v9, 1.0, v9
	v_rcp_f32_e32 v9, v9
	s_nop 0
	v_pk_mul_f32 v[6:7], v[6:7], v[8:9]
	s_nop 0
	v_cvt_pk_bf16_f32 v5, v6, v7
	ds_write2_b64 v1, v[2:3], v[4:5] offset0:136 offset1:138
	v_accvgpr_read_b32 v2, a104
	v_mul_f32_e32 v3, 0xbfb8aa3b, v2
	v_exp_f32_e32 v3, v3
	s_nop 0
	v_add_f32_e32 v3, 1.0, v3
	v_rcp_f32_e32 v4, v3
	v_accvgpr_read_b32 v3, a105
	v_mul_f32_e32 v5, 0xbfb8aa3b, v3
	v_exp_f32_e32 v5, v5
	s_nop 0
	v_add_f32_e32 v5, 1.0, v5
	v_rcp_f32_e32 v5, v5
	s_nop 0
	v_pk_mul_f32 v[2:3], v[2:3], v[4:5]
	v_accvgpr_read_b32 v4, a106
	v_mul_f32_e32 v5, 0xbfb8aa3b, v4
	v_exp_f32_e32 v5, v5
	v_cvt_pk_bf16_f32 v2, v2, v3
	v_add_f32_e32 v5, 1.0, v5
	v_rcp_f32_e32 v6, v5
	v_accvgpr_read_b32 v5, a107
	v_mul_f32_e32 v7, 0xbfb8aa3b, v5
	v_exp_f32_e32 v7, v7
	s_nop 0
	v_add_f32_e32 v7, 1.0, v7
	v_rcp_f32_e32 v7, v7
	s_nop 0
	v_pk_mul_f32 v[4:5], v[4:5], v[6:7]
	s_nop 0
	v_cvt_pk_bf16_f32 v3, v4, v5
	v_accvgpr_read_b32 v4, a108
	v_mul_f32_e32 v5, 0xbfb8aa3b, v4
	v_exp_f32_e32 v5, v5
	s_nop 0
	v_add_f32_e32 v5, 1.0, v5
	v_rcp_f32_e32 v6, v5
	v_accvgpr_read_b32 v5, a109
	v_mul_f32_e32 v7, 0xbfb8aa3b, v5
	v_exp_f32_e32 v7, v7
	s_nop 0
	v_add_f32_e32 v7, 1.0, v7
	v_rcp_f32_e32 v7, v7
	s_nop 0
	v_pk_mul_f32 v[4:5], v[4:5], v[6:7]
	v_accvgpr_read_b32 v6, a110
	v_mul_f32_e32 v7, 0xbfb8aa3b, v6
	v_exp_f32_e32 v7, v7
	v_cvt_pk_bf16_f32 v4, v4, v5
	v_add_f32_e32 v7, 1.0, v7
	v_rcp_f32_e32 v8, v7
	v_accvgpr_read_b32 v7, a111
	v_mul_f32_e32 v9, 0xbfb8aa3b, v7
	v_exp_f32_e32 v9, v9
	s_nop 0
	v_add_f32_e32 v9, 1.0, v9
	v_rcp_f32_e32 v9, v9
	s_nop 0
	v_pk_mul_f32 v[6:7], v[6:7], v[8:9]
	s_nop 0
	v_cvt_pk_bf16_f32 v5, v6, v7
	ds_write2_b64 v1, v[2:3], v[4:5] offset0:140 offset1:142
	v_accvgpr_read_b32 v2, a80
	v_accvgpr_read_b32 v3, a81
	v_mul_f32_e32 v2, 0xbfb8aa3b, v2
	v_mul_f32_e32 v3, 0xbfb8aa3b, v3
	v_exp_f32_e32 v2, v2
	v_exp_f32_e32 v3, v3
	v_accvgpr_read_b32 v4, a80
	v_accvgpr_read_b32 v5, a81
	v_add_f32_e32 v2, 1.0, v2
	v_add_f32_e32 v3, 1.0, v3
	v_rcp_f32_e32 v2, v2
	v_rcp_f32_e32 v3, v3
	s_nop 0
	v_pk_mul_f32 v[2:3], v[4:5], v[2:3]
	v_accvgpr_read_b32 v4, a82
	v_mul_f32_e32 v5, 0xbfb8aa3b, v4
	v_exp_f32_e32 v5, v5
	v_cvt_pk_bf16_f32 v2, v2, v3
	v_add_f32_e32 v5, 1.0, v5
	v_rcp_f32_e32 v6, v5
	v_accvgpr_read_b32 v5, a83
	v_mul_f32_e32 v7, 0xbfb8aa3b, v5
	v_exp_f32_e32 v7, v7
	s_nop 0
	v_add_f32_e32 v7, 1.0, v7
	v_rcp_f32_e32 v7, v7
	s_nop 0
	v_pk_mul_f32 v[4:5], v[4:5], v[6:7]
	s_nop 0
	v_cvt_pk_bf16_f32 v3, v4, v5
	v_accvgpr_read_b32 v4, a84
	v_mul_f32_e32 v5, 0xbfb8aa3b, v4
	v_exp_f32_e32 v5, v5
	s_nop 0
	v_add_f32_e32 v5, 1.0, v5
	v_rcp_f32_e32 v6, v5
	v_accvgpr_read_b32 v5, a85
	v_mul_f32_e32 v7, 0xbfb8aa3b, v5
	v_exp_f32_e32 v7, v7
	s_nop 0
	v_add_f32_e32 v7, 1.0, v7
	v_rcp_f32_e32 v7, v7
	s_nop 0
	v_pk_mul_f32 v[4:5], v[4:5], v[6:7]
	v_accvgpr_read_b32 v6, a86
	v_mul_f32_e32 v7, 0xbfb8aa3b, v6
	v_exp_f32_e32 v7, v7
	v_cvt_pk_bf16_f32 v4, v4, v5
	v_add_f32_e32 v7, 1.0, v7
	v_rcp_f32_e32 v8, v7
	v_accvgpr_read_b32 v7, a87
	v_mul_f32_e32 v9, 0xbfb8aa3b, v7
	v_exp_f32_e32 v9, v9
	s_nop 0
	v_add_f32_e32 v9, 1.0, v9
	v_rcp_f32_e32 v9, v9
	s_nop 0
	v_pk_mul_f32 v[6:7], v[6:7], v[8:9]
	s_nop 0
	v_cvt_pk_bf16_f32 v5, v6, v7
	ds_write2_b64 v1, v[2:3], v[4:5] offset0:144 offset1:146
	v_accvgpr_read_b32 v2, a88
	v_mul_f32_e32 v3, 0xbfb8aa3b, v2
	v_exp_f32_e32 v3, v3
	s_nop 0
	v_add_f32_e32 v3, 1.0, v3
	v_rcp_f32_e32 v4, v3
	v_accvgpr_read_b32 v3, a89
	v_mul_f32_e32 v5, 0xbfb8aa3b, v3
	v_exp_f32_e32 v5, v5
	s_nop 0
	v_add_f32_e32 v5, 1.0, v5
	v_rcp_f32_e32 v5, v5
	s_nop 0
	v_pk_mul_f32 v[2:3], v[2:3], v[4:5]
	v_accvgpr_read_b32 v4, a90
	v_mul_f32_e32 v5, 0xbfb8aa3b, v4
	v_exp_f32_e32 v5, v5
	v_cvt_pk_bf16_f32 v2, v2, v3
	v_add_f32_e32 v5, 1.0, v5
	v_rcp_f32_e32 v6, v5
	v_accvgpr_read_b32 v5, a91
	v_mul_f32_e32 v7, 0xbfb8aa3b, v5
	v_exp_f32_e32 v7, v7
	s_nop 0
	v_add_f32_e32 v7, 1.0, v7
	v_rcp_f32_e32 v7, v7
	s_nop 0
	v_pk_mul_f32 v[4:5], v[4:5], v[6:7]
	s_nop 0
	v_cvt_pk_bf16_f32 v3, v4, v5
	v_accvgpr_read_b32 v4, a92
	v_mul_f32_e32 v5, 0xbfb8aa3b, v4
	v_exp_f32_e32 v5, v5
	s_nop 0
	v_add_f32_e32 v5, 1.0, v5
	v_rcp_f32_e32 v6, v5
	v_accvgpr_read_b32 v5, a93
	v_mul_f32_e32 v7, 0xbfb8aa3b, v5
	v_exp_f32_e32 v7, v7
	s_nop 0
	v_add_f32_e32 v7, 1.0, v7
	v_rcp_f32_e32 v7, v7
	s_nop 0
	v_pk_mul_f32 v[4:5], v[4:5], v[6:7]
	v_accvgpr_read_b32 v6, a94
	v_mul_f32_e32 v7, 0xbfb8aa3b, v6
	v_exp_f32_e32 v7, v7
	v_cvt_pk_bf16_f32 v4, v4, v5
	v_add_f32_e32 v7, 1.0, v7
	v_rcp_f32_e32 v8, v7
	v_accvgpr_read_b32 v7, a95
	v_mul_f32_e32 v9, 0xbfb8aa3b, v7
	v_exp_f32_e32 v9, v9
	s_nop 0
	v_add_f32_e32 v9, 1.0, v9
	v_rcp_f32_e32 v9, v9
	s_nop 0
	v_pk_mul_f32 v[6:7], v[6:7], v[8:9]
	s_nop 0
	v_cvt_pk_bf16_f32 v5, v6, v7
	ds_write2_b64 v1, v[2:3], v[4:5] offset0:148 offset1:150
	v_accvgpr_read_b32 v2, a64
	v_accvgpr_read_b32 v3, a65
	v_mul_f32_e32 v2, 0xbfb8aa3b, v2
	v_mul_f32_e32 v3, 0xbfb8aa3b, v3
	v_exp_f32_e32 v2, v2
	v_exp_f32_e32 v3, v3
	v_accvgpr_read_b32 v4, a64
	v_accvgpr_read_b32 v5, a65
	v_add_f32_e32 v2, 1.0, v2
	v_add_f32_e32 v3, 1.0, v3
	v_rcp_f32_e32 v2, v2
	v_rcp_f32_e32 v3, v3
	s_nop 0
	v_pk_mul_f32 v[2:3], v[4:5], v[2:3]
	v_accvgpr_read_b32 v4, a66
	v_mul_f32_e32 v5, 0xbfb8aa3b, v4
	v_exp_f32_e32 v5, v5
	v_cvt_pk_bf16_f32 v2, v2, v3
	v_add_f32_e32 v5, 1.0, v5
	v_rcp_f32_e32 v6, v5
	v_accvgpr_read_b32 v5, a67
	v_mul_f32_e32 v7, 0xbfb8aa3b, v5
	v_exp_f32_e32 v7, v7
	s_nop 0
	v_add_f32_e32 v7, 1.0, v7
	v_rcp_f32_e32 v7, v7
	s_nop 0
	v_pk_mul_f32 v[4:5], v[4:5], v[6:7]
	s_nop 0
	v_cvt_pk_bf16_f32 v3, v4, v5
	v_accvgpr_read_b32 v4, a68
	v_mul_f32_e32 v5, 0xbfb8aa3b, v4
	v_exp_f32_e32 v5, v5
	s_nop 0
	v_add_f32_e32 v5, 1.0, v5
	v_rcp_f32_e32 v6, v5
	v_accvgpr_read_b32 v5, a69
	v_mul_f32_e32 v7, 0xbfb8aa3b, v5
	v_exp_f32_e32 v7, v7
	s_nop 0
	v_add_f32_e32 v7, 1.0, v7
	v_rcp_f32_e32 v7, v7
	s_nop 0
	v_pk_mul_f32 v[4:5], v[4:5], v[6:7]
	v_accvgpr_read_b32 v6, a70
	v_mul_f32_e32 v7, 0xbfb8aa3b, v6
	v_exp_f32_e32 v7, v7
	v_cvt_pk_bf16_f32 v4, v4, v5
	v_add_f32_e32 v7, 1.0, v7
	v_rcp_f32_e32 v8, v7
	v_accvgpr_read_b32 v7, a71
	v_mul_f32_e32 v9, 0xbfb8aa3b, v7
	v_exp_f32_e32 v9, v9
	s_nop 0
	v_add_f32_e32 v9, 1.0, v9
	v_rcp_f32_e32 v9, v9
	s_nop 0
	v_pk_mul_f32 v[6:7], v[6:7], v[8:9]
	s_nop 0
	v_cvt_pk_bf16_f32 v5, v6, v7
	ds_write2_b64 v1, v[2:3], v[4:5] offset0:152 offset1:154
	v_accvgpr_read_b32 v2, a72
	v_mul_f32_e32 v3, 0xbfb8aa3b, v2
	v_exp_f32_e32 v3, v3
	s_nop 0
	v_add_f32_e32 v3, 1.0, v3
	v_rcp_f32_e32 v4, v3
	v_accvgpr_read_b32 v3, a73
	v_mul_f32_e32 v5, 0xbfb8aa3b, v3
	v_exp_f32_e32 v5, v5
	s_nop 0
	v_add_f32_e32 v5, 1.0, v5
	v_rcp_f32_e32 v5, v5
	s_nop 0
	v_pk_mul_f32 v[2:3], v[2:3], v[4:5]
	v_accvgpr_read_b32 v4, a74
	v_mul_f32_e32 v5, 0xbfb8aa3b, v4
	v_exp_f32_e32 v5, v5
	v_cvt_pk_bf16_f32 v2, v2, v3
	v_add_f32_e32 v5, 1.0, v5
	v_rcp_f32_e32 v6, v5
	v_accvgpr_read_b32 v5, a75
	v_mul_f32_e32 v7, 0xbfb8aa3b, v5
	v_exp_f32_e32 v7, v7
	s_nop 0
	v_add_f32_e32 v7, 1.0, v7
	v_rcp_f32_e32 v7, v7
	s_nop 0
	v_pk_mul_f32 v[4:5], v[4:5], v[6:7]
	s_nop 0
	v_cvt_pk_bf16_f32 v3, v4, v5
	v_accvgpr_read_b32 v4, a76
	v_mul_f32_e32 v5, 0xbfb8aa3b, v4
	v_exp_f32_e32 v5, v5
	s_nop 0
	v_add_f32_e32 v5, 1.0, v5
	v_rcp_f32_e32 v6, v5
	v_accvgpr_read_b32 v5, a77
	v_mul_f32_e32 v7, 0xbfb8aa3b, v5
	v_exp_f32_e32 v7, v7
	s_nop 0
	v_add_f32_e32 v7, 1.0, v7
	v_rcp_f32_e32 v7, v7
	s_nop 0
	v_pk_mul_f32 v[4:5], v[4:5], v[6:7]
	v_accvgpr_read_b32 v6, a78
	v_mul_f32_e32 v7, 0xbfb8aa3b, v6
	v_exp_f32_e32 v7, v7
	v_cvt_pk_bf16_f32 v4, v4, v5
	v_add_f32_e32 v7, 1.0, v7
	v_rcp_f32_e32 v8, v7
	v_accvgpr_read_b32 v7, a79
	v_mul_f32_e32 v9, 0xbfb8aa3b, v7
	v_exp_f32_e32 v9, v9
	s_nop 0
	v_add_f32_e32 v9, 1.0, v9
	v_rcp_f32_e32 v9, v9
	s_nop 0
	v_pk_mul_f32 v[6:7], v[6:7], v[8:9]
	s_nop 0
	v_cvt_pk_bf16_f32 v5, v6, v7
	ds_write2_b64 v1, v[2:3], v[4:5] offset0:156 offset1:158
	v_accvgpr_read_b32 v1, a48
	v_mul_f32_e32 v1, 0xbfb8aa3b, v1
	v_exp_f32_e32 v1, v1
	v_accvgpr_read_b32 v4, a48
	v_accvgpr_read_b32 v5, a49
	v_add_u32_e32 v0, 0xc000, v0
	v_add_f32_e32 v1, 1.0, v1
	v_rcp_f32_e32 v2, v1
	v_accvgpr_read_b32 v1, a49
	v_mul_f32_e32 v1, 0xbfb8aa3b, v1
	v_exp_f32_e32 v1, v1
	s_nop 0
	v_add_f32_e32 v1, 1.0, v1
	v_rcp_f32_e32 v3, v1
	s_nop 0
	v_pk_mul_f32 v[2:3], v[4:5], v[2:3]
	v_accvgpr_read_b32 v4, a50
	v_mul_f32_e32 v1, 0xbfb8aa3b, v4
	v_exp_f32_e32 v1, v1
	v_accvgpr_read_b32 v5, a51
	v_cvt_pk_bf16_f32 v2, v2, v3
	v_add_f32_e32 v1, 1.0, v1
	v_rcp_f32_e32 v6, v1
	v_mul_f32_e32 v1, 0xbfb8aa3b, v5
	v_exp_f32_e32 v1, v1
	s_nop 0
	v_add_f32_e32 v1, 1.0, v1
	v_rcp_f32_e32 v7, v1
	s_nop 0
	v_pk_mul_f32 v[4:5], v[4:5], v[6:7]
	s_nop 0
	v_cvt_pk_bf16_f32 v3, v4, v5
	v_accvgpr_read_b32 v4, a52
	v_mul_f32_e32 v1, 0xbfb8aa3b, v4
	v_exp_f32_e32 v1, v1
	v_accvgpr_read_b32 v5, a53
	v_add_f32_e32 v1, 1.0, v1
	v_rcp_f32_e32 v6, v1
	v_mul_f32_e32 v1, 0xbfb8aa3b, v5
	v_exp_f32_e32 v1, v1
	s_nop 0
	v_add_f32_e32 v1, 1.0, v1
	v_rcp_f32_e32 v7, v1
	s_nop 0
	v_pk_mul_f32 v[4:5], v[4:5], v[6:7]
	v_accvgpr_read_b32 v6, a54
	v_mul_f32_e32 v1, 0xbfb8aa3b, v6
	v_exp_f32_e32 v1, v1
	v_accvgpr_read_b32 v7, a55
	v_cvt_pk_bf16_f32 v4, v4, v5
	v_add_f32_e32 v1, 1.0, v1
	v_rcp_f32_e32 v8, v1
	v_mul_f32_e32 v1, 0xbfb8aa3b, v7
	v_exp_f32_e32 v1, v1
	s_nop 0
	v_add_f32_e32 v1, 1.0, v1
	v_rcp_f32_e32 v9, v1
	s_nop 0
	v_pk_mul_f32 v[6:7], v[6:7], v[8:9]
	s_nop 0
	v_cvt_pk_bf16_f32 v5, v6, v7
	ds_write2_b64 v0, v[2:3], v[4:5] offset0:192 offset1:194
	v_accvgpr_read_b32 v2, a56
	v_mul_f32_e32 v1, 0xbfb8aa3b, v2
	v_exp_f32_e32 v1, v1
	v_accvgpr_read_b32 v3, a57
	v_add_f32_e32 v1, 1.0, v1
	v_rcp_f32_e32 v4, v1
	v_mul_f32_e32 v1, 0xbfb8aa3b, v3
	v_exp_f32_e32 v1, v1
	s_nop 0
	v_add_f32_e32 v1, 1.0, v1
	v_rcp_f32_e32 v5, v1
	s_nop 0
	v_pk_mul_f32 v[2:3], v[2:3], v[4:5]
	v_accvgpr_read_b32 v4, a58
	v_mul_f32_e32 v1, 0xbfb8aa3b, v4
	v_exp_f32_e32 v1, v1
	v_accvgpr_read_b32 v5, a59
	v_cvt_pk_bf16_f32 v2, v2, v3
	v_add_f32_e32 v1, 1.0, v1
	v_rcp_f32_e32 v6, v1
	v_mul_f32_e32 v1, 0xbfb8aa3b, v5
	v_exp_f32_e32 v1, v1
	s_nop 0
	v_add_f32_e32 v1, 1.0, v1
	v_rcp_f32_e32 v7, v1
	s_nop 0
	v_pk_mul_f32 v[4:5], v[4:5], v[6:7]
	s_nop 0
	v_cvt_pk_bf16_f32 v3, v4, v5
	v_accvgpr_read_b32 v4, a60
	v_mul_f32_e32 v1, 0xbfb8aa3b, v4
	v_exp_f32_e32 v1, v1
	v_accvgpr_read_b32 v5, a61
	v_add_f32_e32 v1, 1.0, v1
	v_rcp_f32_e32 v6, v1
	v_mul_f32_e32 v1, 0xbfb8aa3b, v5
	v_exp_f32_e32 v1, v1
	s_nop 0
	v_add_f32_e32 v1, 1.0, v1
	v_rcp_f32_e32 v7, v1
	s_nop 0
	v_pk_mul_f32 v[4:5], v[4:5], v[6:7]
	v_accvgpr_read_b32 v6, a62
	v_mul_f32_e32 v1, 0xbfb8aa3b, v6
	v_exp_f32_e32 v1, v1
	v_accvgpr_read_b32 v7, a63
	v_cvt_pk_bf16_f32 v4, v4, v5
	v_add_f32_e32 v1, 1.0, v1
	v_rcp_f32_e32 v8, v1
	v_mul_f32_e32 v1, 0xbfb8aa3b, v7
	v_exp_f32_e32 v1, v1
	s_nop 0
	v_add_f32_e32 v1, 1.0, v1
	v_rcp_f32_e32 v9, v1
	v_accvgpr_read_b32 v1, a32
	v_mul_f32_e32 v1, 0xbfb8aa3b, v1
	v_exp_f32_e32 v1, v1
	v_pk_mul_f32 v[6:7], v[6:7], v[8:9]
	v_add_f32_e32 v1, 1.0, v1
	v_cvt_pk_bf16_f32 v5, v6, v7
	ds_write2_b64 v0, v[2:3], v[4:5] offset0:196 offset1:198
	v_rcp_f32_e32 v2, v1
	v_accvgpr_read_b32 v1, a33
	v_mul_f32_e32 v1, 0xbfb8aa3b, v1
	v_exp_f32_e32 v1, v1
	v_accvgpr_read_b32 v4, a32
	v_accvgpr_read_b32 v5, a33
	v_add_f32_e32 v1, 1.0, v1
	v_rcp_f32_e32 v3, v1
	s_nop 0
	v_pk_mul_f32 v[2:3], v[4:5], v[2:3]
	v_accvgpr_read_b32 v4, a34
	v_mul_f32_e32 v1, 0xbfb8aa3b, v4
	v_exp_f32_e32 v1, v1
	v_accvgpr_read_b32 v5, a35
	v_cvt_pk_bf16_f32 v2, v2, v3
	v_add_f32_e32 v1, 1.0, v1
	v_rcp_f32_e32 v6, v1
	v_mul_f32_e32 v1, 0xbfb8aa3b, v5
	v_exp_f32_e32 v1, v1
	s_nop 0
	v_add_f32_e32 v1, 1.0, v1
	v_rcp_f32_e32 v7, v1
	s_nop 0
	v_pk_mul_f32 v[4:5], v[4:5], v[6:7]
	s_nop 0
	v_cvt_pk_bf16_f32 v3, v4, v5
	v_accvgpr_read_b32 v4, a36
	v_mul_f32_e32 v1, 0xbfb8aa3b, v4
	v_exp_f32_e32 v1, v1
	v_accvgpr_read_b32 v5, a37
	v_add_f32_e32 v1, 1.0, v1
	v_rcp_f32_e32 v6, v1
	v_mul_f32_e32 v1, 0xbfb8aa3b, v5
	v_exp_f32_e32 v1, v1
	s_nop 0
	v_add_f32_e32 v1, 1.0, v1
	v_rcp_f32_e32 v7, v1
	s_nop 0
	v_pk_mul_f32 v[4:5], v[4:5], v[6:7]
	v_accvgpr_read_b32 v6, a38
	v_mul_f32_e32 v1, 0xbfb8aa3b, v6
	v_exp_f32_e32 v1, v1
	v_accvgpr_read_b32 v7, a39
	v_cvt_pk_bf16_f32 v4, v4, v5
	v_add_f32_e32 v1, 1.0, v1
	v_rcp_f32_e32 v8, v1
	v_mul_f32_e32 v1, 0xbfb8aa3b, v7
	v_exp_f32_e32 v1, v1
	s_nop 0
	v_add_f32_e32 v1, 1.0, v1
	v_rcp_f32_e32 v9, v1
	s_nop 0
	v_pk_mul_f32 v[6:7], v[6:7], v[8:9]
	s_nop 0
	v_cvt_pk_bf16_f32 v5, v6, v7
	ds_write2_b64 v0, v[2:3], v[4:5] offset0:200 offset1:202
	v_accvgpr_read_b32 v2, a40
	v_mul_f32_e32 v1, 0xbfb8aa3b, v2
	v_exp_f32_e32 v1, v1
	v_accvgpr_read_b32 v3, a41
	v_add_f32_e32 v1, 1.0, v1
	v_rcp_f32_e32 v4, v1
	v_mul_f32_e32 v1, 0xbfb8aa3b, v3
	v_exp_f32_e32 v1, v1
	s_nop 0
	v_add_f32_e32 v1, 1.0, v1
	v_rcp_f32_e32 v5, v1
	s_nop 0
	v_pk_mul_f32 v[2:3], v[2:3], v[4:5]
	v_accvgpr_read_b32 v4, a42
	v_mul_f32_e32 v1, 0xbfb8aa3b, v4
	v_exp_f32_e32 v1, v1
	v_accvgpr_read_b32 v5, a43
	v_cvt_pk_bf16_f32 v2, v2, v3
	v_add_f32_e32 v1, 1.0, v1
	v_rcp_f32_e32 v6, v1
	v_mul_f32_e32 v1, 0xbfb8aa3b, v5
	v_exp_f32_e32 v1, v1
	s_nop 0
	v_add_f32_e32 v1, 1.0, v1
	v_rcp_f32_e32 v7, v1
	s_nop 0
	v_pk_mul_f32 v[4:5], v[4:5], v[6:7]
	s_nop 0
	v_cvt_pk_bf16_f32 v3, v4, v5
	v_accvgpr_read_b32 v4, a44
	v_mul_f32_e32 v1, 0xbfb8aa3b, v4
	v_exp_f32_e32 v1, v1
	v_accvgpr_read_b32 v5, a45
	v_add_f32_e32 v1, 1.0, v1
	v_rcp_f32_e32 v6, v1
	v_mul_f32_e32 v1, 0xbfb8aa3b, v5
	v_exp_f32_e32 v1, v1
	s_nop 0
	v_add_f32_e32 v1, 1.0, v1
	v_rcp_f32_e32 v7, v1
	s_nop 0
	v_pk_mul_f32 v[4:5], v[4:5], v[6:7]
	v_accvgpr_read_b32 v6, a46
	v_mul_f32_e32 v1, 0xbfb8aa3b, v6
	v_exp_f32_e32 v1, v1
	v_accvgpr_read_b32 v7, a47
	v_cvt_pk_bf16_f32 v4, v4, v5
	v_add_f32_e32 v1, 1.0, v1
	v_rcp_f32_e32 v8, v1
	v_mul_f32_e32 v1, 0xbfb8aa3b, v7
	v_exp_f32_e32 v1, v1
	s_nop 0
	v_add_f32_e32 v1, 1.0, v1
	v_rcp_f32_e32 v9, v1
	v_accvgpr_read_b32 v1, a16
	v_mul_f32_e32 v1, 0xbfb8aa3b, v1
	v_exp_f32_e32 v1, v1
	v_pk_mul_f32 v[6:7], v[6:7], v[8:9]
	v_add_f32_e32 v1, 1.0, v1
	v_cvt_pk_bf16_f32 v5, v6, v7
	ds_write2_b64 v0, v[2:3], v[4:5] offset0:204 offset1:206
	v_rcp_f32_e32 v2, v1
	v_accvgpr_read_b32 v1, a17
	v_mul_f32_e32 v1, 0xbfb8aa3b, v1
	v_exp_f32_e32 v1, v1
	v_accvgpr_read_b32 v4, a16
	v_accvgpr_read_b32 v5, a17
	v_add_f32_e32 v1, 1.0, v1
	v_rcp_f32_e32 v3, v1
	s_nop 0
	v_pk_mul_f32 v[2:3], v[4:5], v[2:3]
	v_accvgpr_read_b32 v4, a18
	v_mul_f32_e32 v1, 0xbfb8aa3b, v4
	v_exp_f32_e32 v1, v1
	v_accvgpr_read_b32 v5, a19
	v_cvt_pk_bf16_f32 v2, v2, v3
	v_add_f32_e32 v1, 1.0, v1
	v_rcp_f32_e32 v6, v1
	v_mul_f32_e32 v1, 0xbfb8aa3b, v5
	v_exp_f32_e32 v1, v1
	s_nop 0
	v_add_f32_e32 v1, 1.0, v1
	v_rcp_f32_e32 v7, v1
	s_nop 0
	v_pk_mul_f32 v[4:5], v[4:5], v[6:7]
	s_nop 0
	v_cvt_pk_bf16_f32 v3, v4, v5
	v_accvgpr_read_b32 v4, a20
	v_mul_f32_e32 v1, 0xbfb8aa3b, v4
	v_exp_f32_e32 v1, v1
	v_accvgpr_read_b32 v5, a21
	v_add_f32_e32 v1, 1.0, v1
	v_rcp_f32_e32 v6, v1
	v_mul_f32_e32 v1, 0xbfb8aa3b, v5
	v_exp_f32_e32 v1, v1
	s_nop 0
	v_add_f32_e32 v1, 1.0, v1
	v_rcp_f32_e32 v7, v1
	s_nop 0
	v_pk_mul_f32 v[4:5], v[4:5], v[6:7]
	v_accvgpr_read_b32 v6, a22
	v_mul_f32_e32 v1, 0xbfb8aa3b, v6
	v_exp_f32_e32 v1, v1
	v_accvgpr_read_b32 v7, a23
	v_cvt_pk_bf16_f32 v4, v4, v5
	v_add_f32_e32 v1, 1.0, v1
	v_rcp_f32_e32 v8, v1
	v_mul_f32_e32 v1, 0xbfb8aa3b, v7
	v_exp_f32_e32 v1, v1
	s_nop 0
	v_add_f32_e32 v1, 1.0, v1
	v_rcp_f32_e32 v9, v1
	s_nop 0
	v_pk_mul_f32 v[6:7], v[6:7], v[8:9]
	s_nop 0
	v_cvt_pk_bf16_f32 v5, v6, v7
	ds_write2_b64 v0, v[2:3], v[4:5] offset0:208 offset1:210
	v_accvgpr_read_b32 v2, a24
	v_mul_f32_e32 v1, 0xbfb8aa3b, v2
	v_exp_f32_e32 v1, v1
	v_accvgpr_read_b32 v3, a25
	v_add_f32_e32 v1, 1.0, v1
	v_rcp_f32_e32 v4, v1
	v_mul_f32_e32 v1, 0xbfb8aa3b, v3
	v_exp_f32_e32 v1, v1
	s_nop 0
	v_add_f32_e32 v1, 1.0, v1
	v_rcp_f32_e32 v5, v1
	s_nop 0
	v_pk_mul_f32 v[2:3], v[2:3], v[4:5]
	v_accvgpr_read_b32 v4, a26
	v_mul_f32_e32 v1, 0xbfb8aa3b, v4
	v_exp_f32_e32 v1, v1
	v_accvgpr_read_b32 v5, a27
	v_cvt_pk_bf16_f32 v2, v2, v3
	v_add_f32_e32 v1, 1.0, v1
	v_rcp_f32_e32 v6, v1
	v_mul_f32_e32 v1, 0xbfb8aa3b, v5
	v_exp_f32_e32 v1, v1
	s_nop 0
	v_add_f32_e32 v1, 1.0, v1
	v_rcp_f32_e32 v7, v1
	s_nop 0
	v_pk_mul_f32 v[4:5], v[4:5], v[6:7]
	s_nop 0
	v_cvt_pk_bf16_f32 v3, v4, v5
	v_accvgpr_read_b32 v4, a28
	v_mul_f32_e32 v1, 0xbfb8aa3b, v4
	v_exp_f32_e32 v1, v1
	v_accvgpr_read_b32 v5, a29
	v_add_f32_e32 v1, 1.0, v1
	v_rcp_f32_e32 v6, v1
	v_mul_f32_e32 v1, 0xbfb8aa3b, v5
	v_exp_f32_e32 v1, v1
	s_nop 0
	v_add_f32_e32 v1, 1.0, v1
	v_rcp_f32_e32 v7, v1
	s_nop 0
	v_pk_mul_f32 v[4:5], v[4:5], v[6:7]
	v_accvgpr_read_b32 v6, a30
	v_mul_f32_e32 v1, 0xbfb8aa3b, v6
	v_exp_f32_e32 v1, v1
	v_accvgpr_read_b32 v7, a31
	v_cvt_pk_bf16_f32 v4, v4, v5
	v_add_f32_e32 v1, 1.0, v1
	v_rcp_f32_e32 v8, v1
	v_mul_f32_e32 v1, 0xbfb8aa3b, v7
	v_exp_f32_e32 v1, v1
	s_nop 0
	v_add_f32_e32 v1, 1.0, v1
	v_rcp_f32_e32 v9, v1
	v_accvgpr_read_b32 v1, a0
	v_mul_f32_e32 v1, 0xbfb8aa3b, v1
	v_exp_f32_e32 v1, v1
	v_pk_mul_f32 v[6:7], v[6:7], v[8:9]
	v_add_f32_e32 v1, 1.0, v1
	v_cvt_pk_bf16_f32 v5, v6, v7
	ds_write2_b64 v0, v[2:3], v[4:5] offset0:212 offset1:214
	v_rcp_f32_e32 v2, v1
	v_accvgpr_read_b32 v1, a1
	v_mul_f32_e32 v1, 0xbfb8aa3b, v1
	v_exp_f32_e32 v1, v1
	v_accvgpr_read_b32 v5, a1
	v_accvgpr_read_b32 v4, a0
	v_add_f32_e32 v1, 1.0, v1
	v_rcp_f32_e32 v3, v1
	s_nop 0
	v_pk_mul_f32 v[2:3], v[4:5], v[2:3]
	v_accvgpr_read_b32 v4, a2
	v_mul_f32_e32 v1, 0xbfb8aa3b, v4
	v_exp_f32_e32 v1, v1
	v_accvgpr_read_b32 v5, a3
	v_cvt_pk_bf16_f32 v2, v2, v3
	v_add_f32_e32 v1, 1.0, v1
	v_rcp_f32_e32 v6, v1
	v_mul_f32_e32 v1, 0xbfb8aa3b, v5
	v_exp_f32_e32 v1, v1
	s_nop 0
	v_add_f32_e32 v1, 1.0, v1
	v_rcp_f32_e32 v7, v1
	s_nop 0
	v_pk_mul_f32 v[4:5], v[4:5], v[6:7]
	s_nop 0
	v_cvt_pk_bf16_f32 v3, v4, v5
	v_accvgpr_read_b32 v4, a4
	v_mul_f32_e32 v1, 0xbfb8aa3b, v4
	v_exp_f32_e32 v1, v1
	v_accvgpr_read_b32 v5, a5
	v_add_f32_e32 v1, 1.0, v1
	v_rcp_f32_e32 v6, v1
	v_mul_f32_e32 v1, 0xbfb8aa3b, v5
	v_exp_f32_e32 v1, v1
	s_nop 0
	v_add_f32_e32 v1, 1.0, v1
	v_rcp_f32_e32 v7, v1
	s_nop 0
	v_pk_mul_f32 v[4:5], v[4:5], v[6:7]
	v_accvgpr_read_b32 v6, a6
	v_mul_f32_e32 v1, 0xbfb8aa3b, v6
	v_exp_f32_e32 v1, v1
	v_accvgpr_read_b32 v7, a7
	v_cvt_pk_bf16_f32 v4, v4, v5
	v_add_f32_e32 v1, 1.0, v1
	v_rcp_f32_e32 v8, v1
	v_mul_f32_e32 v1, 0xbfb8aa3b, v7
	v_exp_f32_e32 v1, v1
	s_nop 0
	v_add_f32_e32 v1, 1.0, v1
	v_rcp_f32_e32 v9, v1
	s_nop 0
	v_pk_mul_f32 v[6:7], v[6:7], v[8:9]
	s_nop 0
	v_cvt_pk_bf16_f32 v5, v6, v7
	ds_write2_b64 v0, v[2:3], v[4:5] offset0:216 offset1:218
	v_accvgpr_read_b32 v2, a8
	v_mul_f32_e32 v1, 0xbfb8aa3b, v2
	v_exp_f32_e32 v1, v1
	v_accvgpr_read_b32 v3, a9
	v_add_f32_e32 v1, 1.0, v1
	v_rcp_f32_e32 v4, v1
	v_mul_f32_e32 v1, 0xbfb8aa3b, v3
	v_exp_f32_e32 v1, v1
	s_nop 0
	v_add_f32_e32 v1, 1.0, v1
	v_rcp_f32_e32 v5, v1
	s_nop 0
	v_pk_mul_f32 v[2:3], v[2:3], v[4:5]
	v_accvgpr_read_b32 v4, a10
	v_mul_f32_e32 v1, 0xbfb8aa3b, v4
	v_exp_f32_e32 v1, v1
	v_accvgpr_read_b32 v5, a11
	v_cvt_pk_bf16_f32 v2, v2, v3
	v_add_f32_e32 v1, 1.0, v1
	v_rcp_f32_e32 v6, v1
	v_mul_f32_e32 v1, 0xbfb8aa3b, v5
	v_exp_f32_e32 v1, v1
	s_nop 0
	v_add_f32_e32 v1, 1.0, v1
	v_rcp_f32_e32 v7, v1
	s_nop 0
	v_pk_mul_f32 v[4:5], v[4:5], v[6:7]
	s_nop 0
	v_cvt_pk_bf16_f32 v3, v4, v5
	v_accvgpr_read_b32 v4, a12
	v_mul_f32_e32 v1, 0xbfb8aa3b, v4
	v_exp_f32_e32 v1, v1
	v_accvgpr_read_b32 v5, a13
	v_add_f32_e32 v1, 1.0, v1
	v_rcp_f32_e32 v6, v1
	v_mul_f32_e32 v1, 0xbfb8aa3b, v5
	v_exp_f32_e32 v1, v1
	s_nop 0
	v_add_f32_e32 v1, 1.0, v1
	v_rcp_f32_e32 v7, v1
	s_nop 0
	v_pk_mul_f32 v[4:5], v[4:5], v[6:7]
	v_accvgpr_read_b32 v6, a14
	v_mul_f32_e32 v1, 0xbfb8aa3b, v6
	v_exp_f32_e32 v1, v1
	v_accvgpr_read_b32 v7, a15
	v_cvt_pk_bf16_f32 v4, v4, v5
	v_add_f32_e32 v1, 1.0, v1
	v_rcp_f32_e32 v8, v1
	v_mul_f32_e32 v1, 0xbfb8aa3b, v7
	v_exp_f32_e32 v1, v1
	s_nop 0
	v_add_f32_e32 v1, 1.0, v1
	v_rcp_f32_e32 v9, v1
	s_nop 0
	v_pk_mul_f32 v[6:7], v[6:7], v[8:9]
	s_nop 0
	v_cvt_pk_bf16_f32 v5, v6, v7
	ds_write2_b64 v0, v[2:3], v[4:5] offset0:220 offset1:222
	s_lshl_b64 s[14:15], s[12:13], 12
	s_add_u32 s5, s92, s14
	s_addc_u32 s11, s93, s15
	s_lshl_b32 s13, s10, 9
	s_add_u32 s14, s5, s13
	s_mov_b32 s5, 0
	s_waitcnt lgkmcnt(0)
	s_barrier
	s_addc_u32 s15, s11, 0
	v_mbcnt_lo_u32_b32 v0, -1, s5
	v_mbcnt_hi_u32_b32 v0, -1, v0
	v_or_b32_e32 v2, s60, v0
	v_lshlrev_b32_e32 v0, 4, v0
	v_and_b32_e32 v252, 0x1f0, v0
	v_lshl_add_u64 v[0:1], s[14:15], 0, v[252:253]
	s_mov_b64 s[14:15], 0x2a0fe000
	v_lshl_add_u64 v[0:1], v[0:1], 0, s[14:15]

.LBB0_214:
	s_add_i32 s11, s13, 0xffff8000
	s_and_b32 s11, s11, 0x8000
	s_lshl_b32 s11, s11, 1
	v_lshl_or_b32 v250, v13, 1, s11
	v_add_u32_e32 v249, v250, v9
	v_add_u32_e32 v250, v250, v8
	ds_read_b128 v[14:17], v249
	ds_read_b128 v[18:21], v250 offset:32768
	ds_read_b128 v[22:25], v250 offset:36864
	ds_read_b128 v[26:29], v250 offset:40960
	ds_read_b128 v[30:33], v250 offset:45056
	ds_read_b128 v[48:51], v249 offset:4096
	s_waitcnt lgkmcnt(4)
	v_mfma_f32_32x32x16_bf16 a[240:255], v[14:17], v[18:21], a[240:255]
	s_waitcnt lgkmcnt(3)
	v_mfma_f32_32x32x16_bf16 a[176:191], v[14:17], v[22:25], a[176:191]
	s_and_b32 s98, s13, 0x8000
	s_lshl_b32 s98, s98, 1
	s_add_i32 s98, s62, s98
	v_lshl_add_u64 v[38:39], v[0:1], 0, s[4:5]
	v_lshl_add_u64 v[40:41], v[38:39], 0, s[38:39]
	s_mov_b32 m0, s98
	s_add_i32 s14, s98, 0x8000
	global_load_lds_dwordx4 v[40:41], off
	s_waitcnt lgkmcnt(2)
	v_mfma_f32_32x32x16_bf16 a[112:127], v[14:17], v[26:29], a[112:127]
	v_lshl_add_u64 v[40:41], v[4:5], 0, s[4:5]
	v_lshl_add_u64 v[42:43], v[40:41], 0, s[16:17]
	s_mov_b32 m0, s14
	s_nop 0
	global_load_lds_dwordx4 v[42:43], off
	s_waitcnt lgkmcnt(1)
	v_mfma_f32_32x32x16_bf16 a[48:63], v[14:17], v[30:33], a[48:63]
	v_lshl_add_u64 v[42:43], v[2:3], 0, s[4:5]
	v_lshl_add_u64 v[44:45], v[42:43], 0, s[44:45]
	s_add_i32 m0, s98, 0x400
	s_nop 0
	global_load_lds_dwordx4 v[44:45], off
	ds_read_b128 v[14:17], v249 offset:8192
	s_waitcnt lgkmcnt(1)
	v_mfma_f32_32x32x16_bf16 a[224:239], v[48:51], v[18:21], a[224:239]
	v_lshl_add_u64 v[44:45], v[6:7], 0, s[4:5]
	v_lshl_add_u64 v[46:47], v[44:45], 0, s[30:31]
	s_add_i32 m0, s98, 0x8400
	s_nop 0
	global_load_lds_dwordx4 v[46:47], off
	v_mfma_f32_32x32x16_bf16 a[160:175], v[48:51], v[22:25], a[160:175]
	v_lshl_add_u64 v[46:47], v[38:39], 0, s[2:3]
	s_add_i32 m0, s98, 0x800
	s_nop 0
	global_load_lds_dwordx4 v[46:47], off
	v_mfma_f32_32x32x16_bf16 a[96:111], v[48:51], v[26:29], a[96:111]
	v_lshl_add_u64 v[46:47], v[40:41], 0, s[40:41]
	s_add_i32 m0, s98, 0x8800
	s_nop 0
	global_load_lds_dwordx4 v[46:47], off
	v_mfma_f32_32x32x16_bf16 a[32:47], v[48:51], v[30:33], a[32:47]
	v_lshl_add_u64 v[46:47], v[42:43], 0, s[46:47]
	s_add_i32 m0, s98, 0xc00
	s_nop 0
	global_load_lds_dwordx4 v[46:47], off
	ds_read_b128 v[48:51], v249 offset:12288
	s_waitcnt lgkmcnt(1)
	v_mfma_f32_32x32x16_bf16 a[208:223], v[14:17], v[18:21], a[208:223]
	v_lshl_add_u64 v[46:47], v[44:45], 0, s[68:69]
	s_add_i32 m0, s98, 0x8c00
	s_nop 0
	global_load_lds_dwordx4 v[46:47], off
	v_mfma_f32_32x32x16_bf16 a[144:159], v[14:17], v[22:25], a[144:159]
	v_lshl_add_u64 v[46:47], v[38:39], 0, s[50:51]
	s_add_i32 m0, s98, 0x1000
	v_lshl_add_u64 v[38:39], v[38:39], 0, s[54:55]
	global_load_lds_dwordx4 v[46:47], off
	v_mfma_f32_32x32x16_bf16 a[80:95], v[14:17], v[26:29], a[80:95]
	v_lshl_add_u64 v[46:47], v[40:41], 0, s[70:71]
	s_add_i32 m0, s98, 0x9000
	s_nop 0
	global_load_lds_dwordx4 v[46:47], off
	v_mfma_f32_32x32x16_bf16 a[16:31], v[14:17], v[30:33], a[16:31]
	v_lshl_add_u64 v[46:47], v[42:43], 0, s[52:53]
	s_add_i32 m0, s98, 0x1400
	s_nop 0
	global_load_lds_dwordx4 v[46:47], off
	v_lshl_or_b32 v250, v12, 1, s11
	v_add_u32_e32 v249, v250, v9
	v_add_u32_e32 v250, v250, v8
	ds_read_b128 v[14:17], v249
	s_waitcnt lgkmcnt(1)
	v_mfma_f32_32x32x16_bf16 a[192:207], v[48:51], v[18:21], a[192:207]
	v_lshl_add_u64 v[46:47], v[44:45], 0, s[76:77]
	s_add_i32 m0, s98, 0x9400
	s_nop 0
	global_load_lds_dwordx4 v[46:47], off
	ds_read_b128 v[18:21], v250 offset:32768
	v_mfma_f32_32x32x16_bf16 a[128:143], v[48:51], v[22:25], a[128:143]
	s_add_i32 m0, s98, 0x1800
	s_nop 0
	global_load_lds_dwordx4 v[38:39], off
	ds_read_b128 v[22:25], v250 offset:36864
	v_mfma_f32_32x32x16_bf16 a[64:79], v[48:51], v[26:29], a[64:79]
	v_lshl_add_u64 v[38:39], v[40:41], 0, s[78:79]
	s_add_i32 m0, s98, 0x9800
	s_nop 0
	global_load_lds_dwordx4 v[38:39], off
	ds_read_b128 v[26:29], v250 offset:40960
	v_mfma_f32_32x32x16_bf16 a[0:15], v[48:51], v[30:33], a[0:15]
	v_lshl_add_u64 v[38:39], v[42:43], 0, s[56:57]
	s_add_i32 m0, s98, 0x1c00
	s_nop 0
	global_load_lds_dwordx4 v[38:39], off
	ds_read_b128 v[30:33], v250 offset:45056
	ds_read_b128 v[48:51], v249 offset:4096
	s_waitcnt lgkmcnt(4)
	v_mfma_f32_32x32x16_bf16 a[240:255], v[14:17], v[18:21], a[240:255]
	v_lshl_add_u64 v[38:39], v[44:45], 0, s[80:81]
	s_add_i32 m0, s98, 0x9c00
	s_nop 0
	global_load_lds_dwordx4 v[38:39], off
	s_waitcnt lgkmcnt(3)
	v_mfma_f32_32x32x16_bf16 a[176:191], v[14:17], v[22:25], a[176:191]
	s_waitcnt lgkmcnt(2)
	v_mfma_f32_32x32x16_bf16 a[112:127], v[14:17], v[26:29], a[112:127]
	s_waitcnt lgkmcnt(1)
	v_mfma_f32_32x32x16_bf16 a[48:63], v[14:17], v[30:33], a[48:63]
	ds_read_b128 v[14:17], v249 offset:8192
	s_waitcnt lgkmcnt(1)
	v_mfma_f32_32x32x16_bf16 a[224:239], v[48:51], v[18:21], a[224:239]
	v_mfma_f32_32x32x16_bf16 a[160:175], v[48:51], v[22:25], a[160:175]
	v_mfma_f32_32x32x16_bf16 a[96:111], v[48:51], v[26:29], a[96:111]
	v_mfma_f32_32x32x16_bf16 a[32:47], v[48:51], v[30:33], a[32:47]
	ds_read_b128 v[48:51], v249 offset:12288
	s_waitcnt lgkmcnt(1)
	v_mfma_f32_32x32x16_bf16 a[208:223], v[14:17], v[18:21], a[208:223]
	v_mfma_f32_32x32x16_bf16 a[144:159], v[14:17], v[22:25], a[144:159]
	v_mfma_f32_32x32x16_bf16 a[80:95], v[14:17], v[26:29], a[80:95]
	v_mfma_f32_32x32x16_bf16 a[16:31], v[14:17], v[30:33], a[16:31]
	v_lshl_or_b32 v250, v11, 1, s11
	v_add_u32_e32 v249, v250, v9
	v_add_u32_e32 v250, v250, v8
	ds_read_b128 v[14:17], v249
	s_waitcnt lgkmcnt(1)
	v_mfma_f32_32x32x16_bf16 a[192:207], v[48:51], v[18:21], a[192:207]
	ds_read_b128 v[18:21], v250 offset:32768
	v_mfma_f32_32x32x16_bf16 a[128:143], v[48:51], v[22:25], a[128:143]
	ds_read_b128 v[22:25], v250 offset:36864
	v_mfma_f32_32x32x16_bf16 a[64:79], v[48:51], v[26:29], a[64:79]
	ds_read_b128 v[26:29], v250 offset:40960
	v_mfma_f32_32x32x16_bf16 a[0:15], v[48:51], v[30:33], a[0:15]
	ds_read_b128 v[30:33], v250 offset:45056
	ds_read_b128 v[48:51], v249 offset:4096
	s_waitcnt lgkmcnt(4)
	v_mfma_f32_32x32x16_bf16 a[240:255], v[14:17], v[18:21], a[240:255]
	s_waitcnt lgkmcnt(3)
	v_mfma_f32_32x32x16_bf16 a[176:191], v[14:17], v[22:25], a[176:191]
	s_waitcnt lgkmcnt(2)
	v_mfma_f32_32x32x16_bf16 a[112:127], v[14:17], v[26:29], a[112:127]
	s_waitcnt lgkmcnt(1)
	v_mfma_f32_32x32x16_bf16 a[48:63], v[14:17], v[30:33], a[48:63]
	ds_read_b128 v[14:17], v249 offset:8192
	s_waitcnt lgkmcnt(1)
	v_mfma_f32_32x32x16_bf16 a[224:239], v[48:51], v[18:21], a[224:239]
	v_mfma_f32_32x32x16_bf16 a[160:175], v[48:51], v[22:25], a[160:175]
	v_mfma_f32_32x32x16_bf16 a[96:111], v[48:51], v[26:29], a[96:111]
	v_mfma_f32_32x32x16_bf16 a[32:47], v[48:51], v[30:33], a[32:47]
	ds_read_b128 v[48:51], v249 offset:12288
	s_waitcnt lgkmcnt(1)
	v_mfma_f32_32x32x16_bf16 a[208:223], v[14:17], v[18:21], a[208:223]
	v_mfma_f32_32x32x16_bf16 a[144:159], v[14:17], v[22:25], a[144:159]
	v_mfma_f32_32x32x16_bf16 a[80:95], v[14:17], v[26:29], a[80:95]
	v_mfma_f32_32x32x16_bf16 a[16:31], v[14:17], v[30:33], a[16:31]
	v_lshl_or_b32 v250, v10, 1, s11
	v_add_u32_e32 v249, v250, v9
	v_add_u32_e32 v250, v250, v8
	ds_read_b128 v[14:17], v249
	s_waitcnt lgkmcnt(1)
	v_mfma_f32_32x32x16_bf16 a[192:207], v[48:51], v[18:21], a[192:207]
	ds_read_b128 v[18:21], v250 offset:32768
	v_mfma_f32_32x32x16_bf16 a[128:143], v[48:51], v[22:25], a[128:143]
	ds_read_b128 v[22:25], v250 offset:36864
	v_mfma_f32_32x32x16_bf16 a[64:79], v[48:51], v[26:29], a[64:79]
	ds_read_b128 v[26:29], v250 offset:40960
	v_mfma_f32_32x32x16_bf16 a[0:15], v[48:51], v[30:33], a[0:15]
	ds_read_b128 v[30:33], v250 offset:45056
	ds_read_b128 v[48:51], v249 offset:4096
	s_waitcnt lgkmcnt(4)
	v_mfma_f32_32x32x16_bf16 a[240:255], v[14:17], v[18:21], a[240:255]
	s_waitcnt lgkmcnt(3)
	v_mfma_f32_32x32x16_bf16 a[176:191], v[14:17], v[22:25], a[176:191]
	s_waitcnt lgkmcnt(2)
	v_mfma_f32_32x32x16_bf16 a[112:127], v[14:17], v[26:29], a[112:127]
	s_waitcnt lgkmcnt(1)
	v_mfma_f32_32x32x16_bf16 a[48:63], v[14:17], v[30:33], a[48:63]
	ds_read_b128 v[14:17], v249 offset:8192
	s_waitcnt lgkmcnt(1)
	v_mfma_f32_32x32x16_bf16 a[224:239], v[48:51], v[18:21], a[224:239]
	v_mfma_f32_32x32x16_bf16 a[160:175], v[48:51], v[22:25], a[160:175]
	v_mfma_f32_32x32x16_bf16 a[96:111], v[48:51], v[26:29], a[96:111]
	v_mfma_f32_32x32x16_bf16 a[32:47], v[48:51], v[30:33], a[32:47]
	ds_read_b128 v[48:51], v249 offset:12288
	s_waitcnt lgkmcnt(1)
	v_mfma_f32_32x32x16_bf16 a[208:223], v[14:17], v[18:21], a[208:223]
	v_mfma_f32_32x32x16_bf16 a[144:159], v[14:17], v[22:25], a[144:159]
	v_mfma_f32_32x32x16_bf16 a[80:95], v[14:17], v[26:29], a[80:95]
	v_mfma_f32_32x32x16_bf16 a[16:31], v[14:17], v[30:33], a[16:31]
	s_waitcnt vmcnt(0)
	s_waitcnt vmcnt(0) lgkmcnt(0)
	s_barrier
	s_add_u32 s4, s4, 0x80
	s_addc_u32 s5, s5, 0
	s_add_i32 s13, s13, 0x8000
	s_cmpk_lg_i32 s4, 0x780
	v_mfma_f32_32x32x16_bf16 a[192:207], v[48:51], v[18:21], a[192:207]
	v_mfma_f32_32x32x16_bf16 a[128:143], v[48:51], v[22:25], a[128:143]
	v_mfma_f32_32x32x16_bf16 a[64:79], v[48:51], v[26:29], a[64:79]
	v_mfma_f32_32x32x16_bf16 a[0:15], v[48:51], v[30:33], a[0:15]
	s_cbranch_scc1 .LBB0_214
	v_lshlrev_b32_e32 v13, 1, v13
	s_mov_b32 s4, 0x10000
	s_mov_b32 s5, 0x18000
	v_add3_u32 v18, v9, v13, s4
	v_add3_u32 v13, v8, v13, s5
	ds_read_b128 v[0:3], v18
	ds_read_b128 v[4:7], v18 offset:4096
	ds_read_b128 v[14:17], v18 offset:8192
	ds_read_b128 v[18:21], v18 offset:12288
	ds_read_b128 v[22:25], v13
	ds_read_b128 v[26:29], v13 offset:4096
	ds_read_b128 v[30:33], v13 offset:8192
	ds_read_b128 v[34:37], v13 offset:12288
	s_waitcnt lgkmcnt(3)
	v_mfma_f32_32x32x16_bf16 a[240:255], v[0:3], v[22:25], a[240:255]
	v_lshlrev_b32_e32 v11, 1, v11
	s_lshl_b32 s11, s10, 8
	s_waitcnt lgkmcnt(2)
	v_mfma_f32_32x32x16_bf16 a[176:191], v[0:3], v[26:29], a[176:191]
	s_waitcnt lgkmcnt(1)
	v_mfma_f32_32x32x16_bf16 a[112:127], v[0:3], v[30:33], a[112:127]
	s_waitcnt lgkmcnt(0)
	v_mfma_f32_32x32x16_bf16 a[48:63], v[0:3], v[34:37], a[48:63]
	v_mfma_f32_32x32x16_bf16 a[192:207], v[18:21], v[22:25], a[192:207]
	v_mfma_f32_32x32x16_bf16 a[128:143], v[18:21], v[26:29], a[128:143]
	v_mfma_f32_32x32x16_bf16 a[64:79], v[18:21], v[30:33], a[64:79]
	v_mfma_f32_32x32x16_bf16 a[0:15], v[18:21], v[34:37], a[0:15]
	v_lshlrev_b32_e32 v20, 1, v12
	v_mfma_f32_32x32x16_bf16 a[96:111], v[4:7], v[30:33], a[96:111]
	v_mfma_f32_32x32x16_bf16 a[208:223], v[14:17], v[22:25], a[208:223]
	v_mfma_f32_32x32x16_bf16 a[144:159], v[14:17], v[26:29], a[144:159]
	v_mfma_f32_32x32x16_bf16 a[80:95], v[14:17], v[30:33], a[80:95]
	v_add3_u32 v32, v8, v20, s5
	v_mfma_f32_32x32x16_bf16 a[16:31], v[14:17], v[34:37], a[16:31]
	v_add3_u32 v16, v9, v20, s4
	v_mfma_f32_32x32x16_bf16 a[224:239], v[4:7], v[22:25], a[224:239]
	v_mfma_f32_32x32x16_bf16 a[160:175], v[4:7], v[26:29], a[160:175]
	v_mfma_f32_32x32x16_bf16 a[32:47], v[4:7], v[34:37], a[32:47]
	ds_read_b128 v[0:3], v16
	ds_read_b128 v[4:7], v16 offset:4096
	ds_read_b128 v[12:15], v16 offset:8192
	ds_read_b128 v[16:19], v16 offset:12288
	ds_read_b128 v[20:23], v32
	ds_read_b128 v[24:27], v32 offset:4096
	ds_read_b128 v[28:31], v32 offset:8192
	ds_read_b128 v[32:35], v32 offset:12288
	s_waitcnt lgkmcnt(3)
	v_mfma_f32_32x32x16_bf16 a[240:255], v[0:3], v[20:23], a[240:255]
	s_waitcnt lgkmcnt(2)
	v_mfma_f32_32x32x16_bf16 a[176:191], v[0:3], v[24:27], a[176:191]
	s_waitcnt lgkmcnt(1)
	v_mfma_f32_32x32x16_bf16 a[112:127], v[0:3], v[28:31], a[112:127]
	s_waitcnt lgkmcnt(0)
	v_mfma_f32_32x32x16_bf16 a[48:63], v[0:3], v[32:35], a[48:63]
	v_mfma_f32_32x32x16_bf16 a[192:207], v[16:19], v[20:23], a[192:207]
	v_mfma_f32_32x32x16_bf16 a[128:143], v[16:19], v[24:27], a[128:143]
	v_mfma_f32_32x32x16_bf16 a[64:79], v[16:19], v[28:31], a[64:79]
	v_mfma_f32_32x32x16_bf16 a[0:15], v[16:19], v[32:35], a[0:15]
	v_add3_u32 v16, v9, v11, s4
	v_add3_u32 v11, v8, v11, s5
	v_mfma_f32_32x32x16_bf16 a[224:239], v[4:7], v[20:23], a[224:239]
	v_mfma_f32_32x32x16_bf16 a[160:175], v[4:7], v[24:27], a[160:175]
	v_mfma_f32_32x32x16_bf16 a[96:111], v[4:7], v[28:31], a[96:111]
	v_mfma_f32_32x32x16_bf16 a[32:47], v[4:7], v[32:35], a[32:47]
	v_mfma_f32_32x32x16_bf16 a[208:223], v[12:15], v[20:23], a[208:223]
	v_mfma_f32_32x32x16_bf16 a[144:159], v[12:15], v[24:27], a[144:159]
	v_mfma_f32_32x32x16_bf16 a[80:95], v[12:15], v[28:31], a[80:95]
	v_mfma_f32_32x32x16_bf16 a[16:31], v[12:15], v[32:35], a[16:31]
	ds_read_b128 v[0:3], v16
	ds_read_b128 v[4:7], v16 offset:4096
	ds_read_b128 v[12:15], v16 offset:8192
	ds_read_b128 v[16:19], v16 offset:12288
	ds_read_b128 v[20:23], v11
	ds_read_b128 v[24:27], v11 offset:4096
	ds_read_b128 v[28:31], v11 offset:8192
	ds_read_b128 v[32:35], v11 offset:12288
	s_waitcnt lgkmcnt(3)
	v_mfma_f32_32x32x16_bf16 a[240:255], v[0:3], v[20:23], a[240:255]
	s_waitcnt lgkmcnt(2)
	v_mfma_f32_32x32x16_bf16 a[176:191], v[0:3], v[24:27], a[176:191]
	s_waitcnt lgkmcnt(1)
	v_mfma_f32_32x32x16_bf16 a[112:127], v[0:3], v[28:31], a[112:127]
	s_waitcnt lgkmcnt(0)
	v_mfma_f32_32x32x16_bf16 a[48:63], v[0:3], v[32:35], a[48:63]
	v_mfma_f32_32x32x16_bf16 a[192:207], v[16:19], v[20:23], a[192:207]
	v_mfma_f32_32x32x16_bf16 a[128:143], v[16:19], v[24:27], a[128:143]
	v_mfma_f32_32x32x16_bf16 a[64:79], v[16:19], v[28:31], a[64:79]
	v_mfma_f32_32x32x16_bf16 a[0:15], v[16:19], v[32:35], a[0:15]
	v_lshlrev_b32_e32 v18, 1, v10
	v_add3_u32 v9, v9, v18, s4
	v_add3_u32 v8, v8, v18, s5
	s_mov_b32 s5, 0
	s_mov_b32 s4, 0
	v_mfma_f32_32x32x16_bf16 a[224:239], v[4:7], v[20:23], a[224:239]
	v_mfma_f32_32x32x16_bf16 a[160:175], v[4:7], v[24:27], a[160:175]
	v_mfma_f32_32x32x16_bf16 a[96:111], v[4:7], v[28:31], a[96:111]
	v_mfma_f32_32x32x16_bf16 a[32:47], v[4:7], v[32:35], a[32:47]
	v_mfma_f32_32x32x16_bf16 a[208:223], v[12:15], v[20:23], a[208:223]
	v_mfma_f32_32x32x16_bf16 a[144:159], v[12:15], v[24:27], a[144:159]
	v_mfma_f32_32x32x16_bf16 a[80:95], v[12:15], v[28:31], a[80:95]
	v_mfma_f32_32x32x16_bf16 a[16:31], v[12:15], v[32:35], a[16:31]
	ds_read_b128 v[0:3], v9
	ds_read_b128 v[4:7], v9 offset:4096
	ds_read_b128 v[10:13], v9 offset:8192
	ds_read_b128 v[14:17], v9 offset:12288
	ds_read_b128 v[18:21], v8
	ds_read_b128 v[22:25], v8 offset:4096
	ds_read_b128 v[26:29], v8 offset:8192
	ds_read_b128 v[30:33], v8 offset:12288
	s_waitcnt vmcnt(0)
	s_waitcnt lgkmcnt(0)
	s_barrier
	v_mfma_f32_32x32x16_bf16 a[240:255], v[0:3], v[18:21], a[240:255]
	v_mfma_f32_32x32x16_bf16 a[176:191], v[0:3], v[22:25], a[176:191]
	v_mfma_f32_32x32x16_bf16 a[112:127], v[0:3], v[26:29], a[112:127]
	v_mfma_f32_32x32x16_bf16 a[48:63], v[0:3], v[30:33], a[48:63]
	v_mbcnt_lo_u32_b32 v0, -1, s5
	v_mbcnt_hi_u32_b32 v0, -1, v0
	v_or_b32_e32 v1, s60, v0
	v_and_b32_e32 v2, 31, v0
	v_lshlrev_b32_e32 v1, 1, v1
	v_and_or_b32 v1, v1, s15, v2
	v_mov_b32_e32 v2, s60
	s_mov_b32 s5, 0x7fffff80
	v_bitop3_b32 v2, v0, s5, v2 bitop3:0xc8
	v_lshrrev_b32_e32 v0, 2, v0
	v_and_b32_e32 v0, 8, v0
	v_lshl_or_b32 v0, v2, 1, v0
	v_mad_u32_u24 v0, v1, s25, v0
	v_accvgpr_read_b32 v1, a241
	v_accvgpr_read_b32 v2, a240
	v_cvt_pk_bf16_f32 v2, v2, v1
	v_accvgpr_read_b32 v1, a243
	v_accvgpr_read_b32 v3, a242
	v_mfma_f32_32x32x16_bf16 a[224:239], v[4:7], v[18:21], a[224:239]
	v_cvt_pk_bf16_f32 v3, v3, v1
	v_accvgpr_read_b32 v1, a245
	s_lshl_b32 s5, s67, 11
	s_add_i32 s5, s11, s5
	s_add_i32 s14, s5, 0xfffff800
	s_ashr_i32 s15, s14, 31
	s_lshl_b64 s[14:15], s[14:15], 12
	v_mfma_f32_32x32x16_bf16 a[160:175], v[4:7], v[22:25], a[160:175]
	s_add_u32 s5, s34, s14
	s_addc_u32 s11, s42, s15
	s_lshl_b32 s13, s66, 1
	s_add_u32 s14, s5, s13
	s_mov_b32 s5, 0
	s_addc_u32 s15, s11, 0
	v_mfma_f32_32x32x16_bf16 a[96:111], v[4:7], v[26:29], a[96:111]
	v_mfma_f32_32x32x16_bf16 a[32:47], v[4:7], v[30:33], a[32:47]
	v_accvgpr_read_b32 v4, a244
	v_cvt_pk_bf16_f32 v4, v4, v1
	v_accvgpr_read_b32 v1, a247
	v_accvgpr_read_b32 v5, a246
	v_cvt_pk_bf16_f32 v5, v5, v1
	ds_write2_b64 v0, v[2:3], v[4:5] offset1:2
	v_accvgpr_read_b32 v1, a249
	v_accvgpr_read_b32 v2, a248
	v_cvt_pk_bf16_f32 v2, v2, v1
	v_accvgpr_read_b32 v1, a251
	v_accvgpr_read_b32 v3, a250
	v_cvt_pk_bf16_f32 v3, v3, v1
	v_accvgpr_read_b32 v1, a253
	v_accvgpr_read_b32 v4, a252
	v_cvt_pk_bf16_f32 v4, v4, v1
	v_accvgpr_read_b32 v1, a255
	v_accvgpr_read_b32 v5, a254
	v_cvt_pk_bf16_f32 v5, v5, v1
	ds_write2_b64 v0, v[2:3], v[4:5] offset0:4 offset1:6
	v_accvgpr_read_b32 v1, a225
	v_accvgpr_read_b32 v2, a224
	v_cvt_pk_bf16_f32 v2, v2, v1
	v_accvgpr_read_b32 v1, a227
	v_accvgpr_read_b32 v3, a226
	v_mfma_f32_32x32x16_bf16 a[208:223], v[10:13], v[18:21], a[208:223]
	v_cvt_pk_bf16_f32 v3, v3, v1
	v_accvgpr_read_b32 v1, a229
	v_accvgpr_read_b32 v4, a228
	v_cvt_pk_bf16_f32 v4, v4, v1
	v_accvgpr_read_b32 v1, a231
	v_accvgpr_read_b32 v5, a230
	v_cvt_pk_bf16_f32 v5, v5, v1
	ds_write2_b64 v0, v[2:3], v[4:5] offset0:8 offset1:10
	v_accvgpr_read_b32 v1, a233
	v_accvgpr_read_b32 v2, a232
	v_cvt_pk_bf16_f32 v2, v2, v1
	v_accvgpr_read_b32 v1, a235
	v_accvgpr_read_b32 v3, a234
	v_cvt_pk_bf16_f32 v3, v3, v1
	v_accvgpr_read_b32 v1, a237
	v_accvgpr_read_b32 v4, a236
	v_cvt_pk_bf16_f32 v4, v4, v1
	v_accvgpr_read_b32 v1, a239
	v_accvgpr_read_b32 v5, a238
	v_cvt_pk_bf16_f32 v5, v5, v1
	ds_write2_b64 v0, v[2:3], v[4:5] offset0:12 offset1:14
	v_accvgpr_read_b32 v1, a209
	v_accvgpr_read_b32 v2, a208
	v_cvt_pk_bf16_f32 v2, v2, v1
	v_accvgpr_read_b32 v1, a211
	v_accvgpr_read_b32 v3, a210
	v_mfma_f32_32x32x16_bf16 a[192:207], v[14:17], v[18:21], a[192:207]
	v_cvt_pk_bf16_f32 v3, v3, v1
	v_accvgpr_read_b32 v1, a213
	v_accvgpr_read_b32 v4, a212
	v_cvt_pk_bf16_f32 v4, v4, v1
	v_accvgpr_read_b32 v1, a215
	v_accvgpr_read_b32 v5, a214
	v_cvt_pk_bf16_f32 v5, v5, v1
	ds_write2_b64 v0, v[2:3], v[4:5] offset0:16 offset1:18
	v_accvgpr_read_b32 v1, a217
	v_accvgpr_read_b32 v2, a216
	v_cvt_pk_bf16_f32 v2, v2, v1
	v_accvgpr_read_b32 v1, a219
	v_accvgpr_read_b32 v3, a218
	v_cvt_pk_bf16_f32 v3, v3, v1
	v_accvgpr_read_b32 v1, a221
	v_accvgpr_read_b32 v4, a220
	v_cvt_pk_bf16_f32 v4, v4, v1
	v_accvgpr_read_b32 v1, a223
	v_accvgpr_read_b32 v5, a222
	v_cvt_pk_bf16_f32 v5, v5, v1
	ds_write2_b64 v0, v[2:3], v[4:5] offset0:20 offset1:22
	v_accvgpr_read_b32 v1, a193
	v_accvgpr_read_b32 v2, a192
	v_cvt_pk_bf16_f32 v2, v2, v1
	v_accvgpr_read_b32 v1, a195
	v_accvgpr_read_b32 v3, a194
	v_cvt_pk_bf16_f32 v3, v3, v1
	v_accvgpr_read_b32 v1, a197
	v_accvgpr_read_b32 v4, a196
	v_cvt_pk_bf16_f32 v4, v4, v1
	v_accvgpr_read_b32 v1, a199
	v_accvgpr_read_b32 v5, a198
	v_cvt_pk_bf16_f32 v5, v5, v1
	ds_write2_b64 v0, v[2:3], v[4:5] offset0:24 offset1:26
	v_accvgpr_read_b32 v1, a201
	v_accvgpr_read_b32 v2, a200
	v_cvt_pk_bf16_f32 v2, v2, v1
	v_accvgpr_read_b32 v1, a203
	v_accvgpr_read_b32 v3, a202
	v_cvt_pk_bf16_f32 v3, v3, v1
	v_accvgpr_read_b32 v1, a205
	v_accvgpr_read_b32 v4, a204
	v_cvt_pk_bf16_f32 v4, v4, v1
	v_accvgpr_read_b32 v1, a207
	v_accvgpr_read_b32 v5, a206
	v_cvt_pk_bf16_f32 v5, v5, v1
	ds_write2_b64 v0, v[2:3], v[4:5] offset0:28 offset1:30
	v_accvgpr_read_b32 v1, a177
	v_accvgpr_read_b32 v2, a176
	v_cvt_pk_bf16_f32 v2, v2, v1
	v_accvgpr_read_b32 v1, a179
	v_accvgpr_read_b32 v3, a178
	v_cvt_pk_bf16_f32 v3, v3, v1
	v_accvgpr_read_b32 v1, a181
	v_accvgpr_read_b32 v4, a180
	v_cvt_pk_bf16_f32 v4, v4, v1
	v_accvgpr_read_b32 v1, a183
	v_accvgpr_read_b32 v5, a182
	v_cvt_pk_bf16_f32 v5, v5, v1
	v_add_u32_e32 v1, 0x4000, v0
	ds_write2_b64 v1, v[2:3], v[4:5] offset0:64 offset1:66
	v_accvgpr_read_b32 v2, a185
	v_accvgpr_read_b32 v3, a184
	v_cvt_pk_bf16_f32 v2, v3, v2
	v_accvgpr_read_b32 v3, a187
	v_accvgpr_read_b32 v4, a186
	v_cvt_pk_bf16_f32 v3, v4, v3
	v_accvgpr_read_b32 v4, a189
	v_accvgpr_read_b32 v5, a188
	v_cvt_pk_bf16_f32 v4, v5, v4
	v_accvgpr_read_b32 v5, a191
	v_accvgpr_read_b32 v6, a190
	v_cvt_pk_bf16_f32 v5, v6, v5
	ds_write2_b64 v1, v[2:3], v[4:5] offset0:68 offset1:70
	v_accvgpr_read_b32 v2, a161
	v_accvgpr_read_b32 v3, a160
	v_cvt_pk_bf16_f32 v2, v3, v2
	v_accvgpr_read_b32 v3, a163
	v_accvgpr_read_b32 v4, a162
	v_mfma_f32_32x32x16_bf16 a[144:159], v[10:13], v[22:25], a[144:159]
	v_cvt_pk_bf16_f32 v3, v4, v3
	v_accvgpr_read_b32 v4, a165
	v_accvgpr_read_b32 v5, a164
	v_cvt_pk_bf16_f32 v4, v5, v4
	v_accvgpr_read_b32 v5, a167
	v_accvgpr_read_b32 v6, a166
	v_cvt_pk_bf16_f32 v5, v6, v5
	ds_write2_b64 v1, v[2:3], v[4:5] offset0:72 offset1:74
	v_accvgpr_read_b32 v2, a169
	v_accvgpr_read_b32 v3, a168
	v_cvt_pk_bf16_f32 v2, v3, v2
	v_accvgpr_read_b32 v3, a171
	v_accvgpr_read_b32 v4, a170
	v_cvt_pk_bf16_f32 v3, v4, v3
	v_accvgpr_read_b32 v4, a173
	v_accvgpr_read_b32 v5, a172
	v_cvt_pk_bf16_f32 v4, v5, v4
	v_accvgpr_read_b32 v5, a175
	v_accvgpr_read_b32 v6, a174
	v_cvt_pk_bf16_f32 v5, v6, v5
	ds_write2_b64 v1, v[2:3], v[4:5] offset0:76 offset1:78
	v_accvgpr_read_b32 v2, a145
	v_accvgpr_read_b32 v3, a144
	v_cvt_pk_bf16_f32 v2, v3, v2
	v_accvgpr_read_b32 v3, a147
	v_accvgpr_read_b32 v4, a146
	v_mfma_f32_32x32x16_bf16 a[128:143], v[14:17], v[22:25], a[128:143]
	v_cvt_pk_bf16_f32 v3, v4, v3
	v_accvgpr_read_b32 v4, a149
	v_accvgpr_read_b32 v5, a148
	v_cvt_pk_bf16_f32 v4, v5, v4
	v_accvgpr_read_b32 v5, a151
	v_accvgpr_read_b32 v6, a150
	v_cvt_pk_bf16_f32 v5, v6, v5
	ds_write2_b64 v1, v[2:3], v[4:5] offset0:80 offset1:82
	v_accvgpr_read_b32 v2, a153
	v_accvgpr_read_b32 v3, a152
	v_cvt_pk_bf16_f32 v2, v3, v2
	v_accvgpr_read_b32 v3, a155
	v_accvgpr_read_b32 v4, a154
	v_cvt_pk_bf16_f32 v3, v4, v3
	v_accvgpr_read_b32 v4, a157
	v_accvgpr_read_b32 v5, a156
	v_cvt_pk_bf16_f32 v4, v5, v4
	v_accvgpr_read_b32 v5, a159
	v_accvgpr_read_b32 v6, a158
	v_cvt_pk_bf16_f32 v5, v6, v5
	ds_write2_b64 v1, v[2:3], v[4:5] offset0:84 offset1:86
	v_accvgpr_read_b32 v2, a129
	v_accvgpr_read_b32 v3, a128
	v_cvt_pk_bf16_f32 v2, v3, v2
	v_accvgpr_read_b32 v3, a131
	v_accvgpr_read_b32 v4, a130
	v_cvt_pk_bf16_f32 v3, v4, v3
	v_accvgpr_read_b32 v4, a133
	v_accvgpr_read_b32 v5, a132
	v_cvt_pk_bf16_f32 v4, v5, v4
	v_accvgpr_read_b32 v5, a135
	v_accvgpr_read_b32 v6, a134
	v_cvt_pk_bf16_f32 v5, v6, v5
	ds_write2_b64 v1, v[2:3], v[4:5] offset0:88 offset1:90
	v_accvgpr_read_b32 v2, a137
	v_accvgpr_read_b32 v3, a136
	v_cvt_pk_bf16_f32 v2, v3, v2
	v_accvgpr_read_b32 v3, a139
	v_accvgpr_read_b32 v4, a138
	v_cvt_pk_bf16_f32 v3, v4, v3
	v_accvgpr_read_b32 v4, a141
	v_accvgpr_read_b32 v5, a140
	v_cvt_pk_bf16_f32 v4, v5, v4
	v_accvgpr_read_b32 v5, a143
	v_accvgpr_read_b32 v6, a142
	v_cvt_pk_bf16_f32 v5, v6, v5
	ds_write2_b64 v1, v[2:3], v[4:5] offset0:92 offset1:94
	v_accvgpr_read_b32 v1, a113
	v_accvgpr_read_b32 v2, a112
	v_cvt_pk_bf16_f32 v2, v2, v1
	v_accvgpr_read_b32 v1, a115
	v_accvgpr_read_b32 v3, a114
	v_cvt_pk_bf16_f32 v3, v3, v1
	v_accvgpr_read_b32 v1, a117
	v_accvgpr_read_b32 v4, a116
	v_cvt_pk_bf16_f32 v4, v4, v1
	v_accvgpr_read_b32 v1, a119
	v_accvgpr_read_b32 v5, a118
	v_cvt_pk_bf16_f32 v5, v5, v1
	v_add_u32_e32 v1, 0x8000, v0
	ds_write2_b64 v1, v[2:3], v[4:5] offset0:128 offset1:130
	v_accvgpr_read_b32 v2, a121
	v_accvgpr_read_b32 v3, a120
	v_cvt_pk_bf16_f32 v2, v3, v2
	v_accvgpr_read_b32 v3, a123
	v_accvgpr_read_b32 v4, a122
	v_cvt_pk_bf16_f32 v3, v4, v3
	v_accvgpr_read_b32 v4, a125
	v_accvgpr_read_b32 v5, a124
	v_cvt_pk_bf16_f32 v4, v5, v4
	v_accvgpr_read_b32 v5, a127
	v_accvgpr_read_b32 v6, a126
	v_cvt_pk_bf16_f32 v5, v6, v5
	ds_write2_b64 v1, v[2:3], v[4:5] offset0:132 offset1:134
	v_accvgpr_read_b32 v2, a97
	v_accvgpr_read_b32 v3, a96
	v_cvt_pk_bf16_f32 v2, v3, v2
	v_accvgpr_read_b32 v3, a99
	v_accvgpr_read_b32 v4, a98
	v_mfma_f32_32x32x16_bf16 a[80:95], v[10:13], v[26:29], a[80:95]
	v_cvt_pk_bf16_f32 v3, v4, v3
	v_accvgpr_read_b32 v4, a101
	v_accvgpr_read_b32 v5, a100
	v_cvt_pk_bf16_f32 v4, v5, v4
	v_accvgpr_read_b32 v5, a103
	v_accvgpr_read_b32 v6, a102
	v_cvt_pk_bf16_f32 v5, v6, v5
	ds_write2_b64 v1, v[2:3], v[4:5] offset0:136 offset1:138
	v_accvgpr_read_b32 v2, a105
	v_accvgpr_read_b32 v3, a104
	v_cvt_pk_bf16_f32 v2, v3, v2
	v_accvgpr_read_b32 v3, a107
	v_accvgpr_read_b32 v4, a106
	v_cvt_pk_bf16_f32 v3, v4, v3
	v_accvgpr_read_b32 v4, a109
	v_accvgpr_read_b32 v5, a108
	v_cvt_pk_bf16_f32 v4, v5, v4
	v_accvgpr_read_b32 v5, a111
	v_accvgpr_read_b32 v6, a110
	v_cvt_pk_bf16_f32 v5, v6, v5
	ds_write2_b64 v1, v[2:3], v[4:5] offset0:140 offset1:142
	v_accvgpr_read_b32 v2, a81
	v_accvgpr_read_b32 v3, a80
	v_cvt_pk_bf16_f32 v2, v3, v2
	v_accvgpr_read_b32 v3, a83
	v_accvgpr_read_b32 v4, a82
	v_mfma_f32_32x32x16_bf16 a[64:79], v[14:17], v[26:29], a[64:79]
	v_cvt_pk_bf16_f32 v3, v4, v3
	v_accvgpr_read_b32 v4, a85
	v_accvgpr_read_b32 v5, a84
	v_cvt_pk_bf16_f32 v4, v5, v4
	v_accvgpr_read_b32 v5, a87
	v_accvgpr_read_b32 v6, a86
	v_cvt_pk_bf16_f32 v5, v6, v5
	ds_write2_b64 v1, v[2:3], v[4:5] offset0:144 offset1:146
	v_accvgpr_read_b32 v2, a89
	v_accvgpr_read_b32 v3, a88
	v_cvt_pk_bf16_f32 v2, v3, v2
	v_accvgpr_read_b32 v3, a91
	v_accvgpr_read_b32 v4, a90
	v_cvt_pk_bf16_f32 v3, v4, v3
	v_accvgpr_read_b32 v4, a93
	v_accvgpr_read_b32 v5, a92
	v_cvt_pk_bf16_f32 v4, v5, v4
	v_accvgpr_read_b32 v5, a95
	v_accvgpr_read_b32 v6, a94
	v_cvt_pk_bf16_f32 v5, v6, v5
	ds_write2_b64 v1, v[2:3], v[4:5] offset0:148 offset1:150
	v_accvgpr_read_b32 v2, a65
	v_accvgpr_read_b32 v3, a64
	v_cvt_pk_bf16_f32 v2, v3, v2
	v_accvgpr_read_b32 v3, a67
	v_accvgpr_read_b32 v4, a66
	v_cvt_pk_bf16_f32 v3, v4, v3
	v_accvgpr_read_b32 v4, a69
	v_accvgpr_read_b32 v5, a68
	v_cvt_pk_bf16_f32 v4, v5, v4
	v_accvgpr_read_b32 v5, a71
	v_accvgpr_read_b32 v6, a70
	v_cvt_pk_bf16_f32 v5, v6, v5
	ds_write2_b64 v1, v[2:3], v[4:5] offset0:152 offset1:154
	v_accvgpr_read_b32 v2, a73
	v_accvgpr_read_b32 v3, a72
	v_cvt_pk_bf16_f32 v2, v3, v2
	v_accvgpr_read_b32 v3, a75
	v_accvgpr_read_b32 v4, a74
	v_cvt_pk_bf16_f32 v3, v4, v3
	v_accvgpr_read_b32 v4, a77
	v_accvgpr_read_b32 v5, a76
	v_cvt_pk_bf16_f32 v4, v5, v4
	v_accvgpr_read_b32 v5, a79
	v_accvgpr_read_b32 v6, a78
	v_cvt_pk_bf16_f32 v5, v6, v5
	ds_write2_b64 v1, v[2:3], v[4:5] offset0:156 offset1:158
	v_accvgpr_read_b32 v1, a49
	v_accvgpr_read_b32 v2, a48
	v_cvt_pk_bf16_f32 v2, v2, v1
	v_accvgpr_read_b32 v1, a51
	v_accvgpr_read_b32 v3, a50
	v_cvt_pk_bf16_f32 v3, v3, v1
	v_accvgpr_read_b32 v1, a53
	v_accvgpr_read_b32 v4, a52
	v_cvt_pk_bf16_f32 v4, v4, v1
	v_accvgpr_read_b32 v1, a55
	v_accvgpr_read_b32 v5, a54
	v_cvt_pk_bf16_f32 v5, v5, v1
	v_add_u32_e32 v6, 0xc000, v0
	v_accvgpr_read_b32 v0, a57
	v_accvgpr_read_b32 v1, a56
	ds_write2_b64 v6, v[2:3], v[4:5] offset0:192 offset1:194
	v_cvt_pk_bf16_f32 v0, v1, v0
	v_accvgpr_read_b32 v1, a59
	v_accvgpr_read_b32 v2, a58
	v_cvt_pk_bf16_f32 v1, v2, v1
	v_accvgpr_read_b32 v2, a61
	v_accvgpr_read_b32 v3, a60
	v_cvt_pk_bf16_f32 v2, v3, v2
	v_accvgpr_read_b32 v3, a63
	v_accvgpr_read_b32 v4, a62
	v_cvt_pk_bf16_f32 v3, v4, v3
	ds_write2_b64 v6, v[0:1], v[2:3] offset0:196 offset1:198
	v_accvgpr_read_b32 v0, a33
	v_accvgpr_read_b32 v1, a32
	v_cvt_pk_bf16_f32 v0, v1, v0
	v_accvgpr_read_b32 v1, a35
	v_accvgpr_read_b32 v2, a34
	v_mfma_f32_32x32x16_bf16 a[16:31], v[10:13], v[30:33], a[16:31]
	v_cvt_pk_bf16_f32 v1, v2, v1
	v_accvgpr_read_b32 v2, a37
	v_accvgpr_read_b32 v3, a36
	v_cvt_pk_bf16_f32 v2, v3, v2
	v_accvgpr_read_b32 v3, a39
	v_accvgpr_read_b32 v4, a38
	v_cvt_pk_bf16_f32 v3, v4, v3
	ds_write2_b64 v6, v[0:1], v[2:3] offset0:200 offset1:202
	v_accvgpr_read_b32 v0, a41
	v_accvgpr_read_b32 v1, a40
	v_cvt_pk_bf16_f32 v0, v1, v0
	v_accvgpr_read_b32 v1, a43
	v_accvgpr_read_b32 v2, a42
	v_cvt_pk_bf16_f32 v1, v2, v1
	v_accvgpr_read_b32 v2, a45
	v_accvgpr_read_b32 v3, a44
	v_cvt_pk_bf16_f32 v2, v3, v2
	v_accvgpr_read_b32 v3, a47
	v_accvgpr_read_b32 v4, a46
	v_cvt_pk_bf16_f32 v3, v4, v3
	ds_write2_b64 v6, v[0:1], v[2:3] offset0:204 offset1:206
	v_accvgpr_read_b32 v0, a17
	v_accvgpr_read_b32 v1, a16
	v_cvt_pk_bf16_f32 v0, v1, v0
	v_accvgpr_read_b32 v1, a19
	v_accvgpr_read_b32 v2, a18
	v_mfma_f32_32x32x16_bf16 a[0:15], v[14:17], v[30:33], a[0:15]
	v_cvt_pk_bf16_f32 v1, v2, v1
	v_accvgpr_read_b32 v2, a21
	v_accvgpr_read_b32 v3, a20
	v_cvt_pk_bf16_f32 v2, v3, v2
	v_accvgpr_read_b32 v3, a23
	v_accvgpr_read_b32 v4, a22
	v_cvt_pk_bf16_f32 v3, v4, v3
	ds_write2_b64 v6, v[0:1], v[2:3] offset0:208 offset1:210
	v_accvgpr_read_b32 v0, a25
	v_accvgpr_read_b32 v1, a24
	v_cvt_pk_bf16_f32 v0, v1, v0
	v_accvgpr_read_b32 v1, a27
	v_accvgpr_read_b32 v2, a26
	v_cvt_pk_bf16_f32 v1, v2, v1
	v_accvgpr_read_b32 v2, a29
	v_accvgpr_read_b32 v3, a28
	v_cvt_pk_bf16_f32 v2, v3, v2
	v_accvgpr_read_b32 v3, a31
	v_accvgpr_read_b32 v4, a30
	v_cvt_pk_bf16_f32 v3, v4, v3
	ds_write2_b64 v6, v[0:1], v[2:3] offset0:212 offset1:214
	v_accvgpr_read_b32 v0, a1
	v_accvgpr_read_b32 v1, a0
	v_cvt_pk_bf16_f32 v0, v1, v0
	v_accvgpr_read_b32 v1, a3
	v_accvgpr_read_b32 v2, a2
	v_cvt_pk_bf16_f32 v1, v2, v1
	v_accvgpr_read_b32 v2, a5
	v_accvgpr_read_b32 v3, a4
	v_cvt_pk_bf16_f32 v2, v3, v2
	v_accvgpr_read_b32 v3, a7
	v_accvgpr_read_b32 v4, a6
	v_cvt_pk_bf16_f32 v3, v4, v3
	ds_write2_b64 v6, v[0:1], v[2:3] offset0:216 offset1:218
	v_accvgpr_read_b32 v0, a9
	v_accvgpr_read_b32 v1, a8
	v_cvt_pk_bf16_f32 v0, v1, v0
	v_accvgpr_read_b32 v1, a11
	v_accvgpr_read_b32 v2, a10
	v_cvt_pk_bf16_f32 v1, v2, v1
	v_accvgpr_read_b32 v2, a13
	v_accvgpr_read_b32 v3, a12
	v_cvt_pk_bf16_f32 v2, v3, v2
	v_accvgpr_read_b32 v3, a15
	v_accvgpr_read_b32 v4, a14
	v_cvt_pk_bf16_f32 v3, v4, v3
	ds_write2_b64 v6, v[0:1], v[2:3] offset0:220 offset1:222
	s_waitcnt lgkmcnt(0)
	s_barrier
	s_nop 0
	v_mbcnt_lo_u32_b32 v0, -1, s5
	v_mbcnt_hi_u32_b32 v0, -1, v0
	v_or_b32_e32 v2, s60, v0
	v_lshlrev_b32_e32 v0, 4, v0
	v_and_b32_e32 v252, 0x1f0, v0
	v_lshl_add_u64 v[0:1], s[14:15], 0, v[252:253]

.LBB0_220:
	s_add_i32 s12, s11, 0xffff8000
	s_and_b32 s12, s12, 0x8000
	s_lshl_b32 s12, s12, 1
	v_lshl_or_b32 v235, v14, 1, s12
	v_add_u32_e32 v234, v235, v10
	v_add_u32_e32 v235, v235, v8
	ds_read_b128 v[16:19], v234
	ds_read_b128 v[20:23], v235 offset:32768
	ds_read_b128 v[24:27], v235 offset:36864
	ds_read_b128 v[28:31], v235 offset:40960
	ds_read_b128 v[32:35], v235 offset:45056
	ds_read_b128 v[148:151], v234 offset:4096
	s_waitcnt lgkmcnt(4)
	v_mfma_f32_32x32x16_bf16 a[224:239], v[16:19], v[20:23], a[224:239]
	s_waitcnt lgkmcnt(3)
	v_mfma_f32_32x32x16_bf16 a[160:175], v[16:19], v[24:27], a[160:175]
	s_and_b32 s98, s11, 0x8000
	s_lshl_b32 s98, s98, 1
	s_add_i32 s98, s62, s98
	v_lshl_add_u64 v[100:101], v[0:1], 0, s[4:5]
	v_lshl_add_u64 v[104:105], v[100:101], 0, s[16:17]
	s_mov_b32 m0, s98
	s_add_i32 s99, s98, 0x8000
	global_load_lds_dwordx4 v[104:105], off
	s_waitcnt lgkmcnt(2)
	v_mfma_f32_32x32x16_bf16 a[96:111], v[16:19], v[28:31], a[96:111]
	v_lshl_add_u64 v[104:105], v[4:5], 0, s[4:5]
	v_lshl_add_u64 v[114:115], v[104:105], 0, s[38:39]
	s_mov_b32 m0, s99
	s_nop 0
	global_load_lds_dwordx4 v[114:115], off
	s_waitcnt lgkmcnt(1)
	v_mfma_f32_32x32x16_bf16 a[32:47], v[16:19], v[32:35], a[32:47]
	v_lshl_add_u64 v[114:115], v[2:3], 0, s[4:5]
	v_lshl_add_u64 v[118:119], v[114:115], 0, s[30:31]
	s_add_i32 m0, s98, 0x400
	s_nop 0
	global_load_lds_dwordx4 v[118:119], off
	ds_read_b128 v[16:19], v234 offset:16384
	s_waitcnt lgkmcnt(1)
	v_mfma_f32_32x32x16_bf16 a[192:207], v[148:151], v[20:23], a[192:207]
	v_lshl_add_u64 v[118:119], v[6:7], 0, s[4:5]
	v_lshl_add_u64 v[144:145], v[118:119], 0, s[44:45]
	s_add_i32 m0, s98, 0x8400
	s_nop 0
	global_load_lds_dwordx4 v[144:145], off
	v_mfma_f32_32x32x16_bf16 a[128:143], v[148:151], v[24:27], a[128:143]
	v_lshl_add_u64 v[144:145], v[100:101], 0, s[68:69]
	s_add_i32 m0, s98, 0x800
	s_nop 0
	global_load_lds_dwordx4 v[144:145], off
	v_mfma_f32_32x32x16_bf16 a[64:79], v[148:151], v[28:31], a[64:79]
	v_lshl_add_u64 v[144:145], v[104:105], 0, s[2:3]
	s_add_i32 m0, s98, 0x8800
	s_nop 0
	global_load_lds_dwordx4 v[144:145], off
	v_mfma_f32_32x32x16_bf16 a[0:15], v[148:151], v[32:35], a[0:15]
	v_lshl_add_u64 v[144:145], v[114:115], 0, s[70:71]
	s_add_i32 m0, s98, 0xc00
	s_nop 0
	global_load_lds_dwordx4 v[144:145], off
	ds_read_b128 v[148:151], v234 offset:20480
	s_waitcnt lgkmcnt(1)
	v_mfma_f32_32x32x16_bf16 a[240:255], v[16:19], v[20:23], a[240:255]
	v_lshl_add_u64 v[144:145], v[118:119], 0, s[46:47]
	s_add_i32 m0, s98, 0x8c00
	s_nop 0
	global_load_lds_dwordx4 v[144:145], off
	v_mfma_f32_32x32x16_bf16 a[176:191], v[16:19], v[24:27], a[176:191]
	v_lshl_add_u64 v[144:145], v[100:101], 0, s[76:77]
	s_add_i32 m0, s98, 0x1000
	v_lshl_add_u64 v[100:101], v[100:101], 0, s[80:81]
	global_load_lds_dwordx4 v[144:145], off
	v_mfma_f32_32x32x16_bf16 a[112:127], v[16:19], v[28:31], a[112:127]
	v_lshl_add_u64 v[144:145], v[104:105], 0, s[50:51]
	s_add_i32 m0, s98, 0x9000
	s_nop 0
	global_load_lds_dwordx4 v[144:145], off
	v_mfma_f32_32x32x16_bf16 a[48:63], v[16:19], v[32:35], a[48:63]
	v_lshl_add_u64 v[144:145], v[114:115], 0, s[78:79]
	s_add_i32 m0, s98, 0x1400
	s_nop 0
	global_load_lds_dwordx4 v[144:145], off
	v_lshl_or_b32 v235, v13, 1, s12
	v_add_u32_e32 v234, v235, v10
	v_add_u32_e32 v235, v235, v8
	ds_read_b128 v[16:19], v234
	s_waitcnt lgkmcnt(1)
	v_mfma_f32_32x32x16_bf16 a[208:223], v[148:151], v[20:23], a[208:223]
	v_lshl_add_u64 v[144:145], v[118:119], 0, s[52:53]
	s_add_i32 m0, s98, 0x9400
	s_nop 0
	global_load_lds_dwordx4 v[144:145], off
	ds_read_b128 v[20:23], v235 offset:32768
	v_mfma_f32_32x32x16_bf16 a[144:159], v[148:151], v[24:27], a[144:159]
	s_add_i32 m0, s98, 0x1800
	s_nop 0
	global_load_lds_dwordx4 v[100:101], off
	ds_read_b128 v[24:27], v235 offset:36864
	v_mfma_f32_32x32x16_bf16 a[80:95], v[148:151], v[28:31], a[80:95]
	v_lshl_add_u64 v[100:101], v[104:105], 0, s[54:55]
	s_add_i32 m0, s98, 0x9800
	s_nop 0
	global_load_lds_dwordx4 v[100:101], off
	ds_read_b128 v[28:31], v235 offset:40960
	v_mfma_f32_32x32x16_bf16 a[16:31], v[148:151], v[32:35], a[16:31]
	v_lshl_add_u64 v[100:101], v[114:115], 0, s[82:83]
	s_add_i32 m0, s98, 0x1c00
	s_nop 0
	global_load_lds_dwordx4 v[100:101], off
	ds_read_b128 v[32:35], v235 offset:45056
	ds_read_b128 v[148:151], v234 offset:4096
	s_waitcnt lgkmcnt(4)
	v_mfma_f32_32x32x16_bf16 a[224:239], v[16:19], v[20:23], a[224:239]
	v_lshl_add_u64 v[100:101], v[118:119], 0, s[56:57]
	s_add_i32 m0, s98, 0x9c00
	s_nop 0
	global_load_lds_dwordx4 v[100:101], off
	s_waitcnt lgkmcnt(3)
	v_mfma_f32_32x32x16_bf16 a[160:175], v[16:19], v[24:27], a[160:175]
	s_waitcnt lgkmcnt(2)
	v_mfma_f32_32x32x16_bf16 a[96:111], v[16:19], v[28:31], a[96:111]
	s_waitcnt lgkmcnt(1)
	v_mfma_f32_32x32x16_bf16 a[32:47], v[16:19], v[32:35], a[32:47]
	ds_read_b128 v[16:19], v234 offset:16384
	s_waitcnt lgkmcnt(1)
	v_mfma_f32_32x32x16_bf16 a[192:207], v[148:151], v[20:23], a[192:207]
	v_mfma_f32_32x32x16_bf16 a[128:143], v[148:151], v[24:27], a[128:143]
	v_mfma_f32_32x32x16_bf16 a[64:79], v[148:151], v[28:31], a[64:79]
	v_mfma_f32_32x32x16_bf16 a[0:15], v[148:151], v[32:35], a[0:15]
	ds_read_b128 v[148:151], v234 offset:20480
	s_waitcnt lgkmcnt(1)
	v_mfma_f32_32x32x16_bf16 a[240:255], v[16:19], v[20:23], a[240:255]
	v_mfma_f32_32x32x16_bf16 a[176:191], v[16:19], v[24:27], a[176:191]
	v_mfma_f32_32x32x16_bf16 a[112:127], v[16:19], v[28:31], a[112:127]
	v_mfma_f32_32x32x16_bf16 a[48:63], v[16:19], v[32:35], a[48:63]
	v_lshl_or_b32 v235, v12, 1, s12
	v_add_u32_e32 v234, v235, v10
	v_add_u32_e32 v235, v235, v8
	ds_read_b128 v[16:19], v234
	s_waitcnt lgkmcnt(1)
	v_mfma_f32_32x32x16_bf16 a[208:223], v[148:151], v[20:23], a[208:223]
	ds_read_b128 v[20:23], v235 offset:32768
	v_mfma_f32_32x32x16_bf16 a[144:159], v[148:151], v[24:27], a[144:159]
	ds_read_b128 v[24:27], v235 offset:36864
	v_mfma_f32_32x32x16_bf16 a[80:95], v[148:151], v[28:31], a[80:95]
	ds_read_b128 v[28:31], v235 offset:40960
	v_mfma_f32_32x32x16_bf16 a[16:31], v[148:151], v[32:35], a[16:31]
	ds_read_b128 v[32:35], v235 offset:45056
	ds_read_b128 v[148:151], v234 offset:4096
	s_waitcnt lgkmcnt(4)
	v_mfma_f32_32x32x16_bf16 a[224:239], v[16:19], v[20:23], a[224:239]
	s_waitcnt lgkmcnt(3)
	v_mfma_f32_32x32x16_bf16 a[160:175], v[16:19], v[24:27], a[160:175]
	s_waitcnt lgkmcnt(2)
	v_mfma_f32_32x32x16_bf16 a[96:111], v[16:19], v[28:31], a[96:111]
	s_waitcnt lgkmcnt(1)
	v_mfma_f32_32x32x16_bf16 a[32:47], v[16:19], v[32:35], a[32:47]
	ds_read_b128 v[16:19], v234 offset:16384
	s_waitcnt lgkmcnt(1)
	v_mfma_f32_32x32x16_bf16 a[192:207], v[148:151], v[20:23], a[192:207]
	v_mfma_f32_32x32x16_bf16 a[128:143], v[148:151], v[24:27], a[128:143]
	v_mfma_f32_32x32x16_bf16 a[64:79], v[148:151], v[28:31], a[64:79]
	v_mfma_f32_32x32x16_bf16 a[0:15], v[148:151], v[32:35], a[0:15]
	ds_read_b128 v[148:151], v234 offset:20480
	s_waitcnt lgkmcnt(1)
	v_mfma_f32_32x32x16_bf16 a[240:255], v[16:19], v[20:23], a[240:255]
	v_mfma_f32_32x32x16_bf16 a[176:191], v[16:19], v[24:27], a[176:191]
	v_mfma_f32_32x32x16_bf16 a[112:127], v[16:19], v[28:31], a[112:127]
	v_mfma_f32_32x32x16_bf16 a[48:63], v[16:19], v[32:35], a[48:63]
	v_lshl_or_b32 v235, v11, 1, s12
	v_add_u32_e32 v234, v235, v10
	v_add_u32_e32 v235, v235, v8
	ds_read_b128 v[16:19], v234
	s_waitcnt lgkmcnt(1)
	v_mfma_f32_32x32x16_bf16 a[208:223], v[148:151], v[20:23], a[208:223]
	ds_read_b128 v[20:23], v235 offset:32768
	v_mfma_f32_32x32x16_bf16 a[144:159], v[148:151], v[24:27], a[144:159]
	ds_read_b128 v[24:27], v235 offset:36864
	v_mfma_f32_32x32x16_bf16 a[80:95], v[148:151], v[28:31], a[80:95]
	ds_read_b128 v[28:31], v235 offset:40960
	v_mfma_f32_32x32x16_bf16 a[16:31], v[148:151], v[32:35], a[16:31]
	ds_read_b128 v[32:35], v235 offset:45056
	ds_read_b128 v[148:151], v234 offset:4096
	s_waitcnt lgkmcnt(4)
	v_mfma_f32_32x32x16_bf16 a[224:239], v[16:19], v[20:23], a[224:239]
	s_waitcnt lgkmcnt(3)
	v_mfma_f32_32x32x16_bf16 a[160:175], v[16:19], v[24:27], a[160:175]
	s_waitcnt lgkmcnt(2)
	v_mfma_f32_32x32x16_bf16 a[96:111], v[16:19], v[28:31], a[96:111]
	s_waitcnt lgkmcnt(1)
	v_mfma_f32_32x32x16_bf16 a[32:47], v[16:19], v[32:35], a[32:47]
	ds_read_b128 v[16:19], v234 offset:16384
	s_waitcnt lgkmcnt(1)
	v_mfma_f32_32x32x16_bf16 a[192:207], v[148:151], v[20:23], a[192:207]
	v_mfma_f32_32x32x16_bf16 a[128:143], v[148:151], v[24:27], a[128:143]
	v_mfma_f32_32x32x16_bf16 a[64:79], v[148:151], v[28:31], a[64:79]
	v_mfma_f32_32x32x16_bf16 a[0:15], v[148:151], v[32:35], a[0:15]
	ds_read_b128 v[148:151], v234 offset:20480
	s_waitcnt lgkmcnt(1)
	v_mfma_f32_32x32x16_bf16 a[240:255], v[16:19], v[20:23], a[240:255]
	v_mfma_f32_32x32x16_bf16 a[176:191], v[16:19], v[24:27], a[176:191]
	v_mfma_f32_32x32x16_bf16 a[112:127], v[16:19], v[28:31], a[112:127]
	v_mfma_f32_32x32x16_bf16 a[48:63], v[16:19], v[32:35], a[48:63]
	s_waitcnt vmcnt(0)
	s_waitcnt vmcnt(0) lgkmcnt(0)
	s_barrier
	s_add_u32 s4, s4, 0x80
	s_addc_u32 s5, s5, 0
	s_add_i32 s11, s11, 0x8000
	s_cmpk_lg_i32 s4, 0x780
	v_mfma_f32_32x32x16_bf16 a[208:223], v[148:151], v[20:23], a[208:223]
	v_mfma_f32_32x32x16_bf16 a[144:159], v[148:151], v[24:27], a[144:159]
	v_mfma_f32_32x32x16_bf16 a[80:95], v[148:151], v[28:31], a[80:95]
	v_mfma_f32_32x32x16_bf16 a[16:31], v[148:151], v[32:35], a[16:31]
	s_cbranch_scc1 .LBB0_220
	v_lshlrev_b32_e32 v4, 1, v14
	s_mov_b32 s4, 0x10000
	v_add3_u32 v9, v10, v4, s4
	ds_read_b128 v[0:3], v9
	ds_read_b128 v[36:39], v9 offset:20480
	s_mov_b32 s5, 0x18000
	v_add3_u32 v22, v8, v4, s5
	ds_read_b128 v[4:7], v22
	ds_read_b128 v[14:17], v22 offset:4096
	ds_read_b128 v[18:21], v22 offset:8192
	ds_read_b128 v[124:127], v22 offset:12288
	s_waitcnt lgkmcnt(3)
	v_mfma_f32_32x32x16_bf16 a[224:239], v[0:3], v[4:7], a[224:239]
	v_lshlrev_b32_e32 v11, 1, v11
	s_waitcnt lgkmcnt(2)
	v_mfma_f32_32x32x16_bf16 a[160:175], v[0:3], v[14:17], a[160:175]
	s_waitcnt lgkmcnt(1)
	v_mfma_f32_32x32x16_bf16 a[96:111], v[0:3], v[18:21], a[96:111]
	s_waitcnt lgkmcnt(0)
	v_mfma_f32_32x32x16_bf16 a[32:47], v[0:3], v[124:127], a[32:47]
	ds_read_b128 v[0:3], v9 offset:4096
	s_waitcnt lgkmcnt(0)
	v_mfma_f32_32x32x16_bf16 a[192:207], v[0:3], v[4:7], a[192:207]
	v_mfma_f32_32x32x16_bf16 a[128:143], v[0:3], v[14:17], a[128:143]
	v_mfma_f32_32x32x16_bf16 a[64:79], v[0:3], v[18:21], a[64:79]
	v_mfma_f32_32x32x16_bf16 a[0:15], v[0:3], v[124:127], a[0:15]
	ds_read_b128 v[0:3], v9 offset:16384
	s_waitcnt lgkmcnt(0)
	v_mfma_f32_32x32x16_bf16 a[240:255], v[0:3], v[4:7], a[240:255]
	v_mfma_f32_32x32x16_bf16 a[208:223], v[36:39], v[4:7], a[208:223]
	v_lshlrev_b32_e32 v4, 1, v13
	v_add3_u32 v9, v10, v4, s4
	v_add3_u32 v4, v8, v4, s5
	ds_read_b128 v[40:43], v4
	ds_read_b128 v[32:35], v4 offset:4096
	ds_read_b128 v[140:143], v4 offset:8192
	ds_read_b128 v[180:183], v4 offset:12288
	v_mfma_f32_32x32x16_bf16 a[176:191], v[0:3], v[14:17], a[176:191]
	v_lshlrev_b32_e32 v4, 1, v12
	v_mfma_f32_32x32x16_bf16 a[112:127], v[0:3], v[18:21], a[112:127]
	v_mfma_f32_32x32x16_bf16 a[48:63], v[0:3], v[124:127], a[48:63]
	ds_read_b128 v[0:3], v9
	v_mfma_f32_32x32x16_bf16 a[144:159], v[36:39], v[14:17], a[144:159]
	v_add3_u32 v16, v10, v4, s4
	v_add3_u32 v10, v10, v11, s4
	v_add3_u32 v17, v8, v4, s5
	ds_read_b128 v[4:7], v10
	ds_read_b128 v[48:51], v17
	s_mov_b32 s4, 0
	s_waitcnt lgkmcnt(2)
	v_mfma_f32_32x32x16_bf16 a[224:239], v[0:3], v[40:43], a[224:239]
	v_mfma_f32_32x32x16_bf16 a[160:175], v[0:3], v[32:35], a[160:175]
	v_mfma_f32_32x32x16_bf16 a[96:111], v[0:3], v[140:143], a[96:111]
	v_mfma_f32_32x32x16_bf16 a[32:47], v[0:3], v[180:183], a[32:47]
	ds_read_b128 v[0:3], v9 offset:4096
	s_waitcnt lgkmcnt(0)
	v_mfma_f32_32x32x16_bf16 a[192:207], v[0:3], v[40:43], a[192:207]
	v_mfma_f32_32x32x16_bf16 a[128:143], v[0:3], v[32:35], a[128:143]
	v_mfma_f32_32x32x16_bf16 a[64:79], v[0:3], v[140:143], a[64:79]
	v_mfma_f32_32x32x16_bf16 a[0:15], v[0:3], v[180:183], a[0:15]
	ds_read_b128 v[0:3], v9 offset:16384
	s_waitcnt lgkmcnt(0)
	v_mfma_f32_32x32x16_bf16 a[240:255], v[0:3], v[40:43], a[240:255]
	v_mfma_f32_32x32x16_bf16 a[176:191], v[0:3], v[32:35], a[176:191]
	v_mfma_f32_32x32x16_bf16 a[112:127], v[0:3], v[140:143], a[112:127]
	v_mfma_f32_32x32x16_bf16 a[48:63], v[0:3], v[180:183], a[48:63]
	ds_read_b128 v[0:3], v16
	v_mfma_f32_32x32x16_bf16 a[80:95], v[36:39], v[18:21], a[80:95]
	v_add3_u32 v18, v8, v11, s5
	ds_read_b128 v[44:47], v18
	ds_read_b128 v[28:31], v9 offset:20480
	ds_read_b128 v[12:15], v16 offset:4096
	ds_read_b128 v[64:67], v17 offset:4096
	ds_read_b128 v[68:71], v16 offset:16384
	ds_read_b128 v[238:241], v16 offset:20480
	ds_read_b128 v[52:55], v17 offset:8192
	ds_read_b128 v[248:251], v17 offset:12288
	ds_read_b128 v[82:85], v10 offset:4096
	ds_read_b128 v[60:63], v18 offset:4096
	ds_read_b128 v[72:75], v10 offset:16384
	ds_read_b128 v[8:11], v10 offset:20480
	ds_read_b128 v[56:59], v18 offset:8192
	ds_read_b128 v[20:23], v18 offset:12288
	s_waitcnt vmcnt(0)
	s_waitcnt lgkmcnt(0)
	s_barrier
	v_mfma_f32_32x32x16_bf16 a[224:239], v[0:3], v[48:51], a[224:239]
	s_mov_b32 s5, 0
	v_mfma_f32_32x32x16_bf16 a[160:175], v[0:3], v[64:67], a[160:175]
	v_mfma_f32_32x32x16_bf16 a[96:111], v[0:3], v[52:55], a[96:111]
	v_mfma_f32_32x32x16_bf16 a[32:47], v[0:3], v[248:251], a[32:47]
	v_mfma_f32_32x32x16_bf16 a[240:255], v[68:71], v[48:51], a[240:255]
	v_mfma_f32_32x32x16_bf16 a[176:191], v[68:71], v[64:67], a[176:191]
	v_mfma_f32_32x32x16_bf16 a[112:127], v[68:71], v[52:55], a[112:127]
	v_mfma_f32_32x32x16_bf16 a[48:63], v[68:71], v[248:251], a[48:63]
	v_mfma_f32_32x32x16_bf16 a[224:239], v[4:7], v[44:47], a[224:239]
	v_mfma_f32_32x32x16_bf16 a[160:175], v[4:7], v[60:63], a[160:175]
	s_nop 10
	v_accvgpr_read_b32 v117, a227
	v_accvgpr_read_b32 v116, a226
	v_accvgpr_read_b32 v103, a229
	v_mfma_f32_32x32x16_bf16 a[96:111], v[4:7], v[56:59], a[96:111]
	v_accvgpr_read_b32 v102, a228
	v_accvgpr_read_b32 v227, a239
	v_accvgpr_read_b32 v226, a238
	v_accvgpr_read_b32 v229, a237
	v_accvgpr_read_b32 v228, a236
	v_accvgpr_read_b32 v253, a235
	v_accvgpr_read_b32 v252, a234
	v_mfma_f32_32x32x16_bf16 a[32:47], v[4:7], v[20:23], a[32:47]
	v_mbcnt_lo_u32_b32 v4, -1, s4
	v_mbcnt_hi_u32_b32 v16, -1, v4
	v_or_b32_e32 v4, s60, v16
	v_and_b32_e32 v5, 31, v16
	v_lshrrev_b32_e32 v16, 3, v16
	s_and_b32 s4, s10, 3
	s_cmp_gt_i32 s10, 3
	v_mfma_f32_32x32x16_bf16 a[192:207], v[12:15], v[48:51], a[192:207]
	s_cselect_b64 vcc, -1, 0
	v_accvgpr_read_b32 v81, a233
	v_accvgpr_read_b32 v80, a232
	v_accvgpr_read_b32 v79, a231
	v_accvgpr_read_b32 v99, a39
	v_accvgpr_read_b32 v98, a38
	v_accvgpr_read_b32 v129, a35
	v_mfma_f32_32x32x16_bf16 a[128:143], v[12:15], v[64:67], a[128:143]
	v_accvgpr_read_b32 v128, a34
	v_accvgpr_read_b32 v78, a230
	v_accvgpr_read_b32 v131, a175
	v_accvgpr_read_b32 v130, a174
	v_accvgpr_read_b32 v133, a173
	v_accvgpr_read_b32 v132, a172
	v_accvgpr_read_b32 v111, a171
	v_mfma_f32_32x32x16_bf16 a[64:79], v[12:15], v[52:55], a[64:79]
	v_accvgpr_read_b32 v110, a170
	v_accvgpr_read_b32 v113, a169
	v_accvgpr_read_b32 v112, a168
	v_accvgpr_read_b32 v135, a167
	v_accvgpr_read_b32 v134, a166
	v_accvgpr_read_b32 v121, a165
	v_accvgpr_read_b32 v120, a164
	v_mfma_f32_32x32x16_bf16 a[0:15], v[12:15], v[248:251], a[0:15]
	v_lshlrev_b32_e32 v12, 1, v4
	v_ashrrev_i32_e32 v4, 1, v4
	v_and_b32_e32 v24, 0xffffffc0, v4
	v_ashrrev_i32_e32 v25, 31, v24
	v_accvgpr_read_b32 v109, a163
	v_accvgpr_read_b32 v108, a162
	v_accvgpr_read_b32 v209, a111
	v_mfma_f32_32x32x16_bf16 a[240:255], v[72:75], v[44:47], a[240:255]
	v_accvgpr_read_b32 v208, a110
	v_accvgpr_read_b32 v213, a109
	v_accvgpr_read_b32 v212, a108
	v_accvgpr_read_b32 v219, a107
	v_accvgpr_read_b32 v218, a106
	v_accvgpr_read_b32 v221, a105
	v_accvgpr_read_b32 v220, a104
	v_mfma_f32_32x32x16_bf16 a[176:191], v[72:75], v[60:63], a[176:191]
	v_accvgpr_read_b32 v203, a103
	v_accvgpr_read_b32 v202, a102
	v_accvgpr_read_b32 v205, a101
	v_accvgpr_read_b32 v204, a100
	v_accvgpr_read_b32 v139, a243
	v_accvgpr_read_b32 v138, a242
	v_accvgpr_read_b32 v123, a245
	v_mfma_f32_32x32x16_bf16 a[112:127], v[72:75], v[56:59], a[112:127]
	v_accvgpr_read_b32 v122, a244
	v_accvgpr_read_b32 v173, a99
	v_accvgpr_read_b32 v172, a98
	v_accvgpr_read_b32 v89, a47
	v_accvgpr_read_b32 v88, a46
	v_accvgpr_read_b32 v91, a45
	v_accvgpr_read_b32 v90, a44
	v_mfma_f32_32x32x16_bf16 a[48:63], v[72:75], v[20:23], a[48:63]
	v_and_or_b32 v74, v12, s14, v5
	v_lshlrev_b64 v[4:5], 2, v[24:25]
	v_and_b32_e32 v25, 4, v16
	v_lshl_add_u64 v[12:13], s[0:1], 0, v[4:5]
	v_lshlrev_b32_e32 v94, 2, v25
	v_lshl_add_u64 v[4:5], s[6:7], 0, v[4:5]
	v_lshl_add_u64 v[186:187], v[4:5], 0, v[94:95]
	v_or_b32_e32 v4, s66, v74
	v_lshl_add_u64 v[184:185], v[12:13], 0, v[94:95]
	v_lshlrev_b32_e32 v94, 9, v4
	v_mfma_f32_32x32x16_bf16 a[144:159], v[28:31], v[32:35], a[144:159]
	v_lshl_add_u64 v[68:69], v[186:187], 0, v[94:95]
	v_lshl_add_u64 v[72:73], v[184:185], 0, v[94:95]
	global_load_dwordx4 v[32:35], v[68:69], off
	v_or_b32_e32 v24, v24, v25
	v_accvgpr_read_b32 v87, a43
	v_accvgpr_read_b32 v86, a42
	v_accvgpr_read_b32 v97, a41
	v_mfma_f32_32x32x16_bf16 a[208:223], v[28:31], v[40:43], a[208:223]
	global_load_dwordx4 v[40:43], v[72:73], off
	v_accvgpr_read_b32 v96, a40
	v_accvgpr_read_b32 v107, a37
	v_accvgpr_read_b32 v106, a36
	v_accvgpr_read_b32 v3, a253
	v_accvgpr_read_b32 v2, a252
	v_accvgpr_read_b32 v7, a249
	v_mfma_f32_32x32x16_bf16 a[144:159], v[238:241], v[64:67], a[144:159]
	global_load_dwordx4 v[64:67], v[68:69], off offset:32
	global_load_dwordx4 v[16:19], v[72:73], off offset:32
	v_accvgpr_read_b32 v6, a248
	v_accvgpr_read_b32 v15, a247
	v_accvgpr_read_b32 v14, a246
	v_accvgpr_read_b32 v147, a191
	v_accvgpr_read_b32 v146, a190
	v_accvgpr_read_b32 v155, a189
	v_mfma_f32_32x32x16_bf16 a[16:31], v[36:39], v[124:127], a[16:31]
	v_accvgpr_read_b32 v154, a188
	v_accvgpr_read_b32 v153, a187
	v_accvgpr_read_b32 v152, a186
	v_accvgpr_read_b32 v137, a185
	v_accvgpr_read_b32 v136, a184
	v_accvgpr_read_b32 v165, a183
	v_accvgpr_read_b32 v164, a182
	v_mfma_f32_32x32x16_bf16 a[80:95], v[28:31], v[140:143], a[80:95]
	v_accvgpr_read_b32 v207, a181
	v_accvgpr_read_b32 v206, a180
	v_accvgpr_read_b32 v71, a179
	v_accvgpr_read_b32 v70, a178
	v_accvgpr_read_b32 v243, a127
	v_accvgpr_read_b32 v242, a126
	v_accvgpr_read_b32 v245, a125
	v_mfma_f32_32x32x16_bf16 a[16:31], v[28:31], v[180:183], a[16:31]
	v_mov_b32_e32 v30, 0x3d800000
	v_accvgpr_read_b32 v244, a124
	v_accvgpr_read_b32 v247, a123
	v_accvgpr_read_b32 v246, a122
	v_accvgpr_read_b32 v237, a121
	v_accvgpr_read_b32 v236, a120
	v_accvgpr_read_b32 v225, a119
	v_mfma_f32_32x32x16_bf16 a[208:223], v[238:241], v[48:51], a[208:223]
	v_cndmask_b32_e32 v50, 1.0, v30, vcc
	v_accvgpr_read_b32 v224, a118
	v_accvgpr_read_b32 v233, a117
	v_accvgpr_read_b32 v232, a116
	v_accvgpr_read_b32 v217, a115
	v_accvgpr_read_b32 v216, a114
	v_accvgpr_read_b32 v125, a63
	v_mfma_f32_32x32x16_bf16 a[80:95], v[238:241], v[52:55], a[80:95]
	v_accvgpr_read_b32 v124, a62
	v_accvgpr_read_b32 v127, a61
	v_accvgpr_read_b32 v126, a60
	v_accvgpr_read_b32 v141, a59
	v_accvgpr_read_b32 v140, a58
	v_accvgpr_read_b32 v143, a57
	v_accvgpr_read_b32 v142, a56
	v_mfma_f32_32x32x16_bf16 a[16:31], v[238:241], v[248:251], a[16:31]
	v_accvgpr_read_b32 v161, a55
	v_accvgpr_read_b32 v160, a54
	v_accvgpr_read_b32 v167, a53
	v_accvgpr_read_b32 v166, a52
	v_accvgpr_read_b32 v193, a51
	v_accvgpr_read_b32 v192, a50
	v_accvgpr_read_b32 v77, a255
	v_mfma_f32_32x32x16_bf16 a[0:15], v[82:85], v[20:23], a[0:15]
	v_accvgpr_read_b32 v76, a254
	s_waitcnt vmcnt(3)
	v_mul_f32_e64 v26, v116, v34
	v_mul_f32_e64 v27, v117, v35
	v_mfma_f32_32x32x16_bf16 a[208:223], v[8:11], v[44:47], a[208:223]
	s_nop 6
	v_accvgpr_read_b32 v1, a15
	v_accvgpr_read_b32 v0, a14
	v_accvgpr_write_b32 a15, v1
	v_accvgpr_write_b32 a14, v0
	s_waitcnt vmcnt(2)
	v_pk_fma_f32 v[26:27], v[138:139], v[42:43], v[26:27]
	v_accvgpr_read_b32 v1, a13
	v_accvgpr_read_b32 v0, a12
	v_mfma_f32_32x32x16_bf16 a[144:159], v[8:11], v[60:63], a[144:159]
	v_accvgpr_write_b32 a13, v1
	v_accvgpr_write_b32 a12, v0
	v_accvgpr_read_b32 v1, a9
	v_accvgpr_read_b32 v0, a8
	v_accvgpr_write_b32 a39, v1
	v_accvgpr_read_b32 v93, a3
	v_accvgpr_read_b32 v92, a2
	v_mfma_f32_32x32x16_bf16 a[80:95], v[8:11], v[56:59], a[80:95]
	v_accvgpr_write_b32 a38, v0
	v_accvgpr_read_b32 v1, a251
	v_accvgpr_read_b32 v0, a250
	v_accvgpr_read_b32 v49, a219
	v_accvgpr_read_b32 v48, a218
	v_accvgpr_read_b32 v37, a215
	v_accvgpr_read_b32 v36, a214
	v_mfma_f32_32x32x16_bf16 a[16:31], v[8:11], v[20:23], a[16:31]
	v_accvgpr_read_b32 v10, a240
	v_accvgpr_read_b32 v8, a224
	v_accvgpr_read_b32 v11, a241
	v_accvgpr_read_b32 v9, a225
	v_mul_f32_e64 v20, v10, v32
	v_mul_f32_e64 v21, v11, v33
	v_pk_mul_f32 v[22:23], v[138:139], v[34:35]
	v_pk_fma_f32 v[20:21], v[8:9], v[40:41], v[20:21] neg_lo:[0,0,1] neg_hi:[0,0,1]
	v_mfma_f32_32x32x16_bf16 a[192:207], v[82:85], v[44:47], a[192:207]
	v_mul_f32_e64 v8, v8, v32
	v_mul_f32_e64 v9, v9, v33
	v_fma_f32 v22, v116, v42, -v22
	v_fma_f32 v23, v117, v43, -v23
	v_fma_f32 v8, v10, v40, v8
	v_fma_f32 v9, v11, v41, v9
	v_pk_mul_f32 v[32:33], v[50:51], v[20:21] op_sel_hi:[0,1]
	v_pk_mul_f32 v[20:21], v[50:51], v[8:9] op_sel_hi:[0,1]
	v_pk_mul_f32 v[30:31], v[50:51], v[22:23] op_sel_hi:[0,1]
	v_pk_mul_f32 v[22:23], v[50:51], v[26:27] op_sel_hi:[0,1]
	v_mfma_f32_32x32x16_bf16 a[128:143], v[82:85], v[60:63], a[128:143]
	v_lshlrev_b32_e32 v51, 1, v24
	v_cvt_pk_bf16_f32 v8, v32, v33
	v_cvt_pk_bf16_f32 v9, v30, v31
	v_mad_u32_u24 v75, v74, s25, v51
	v_accvgpr_read_b32 v47, a31
	v_accvgpr_read_b32 v46, a30
	v_accvgpr_write_b32 a35, v33
	v_mfma_f32_32x32x16_bf16 a[64:79], v[82:85], v[56:59], a[64:79]
	v_accvgpr_read_b32 v83, a5
	v_accvgpr_read_b32 v82, a4
	v_accvgpr_write_b32 a4, v20
	v_accvgpr_write_b32 a5, v21
	v_cvt_pk_bf16_f32 v20, v20, v21
	v_cvt_pk_bf16_f32 v21, v22, v23
	ds_write2_b64 v75, v[8:9], v[20:21] offset1:32
	s_waitcnt vmcnt(1)
	v_pk_mul_f32 v[8:9], v[122:123], v[64:65]
	v_accvgpr_write_b32 a30, v30
	s_waitcnt vmcnt(0)
	v_pk_fma_f32 v[20:21], v[102:103], v[16:17], v[8:9] neg_lo:[0,0,1] neg_hi:[0,0,1]
	v_pk_mul_f32 v[8:9], v[102:103], v[64:65]
	v_accvgpr_write_b32 a2, v22
	v_pk_fma_f32 v[16:17], v[122:123], v[16:17], v[8:9]
	v_accvgpr_read_b32 v169, a207
	v_accvgpr_read_b32 v168, a206
	v_accvgpr_read_b32 v119, a205
	v_accvgpr_read_b32 v118, a204
	v_accvgpr_read_b32 v115, a203
	v_accvgpr_read_b32 v114, a202
	v_accvgpr_read_b32 v105, a201
	v_accvgpr_read_b32 v104, a200
	v_accvgpr_read_b32 v101, a199
	v_accvgpr_read_b32 v100, a198
	v_accvgpr_read_b32 v211, a197
	v_accvgpr_read_b32 v210, a196
	v_accvgpr_read_b32 v235, a195
	v_accvgpr_read_b32 v234, a194
	v_accvgpr_read_b32 v175, a143
	v_accvgpr_read_b32 v174, a142
	v_accvgpr_read_b32 v195, a141
	v_accvgpr_read_b32 v194, a140
	v_accvgpr_read_b32 v177, a139
	v_accvgpr_read_b32 v176, a138
	v_accvgpr_read_b32 v179, a137
	v_accvgpr_read_b32 v178, a136
	v_accvgpr_read_b32 v157, a135
	v_accvgpr_read_b32 v156, a134
	v_accvgpr_read_b32 v159, a133
	v_accvgpr_read_b32 v158, a132
	v_accvgpr_read_b32 v145, a131
	v_accvgpr_read_b32 v144, a130
	v_accvgpr_read_b32 v149, a79
	v_accvgpr_read_b32 v148, a78
	v_accvgpr_read_b32 v151, a77
	v_accvgpr_read_b32 v150, a76
	v_accvgpr_read_b32 v163, a75
	v_accvgpr_read_b32 v162, a74
	v_accvgpr_read_b32 v171, a73
	v_accvgpr_read_b32 v170, a72
	v_accvgpr_read_b32 v189, a71
	v_accvgpr_read_b32 v188, a70
	v_accvgpr_read_b32 v191, a69
	v_accvgpr_read_b32 v190, a68
	v_accvgpr_read_b32 v215, a67
	v_accvgpr_read_b32 v214, a66
	v_accvgpr_read_b32 v85, a7
	v_accvgpr_read_b32 v84, a6
	v_accvgpr_read_b32 v45, a223
	v_accvgpr_read_b32 v44, a222
	v_accvgpr_read_b32 v63, a217
	v_accvgpr_read_b32 v62, a216
	v_accvgpr_read_b32 v39, a213
	v_accvgpr_read_b32 v38, a212
	v_accvgpr_read_b32 v29, a211
	v_accvgpr_read_b32 v28, a210
	v_accvgpr_read_b32 v197, a157
	v_accvgpr_read_b32 v196, a156
	v_accvgpr_read_b32 v5, a155
	v_accvgpr_read_b32 v4, a154
	v_accvgpr_read_b32 v199, a153
	v_accvgpr_read_b32 v198, a152
	v_accvgpr_read_b32 v201, a151
	v_accvgpr_read_b32 v200, a150
	v_accvgpr_read_b32 v183, a149
	v_accvgpr_read_b32 v182, a148
	v_accvgpr_read_b32 v181, a147
	v_accvgpr_read_b32 v180, a146
	v_accvgpr_read_b32 v223, a95
	v_accvgpr_read_b32 v222, a94
	v_accvgpr_read_b32 v231, a93
	v_accvgpr_read_b32 v230, a92
	v_accvgpr_read_b32 v239, a91
	v_accvgpr_read_b32 v238, a90
	v_accvgpr_read_b32 v241, a89
	v_accvgpr_read_b32 v240, a88
	v_accvgpr_read_b32 v249, a87
	v_accvgpr_read_b32 v248, a86
	v_accvgpr_read_b32 v251, a85
	v_accvgpr_read_b32 v250, a84
	v_accvgpr_write_b32 a34, v32
	v_accvgpr_write_b32 a31, v31
	v_accvgpr_write_b32 a3, v23
	v_accvgpr_read_b32 v57, a29
	v_accvgpr_read_b32 v56, a28
	v_accvgpr_read_b32 v8, a26
	v_accvgpr_read_b32 v103, a25
	v_accvgpr_read_b32 v102, a24
	v_accvgpr_read_b32 v117, a23
	v_accvgpr_read_b32 v116, a22
	v_accvgpr_read_b32 v123, a21
	v_accvgpr_read_b32 v122, a20
	v_accvgpr_read_b32 v139, a19
	v_accvgpr_read_b32 v138, a18
	v_pk_mul_f32 v[24:25], v[50:51], v[20:21] op_sel_hi:[0,1]
	v_pk_mul_f32 v[20:21], v[50:51], v[16:17] op_sel_hi:[0,1]
	v_accvgpr_mov_b32 a37, a11
	v_accvgpr_mov_b32 a36, a10
	v_accvgpr_read_b32 v61, a221
	v_accvgpr_read_b32 v60, a220
	v_accvgpr_read_b32 v13, a159
	v_accvgpr_read_b32 v12, a158
	v_accvgpr_read_b32 v11, a83
	v_accvgpr_read_b32 v10, a82
	v_accvgpr_read_b32 v9, a27
	v_pk_mul_f32 v[16:17], v[14:15], v[66:67]
	v_accvgpr_write_b32 a8, v20
	v_pk_fma_f32 v[16:17], v[78:79], v[18:19], v[16:17] neg_lo:[0,0,1] neg_hi:[0,0,1]
	v_accvgpr_write_b32 a9, v21
	v_pk_mul_f32 v[22:23], v[50:51], v[16:17] op_sel_hi:[0,1]
	v_pk_mul_f32 v[16:17], v[78:79], v[66:67]
	v_accvgpr_write_b32 a22, v24
	v_pk_fma_f32 v[14:15], v[14:15], v[18:19], v[16:17]
	v_cvt_pk_bf16_f32 v16, v20, v21
	v_pk_mul_f32 v[18:19], v[50:51], v[14:15] op_sel_hi:[0,1]
	v_cvt_pk_bf16_f32 v14, v24, v25
	v_cvt_pk_bf16_f32 v15, v22, v23
	v_cvt_pk_bf16_f32 v17, v18, v19
	v_accvgpr_write_b32 a6, v18
	ds_write2_b64 v75, v[14:15], v[16:17] offset0:2 offset1:34
	v_accvgpr_write_b32 a7, v19
	global_load_dwordx4 v[18:21], v[72:73], off offset:64
	global_load_dwordx4 v[30:33], v[68:69], off offset:64
	v_accvgpr_write_b32 a23, v25
	v_accvgpr_write_b32 a20, v22
	v_accvgpr_write_b32 a21, v23
	s_waitcnt vmcnt(0)
	v_pk_mul_f32 v[14:15], v[6:7], v[30:31]
	s_nop 0
	v_pk_fma_f32 v[14:15], v[80:81], v[18:19], v[14:15] neg_lo:[0,0,1] neg_hi:[0,0,1]
	s_nop 0
	v_pk_mul_f32 v[24:25], v[50:51], v[14:15] op_sel_hi:[0,1]
	v_pk_mul_f32 v[14:15], v[80:81], v[30:31]
	s_nop 0
	v_pk_fma_f32 v[6:7], v[6:7], v[18:19], v[14:15]
	s_nop 0
	v_pk_mul_f32 v[16:17], v[50:51], v[6:7] op_sel_hi:[0,1]
	v_pk_mul_f32 v[6:7], v[0:1], v[32:33]
	v_accvgpr_write_b32 a19, v17
	v_pk_fma_f32 v[6:7], v[252:253], v[20:21], v[6:7] neg_lo:[0,0,1] neg_hi:[0,0,1]
	v_accvgpr_write_b32 a18, v16
	v_pk_mul_f32 v[26:27], v[50:51], v[6:7] op_sel_hi:[0,1]
	v_pk_mul_f32 v[6:7], v[252:253], v[32:33]
	s_nop 0
	v_pk_fma_f32 v[0:1], v[0:1], v[20:21], v[6:7]
	v_cvt_pk_bf16_f32 v6, v16, v17
	v_pk_mul_f32 v[14:15], v[50:51], v[0:1] op_sel_hi:[0,1]
	v_cvt_pk_bf16_f32 v0, v24, v25
	v_cvt_pk_bf16_f32 v1, v26, v27
	v_cvt_pk_bf16_f32 v7, v14, v15
	ds_write2_b64 v75, v[0:1], v[6:7] offset0:4 offset1:36
	global_load_dwordx4 v[18:21], v[72:73], off offset:96
	global_load_dwordx4 v[40:43], v[68:69], off offset:96
	v_accvgpr_write_b32 a10, v14
	v_accvgpr_write_b32 a11, v15
	s_waitcnt vmcnt(0)
	v_pk_mul_f32 v[0:1], v[2:3], v[40:41]
	s_nop 0
	v_pk_fma_f32 v[0:1], v[228:229], v[18:19], v[0:1] neg_lo:[0,0,1] neg_hi:[0,0,1]
	s_nop 0
	v_pk_mul_f32 v[32:33], v[50:51], v[0:1] op_sel_hi:[0,1]
	v_pk_mul_f32 v[0:1], v[228:229], v[40:41]
	s_nop 0
	v_pk_fma_f32 v[0:1], v[2:3], v[18:19], v[0:1]
	s_nop 0
	v_pk_mul_f32 v[22:23], v[50:51], v[0:1] op_sel_hi:[0,1]
	v_pk_mul_f32 v[0:1], v[76:77], v[42:43]
	v_cvt_pk_bf16_f32 v2, v22, v23
	v_pk_fma_f32 v[0:1], v[226:227], v[20:21], v[0:1] neg_lo:[0,0,1] neg_hi:[0,0,1]
	v_accvgpr_read_b32 v14, a208
	v_pk_mul_f32 v[34:35], v[50:51], v[0:1] op_sel_hi:[0,1]
	v_pk_mul_f32 v[0:1], v[226:227], v[42:43]
	v_accvgpr_read_b32 v15, a209
	v_pk_fma_f32 v[0:1], v[76:77], v[20:21], v[0:1]
	s_nop 0
	v_pk_mul_f32 v[6:7], v[50:51], v[0:1] op_sel_hi:[0,1]
	v_cvt_pk_bf16_f32 v0, v32, v33
	v_cvt_pk_bf16_f32 v1, v34, v35
	v_cvt_pk_bf16_f32 v3, v6, v7
	ds_write2_b64 v75, v[0:1], v[2:3] offset0:6 offset1:38
	global_load_dwordx4 v[0:3], v[72:73], off offset:128
	global_load_dwordx4 v[52:55], v[68:69], off offset:128
	v_accvgpr_write_b32 a25, v7
	v_accvgpr_write_b32 a24, v6
	v_accvgpr_read_b32 v6, a192
	v_accvgpr_read_b32 v7, a193
	s_waitcnt vmcnt(0)
	v_pk_mul_f32 v[16:17], v[14:15], v[52:53]
	s_nop 0
	v_pk_fma_f32 v[16:17], v[6:7], v[0:1], v[16:17] neg_lo:[0,0,1] neg_hi:[0,0,1]
	v_pk_mul_f32 v[6:7], v[6:7], v[52:53]
	v_pk_mul_f32 v[40:41], v[50:51], v[16:17] op_sel_hi:[0,1]
	v_pk_fma_f32 v[0:1], v[14:15], v[0:1], v[6:7]
	s_nop 0
	v_pk_mul_f32 v[30:31], v[50:51], v[0:1] op_sel_hi:[0,1]
	v_pk_mul_f32 v[0:1], v[28:29], v[54:55]
	s_nop 0
	v_pk_fma_f32 v[0:1], v[234:235], v[2:3], v[0:1] neg_lo:[0,0,1] neg_hi:[0,0,1]
	s_nop 0
	v_pk_mul_f32 v[42:43], v[50:51], v[0:1] op_sel_hi:[0,1]
	v_pk_mul_f32 v[0:1], v[234:235], v[54:55]
	s_nop 0
	v_pk_fma_f32 v[0:1], v[28:29], v[2:3], v[0:1]
	v_cvt_pk_bf16_f32 v2, v30, v31
	v_pk_mul_f32 v[28:29], v[50:51], v[0:1] op_sel_hi:[0,1]
	v_cvt_pk_bf16_f32 v0, v40, v41
	v_cvt_pk_bf16_f32 v1, v42, v43
	v_cvt_pk_bf16_f32 v3, v28, v29
	ds_write2_b64 v75, v[0:1], v[2:3] offset0:8 offset1:40
	global_load_dwordx4 v[0:3], v[72:73], off offset:160
	global_load_dwordx4 v[52:55], v[68:69], off offset:160
	s_waitcnt vmcnt(0)
	v_pk_mul_f32 v[6:7], v[38:39], v[52:53]
	s_nop 0
	v_pk_fma_f32 v[6:7], v[210:211], v[0:1], v[6:7] neg_lo:[0,0,1] neg_hi:[0,0,1]
	s_nop 0
	v_pk_mul_f32 v[58:59], v[50:51], v[6:7] op_sel_hi:[0,1]
	v_pk_mul_f32 v[6:7], v[210:211], v[52:53]
	s_nop 0
	v_pk_fma_f32 v[0:1], v[38:39], v[0:1], v[6:7]
	s_nop 0
	v_pk_mul_f32 v[38:39], v[50:51], v[0:1] op_sel_hi:[0,1]
	v_pk_mul_f32 v[0:1], v[36:37], v[54:55]
	s_nop 0
	v_pk_fma_f32 v[0:1], v[100:101], v[2:3], v[0:1] neg_lo:[0,0,1] neg_hi:[0,0,1]
	s_nop 0
	v_pk_mul_f32 v[14:15], v[50:51], v[0:1] op_sel_hi:[0,1]
	v_pk_mul_f32 v[0:1], v[100:101], v[54:55]
	s_nop 0
	v_pk_fma_f32 v[0:1], v[36:37], v[2:3], v[0:1]
	v_cvt_pk_bf16_f32 v2, v38, v39
	v_pk_mul_f32 v[36:37], v[50:51], v[0:1] op_sel_hi:[0,1]
	v_cvt_pk_bf16_f32 v0, v58, v59
	v_cvt_pk_bf16_f32 v1, v14, v15
	v_cvt_pk_bf16_f32 v3, v36, v37
	ds_write2_b64 v75, v[0:1], v[2:3] offset0:10 offset1:42
	global_load_dwordx4 v[0:3], v[72:73], off offset:192
	global_load_dwordx4 v[64:67], v[68:69], off offset:192
	s_waitcnt vmcnt(0)
	v_pk_mul_f32 v[6:7], v[62:63], v[64:65]
	s_nop 0
	v_pk_fma_f32 v[6:7], v[104:105], v[0:1], v[6:7] neg_lo:[0,0,1] neg_hi:[0,0,1]
	s_nop 0
	v_pk_mul_f32 v[100:101], v[50:51], v[6:7] op_sel_hi:[0,1]
	v_pk_mul_f32 v[6:7], v[104:105], v[64:65]
	s_nop 0
	v_pk_fma_f32 v[0:1], v[62:63], v[0:1], v[6:7]
	s_nop 0
	v_pk_mul_f32 v[54:55], v[50:51], v[0:1] op_sel_hi:[0,1]
	v_pk_mul_f32 v[0:1], v[48:49], v[66:67]
	s_nop 0
	v_pk_fma_f32 v[0:1], v[114:115], v[2:3], v[0:1] neg_lo:[0,0,1] neg_hi:[0,0,1]
	s_nop 0
	v_pk_mul_f32 v[104:105], v[50:51], v[0:1] op_sel_hi:[0,1]
	v_pk_mul_f32 v[0:1], v[114:115], v[66:67]
	s_nop 0
	v_pk_fma_f32 v[0:1], v[48:49], v[2:3], v[0:1]
	v_cvt_pk_bf16_f32 v2, v54, v55
	v_pk_mul_f32 v[52:53], v[50:51], v[0:1] op_sel_hi:[0,1]
	v_cvt_pk_bf16_f32 v0, v100, v101
	v_cvt_pk_bf16_f32 v1, v104, v105
	v_cvt_pk_bf16_f32 v3, v52, v53
	ds_write2_b64 v75, v[0:1], v[2:3] offset0:12 offset1:44
	global_load_dwordx4 v[0:3], v[72:73], off offset:224
	global_load_dwordx4 v[64:67], v[68:69], off offset:224
	s_waitcnt vmcnt(0)
	v_pk_mul_f32 v[6:7], v[60:61], v[64:65]
	s_nop 0
	v_pk_fma_f32 v[6:7], v[118:119], v[0:1], v[6:7] neg_lo:[0,0,1] neg_hi:[0,0,1]
	s_nop 0
	v_pk_mul_f32 v[114:115], v[50:51], v[6:7] op_sel_hi:[0,1]
	v_pk_mul_f32 v[6:7], v[118:119], v[64:65]
	s_nop 0
	v_pk_fma_f32 v[0:1], v[60:61], v[0:1], v[6:7]
	s_nop 0
	v_pk_mul_f32 v[64:65], v[50:51], v[0:1] op_sel_hi:[0,1]
	v_pk_mul_f32 v[0:1], v[44:45], v[66:67]
	s_nop 0
	v_pk_fma_f32 v[0:1], v[168:169], v[2:3], v[0:1] neg_lo:[0,0,1] neg_hi:[0,0,1]
	s_nop 0
	v_pk_mul_f32 v[118:119], v[50:51], v[0:1] op_sel_hi:[0,1]
	v_pk_mul_f32 v[0:1], v[168:169], v[66:67]
	s_nop 0
	v_pk_fma_f32 v[0:1], v[44:45], v[2:3], v[0:1]
	v_cvt_pk_bf16_f32 v2, v64, v65
	v_pk_mul_f32 v[66:67], v[50:51], v[0:1] op_sel_hi:[0,1]
	v_cvt_pk_bf16_f32 v0, v114, v115
	v_cvt_pk_bf16_f32 v1, v118, v119
	v_cvt_pk_bf16_f32 v3, v66, v67
	ds_write2_b64 v75, v[0:1], v[2:3] offset0:14 offset1:46
	v_or_b32_e32 v60, 32, v74
	v_or_b32_e32 v0, s66, v60
	v_lshlrev_b32_e32 v94, 9, v0
	v_lshl_add_u64 v[76:77], v[184:185], 0, v[94:95]
	v_lshl_add_u64 v[6:7], v[186:187], 0, v[94:95]
	global_load_dwordx4 v[0:3], v[76:77], off
	global_load_dwordx4 v[78:81], v[6:7], off
	v_accvgpr_read_b32 v18, a176
	v_accvgpr_read_b32 v16, a160
	v_accvgpr_read_b32 v19, a177
	v_accvgpr_read_b32 v17, a161
	s_waitcnt vmcnt(0)
	v_pk_mul_f32 v[44:45], v[18:19], v[78:79]
	s_nop 0
	v_pk_fma_f32 v[44:45], v[16:17], v[0:1], v[44:45] neg_lo:[0,0,1] neg_hi:[0,0,1]
	v_pk_mul_f32 v[16:17], v[16:17], v[78:79]
	v_pk_mul_f32 v[68:69], v[50:51], v[44:45] op_sel_hi:[0,1]
	v_pk_fma_f32 v[0:1], v[18:19], v[0:1], v[16:17]
	s_nop 0
	v_pk_mul_f32 v[48:49], v[50:51], v[0:1] op_sel_hi:[0,1]
	v_pk_mul_f32 v[0:1], v[70:71], v[80:81]
	v_cvt_pk_bf16_f32 v16, v48, v49
	v_pk_fma_f32 v[0:1], v[108:109], v[2:3], v[0:1] neg_lo:[0,0,1] neg_hi:[0,0,1]
	s_nop 0
	v_pk_mul_f32 v[62:63], v[50:51], v[0:1] op_sel_hi:[0,1]
	v_pk_mul_f32 v[0:1], v[108:109], v[80:81]
	s_nop 0
	v_pk_fma_f32 v[0:1], v[70:71], v[2:3], v[0:1]
	v_cvt_pk_bf16_f32 v2, v68, v69
	v_pk_mul_f32 v[44:45], v[50:51], v[0:1] op_sel_hi:[0,1]
	v_cvt_pk_bf16_f32 v3, v62, v63
	v_cvt_pk_bf16_f32 v17, v44, v45
	v_mad_u32_u24 v0, v60, s25, v51
	ds_write2_b64 v0, v[2:3], v[16:17] offset1:32
	global_load_dwordx4 v[78:81], v[76:77], off offset:32
	global_load_dwordx4 v[226:229], v[6:7], off offset:32
	s_waitcnt vmcnt(0)
	v_pk_mul_f32 v[2:3], v[206:207], v[226:227]
	s_nop 0
	v_pk_fma_f32 v[2:3], v[120:121], v[78:79], v[2:3] neg_lo:[0,0,1] neg_hi:[0,0,1]
	s_nop 0
	v_pk_mul_f32 v[108:109], v[50:51], v[2:3] op_sel_hi:[0,1]
	v_pk_mul_f32 v[2:3], v[120:121], v[226:227]
	s_nop 0
	v_pk_fma_f32 v[2:3], v[206:207], v[78:79], v[2:3]
	s_nop 0
	v_pk_mul_f32 v[72:73], v[50:51], v[2:3] op_sel_hi:[0,1]
	v_pk_mul_f32 v[2:3], v[164:165], v[228:229]
	v_cvt_pk_bf16_f32 v16, v72, v73
	v_pk_fma_f32 v[2:3], v[134:135], v[80:81], v[2:3] neg_lo:[0,0,1] neg_hi:[0,0,1]
	s_nop 0
	v_pk_mul_f32 v[120:121], v[50:51], v[2:3] op_sel_hi:[0,1]
	v_pk_mul_f32 v[2:3], v[134:135], v[228:229]
	s_nop 0
	v_pk_fma_f32 v[2:3], v[164:165], v[80:81], v[2:3]
	s_nop 0
	v_pk_mul_f32 v[70:71], v[50:51], v[2:3] op_sel_hi:[0,1]
	v_cvt_pk_bf16_f32 v2, v108, v109
	v_cvt_pk_bf16_f32 v3, v120, v121
	v_cvt_pk_bf16_f32 v17, v70, v71
	ds_write2_b64 v0, v[2:3], v[16:17] offset0:2 offset1:34
	global_load_dwordx4 v[78:81], v[76:77], off offset:64
	global_load_dwordx4 v[226:229], v[6:7], off offset:64
	s_waitcnt vmcnt(0)
	v_pk_mul_f32 v[2:3], v[136:137], v[226:227]
	s_nop 0
	v_pk_fma_f32 v[2:3], v[112:113], v[78:79], v[2:3] neg_lo:[0,0,1] neg_hi:[0,0,1]
	s_nop 0
	v_pk_mul_f32 v[134:135], v[50:51], v[2:3] op_sel_hi:[0,1]
	v_pk_mul_f32 v[2:3], v[112:113], v[226:227]
	s_nop 0
	v_pk_fma_f32 v[2:3], v[136:137], v[78:79], v[2:3]
	s_nop 0
	v_pk_mul_f32 v[112:113], v[50:51], v[2:3] op_sel_hi:[0,1]
	v_pk_mul_f32 v[2:3], v[152:153], v[228:229]
	v_cvt_pk_bf16_f32 v16, v112, v113
	v_pk_fma_f32 v[2:3], v[110:111], v[80:81], v[2:3] neg_lo:[0,0,1] neg_hi:[0,0,1]
	s_nop 0
	v_pk_mul_f32 v[136:137], v[50:51], v[2:3] op_sel_hi:[0,1]
	v_pk_mul_f32 v[2:3], v[110:111], v[228:229]
	s_nop 0
	v_pk_fma_f32 v[2:3], v[152:153], v[80:81], v[2:3]
	s_nop 0
	v_pk_mul_f32 v[110:111], v[50:51], v[2:3] op_sel_hi:[0,1]
	v_cvt_pk_bf16_f32 v2, v134, v135
	v_cvt_pk_bf16_f32 v3, v136, v137
	v_cvt_pk_bf16_f32 v17, v110, v111
	ds_write2_b64 v0, v[2:3], v[16:17] offset0:4 offset1:36
	global_load_dwordx4 v[78:81], v[76:77], off offset:96
	global_load_dwordx4 v[226:229], v[6:7], off offset:96
	s_waitcnt vmcnt(0)
	v_pk_mul_f32 v[2:3], v[154:155], v[226:227]
	s_nop 0
	v_pk_fma_f32 v[2:3], v[132:133], v[78:79], v[2:3] neg_lo:[0,0,1] neg_hi:[0,0,1]
	s_nop 0
	v_pk_mul_f32 v[152:153], v[50:51], v[2:3] op_sel_hi:[0,1]
	v_pk_mul_f32 v[2:3], v[132:133], v[226:227]
	s_nop 0
	v_pk_fma_f32 v[2:3], v[154:155], v[78:79], v[2:3]
	s_nop 0
	v_pk_mul_f32 v[132:133], v[50:51], v[2:3] op_sel_hi:[0,1]
	v_pk_mul_f32 v[2:3], v[146:147], v[228:229]
	v_cvt_pk_bf16_f32 v16, v132, v133
	v_pk_fma_f32 v[2:3], v[130:131], v[80:81], v[2:3] neg_lo:[0,0,1] neg_hi:[0,0,1]
	s_nop 0
	v_pk_mul_f32 v[154:155], v[50:51], v[2:3] op_sel_hi:[0,1]
	v_pk_mul_f32 v[2:3], v[130:131], v[228:229]
	s_nop 0
	v_pk_fma_f32 v[2:3], v[146:147], v[80:81], v[2:3]
	s_nop 0
	v_pk_mul_f32 v[130:131], v[50:51], v[2:3] op_sel_hi:[0,1]
	v_cvt_pk_bf16_f32 v2, v152, v153
	v_cvt_pk_bf16_f32 v3, v154, v155
	v_cvt_pk_bf16_f32 v17, v130, v131
	ds_write2_b64 v0, v[2:3], v[16:17] offset0:6 offset1:38
	global_load_dwordx4 v[78:81], v[76:77], off offset:128
	global_load_dwordx4 v[226:229], v[6:7], off offset:128
	v_accvgpr_read_b32 v16, a144
	v_accvgpr_read_b32 v2, a128
	v_accvgpr_read_b32 v17, a145
	v_accvgpr_read_b32 v3, a129
	s_waitcnt vmcnt(0)
	v_pk_mul_f32 v[18:19], v[16:17], v[226:227]
	s_nop 0
	v_pk_fma_f32 v[18:19], v[2:3], v[78:79], v[18:19] neg_lo:[0,0,1] neg_hi:[0,0,1]
	v_pk_mul_f32 v[2:3], v[2:3], v[226:227]
	v_pk_mul_f32 v[164:165], v[50:51], v[18:19] op_sel_hi:[0,1]
	v_pk_fma_f32 v[2:3], v[16:17], v[78:79], v[2:3]
	s_nop 0
	v_pk_mul_f32 v[146:147], v[50:51], v[2:3] op_sel_hi:[0,1]
	v_pk_mul_f32 v[2:3], v[180:181], v[228:229]
	v_cvt_pk_bf16_f32 v16, v146, v147
	v_pk_fma_f32 v[2:3], v[144:145], v[80:81], v[2:3] neg_lo:[0,0,1] neg_hi:[0,0,1]
	s_nop 0
	v_pk_mul_f32 v[168:169], v[50:51], v[2:3] op_sel_hi:[0,1]
	v_pk_mul_f32 v[2:3], v[144:145], v[228:229]
	s_nop 0
	v_pk_fma_f32 v[2:3], v[180:181], v[80:81], v[2:3]
	s_nop 0
	v_pk_mul_f32 v[144:145], v[50:51], v[2:3] op_sel_hi:[0,1]
	v_cvt_pk_bf16_f32 v2, v164, v165
	v_cvt_pk_bf16_f32 v3, v168, v169
	v_cvt_pk_bf16_f32 v17, v144, v145
	ds_write2_b64 v0, v[2:3], v[16:17] offset0:8 offset1:40
	global_load_dwordx4 v[78:81], v[76:77], off offset:160
	global_load_dwordx4 v[226:229], v[6:7], off offset:160
	s_waitcnt vmcnt(0)
	v_pk_mul_f32 v[2:3], v[182:183], v[226:227]
	s_nop 0
	v_pk_fma_f32 v[2:3], v[158:159], v[78:79], v[2:3] neg_lo:[0,0,1] neg_hi:[0,0,1]
	s_nop 0
	v_pk_mul_f32 v[180:181], v[50:51], v[2:3] op_sel_hi:[0,1]
	v_pk_mul_f32 v[2:3], v[158:159], v[226:227]
	s_nop 0
	v_pk_fma_f32 v[2:3], v[182:183], v[78:79], v[2:3]
	s_nop 0
	v_pk_mul_f32 v[158:159], v[50:51], v[2:3] op_sel_hi:[0,1]
	v_pk_mul_f32 v[2:3], v[200:201], v[228:229]
	v_cvt_pk_bf16_f32 v16, v158, v159
	v_pk_fma_f32 v[2:3], v[156:157], v[80:81], v[2:3] neg_lo:[0,0,1] neg_hi:[0,0,1]
	s_nop 0
	v_pk_mul_f32 v[182:183], v[50:51], v[2:3] op_sel_hi:[0,1]
	v_pk_mul_f32 v[2:3], v[156:157], v[228:229]
	s_nop 0
	v_pk_fma_f32 v[2:3], v[200:201], v[80:81], v[2:3]
	s_nop 0
	v_pk_mul_f32 v[156:157], v[50:51], v[2:3] op_sel_hi:[0,1]
	v_cvt_pk_bf16_f32 v2, v180, v181
	v_cvt_pk_bf16_f32 v3, v182, v183
	v_cvt_pk_bf16_f32 v17, v156, v157
	ds_write2_b64 v0, v[2:3], v[16:17] offset0:10 offset1:42
	global_load_dwordx4 v[78:81], v[76:77], off offset:192
	global_load_dwordx4 v[226:229], v[6:7], off offset:192
	s_waitcnt vmcnt(0)
	v_pk_mul_f32 v[2:3], v[198:199], v[226:227]
	s_nop 0
	v_pk_fma_f32 v[2:3], v[178:179], v[78:79], v[2:3] neg_lo:[0,0,1] neg_hi:[0,0,1]
	s_nop 0
	v_pk_mul_f32 v[206:207], v[50:51], v[2:3] op_sel_hi:[0,1]
	v_pk_mul_f32 v[2:3], v[178:179], v[226:227]
	s_nop 0
	v_pk_fma_f32 v[2:3], v[198:199], v[78:79], v[2:3]
	s_nop 0
	v_pk_mul_f32 v[178:179], v[50:51], v[2:3] op_sel_hi:[0,1]
	v_pk_mul_f32 v[2:3], v[4:5], v[228:229]
	s_nop 0
	v_pk_fma_f32 v[2:3], v[176:177], v[80:81], v[2:3] neg_lo:[0,0,1] neg_hi:[0,0,1]
	s_nop 0
	v_pk_mul_f32 v[210:211], v[50:51], v[2:3] op_sel_hi:[0,1]
	v_pk_mul_f32 v[2:3], v[176:177], v[228:229]
	s_nop 0
	v_pk_fma_f32 v[2:3], v[4:5], v[80:81], v[2:3]
	v_cvt_pk_bf16_f32 v4, v178, v179
	v_pk_mul_f32 v[176:177], v[50:51], v[2:3] op_sel_hi:[0,1]
	v_cvt_pk_bf16_f32 v2, v206, v207
	v_cvt_pk_bf16_f32 v3, v210, v211
	v_cvt_pk_bf16_f32 v5, v176, v177
	ds_write2_b64 v0, v[2:3], v[4:5] offset0:12 offset1:44
	global_load_dwordx4 v[2:5], v[76:77], off offset:224
	s_nop 0
	global_load_dwordx4 v[76:79], v[6:7], off offset:224
	s_waitcnt vmcnt(0)
	v_pk_mul_f32 v[6:7], v[196:197], v[76:77]
	s_nop 0
	v_pk_fma_f32 v[6:7], v[194:195], v[2:3], v[6:7] neg_lo:[0,0,1] neg_hi:[0,0,1]
	s_nop 0
	v_pk_mul_f32 v[226:227], v[50:51], v[6:7] op_sel_hi:[0,1]
	v_pk_mul_f32 v[6:7], v[194:195], v[76:77]
	s_nop 0
	v_pk_fma_f32 v[2:3], v[196:197], v[2:3], v[6:7]
	s_nop 0
	v_pk_mul_f32 v[196:197], v[50:51], v[2:3] op_sel_hi:[0,1]
	v_pk_mul_f32 v[2:3], v[12:13], v[78:79]
	s_nop 0
	v_pk_fma_f32 v[2:3], v[174:175], v[4:5], v[2:3] neg_lo:[0,0,1] neg_hi:[0,0,1]
	s_nop 0
	v_pk_mul_f32 v[228:229], v[50:51], v[2:3] op_sel_hi:[0,1]
	v_pk_mul_f32 v[2:3], v[174:175], v[78:79]
	s_nop 0
	v_pk_fma_f32 v[2:3], v[12:13], v[4:5], v[2:3]
	v_cvt_pk_bf16_f32 v4, v196, v197
	v_pk_mul_f32 v[198:199], v[50:51], v[2:3] op_sel_hi:[0,1]
	v_cvt_pk_bf16_f32 v2, v226, v227
	v_cvt_pk_bf16_f32 v3, v228, v229
	v_cvt_pk_bf16_f32 v5, v198, v199
	ds_write2_b64 v0, v[2:3], v[4:5] offset0:14 offset1:46
	v_or_b32_e32 v60, 64, v74
	v_or_b32_e32 v0, s66, v60
	v_lshlrev_b32_e32 v94, 9, v0
	v_lshl_add_u64 v[6:7], v[184:185], 0, v[94:95]
	v_lshl_add_u64 v[4:5], v[186:187], 0, v[94:95]
	global_load_dwordx4 v[0:3], v[6:7], off
	global_load_dwordx4 v[76:79], v[4:5], off
	v_accvgpr_read_b32 v16, a112
	v_accvgpr_read_b32 v12, a96
	v_accvgpr_read_b32 v17, a113
	v_accvgpr_read_b32 v13, a97
	s_waitcnt vmcnt(0)
	v_pk_mul_f32 v[18:19], v[16:17], v[76:77]
	s_nop 0
	v_pk_fma_f32 v[18:19], v[12:13], v[0:1], v[18:19] neg_lo:[0,0,1] neg_hi:[0,0,1]
	v_pk_mul_f32 v[12:13], v[12:13], v[76:77]
	v_pk_mul_f32 v[200:201], v[50:51], v[18:19] op_sel_hi:[0,1]
	v_pk_fma_f32 v[0:1], v[16:17], v[0:1], v[12:13]
	v_mad_u32_u24 v12, v60, s25, v51
	v_pk_mul_f32 v[174:175], v[50:51], v[0:1] op_sel_hi:[0,1]
	v_pk_mul_f32 v[0:1], v[216:217], v[78:79]
	s_nop 0
	v_pk_fma_f32 v[0:1], v[172:173], v[2:3], v[0:1] neg_lo:[0,0,1] neg_hi:[0,0,1]
	s_nop 0
	v_pk_mul_f32 v[194:195], v[50:51], v[0:1] op_sel_hi:[0,1]
	v_pk_mul_f32 v[0:1], v[172:173], v[78:79]
	s_nop 0
	v_pk_fma_f32 v[0:1], v[216:217], v[2:3], v[0:1]
	v_cvt_pk_bf16_f32 v2, v174, v175
	v_pk_mul_f32 v[172:173], v[50:51], v[0:1] op_sel_hi:[0,1]
	v_cvt_pk_bf16_f32 v0, v200, v201
	v_cvt_pk_bf16_f32 v1, v194, v195
	v_cvt_pk_bf16_f32 v3, v172, v173
	ds_write2_b64 v12, v[0:1], v[2:3] offset1:32
	global_load_dwordx4 v[0:3], v[6:7], off offset:32
	global_load_dwordx4 v[76:79], v[4:5], off offset:32
	s_waitcnt vmcnt(0)
	v_pk_mul_f32 v[16:17], v[232:233], v[76:77]
	s_nop 0
	v_pk_fma_f32 v[16:17], v[204:205], v[0:1], v[16:17] neg_lo:[0,0,1] neg_hi:[0,0,1]
	s_nop 0
	v_pk_mul_f32 v[216:217], v[50:51], v[16:17] op_sel_hi:[0,1]
	v_pk_mul_f32 v[16:17], v[204:205], v[76:77]
	s_nop 0
	v_pk_fma_f32 v[0:1], v[232:233], v[0:1], v[16:17]
	s_nop 0
	v_pk_mul_f32 v[204:205], v[50:51], v[0:1] op_sel_hi:[0,1]
	v_pk_mul_f32 v[0:1], v[224:225], v[78:79]
	s_nop 0
	v_pk_fma_f32 v[0:1], v[202:203], v[2:3], v[0:1] neg_lo:[0,0,1] neg_hi:[0,0,1]
	s_nop 0
	v_pk_mul_f32 v[232:233], v[50:51], v[0:1] op_sel_hi:[0,1]
	v_pk_mul_f32 v[0:1], v[202:203], v[78:79]
	s_nop 0
	v_pk_fma_f32 v[0:1], v[224:225], v[2:3], v[0:1]
	v_cvt_pk_bf16_f32 v2, v204, v205
	v_pk_mul_f32 v[202:203], v[50:51], v[0:1] op_sel_hi:[0,1]
	v_cvt_pk_bf16_f32 v0, v216, v217
	v_cvt_pk_bf16_f32 v1, v232, v233
	v_cvt_pk_bf16_f32 v3, v202, v203
	ds_write2_b64 v12, v[0:1], v[2:3] offset0:2 offset1:34
	global_load_dwordx4 v[0:3], v[6:7], off offset:64
	global_load_dwordx4 v[76:79], v[4:5], off offset:64
	s_waitcnt vmcnt(0)
	v_pk_mul_f32 v[16:17], v[236:237], v[76:77]
	s_nop 0
	v_pk_fma_f32 v[16:17], v[220:221], v[0:1], v[16:17] neg_lo:[0,0,1] neg_hi:[0,0,1]
	s_nop 0
	v_pk_mul_f32 v[234:235], v[50:51], v[16:17] op_sel_hi:[0,1]
	v_pk_mul_f32 v[16:17], v[220:221], v[76:77]
	s_nop 0
	v_pk_fma_f32 v[0:1], v[236:237], v[0:1], v[16:17]
	s_nop 0
	v_pk_mul_f32 v[220:221], v[50:51], v[0:1] op_sel_hi:[0,1]
	v_pk_mul_f32 v[0:1], v[246:247], v[78:79]
	s_nop 0
	v_pk_fma_f32 v[0:1], v[218:219], v[2:3], v[0:1] neg_lo:[0,0,1] neg_hi:[0,0,1]
	s_nop 0
	v_pk_mul_f32 v[236:237], v[50:51], v[0:1] op_sel_hi:[0,1]
	v_pk_mul_f32 v[0:1], v[218:219], v[78:79]
	s_nop 0
	v_pk_fma_f32 v[0:1], v[246:247], v[2:3], v[0:1]
	v_cvt_pk_bf16_f32 v2, v220, v221
	v_pk_mul_f32 v[218:219], v[50:51], v[0:1] op_sel_hi:[0,1]
	v_cvt_pk_bf16_f32 v0, v234, v235
	v_cvt_pk_bf16_f32 v1, v236, v237
	v_cvt_pk_bf16_f32 v3, v218, v219
	ds_write2_b64 v12, v[0:1], v[2:3] offset0:4 offset1:36
	global_load_dwordx4 v[0:3], v[6:7], off offset:96
	global_load_dwordx4 v[76:79], v[4:5], off offset:96
	s_waitcnt vmcnt(0)
	v_pk_mul_f32 v[16:17], v[244:245], v[76:77]
	s_nop 0
	v_pk_fma_f32 v[16:17], v[212:213], v[0:1], v[16:17] neg_lo:[0,0,1] neg_hi:[0,0,1]
	s_nop 0
	v_pk_mul_f32 v[246:247], v[50:51], v[16:17] op_sel_hi:[0,1]
	v_pk_mul_f32 v[16:17], v[212:213], v[76:77]
	s_nop 0
	v_pk_fma_f32 v[0:1], v[244:245], v[0:1], v[16:17]
	s_nop 0
	v_pk_mul_f32 v[212:213], v[50:51], v[0:1] op_sel_hi:[0,1]
	v_pk_mul_f32 v[0:1], v[242:243], v[78:79]
	v_accvgpr_read_b32 v18, a80
	v_pk_fma_f32 v[0:1], v[208:209], v[2:3], v[0:1] neg_lo:[0,0,1] neg_hi:[0,0,1]
	v_accvgpr_read_b32 v16, a64
	v_pk_mul_f32 v[244:245], v[50:51], v[0:1] op_sel_hi:[0,1]
	v_pk_mul_f32 v[0:1], v[208:209], v[78:79]
	v_accvgpr_read_b32 v19, a81
	v_pk_fma_f32 v[0:1], v[242:243], v[2:3], v[0:1]
	v_cvt_pk_bf16_f32 v2, v212, v213
	v_pk_mul_f32 v[208:209], v[50:51], v[0:1] op_sel_hi:[0,1]
	v_cvt_pk_bf16_f32 v0, v246, v247
	v_cvt_pk_bf16_f32 v1, v244, v245
	v_cvt_pk_bf16_f32 v3, v208, v209
	ds_write2_b64 v12, v[0:1], v[2:3] offset0:6 offset1:38
	global_load_dwordx4 v[0:3], v[6:7], off offset:128
	global_load_dwordx4 v[76:79], v[4:5], off offset:128
	v_accvgpr_read_b32 v17, a65
	s_waitcnt vmcnt(0)
	v_pk_mul_f32 v[60:61], v[18:19], v[76:77]
	s_nop 0
	v_pk_fma_f32 v[60:61], v[16:17], v[0:1], v[60:61] neg_lo:[0,0,1] neg_hi:[0,0,1]
	v_pk_mul_f32 v[16:17], v[16:17], v[76:77]
	v_pk_mul_f32 v[252:253], v[50:51], v[60:61] op_sel_hi:[0,1]
	v_pk_fma_f32 v[0:1], v[18:19], v[0:1], v[16:17]
	s_nop 0
	v_pk_mul_f32 v[242:243], v[50:51], v[0:1] op_sel_hi:[0,1]
	v_pk_mul_f32 v[0:1], v[10:11], v[78:79]
	v_pk_mul_f32 v[16:17], v[214:215], v[78:79]
	v_pk_fma_f32 v[0:1], v[214:215], v[2:3], v[0:1] neg_lo:[0,0,1] neg_hi:[0,0,1]
	v_pk_fma_f32 v[2:3], v[10:11], v[2:3], v[16:17]
	v_pk_mul_f32 v[0:1], v[50:51], v[0:1] op_sel_hi:[0,1]
	v_pk_mul_f32 v[214:215], v[50:51], v[2:3] op_sel_hi:[0,1]
	v_cvt_pk_bf16_f32 v2, v252, v253
	v_cvt_pk_bf16_f32 v3, v0, v1
	v_cvt_pk_bf16_f32 v10, v242, v243
	v_cvt_pk_bf16_f32 v11, v214, v215
	ds_write2_b64 v12, v[2:3], v[10:11] offset0:8 offset1:40
	global_load_dwordx4 v[76:79], v[6:7], off offset:160
	global_load_dwordx4 v[16:19], v[4:5], off offset:160
	s_waitcnt vmcnt(0)
	v_pk_mul_f32 v[2:3], v[250:251], v[16:17]
	v_pk_mul_f32 v[10:11], v[190:191], v[16:17]
	v_pk_fma_f32 v[2:3], v[190:191], v[76:77], v[2:3] neg_lo:[0,0,1] neg_hi:[0,0,1]
	v_pk_fma_f32 v[10:11], v[250:251], v[76:77], v[10:11]
	v_pk_mul_f32 v[2:3], v[50:51], v[2:3] op_sel_hi:[0,1]
	v_pk_mul_f32 v[190:191], v[50:51], v[10:11] op_sel_hi:[0,1]
	v_pk_mul_f32 v[10:11], v[248:249], v[18:19]
	v_cvt_pk_bf16_f32 v16, v190, v191
	v_pk_fma_f32 v[10:11], v[188:189], v[78:79], v[10:11] neg_lo:[0,0,1] neg_hi:[0,0,1]
	s_nop 0
	v_pk_mul_f32 v[250:251], v[50:51], v[10:11] op_sel_hi:[0,1]
	v_pk_mul_f32 v[10:11], v[188:189], v[18:19]
	s_nop 0
	v_pk_fma_f32 v[10:11], v[248:249], v[78:79], v[10:11]
	s_nop 0
	v_pk_mul_f32 v[188:189], v[50:51], v[10:11] op_sel_hi:[0,1]
	v_cvt_pk_bf16_f32 v10, v2, v3
	v_cvt_pk_bf16_f32 v11, v250, v251
	v_cvt_pk_bf16_f32 v17, v188, v189
	ds_write2_b64 v12, v[10:11], v[16:17] offset0:10 offset1:42
	global_load_dwordx4 v[16:19], v[6:7], off offset:192
	global_load_dwordx4 v[76:79], v[4:5], off offset:192
	s_waitcnt vmcnt(0)
	v_pk_mul_f32 v[10:11], v[240:241], v[76:77]
	s_nop 0
	v_pk_fma_f32 v[10:11], v[170:171], v[16:17], v[10:11] neg_lo:[0,0,1] neg_hi:[0,0,1]
	s_nop 0
	v_pk_mul_f32 v[248:249], v[50:51], v[10:11] op_sel_hi:[0,1]
	v_pk_mul_f32 v[10:11], v[170:171], v[76:77]
	s_nop 0
	v_pk_fma_f32 v[10:11], v[240:241], v[16:17], v[10:11]
	s_nop 0
	v_pk_mul_f32 v[170:171], v[50:51], v[10:11] op_sel_hi:[0,1]
	v_pk_mul_f32 v[10:11], v[238:239], v[78:79]
	v_cvt_pk_bf16_f32 v16, v170, v171
	v_pk_fma_f32 v[10:11], v[162:163], v[18:19], v[10:11] neg_lo:[0,0,1] neg_hi:[0,0,1]
	s_nop 0
	v_pk_mul_f32 v[240:241], v[50:51], v[10:11] op_sel_hi:[0,1]
	v_pk_mul_f32 v[10:11], v[162:163], v[78:79]
	s_nop 0
	v_pk_fma_f32 v[10:11], v[238:239], v[18:19], v[10:11]
	s_nop 0
	v_pk_mul_f32 v[162:163], v[50:51], v[10:11] op_sel_hi:[0,1]
	v_cvt_pk_bf16_f32 v10, v248, v249
	v_cvt_pk_bf16_f32 v11, v240, v241
	v_cvt_pk_bf16_f32 v17, v162, v163
	ds_write2_b64 v12, v[10:11], v[16:17] offset0:12 offset1:44
	global_load_dwordx4 v[16:19], v[6:7], off offset:224
	s_nop 0
	global_load_dwordx4 v[4:7], v[4:5], off offset:224
	s_waitcnt vmcnt(0)
	v_pk_mul_f32 v[10:11], v[230:231], v[4:5]
	v_pk_mul_f32 v[4:5], v[150:151], v[4:5]
	v_pk_fma_f32 v[10:11], v[150:151], v[16:17], v[10:11] neg_lo:[0,0,1] neg_hi:[0,0,1]
	v_pk_fma_f32 v[4:5], v[230:231], v[16:17], v[4:5]
	v_pk_mul_f32 v[238:239], v[50:51], v[10:11] op_sel_hi:[0,1]
	v_pk_mul_f32 v[224:225], v[50:51], v[4:5] op_sel_hi:[0,1]
	v_pk_mul_f32 v[4:5], v[222:223], v[6:7]
	s_nop 0
	v_pk_fma_f32 v[4:5], v[148:149], v[18:19], v[4:5] neg_lo:[0,0,1] neg_hi:[0,0,1]
	s_nop 0
	v_pk_mul_f32 v[230:231], v[50:51], v[4:5] op_sel_hi:[0,1]
	v_pk_mul_f32 v[4:5], v[148:149], v[6:7]
	v_cvt_pk_bf16_f32 v6, v224, v225
	v_pk_fma_f32 v[4:5], v[222:223], v[18:19], v[4:5]
	s_nop 0
	v_pk_mul_f32 v[222:223], v[50:51], v[4:5] op_sel_hi:[0,1]
	v_cvt_pk_bf16_f32 v4, v238, v239
	v_cvt_pk_bf16_f32 v5, v230, v231
	v_cvt_pk_bf16_f32 v7, v222, v223
	ds_write2_b64 v12, v[4:5], v[6:7] offset0:14 offset1:46
	v_or_b32_e32 v78, 0x60, v74
	v_or_b32_e32 v4, s66, v78
	v_lshlrev_b32_e32 v94, 9, v4
	v_lshl_add_u64 v[76:77], v[184:185], 0, v[94:95]
	v_lshl_add_u64 v[6:7], v[186:187], 0, v[94:95]
	global_load_dwordx4 v[10:13], v[76:77], off
	global_load_dwordx4 v[16:19], v[6:7], off
	v_accvgpr_read_b32 v61, a49
	v_accvgpr_read_b32 v4, a32
	v_accvgpr_read_b32 v60, a48
	v_accvgpr_read_b32 v5, a33
	s_waitcnt vmcnt(0)
	v_pk_mul_f32 v[74:75], v[60:61], v[16:17]
	s_nop 0
	v_pk_fma_f32 v[74:75], v[4:5], v[10:11], v[74:75] neg_lo:[0,0,1] neg_hi:[0,0,1]
	v_pk_mul_f32 v[4:5], v[4:5], v[16:17]
	v_pk_mul_f32 v[184:185], v[50:51], v[74:75] op_sel_hi:[0,1]
	v_pk_fma_f32 v[4:5], v[60:61], v[10:11], v[4:5]
	v_mad_u32_u24 v10, v78, s25, v51
	v_pk_mul_f32 v[148:149], v[50:51], v[4:5] op_sel_hi:[0,1]
	v_pk_mul_f32 v[4:5], v[192:193], v[18:19]
	s_nop 0
	v_pk_fma_f32 v[4:5], v[128:129], v[12:13], v[4:5] neg_lo:[0,0,1] neg_hi:[0,0,1]
	s_nop 0
	v_pk_mul_f32 v[150:151], v[50:51], v[4:5] op_sel_hi:[0,1]
	v_pk_mul_f32 v[4:5], v[128:129], v[18:19]
	s_nop 0
	v_pk_fma_f32 v[4:5], v[192:193], v[12:13], v[4:5]
	v_cvt_pk_bf16_f32 v12, v148, v149
	v_pk_mul_f32 v[128:129], v[50:51], v[4:5] op_sel_hi:[0,1]
	v_cvt_pk_bf16_f32 v4, v184, v185
	v_cvt_pk_bf16_f32 v5, v150, v151
	v_cvt_pk_bf16_f32 v13, v128, v129
	ds_write2_b64 v10, v[4:5], v[12:13] offset1:32
	global_load_dwordx4 v[16:19], v[76:77], off offset:32
	global_load_dwordx4 v[78:81], v[6:7], off offset:32
	s_waitcnt vmcnt(0)
	v_pk_mul_f32 v[4:5], v[166:167], v[78:79]
	s_nop 0
	v_pk_fma_f32 v[4:5], v[106:107], v[16:17], v[4:5] neg_lo:[0,0,1] neg_hi:[0,0,1]
	s_nop 0
	v_pk_mul_f32 v[186:187], v[50:51], v[4:5] op_sel_hi:[0,1]
	v_pk_mul_f32 v[4:5], v[106:107], v[78:79]
	s_nop 0
	v_pk_fma_f32 v[4:5], v[166:167], v[16:17], v[4:5]
	s_nop 0
	v_pk_mul_f32 v[106:107], v[50:51], v[4:5] op_sel_hi:[0,1]
	v_pk_mul_f32 v[4:5], v[160:161], v[80:81]
	v_cvt_pk_bf16_f32 v12, v106, v107
	v_pk_fma_f32 v[4:5], v[98:99], v[18:19], v[4:5] neg_lo:[0,0,1] neg_hi:[0,0,1]
	s_nop 0
	v_pk_mul_f32 v[166:167], v[50:51], v[4:5] op_sel_hi:[0,1]
	v_pk_mul_f32 v[4:5], v[98:99], v[80:81]
	s_nop 0
	v_pk_fma_f32 v[4:5], v[160:161], v[18:19], v[4:5]
	s_nop 0
	v_pk_mul_f32 v[98:99], v[50:51], v[4:5] op_sel_hi:[0,1]
	v_cvt_pk_bf16_f32 v4, v186, v187
	v_cvt_pk_bf16_f32 v5, v166, v167
	v_cvt_pk_bf16_f32 v13, v98, v99
	ds_write2_b64 v10, v[4:5], v[12:13] offset0:2 offset1:34
	global_load_dwordx4 v[16:19], v[76:77], off offset:64
	global_load_dwordx4 v[78:81], v[6:7], off offset:64
	s_waitcnt vmcnt(0)
	v_pk_mul_f32 v[4:5], v[142:143], v[78:79]
	s_nop 0
	v_pk_fma_f32 v[4:5], v[96:97], v[16:17], v[4:5] neg_lo:[0,0,1] neg_hi:[0,0,1]
	s_nop 0
	v_pk_mul_f32 v[160:161], v[50:51], v[4:5] op_sel_hi:[0,1]
	v_pk_mul_f32 v[4:5], v[96:97], v[78:79]
	s_nop 0
	v_pk_fma_f32 v[4:5], v[142:143], v[16:17], v[4:5]
	s_nop 0
	v_pk_mul_f32 v[96:97], v[50:51], v[4:5] op_sel_hi:[0,1]
	v_pk_mul_f32 v[4:5], v[140:141], v[80:81]
	v_cvt_pk_bf16_f32 v12, v96, v97
	v_pk_fma_f32 v[4:5], v[86:87], v[18:19], v[4:5] neg_lo:[0,0,1] neg_hi:[0,0,1]
	s_nop 0
	v_pk_mul_f32 v[142:143], v[50:51], v[4:5] op_sel_hi:[0,1]
	v_pk_mul_f32 v[4:5], v[86:87], v[80:81]
	s_nop 0
	v_pk_fma_f32 v[4:5], v[140:141], v[18:19], v[4:5]
	s_nop 0
	v_pk_mul_f32 v[20:21], v[50:51], v[4:5] op_sel_hi:[0,1]
	v_cvt_pk_bf16_f32 v4, v160, v161
	v_cvt_pk_bf16_f32 v5, v142, v143
	v_cvt_pk_bf16_f32 v13, v20, v21
	ds_write2_b64 v10, v[4:5], v[12:13] offset0:4 offset1:36
	global_load_dwordx4 v[16:19], v[76:77], off offset:96
	global_load_dwordx4 v[78:81], v[6:7], off offset:96
	s_waitcnt vmcnt(0)
	v_pk_mul_f32 v[4:5], v[126:127], v[78:79]
	s_nop 0
	v_pk_fma_f32 v[4:5], v[90:91], v[16:17], v[4:5] neg_lo:[0,0,1] neg_hi:[0,0,1]
	s_nop 0
	v_pk_mul_f32 v[140:141], v[50:51], v[4:5] op_sel_hi:[0,1]
	v_pk_mul_f32 v[4:5], v[90:91], v[78:79]
	s_nop 0
	v_pk_fma_f32 v[4:5], v[126:127], v[16:17], v[4:5]
	s_nop 0
	v_pk_mul_f32 v[90:91], v[50:51], v[4:5] op_sel_hi:[0,1]
	v_pk_mul_f32 v[4:5], v[124:125], v[80:81]
	v_cvt_pk_bf16_f32 v12, v90, v91
	v_pk_fma_f32 v[4:5], v[88:89], v[18:19], v[4:5] neg_lo:[0,0,1] neg_hi:[0,0,1]
	s_nop 0
	v_pk_mul_f32 v[126:127], v[50:51], v[4:5] op_sel_hi:[0,1]
	v_pk_mul_f32 v[4:5], v[88:89], v[80:81]
	s_nop 0
	v_pk_fma_f32 v[4:5], v[124:125], v[18:19], v[4:5]
	s_nop 0
	v_pk_mul_f32 v[88:89], v[50:51], v[4:5] op_sel_hi:[0,1]
	v_cvt_pk_bf16_f32 v4, v140, v141
	v_cvt_pk_bf16_f32 v5, v126, v127
	v_cvt_pk_bf16_f32 v13, v88, v89
	ds_write2_b64 v10, v[4:5], v[12:13] offset0:6 offset1:38
	global_load_dwordx4 v[16:19], v[76:77], off offset:128
	global_load_dwordx4 v[78:81], v[6:7], off offset:128
	v_accvgpr_read_b32 v12, a16
	v_accvgpr_read_b32 v5, a1
	v_accvgpr_read_b32 v13, a17
	v_accvgpr_read_b32 v4, a0
	s_waitcnt vmcnt(0)
	v_pk_mul_f32 v[60:61], v[12:13], v[78:79]
	s_nop 0
	v_pk_fma_f32 v[60:61], v[4:5], v[16:17], v[60:61] neg_lo:[0,0,1] neg_hi:[0,0,1]
	v_pk_mul_f32 v[4:5], v[4:5], v[78:79]
	v_pk_mul_f32 v[192:193], v[50:51], v[60:61] op_sel_hi:[0,1]
	v_pk_fma_f32 v[4:5], v[12:13], v[16:17], v[4:5]
	s_nop 0
	v_pk_mul_f32 v[124:125], v[50:51], v[4:5] op_sel_hi:[0,1]
	v_pk_mul_f32 v[4:5], v[138:139], v[80:81]
	v_pk_mul_f32 v[12:13], v[92:93], v[80:81]
	v_pk_fma_f32 v[4:5], v[92:93], v[18:19], v[4:5] neg_lo:[0,0,1] neg_hi:[0,0,1]
	v_pk_fma_f32 v[12:13], v[138:139], v[18:19], v[12:13]
	v_pk_mul_f32 v[4:5], v[50:51], v[4:5] op_sel_hi:[0,1]
	v_pk_mul_f32 v[92:93], v[50:51], v[12:13] op_sel_hi:[0,1]
	v_cvt_pk_bf16_f32 v12, v192, v193
	v_cvt_pk_bf16_f32 v13, v4, v5
	v_cvt_pk_bf16_f32 v16, v124, v125
	v_cvt_pk_bf16_f32 v17, v92, v93
	ds_write2_b64 v10, v[12:13], v[16:17] offset0:8 offset1:40
	global_load_dwordx4 v[16:19], v[76:77], off offset:160
	global_load_dwordx4 v[78:81], v[6:7], off offset:160
	s_waitcnt vmcnt(0)
	v_pk_mul_f32 v[12:13], v[122:123], v[78:79]
	s_nop 0
	v_pk_fma_f32 v[12:13], v[82:83], v[16:17], v[12:13] neg_lo:[0,0,1] neg_hi:[0,0,1]
	s_nop 0
	v_pk_mul_f32 v[138:139], v[50:51], v[12:13] op_sel_hi:[0,1]
	v_pk_mul_f32 v[12:13], v[82:83], v[78:79]
	s_nop 0
	v_pk_fma_f32 v[12:13], v[122:123], v[16:17], v[12:13]
	s_nop 0
	v_pk_mul_f32 v[86:87], v[50:51], v[12:13] op_sel_hi:[0,1]
	v_pk_mul_f32 v[12:13], v[116:117], v[80:81]
	v_cvt_pk_bf16_f32 v16, v86, v87
	v_pk_fma_f32 v[12:13], v[84:85], v[18:19], v[12:13] neg_lo:[0,0,1] neg_hi:[0,0,1]
	v_accvgpr_read_b32 v61, a39
	v_pk_mul_f32 v[122:123], v[50:51], v[12:13] op_sel_hi:[0,1]
	v_pk_mul_f32 v[12:13], v[84:85], v[80:81]
	v_accvgpr_read_b32 v60, a38
	v_pk_fma_f32 v[12:13], v[116:117], v[18:19], v[12:13]
	s_nop 0
	v_pk_mul_f32 v[84:85], v[50:51], v[12:13] op_sel_hi:[0,1]
	v_cvt_pk_bf16_f32 v12, v138, v139
	v_cvt_pk_bf16_f32 v13, v122, v123
	v_cvt_pk_bf16_f32 v17, v84, v85
	ds_write2_b64 v10, v[12:13], v[16:17] offset0:10 offset1:42
	global_load_dwordx4 v[16:19], v[76:77], off offset:192
	global_load_dwordx4 v[78:81], v[6:7], off offset:192
	s_waitcnt vmcnt(0)
	v_pk_mul_f32 v[12:13], v[102:103], v[78:79]
	s_nop 0
	v_pk_fma_f32 v[12:13], v[60:61], v[16:17], v[12:13] neg_lo:[0,0,1] neg_hi:[0,0,1]
	s_nop 0
	v_pk_mul_f32 v[116:117], v[50:51], v[12:13] op_sel_hi:[0,1]
	v_pk_mul_f32 v[12:13], v[60:61], v[78:79]
	s_nop 0
	v_pk_fma_f32 v[12:13], v[102:103], v[16:17], v[12:13]
	s_nop 0
	v_pk_mul_f32 v[82:83], v[50:51], v[12:13] op_sel_hi:[0,1]
	v_accvgpr_read_b32 v16, a36
	v_pk_mul_f32 v[12:13], v[8:9], v[80:81]
	v_accvgpr_read_b32 v17, a37
	v_pk_fma_f32 v[12:13], v[16:17], v[18:19], v[12:13] neg_lo:[0,0,1] neg_hi:[0,0,1]
	v_accvgpr_read_b32 v61, a13
	v_pk_mul_f32 v[102:103], v[50:51], v[12:13] op_sel_hi:[0,1]
	v_pk_mul_f32 v[12:13], v[16:17], v[80:81]
	v_accvgpr_read_b32 v60, a12
	v_pk_fma_f32 v[8:9], v[8:9], v[18:19], v[12:13]
	v_cvt_pk_bf16_f32 v12, v82, v83
	v_pk_mul_f32 v[74:75], v[50:51], v[8:9] op_sel_hi:[0,1]
	v_cvt_pk_bf16_f32 v8, v116, v117
	v_cvt_pk_bf16_f32 v9, v102, v103
	v_cvt_pk_bf16_f32 v13, v74, v75
	ds_write2_b64 v10, v[8:9], v[12:13] offset0:12 offset1:44
	global_load_dwordx4 v[16:19], v[76:77], off offset:224
	s_nop 0
	global_load_dwordx4 v[6:9], v[6:7], off offset:224
	s_waitcnt vmcnt(0)
	v_pk_mul_f32 v[12:13], v[56:57], v[6:7]
	v_pk_mul_f32 v[6:7], v[60:61], v[6:7]
	v_pk_fma_f32 v[12:13], v[60:61], v[16:17], v[12:13] neg_lo:[0,0,1] neg_hi:[0,0,1]
	v_pk_fma_f32 v[6:7], v[56:57], v[16:17], v[6:7]
	v_pk_mul_f32 v[80:81], v[50:51], v[12:13] op_sel_hi:[0,1]
	v_pk_mul_f32 v[56:57], v[50:51], v[6:7] op_sel_hi:[0,1]
	v_accvgpr_read_b32 v12, a14
	v_pk_mul_f32 v[6:7], v[46:47], v[8:9]
	v_accvgpr_read_b32 v13, a15
	v_pk_fma_f32 v[6:7], v[12:13], v[18:19], v[6:7] neg_lo:[0,0,1] neg_hi:[0,0,1]
	s_nop 0
	v_pk_mul_f32 v[78:79], v[50:51], v[6:7] op_sel_hi:[0,1]
	v_pk_mul_f32 v[6:7], v[12:13], v[8:9]
	v_cvt_pk_bf16_f32 v8, v56, v57
	v_pk_fma_f32 v[6:7], v[46:47], v[18:19], v[6:7]
	s_nop 0
	v_pk_mul_f32 v[46:47], v[50:51], v[6:7] op_sel_hi:[0,1]
	v_cvt_pk_bf16_f32 v6, v80, v81
	v_cvt_pk_bf16_f32 v7, v78, v79
	v_cvt_pk_bf16_f32 v9, v46, v47
	ds_write2_b64 v10, v[6:7], v[8:9] offset0:14 offset1:46
	s_and_b64 s[10:11], vcc, exec
	s_cselect_b32 s10, s36, 0x16100000
	s_add_u32 s12, s92, s10
	s_addc_u32 s13, s93, 0
	s_lshl_b64 s[10:11], s[40:41], 1
	s_add_u32 s12, s12, s10
	s_addc_u32 s11, s13, s11
	s_lshl_b32 s10, s4, 8
	s_lshl_b32 s13, s4, 9
	s_add_u32 s12, s12, s13
	s_addc_u32 s13, s11, 0
	s_mov_b32 s11, 0
	s_waitcnt lgkmcnt(0)
	s_barrier
	s_nop 0
	v_mbcnt_lo_u32_b32 v6, -1, s11
	v_mbcnt_hi_u32_b32 v6, -1, v6
	v_or_b32_e32 v8, s60, v6
	v_lshlrev_b32_e32 v6, 4, v6
	v_and_b32_e32 v94, 0x1f0, v6
	v_lshl_add_u64 v[6:7], s[12:13], 0, v[94:95]

.LBB0_249:
	v_readlane_b32 s64, v255, 45
	v_readlane_b32 s65, v255, 46
	v_readlane_b32 s0, v255, 47
	v_readlane_b32 s1, v255, 63
	s_and_b32 s0, s0, 0xff
	s_cmp_eq_u32 s0, 7
	s_cselect_b32 s0, 1, 0
	s_cmp_lt_u32 s1, 3
	s_cselect_b32 s0, s0, 0
	s_add_i32 s1, s1, 1
	s_cmp_eq_u32 s0, 1
	s_cselect_b32 s1, s1, 0
	s_nop 0
	v_writelane_b32 v255, s1, 63
	s_xor_b32 s0, s0, 1
	s_add_i32 s64, s64, s0
	v_readlane_b32 s30, v255, 17
	v_readlane_b32 s40, v255, 19
	v_readlane_b32 s66, v255, 21
	v_readlane_b32 s68, v255, 23
	v_readlane_b32 s70, v255, 25
	v_readlane_b32 s76, v255, 27
	v_readlane_b32 s78, v255, 29
	v_readlane_b32 s80, v255, 31
	v_readlane_b32 s82, v255, 33
	v_readlane_b32 s84, v255, 35
	v_readlane_b32 s86, v255, 37
	v_readlane_b32 s88, v255, 39
	v_readlane_b32 s90, v255, 41
	v_readlane_b32 s92, v255, 43
	s_cmp_ge_i32 s64, s65
	s_mov_b64 s[0:1], -1
	v_readlane_b32 s31, v255, 18
	v_readlane_b32 s41, v255, 20
	v_readlane_b32 s67, v255, 22
	v_readlane_b32 s69, v255, 24
	v_readlane_b32 s71, v255, 26
	v_readlane_b32 s77, v255, 28
	v_readlane_b32 s79, v255, 30
	v_readlane_b32 s81, v255, 32
	v_readlane_b32 s83, v255, 34
	v_readlane_b32 s85, v255, 36
	v_readlane_b32 s87, v255, 38
	v_readlane_b32 s89, v255, 40
	v_readlane_b32 s91, v255, 42
	v_readlane_b32 s93, v255, 44
	s_cbranch_scc0 .LBB0_250
	s_getpc_b64 s[98:99]
